# flat->global everywhere; EpiRes epilogue (3 non-last instances): all 16 residual loads issued up front with counted vmcnt, batched ssq reduce
# speedup vs baseline: 1.0050x; 1.0050x over previous
.LBB0_4:
	s_waitcnt vmcnt(0) lgkmcnt(0)
	v_or_b32_e32 v2, s43, v42
	v_add_u32_e32 v2, s68, v2
	v_ashrrev_i32_e32 v5, 31, v2
	v_mad_u64_u32 v[2:3], s[48:49], v2, s42, 0
	v_mov_b32_e32 v4, v3
	v_mad_u64_u32 v[4:5], s[48:49], v5, s42, v[4:5]
	v_mov_b32_e32 v3, v4
	v_lshl_add_u64 v[2:3], v[2:3], 1, s[44:45]
	v_lshl_add_u64 v[2:3], s[46:47], 1, v[2:3]
	v_lshlrev_b32_e32 v44, 1, v40
	s_mov_b32 s43, s41
	v_lshl_add_u64 v[6:7], v[2:3], 0, v[44:45]
	v_cvt_pk_bf16_f32 v2, v62, v68
	v_cvt_pk_bf16_f32 v3, v72, v76
	v_cvt_pk_bf16_f32 v4, v64, v70
	v_cvt_pk_bf16_f32 v5, v74, v30
	v_lshl_add_u64 v[8:9], s[42:43], 1, v[6:7]
	s_lshl_b32 s40, s42, 2
	global_store_dwordx4 v[6:7], v[2:5], off nt
	s_add_i32 s64, s64, s12
	s_add_i32 s66, s66, s12
	v_cvt_pk_bf16_f32 v2, v63, v69
	v_cvt_pk_bf16_f32 v3, v73, v77
	v_cvt_pk_bf16_f32 v4, v65, v71
	v_cvt_pk_bf16_f32 v5, v75, v31
	global_store_dwordx4 v[8:9], v[2:5], off nt
	v_lshl_add_u64 v[8:9], v[6:7], 0, s[40:41]
	s_mul_i32 s40, s42, 3
	v_lshl_add_u64 v[6:7], s[40:41], 1, v[6:7]
	s_add_i32 s40, s64, 0x12000
	v_cvt_pk_bf16_f32 v2, v50, v54
	v_cvt_pk_bf16_f32 v3, v58, v66
	v_cvt_pk_bf16_f32 v4, v52, v56
	v_cvt_pk_bf16_f32 v5, v60, v32
	s_cmp_gt_i32 s40, 0x177ff
	global_store_dwordx4 v[8:9], v[2:5], off nt
	s_nop 1
	v_cvt_pk_bf16_f32 v2, v51, v55
	v_cvt_pk_bf16_f32 v3, v59, v67
	v_cvt_pk_bf16_f32 v4, v53, v57
	v_cvt_pk_bf16_f32 v5, v61, v33
	global_store_dwordx4 v[6:7], v[2:5], off nt
	s_cbranch_scc1 .LBB0_40

.LBB0_35:
	s_lshl_b32 s46, s46, 6
	v_or_b32_e32 v2, s46, v40
	s_ashr_i32 s47, s46, 31
	s_mul_i32 s55, s47, s40
	v_mad_u64_u32 v[2:3], s[52:53], v2, s40, 0
	v_add_u32_e32 v3, s55, v3
	v_lshl_add_u64 v[2:3], v[2:3], 2, s[48:49]
	s_ashr_i32 s55, s54, 31
	v_lshl_add_u64 v[2:3], s[54:55], 2, v[2:3]
	v_lshl_add_u64 v[2:3], v[2:3], 0, v[46:47]
	s_lshl_b64 s[48:49], s[40:41], 2
	v_lshl_add_u64 v[4:5], v[2:3], 0, s[48:49]
	global_load_dwordx4 v[26:29], v[2:3], off nt
	global_load_dwordx4 v[18:21], v[4:5], off nt
	v_lshl_add_u64 v[2:3], v[4:5], 0, s[48:49]
	v_lshl_add_u64 v[4:5], v[2:3], 0, s[48:49]
	global_load_dwordx4 v[22:25], v[2:3], off nt
	global_load_dwordx4 v[10:13], v[4:5], off nt
	v_lshl_add_u64 v[2:3], v[4:5], 0, s[48:49]
	v_lshl_add_u64 v[6:7], v[2:3], 0, s[48:49]
	global_load_dwordx4 v[14:17], v[2:3], off nt
	s_nop 0
	global_load_dwordx4 v[2:5], v[6:7], off nt
	v_lshl_add_u64 v[6:7], v[6:7], 0, s[48:49]
	v_lshl_add_u64 v[30:31], v[6:7], 0, s[48:49]
	global_load_dwordx4 v[6:9], v[6:7], off nt
	s_nop 0
	global_load_dwordx4 v[34:37], v[30:31], off nt
	s_cmp_lg_u64 s[50:51], 0
	s_cbranch_scc0 .LBB0_37
	s_lshl_b64 s[48:49], s[46:47], 2
	s_add_u32 s48, s50, s48
	s_addc_u32 s49, s51, s49
	v_mov_b32_e32 v49, v45
	v_lshl_add_u64 v[50:51], s[48:49], 0, v[48:49]
	global_load_dwordx4 v[30:33], v[50:51], off
	global_load_dwordx4 v[74:77], v[50:51], off offset:16
	s_waitcnt vmcnt(0) lgkmcnt(0)
	v_pk_mul_f32 v[50:51], v[28:29], v[30:31] op_sel_hi:[1,0]
	v_pk_mul_f32 v[62:63], v[26:27], v[30:31] op_sel_hi:[1,0]
	v_pk_mul_f32 v[54:55], v[20:21], v[30:31] op_sel:[0,1]
	v_pk_mul_f32 v[68:69], v[18:19], v[30:31] op_sel:[0,1]
	v_mov_b32_e32 v30, v33
	v_mov_b32_e32 v44, v77
	v_pk_mul_f32 v[52:53], v[16:17], v[74:75] op_sel_hi:[1,0]
	v_pk_mul_f32 v[64:65], v[14:15], v[74:75] op_sel_hi:[1,0]
	v_pk_mul_f32 v[56:57], v[4:5], v[74:75] op_sel:[0,1]
	v_pk_mul_f32 v[70:71], v[2:3], v[74:75] op_sel:[0,1]
	v_pk_mul_f32 v[58:59], v[24:25], v[32:33] op_sel_hi:[1,0]
	v_pk_mul_f32 v[72:73], v[22:23], v[32:33] op_sel_hi:[1,0]
	v_pk_mul_f32 v[60:61], v[8:9], v[76:77] op_sel_hi:[1,0]
	v_pk_mul_f32 v[74:75], v[6:7], v[76:77] op_sel_hi:[1,0]
	v_pk_mul_f32 v[66:67], v[12:13], v[30:31] op_sel_hi:[1,0]
	v_pk_mul_f32 v[76:77], v[10:11], v[30:31] op_sel_hi:[1,0]
	v_pk_mul_f32 v[32:33], v[36:37], v[44:45] op_sel_hi:[1,0]
	v_pk_mul_f32 v[30:31], v[34:35], v[44:45] op_sel_hi:[1,0]
	s_cbranch_execnz .LBB0_4
	s_branch .LBB0_38

.LBB0_47:
	s_lshl_b64 s[24:25], s[28:29], 13
	s_add_u32 s24, s26, s24
	s_addc_u32 s25, s27, s25
	v_lshl_add_u64 v[36:37], s[24:25], 0, v[38:39]
	s_waitcnt lgkmcnt(0)
	global_load_dwordx4 v[20:23], v[36:37], off nt
	global_load_dwordx4 v[24:27], v[36:37], off offset:16 nt
	v_lshl_add_u64 v[28:29], s[8:9], 0, v[4:5]
	v_add_co_u32_e32 v56, vcc, s1, v28
	s_waitcnt vmcnt(0) lgkmcnt(0)
	v_cvt_pk_bf16_f32 v28, v20, v21
	s_nop 0
	v_addc_co_u32_e32 v57, vcc, 0, v29, vcc
	v_cvt_pk_bf16_f32 v29, v22, v23
	v_cvt_pk_bf16_f32 v30, v24, v25
	v_cvt_pk_bf16_f32 v31, v26, v27
	global_store_dwordx4 v[56:57], v[28:31], off
	global_load_dwordx4 v[28:31], v[36:37], off offset:2048 nt
	s_nop 0
	global_load_dwordx4 v[32:35], v[36:37], off offset:2064 nt
	v_lshl_add_u64 v[36:37], s[24:25], 0, v[6:7]
	v_mul_f32_e32 v24, v24, v24
	v_mul_f32_e32 v25, v25, v25
	v_mul_f32_e32 v26, v26, v26
	v_fmac_f32_e32 v24, v20, v20
	v_fmac_f32_e32 v25, v21, v21
	v_mul_f32_e32 v27, v27, v27
	v_fmac_f32_e32 v26, v22, v22
	v_add_f32_e32 v20, v24, v25
	v_fmac_f32_e32 v27, v23, v23
	v_add_f32_e32 v20, v26, v20
	v_add_f32_e32 v20, v27, v20
	v_cmp_lt_i32_e32 vcc, v13, v12
	s_waitcnt vmcnt(0) lgkmcnt(0)
	v_cvt_pk_bf16_f32 v40, v28, v29
	v_cvt_pk_bf16_f32 v41, v30, v31
	v_cvt_pk_bf16_f32 v42, v32, v33
	v_cvt_pk_bf16_f32 v43, v34, v35
	global_store_dwordx4 v[56:57], v[40:43], off offset:1024
	global_load_dwordx4 v[40:43], v[36:37], off nt
	s_nop 0
	global_load_dwordx4 v[44:47], v[36:37], off offset:16 nt
	v_lshl_add_u64 v[36:37], s[24:25], 0, v[8:9]
	v_mul_f32_e32 v21, v32, v32
	v_mul_f32_e32 v22, v33, v33
	v_fmac_f32_e32 v21, v28, v28
	v_mul_f32_e32 v23, v34, v34
	v_fmac_f32_e32 v22, v29, v29
	v_add_f32_e32 v20, v20, v21
	v_mul_f32_e32 v24, v35, v35
	v_fmac_f32_e32 v23, v30, v30
	v_add_f32_e32 v20, v22, v20
	v_fmac_f32_e32 v24, v31, v31
	v_add_f32_e32 v20, v23, v20
	v_add_f32_e32 v20, v24, v20
	v_cndmask_b32_e32 v19, v11, v13, vcc
	v_lshlrev_b32_e32 v19, 2, v19
	v_cmp_lt_i32_e32 vcc, v14, v12
	s_waitcnt vmcnt(0) lgkmcnt(0)
	v_cvt_pk_bf16_f32 v48, v40, v41
	v_cvt_pk_bf16_f32 v49, v42, v43
	v_cvt_pk_bf16_f32 v50, v44, v45
	v_cvt_pk_bf16_f32 v51, v46, v47
	global_store_dwordx4 v[56:57], v[48:51], off offset:2048
	global_load_dwordx4 v[48:51], v[36:37], off offset:16 nt
	s_nop 0
	global_load_dwordx4 v[52:55], v[36:37], off nt
	v_mul_f32_e32 v21, v44, v44
	v_mul_f32_e32 v22, v45, v45
	v_fmac_f32_e32 v21, v40, v40
	v_mul_f32_e32 v23, v46, v46
	v_fmac_f32_e32 v22, v41, v41
	v_add_f32_e32 v20, v20, v21
	v_mul_f32_e32 v24, v47, v47
	v_fmac_f32_e32 v23, v42, v42
	v_add_f32_e32 v20, v22, v20
	v_fmac_f32_e32 v24, v43, v43
	v_add_f32_e32 v20, v23, v20
	v_add_f32_e32 v20, v24, v20
	s_waitcnt vmcnt(0) lgkmcnt(0)
	v_mul_f32_e32 v21, v48, v48
	v_mul_f32_e32 v22, v49, v49
	v_fmac_f32_e32 v21, v52, v52
	v_mul_f32_e32 v23, v50, v50
	v_fmac_f32_e32 v22, v53, v53
	v_add_f32_e32 v20, v20, v21
	v_mul_f32_e32 v24, v51, v51
	v_fmac_f32_e32 v23, v54, v54
	v_add_f32_e32 v20, v22, v20
	v_fmac_f32_e32 v24, v55, v55
	v_add_f32_e32 v20, v23, v20
	v_add_f32_e32 v20, v24, v20
	ds_bpermute_b32 v19, v19, v20
	v_cndmask_b32_e32 v21, v11, v14, vcc
	v_lshlrev_b32_e32 v21, 2, v21
	v_cmp_lt_i32_e32 vcc, v15, v12
	v_cvt_pk_bf16_f32 v22, v52, v53
	s_waitcnt lgkmcnt(0)
	v_add_f32_e32 v19, v20, v19
	ds_bpermute_b32 v20, v21, v19
	v_cndmask_b32_e32 v21, v11, v15, vcc
	v_lshlrev_b32_e32 v21, 2, v21
	v_cmp_lt_i32_e32 vcc, v16, v12
	v_cvt_pk_bf16_f32 v23, v54, v55
	s_waitcnt lgkmcnt(0)
	v_add_f32_e32 v19, v19, v20
	ds_bpermute_b32 v20, v21, v19
	v_cndmask_b32_e32 v21, v11, v16, vcc
	v_lshlrev_b32_e32 v21, 2, v21
	v_cmp_lt_i32_e32 vcc, v17, v12
	v_cvt_pk_bf16_f32 v24, v48, v49
	s_waitcnt lgkmcnt(0)
	v_add_f32_e32 v19, v19, v20
	ds_bpermute_b32 v20, v21, v19
	v_cndmask_b32_e32 v21, v11, v17, vcc
	v_lshlrev_b32_e32 v21, 2, v21
	v_cmp_lt_i32_e32 vcc, v18, v12
	v_cvt_pk_bf16_f32 v25, v50, v51
	s_waitcnt lgkmcnt(0)
	v_add_f32_e32 v19, v19, v20
	ds_bpermute_b32 v20, v21, v19
	v_cndmask_b32_e32 v21, v11, v18, vcc
	global_store_dwordx4 v[56:57], v[22:25], off offset:3072
	s_waitcnt lgkmcnt(0)
	v_add_f32_e32 v19, v19, v20
	v_lshlrev_b32_e32 v20, 2, v21
	ds_bpermute_b32 v20, v20, v19
	s_and_saveexec_b64 s[24:25], s[2:3]
	s_cbranch_execz .LBB0_42
	s_waitcnt lgkmcnt(0)
	v_add_f32_e32 v19, v19, v20
	v_cndmask_b32_e64 v19, 0, v19, s[4:5]
	v_lshl_add_u64 v[20:21], s[8:9], 0, v[2:3]
	global_store_dword v[20:21], v19, off
	s_branch .LBB0_42

.LBB0_53:
	v_add_u32_e32 v8, -2, v8
	v_ashrrev_i32_e32 v13, 31, v5
	v_mov_b32_e32 v12, v5
	v_ashrrev_i32_e32 v15, 31, v4
	v_mov_b32_e32 v14, v4
	v_cmp_eq_u32_e32 vcc, 0, v8
	v_add_u32_e32 v5, 0x400, v5
	v_add_u32_e32 v4, 0x400, v4
	v_lshl_add_u64 v[14:15], v[14:15], 2, s[8:9]
	v_lshl_add_u64 v[12:13], v[12:13], 2, s[8:9]
	s_or_b64 s[10:11], vcc, s[10:11]
	global_store_dword v[14:15], v7, off
	global_store_dword v[12:13], v7, off
	s_andn2_b64 exec, exec, s[10:11]
	s_cbranch_execnz .LBB0_53
	s_or_b64 exec, exec, s[10:11]
	v_cmp_ne_u32_e32 vcc, v1, v6
	v_lshl_add_u32 v2, v6, 9, v2
	s_orn2_b64 s[10:11], vcc, exec

.LBB0_57:
	v_add_u32_e32 v1, 0x200, v1
	v_cmp_lt_i32_e32 vcc, s0, v1
	global_store_dword v[2:3], v4, off
	s_or_b64 s[4:5], vcc, s[4:5]
	v_lshl_add_u64 v[2:3], v[2:3], 0, s[8:9]
	s_andn2_b64 exec, exec, s[4:5]
	s_cbranch_execnz .LBB0_57

.LBB0_97:
	s_add_u32 s22, s22, s20
	s_addc_u32 s23, s23, s21
	s_add_u32 s24, s0, s22
	s_addc_u32 s25, s1, s23
	v_cmp_gt_i64_e32 vcc, s[24:25], v[242:243]
	s_mov_b64 s[24:25], -1
	s_cbranch_vccnz .LBB0_84
	v_lshl_add_u32 v4, s19, 8, v2
	v_ashrrev_i32_e32 v5, 31, v4
	v_lshl_add_u32 v6, s27, 8, v2
	v_lshlrev_b64 v[4:5], 7, v[4:5]
	v_ashrrev_i32_e32 v7, 31, v6
	v_lshl_add_u64 v[4:5], v[0:1], 0, v[4:5]
	v_lshlrev_b64 v[6:7], 7, v[6:7]
	v_lshl_add_u64 v[6:7], v[0:1], 0, v[6:7]
	global_load_dwordx4 v[10:13], v[4:5], off
	global_load_dwordx4 v[14:17], v[4:5], off offset:16
	global_load_dwordx4 v[18:21], v[4:5], off offset:32
	global_load_dwordx4 v[22:25], v[4:5], off offset:48
	global_load_dwordx4 v[26:29], v[6:7], off
	global_load_dwordx4 v[30:33], v[6:7], off offset:16
	global_load_dwordx4 v[34:37], v[6:7], off offset:32
	global_load_dwordx4 v[38:41], v[6:7], off offset:48
	v_mov_b32_e32 v5, v129
	v_mov_b32_e32 v4, v129
	s_waitcnt vmcnt(0) lgkmcnt(0)
	v_pk_add_f32 v[6:7], v[12:13], v[16:17]
	v_pk_add_f32 v[10:11], v[10:11], v[14:15]
	v_pk_add_f32 v[12:13], v[20:21], v[24:25]
	v_pk_add_f32 v[14:15], v[18:19], v[22:23]
	v_pk_add_f32 v[16:17], v[28:29], v[32:33]
	v_pk_add_f32 v[18:19], v[26:27], v[30:31]
	v_pk_add_f32 v[20:21], v[36:37], v[40:41]
	v_pk_add_f32 v[22:23], v[34:35], v[38:39]
	v_pk_add_f32 v[6:7], v[6:7], v[12:13]
	v_pk_add_f32 v[10:11], v[10:11], v[14:15]
	v_pk_add_f32 v[12:13], v[16:17], v[20:21]
	v_pk_add_f32 v[14:15], v[18:19], v[22:23]
	v_add_f32_e32 v9, v10, v11
	v_add_f32_e32 v6, v6, v7
	v_add_f32_e32 v10, v14, v15
	v_add_f32_e32 v11, v12, v13
	v_add_f32_e32 v7, v9, v6
	v_add_f32_e32 v6, v10, v11
	s_nop 0
	v_mov_b32_dpp v5, v7 quad_perm:[1,0,3,2] row_mask:0xf bank_mask:0xf
	v_mov_b32_dpp v4, v6 quad_perm:[1,0,3,2] row_mask:0xf bank_mask:0xf
	s_and_saveexec_b64 s[24:25], s[2:3]
	s_cbranch_execz .LBB0_83
	v_add_f32_e32 v5, v7, v5
	v_fmamk_f32 v5, v5, 0x3a000000, v190
	v_mul_f32_e32 v7, 0x4b800000, v5
	v_cmp_gt_f32_e32 vcc, s70, v5
	s_nop 1
	v_cndmask_b32_e32 v5, v5, v7, vcc
	v_rsq_f32_e32 v5, v5
	s_nop 0
	v_mul_f32_e32 v7, 0x45800000, v5
	v_cndmask_b32_e32 v5, v5, v7, vcc
	s_andn2_b64 vcc, exec, s[4:5]
	ds_write_b32 v3, v5
	s_cbranch_vccnz .LBB0_83
	v_add_f32_e32 v4, v6, v4
	v_fmamk_f32 v4, v4, 0x3a000000, v190
	v_mul_f32_e32 v5, 0x4b800000, v4
	v_cmp_gt_f32_e32 vcc, s70, v4
	s_nop 1
	v_cndmask_b32_e32 v4, v4, v5, vcc
	v_rsq_f32_e32 v4, v4
	s_nop 0
	v_mul_f32_e32 v5, 0x45800000, v4
	v_cndmask_b32_e32 v4, v4, v5, vcc
	ds_write_b32 v3, v4 offset:1024
	s_branch .LBB0_83

.LBB0_115:
	s_add_u32 s36, s49, 0xffffff00
	v_lshl_add_u32 v142, s47, 10, v150
	s_addc_u32 s37, s50, -1
	v_lshl_add_u32 v156, s16, 8, v148
	ds_read2_b32 v[158:159], v142 offset1:16
	ds_read2_b32 v[160:161], v142 offset0:32 offset1:48
	ds_read2_b32 v[146:147], v142 offset0:128 offset1:144
	ds_read2_b32 v[144:145], v142 offset0:160 offset1:176
	s_lshl_b32 s27, s18, 9
	s_and_b32 s94, s27, 0xe00
	v_ashrrev_i32_e32 v157, 31, v156
	v_lshl_add_u64 v[162:163], v[136:137], 0, s[94:95]
	v_lshlrev_b64 v[142:143], 12, v[156:157]
	s_waitcnt lgkmcnt(0)
	v_pk_mul_f32 v[152:153], v[124:125], v[158:159] op_sel_hi:[1,0]
	v_lshl_add_u64 v[142:143], v[162:163], 0, v[142:143]
	v_pk_mul_f32 v[154:155], v[126:127], v[158:159] op_sel_hi:[1,0]
	v_cvt_pk_bf16_f32 v152, v152, v153
	v_pk_mul_f32 v[164:165], v[122:123], v[158:159] op_sel_hi:[1,0]
	v_cvt_pk_bf16_f32 v153, v154, v155
	v_pk_mul_f32 v[166:167], v[120:121], v[158:159] op_sel_hi:[1,0]
	s_mov_b64 s[38:39], 0x90000
	v_cvt_pk_bf16_f32 v154, v166, v167
	v_cvt_pk_bf16_f32 v155, v164, v165
	global_store_dwordx4 v[142:143], v[152:155], off
	v_pk_mul_f32 v[164:165], v[90:91], v[158:159] op_sel_hi:[1,0]
	v_pk_mul_f32 v[166:167], v[88:89], v[158:159] op_sel_hi:[1,0]
	v_pk_mul_f32 v[152:153], v[92:93], v[158:159] op_sel_hi:[1,0]
	v_pk_mul_f32 v[154:155], v[94:95], v[158:159] op_sel_hi:[1,0]
	v_cvt_pk_bf16_f32 v152, v152, v153
	v_mov_b32_e32 v158, v159
	v_cvt_pk_bf16_f32 v153, v154, v155
	v_cvt_pk_bf16_f32 v154, v166, v167
	v_cvt_pk_bf16_f32 v155, v164, v165
	global_store_dwordx4 v[142:143], v[152:155], off offset:256
	v_pk_mul_f32 v[166:167], v[114:115], v[158:159] op_sel_hi:[1,0]
	v_pk_mul_f32 v[168:169], v[112:113], v[158:159] op_sel_hi:[1,0]
	v_or_b32_e32 v152, 16, v156
	v_ashrrev_i32_e32 v153, 31, v152
	v_lshlrev_b64 v[152:153], 12, v[152:153]
	v_lshl_add_u64 v[164:165], v[162:163], 0, v[152:153]
	v_pk_mul_f32 v[152:153], v[116:117], v[158:159] op_sel_hi:[1,0]
	v_pk_mul_f32 v[154:155], v[118:119], v[158:159] op_sel_hi:[1,0]
	v_cvt_pk_bf16_f32 v152, v152, v153
	s_nop 0
	v_cvt_pk_bf16_f32 v153, v154, v155
	v_cvt_pk_bf16_f32 v154, v168, v169
	v_cvt_pk_bf16_f32 v155, v166, v167
	global_store_dwordx4 v[164:165], v[152:155], off
	v_pk_mul_f32 v[166:167], v[82:83], v[158:159] op_sel_hi:[1,0]
	s_nop 0
	v_pk_mul_f32 v[152:153], v[84:85], v[158:159] op_sel_hi:[1,0]
	v_pk_mul_f32 v[154:155], v[86:87], v[158:159] op_sel_hi:[1,0]
	v_cvt_pk_bf16_f32 v152, v152, v153
	v_pk_mul_f32 v[158:159], v[80:81], v[158:159] op_sel_hi:[1,0]
	v_cvt_pk_bf16_f32 v153, v154, v155
	s_nop 0
	v_cvt_pk_bf16_f32 v154, v158, v159
	v_cvt_pk_bf16_f32 v155, v166, v167
	global_store_dwordx4 v[164:165], v[152:155], off offset:256
	v_pk_mul_f32 v[164:165], v[106:107], v[160:161] op_sel_hi:[1,0]
	v_pk_mul_f32 v[166:167], v[104:105], v[160:161] op_sel_hi:[1,0]
	v_or_b32_e32 v152, 32, v156
	v_ashrrev_i32_e32 v153, 31, v152
	v_lshlrev_b64 v[152:153], 12, v[152:153]
	v_lshl_add_u64 v[158:159], v[162:163], 0, v[152:153]
	v_pk_mul_f32 v[152:153], v[108:109], v[160:161] op_sel_hi:[1,0]
	v_pk_mul_f32 v[154:155], v[110:111], v[160:161] op_sel_hi:[1,0]
	v_cvt_pk_bf16_f32 v152, v152, v153
	s_nop 0
	v_cvt_pk_bf16_f32 v153, v154, v155
	v_cvt_pk_bf16_f32 v154, v166, v167
	v_cvt_pk_bf16_f32 v155, v164, v165
	global_store_dwordx4 v[158:159], v[152:155], off
	v_pk_mul_f32 v[164:165], v[74:75], v[160:161] op_sel_hi:[1,0]
	v_pk_mul_f32 v[166:167], v[72:73], v[160:161] op_sel_hi:[1,0]
	v_pk_mul_f32 v[152:153], v[76:77], v[160:161] op_sel_hi:[1,0]
	v_pk_mul_f32 v[154:155], v[78:79], v[160:161] op_sel_hi:[1,0]
	v_cvt_pk_bf16_f32 v152, v152, v153
	s_nop 0
	v_cvt_pk_bf16_f32 v153, v154, v155
	v_cvt_pk_bf16_f32 v154, v166, v167
	v_cvt_pk_bf16_f32 v155, v164, v165
	global_store_dwordx4 v[158:159], v[152:155], off offset:256
	v_mov_b32_e32 v158, v161
	v_pk_mul_f32 v[160:161], v[98:99], v[158:159] op_sel_hi:[1,0]
	v_or_b32_e32 v152, 48, v156
	v_ashrrev_i32_e32 v153, 31, v152
	v_lshlrev_b64 v[152:153], 12, v[152:153]
	v_lshl_add_u64 v[156:157], v[162:163], 0, v[152:153]
	v_pk_mul_f32 v[154:155], v[102:103], v[158:159] op_sel_hi:[1,0]
	v_pk_mul_f32 v[152:153], v[100:101], v[158:159] op_sel_hi:[1,0]
	v_pk_mul_f32 v[162:163], v[96:97], v[158:159] op_sel_hi:[1,0]
	v_cvt_pk_bf16_f32 v152, v152, v153
	v_cvt_pk_bf16_f32 v153, v154, v155
	s_nop 0
	v_cvt_pk_bf16_f32 v154, v162, v163
	v_cvt_pk_bf16_f32 v155, v160, v161
	global_store_dwordx4 v[156:157], v[152:155], off
	v_pk_mul_f32 v[160:161], v[66:67], v[158:159] op_sel_hi:[1,0]
	s_nop 0
	v_pk_mul_f32 v[154:155], v[70:71], v[158:159] op_sel_hi:[1,0]
	v_pk_mul_f32 v[152:153], v[68:69], v[158:159] op_sel_hi:[1,0]
	v_pk_mul_f32 v[158:159], v[64:65], v[158:159] op_sel_hi:[1,0]
	v_cvt_pk_bf16_f32 v152, v152, v153
	v_cvt_pk_bf16_f32 v153, v154, v155
	s_nop 0
	v_cvt_pk_bf16_f32 v154, v158, v159
	v_cvt_pk_bf16_f32 v155, v160, v161
	global_store_dwordx4 v[156:157], v[152:155], off offset:256
	v_pk_mul_f32 v[158:159], v[58:59], v[146:147] op_sel_hi:[1,0]
	v_pk_mul_f32 v[160:161], v[56:57], v[146:147] op_sel_hi:[1,0]
	v_pk_mul_f32 v[154:155], v[62:63], v[146:147] op_sel_hi:[1,0]
	v_pk_mul_f32 v[152:153], v[60:61], v[146:147] op_sel_hi:[1,0]
	v_lshl_add_u64 v[156:157], v[142:143], 0, s[76:77]
	v_cvt_pk_bf16_f32 v152, v152, v153
	v_cvt_pk_bf16_f32 v153, v154, v155
	v_cvt_pk_bf16_f32 v154, v160, v161
	v_cvt_pk_bf16_f32 v155, v158, v159
	v_add_co_u32_e32 v158, vcc, s72, v142
	v_pk_mul_f32 v[160:161], v[24:25], v[146:147] op_sel_hi:[1,0]
	s_nop 0
	v_addc_co_u32_e32 v159, vcc, 0, v143, vcc
	global_store_dwordx4 v[158:159], v[152:155], off
	v_pk_mul_f32 v[158:159], v[26:27], v[146:147] op_sel_hi:[1,0]
	s_nop 0
	v_pk_mul_f32 v[154:155], v[30:31], v[146:147] op_sel_hi:[1,0]
	v_pk_mul_f32 v[152:153], v[28:29], v[146:147] op_sel_hi:[1,0]
	v_mov_b32_e32 v146, v147
	v_cvt_pk_bf16_f32 v152, v152, v153
	v_cvt_pk_bf16_f32 v153, v154, v155
	v_cvt_pk_bf16_f32 v154, v160, v161
	v_cvt_pk_bf16_f32 v155, v158, v159
	global_store_dwordx4 v[156:157], v[152:155], off offset:256
	v_pk_mul_f32 v[158:159], v[50:51], v[146:147] op_sel_hi:[1,0]
	v_pk_mul_f32 v[160:161], v[48:49], v[146:147] op_sel_hi:[1,0]
	v_pk_mul_f32 v[154:155], v[54:55], v[146:147] op_sel_hi:[1,0]
	v_pk_mul_f32 v[152:153], v[52:53], v[146:147] op_sel_hi:[1,0]
	v_lshl_add_u64 v[156:157], v[142:143], 0, s[38:39]
	v_cvt_pk_bf16_f32 v152, v152, v153
	v_cvt_pk_bf16_f32 v153, v154, v155
	v_cvt_pk_bf16_f32 v154, v160, v161
	v_cvt_pk_bf16_f32 v155, v158, v159
	v_add_co_u32_e32 v158, vcc, s81, v142
	s_mov_b64 s[38:39], 0xa0000
	s_nop 0
	v_addc_co_u32_e32 v159, vcc, 0, v143, vcc
	global_store_dwordx4 v[158:159], v[152:155], off
	v_pk_mul_f32 v[158:159], v[18:19], v[146:147] op_sel_hi:[1,0]
	s_nop 0
	v_pk_mul_f32 v[154:155], v[22:23], v[146:147] op_sel_hi:[1,0]
	v_pk_mul_f32 v[152:153], v[20:21], v[146:147] op_sel_hi:[1,0]
	v_pk_mul_f32 v[146:147], v[16:17], v[146:147] op_sel_hi:[1,0]
	v_cvt_pk_bf16_f32 v152, v152, v153
	v_cvt_pk_bf16_f32 v153, v154, v155
	s_nop 0
	v_cvt_pk_bf16_f32 v154, v146, v147
	v_cvt_pk_bf16_f32 v155, v158, v159
	global_store_dwordx4 v[156:157], v[152:155], off offset:256
	v_pk_mul_f32 v[156:157], v[42:43], v[144:145] op_sel_hi:[1,0]
	v_pk_mul_f32 v[158:159], v[40:41], v[144:145] op_sel_hi:[1,0]
	v_pk_mul_f32 v[154:155], v[46:47], v[144:145] op_sel_hi:[1,0]
	v_pk_mul_f32 v[152:153], v[44:45], v[144:145] op_sel_hi:[1,0]
	v_lshl_add_u64 v[146:147], v[142:143], 0, s[38:39]
	v_cvt_pk_bf16_f32 v152, v152, v153
	v_cvt_pk_bf16_f32 v153, v154, v155
	v_cvt_pk_bf16_f32 v154, v158, v159
	v_cvt_pk_bf16_f32 v155, v156, v157
	v_add_co_u32_e32 v156, vcc, s82, v142
	v_pk_mul_f32 v[158:159], v[8:9], v[144:145] op_sel_hi:[1,0]
	s_nop 0
	v_addc_co_u32_e32 v157, vcc, 0, v143, vcc
	global_store_dwordx4 v[156:157], v[152:155], off
	v_pk_mul_f32 v[156:157], v[10:11], v[144:145] op_sel_hi:[1,0]
	s_mov_b64 s[38:39], 0xb0000
	v_pk_mul_f32 v[154:155], v[14:15], v[144:145] op_sel_hi:[1,0]
	v_pk_mul_f32 v[152:153], v[12:13], v[144:145] op_sel_hi:[1,0]
	s_nop 0
	v_cvt_pk_bf16_f32 v152, v152, v153
	v_cvt_pk_bf16_f32 v153, v154, v155
	v_cvt_pk_bf16_f32 v154, v158, v159
	v_cvt_pk_bf16_f32 v155, v156, v157
	global_store_dwordx4 v[146:147], v[152:155], off offset:256
	s_nop 1
	v_mov_b32_e32 v154, v145
	v_lshl_add_u64 v[152:153], v[142:143], 0, s[38:39]
	v_pk_mul_f32 v[144:145], v[36:37], v[154:155] op_sel_hi:[1,0]
	v_add_co_u32_e32 v142, vcc, s83, v142
	v_pk_mul_f32 v[146:147], v[38:39], v[154:155] op_sel_hi:[1,0]
	v_cvt_pk_bf16_f32 v144, v144, v145
	s_nop 0
	v_addc_co_u32_e32 v143, vcc, 0, v143, vcc
	v_cvt_pk_bf16_f32 v145, v146, v147
	v_pk_mul_f32 v[156:157], v[34:35], v[154:155] op_sel_hi:[1,0]
	v_pk_mul_f32 v[158:159], v[32:33], v[154:155] op_sel_hi:[1,0]
	s_andn2_b64 vcc, exec, s[4:5]
	v_cvt_pk_bf16_f32 v146, v158, v159
	v_cvt_pk_bf16_f32 v147, v156, v157
	global_store_dwordx4 v[142:143], v[144:147], off
	v_pk_mul_f32 v[142:143], v[4:5], v[154:155] op_sel_hi:[1,0]
	s_nop 0
	v_pk_mul_f32 v[144:145], v[6:7], v[154:155] op_sel_hi:[1,0]
	v_pk_mul_f32 v[146:147], v[2:3], v[154:155] op_sel_hi:[1,0]
	v_pk_mul_f32 v[154:155], v[0:1], v[154:155] op_sel_hi:[1,0]
	v_cvt_pk_bf16_f32 v142, v142, v143
	v_cvt_pk_bf16_f32 v143, v144, v145
	s_nop 0
	v_cvt_pk_bf16_f32 v144, v154, v155
	v_cvt_pk_bf16_f32 v145, v146, v147
	global_store_dwordx4 v[152:153], v[142:145], off offset:256
	s_cbranch_vccnz .LBB0_118
	s_andn2_b64 vcc, exec, s[20:21]
	s_cbranch_vccnz .LBB0_104
	s_barrier
	s_branch .LBB0_104

.LBB0_122:
	v_lshl_add_u64 v[68:69], v[66:67], 0, s[2:3]
	v_add_co_u32_e32 v78, vcc, s84, v68
	v_lshl_add_u64 v[126:127], v[64:65], 0, s[2:3]
	s_nop 0
	v_addc_co_u32_e32 v79, vcc, 0, v69, vcc
	v_add_co_u32_e32 v74, vcc, s85, v68
	s_mov_b32 s10, 0x5808000
	s_nop 0
	v_addc_co_u32_e32 v75, vcc, 0, v69, vcc
	v_add_co_u32_e32 v72, vcc, s88, v68
	s_mov_b32 s11, 0x5818000
	s_nop 0
	v_addc_co_u32_e32 v73, vcc, 0, v69, vcc
	v_add_co_u32_e32 v70, vcc, s89, v68
	s_add_u32 s2, s2, 0x100
	s_nop 0
	v_addc_co_u32_e32 v71, vcc, 0, v69, vcc
	v_add_co_u32_e32 v76, vcc, s10, v126
	s_mov_b32 s10, 0x5888000
	s_nop 0
	v_addc_co_u32_e32 v77, vcc, 0, v127, vcc
	global_load_dwordx4 v[82:85], v[76:77], off
	global_load_dwordx4 v[86:89], v[78:79], off
	global_load_dwordx4 v[90:93], v[78:79], off offset:64
	global_load_dwordx4 v[94:97], v[76:77], off offset:64
	global_load_dwordx4 v[98:101], v[74:75], off
	global_load_dwordx4 v[102:105], v[74:75], off offset:64
	global_load_dwordx4 v[106:109], v[72:73], off
	global_load_dwordx4 v[110:113], v[72:73], off offset:64
	global_load_dwordx4 v[114:117], v[70:71], off
	global_load_dwordx4 v[118:121], v[70:71], off offset:64
	v_add_co_u32_e32 v68, vcc, s11, v126
	s_addc_u32 s3, s3, 0
	s_nop 0
	v_addc_co_u32_e32 v69, vcc, 0, v127, vcc
	v_add_co_u32_e32 v138, vcc, s10, v126
	s_mov_b32 s10, 0x5898000
	s_nop 0
	v_addc_co_u32_e32 v139, vcc, 0, v127, vcc
	v_add_co_u32_e32 v126, vcc, s10, v126
	s_cmpk_eq_i32 s2, 0x200
	s_nop 0
	v_addc_co_u32_e32 v127, vcc, 0, v127, vcc
	s_waitcnt vmcnt(0) lgkmcnt(0)
	v_mfma_f32_16x16x32_bf16 v[56:59], v[82:85], v[86:89], v[56:59]
	v_mfma_f32_16x16x32_bf16 v[52:55], v[82:85], v[98:101], v[52:55]
	v_mfma_f32_16x16x32_bf16 v[48:51], v[82:85], v[106:109], v[48:51]
	v_mfma_f32_16x16x32_bf16 v[44:47], v[82:85], v[114:117], v[44:47]
	global_load_dwordx4 v[82:85], v[68:69], off
	global_load_dwordx4 v[122:125], v[68:69], off offset:64
	v_mfma_f32_16x16x32_bf16 v[56:59], v[94:97], v[90:93], v[56:59]
	v_mfma_f32_16x16x32_bf16 v[52:55], v[94:97], v[102:105], v[52:55]
	v_mfma_f32_16x16x32_bf16 v[48:51], v[94:97], v[110:113], v[48:51]
	v_mfma_f32_16x16x32_bf16 v[44:47], v[94:97], v[118:121], v[44:47]
	s_waitcnt vmcnt(0) lgkmcnt(0)
	v_mfma_f32_16x16x32_bf16 v[12:15], v[82:85], v[86:89], v[12:15]
	v_mfma_f32_16x16x32_bf16 v[8:11], v[82:85], v[98:101], v[8:11]
	v_mfma_f32_16x16x32_bf16 v[4:7], v[82:85], v[106:109], v[4:7]
	v_mfma_f32_16x16x32_bf16 v[0:3], v[82:85], v[114:117], v[0:3]
	global_load_dwordx4 v[82:85], v[138:139], off
	global_load_dwordx4 v[130:133], v[138:139], off offset:64
	global_load_dwordx4 v[134:137], v[126:127], off
	v_mfma_f32_16x16x32_bf16 v[12:15], v[122:125], v[90:93], v[12:15]
	v_mfma_f32_16x16x32_bf16 v[8:11], v[122:125], v[102:105], v[8:11]
	v_mfma_f32_16x16x32_bf16 v[4:7], v[122:125], v[110:113], v[4:7]
	v_mfma_f32_16x16x32_bf16 v[0:3], v[122:125], v[118:121], v[0:3]
	s_waitcnt vmcnt(0) lgkmcnt(0)
	v_mfma_f32_16x16x32_bf16 v[16:19], v[82:85], v[86:89], v[16:19]
	v_mfma_f32_16x16x32_bf16 v[24:27], v[82:85], v[98:101], v[24:27]
	v_mfma_f32_16x16x32_bf16 v[28:31], v[82:85], v[106:109], v[28:31]
	v_mfma_f32_16x16x32_bf16 v[36:39], v[82:85], v[114:117], v[36:39]
	global_load_dwordx4 v[82:85], v[126:127], off offset:64
	v_mfma_f32_16x16x32_bf16 v[20:23], v[134:137], v[86:89], v[20:23]
	global_load_dwordx4 v[86:89], v[76:77], off offset:128
	v_mfma_f32_16x16x32_bf16 v[32:35], v[134:137], v[98:101], v[32:35]
	v_mfma_f32_16x16x32_bf16 v[40:43], v[134:137], v[106:109], v[40:43]
	v_mfma_f32_16x16x32_bf16 v[60:63], v[134:137], v[114:117], v[60:63]
	v_mfma_f32_16x16x32_bf16 v[16:19], v[130:133], v[90:93], v[16:19]
	v_mfma_f32_16x16x32_bf16 v[24:27], v[130:133], v[102:105], v[24:27]
	v_mfma_f32_16x16x32_bf16 v[28:31], v[130:133], v[110:113], v[28:31]
	s_waitcnt vmcnt(0) lgkmcnt(0)
	v_mfma_f32_16x16x32_bf16 v[20:23], v[82:85], v[90:93], v[20:23]
	v_mfma_f32_16x16x32_bf16 v[32:35], v[82:85], v[102:105], v[32:35]
	v_mfma_f32_16x16x32_bf16 v[40:43], v[82:85], v[110:113], v[40:43]
	v_mfma_f32_16x16x32_bf16 v[60:63], v[82:85], v[118:121], v[60:63]
	global_load_dwordx4 v[82:85], v[78:79], off offset:128
	global_load_dwordx4 v[90:93], v[78:79], off offset:192
	s_nop 0
	global_load_dwordx4 v[76:79], v[76:77], off offset:192
	s_nop 0
	global_load_dwordx4 v[94:97], v[74:75], off offset:128
	global_load_dwordx4 v[98:101], v[74:75], off offset:192
	global_load_dwordx4 v[102:105], v[72:73], off offset:128
	s_nop 0
	global_load_dwordx4 v[72:75], v[72:73], off offset:192
	s_nop 0
	global_load_dwordx4 v[106:109], v[70:71], off offset:128
	global_load_dwordx4 v[110:113], v[70:71], off offset:192
	v_mfma_f32_16x16x32_bf16 v[36:39], v[130:133], v[118:121], v[36:39]
	s_waitcnt vmcnt(0) lgkmcnt(0)
	v_mfma_f32_16x16x32_bf16 v[56:59], v[86:89], v[82:85], v[56:59]
	v_mfma_f32_16x16x32_bf16 v[52:55], v[86:89], v[94:97], v[52:55]
	v_mfma_f32_16x16x32_bf16 v[48:51], v[86:89], v[102:105], v[48:51]
	v_mfma_f32_16x16x32_bf16 v[44:47], v[86:89], v[106:109], v[44:47]
	global_load_dwordx4 v[86:89], v[68:69], off offset:128
	s_nop 0
	global_load_dwordx4 v[68:71], v[68:69], off offset:192
	s_waitcnt vmcnt(0) lgkmcnt(0)
	v_mfma_f32_16x16x32_bf16 v[12:15], v[86:89], v[82:85], v[12:15]
	v_mfma_f32_16x16x32_bf16 v[8:11], v[86:89], v[94:97], v[8:11]
	v_mfma_f32_16x16x32_bf16 v[4:7], v[86:89], v[102:105], v[4:7]
	v_mfma_f32_16x16x32_bf16 v[0:3], v[86:89], v[106:109], v[0:3]
	global_load_dwordx4 v[86:89], v[138:139], off offset:128
	global_load_dwordx4 v[114:117], v[138:139], off offset:192
	global_load_dwordx4 v[118:121], v[126:127], off offset:128
	s_waitcnt vmcnt(0) lgkmcnt(0)
	v_mfma_f32_16x16x32_bf16 v[16:19], v[86:89], v[82:85], v[16:19]
	v_mfma_f32_16x16x32_bf16 v[24:27], v[86:89], v[94:97], v[24:27]
	v_mfma_f32_16x16x32_bf16 v[28:31], v[86:89], v[102:105], v[28:31]
	v_mfma_f32_16x16x32_bf16 v[36:39], v[86:89], v[106:109], v[36:39]
	global_load_dwordx4 v[86:89], v[126:127], off offset:192
	v_mfma_f32_16x16x32_bf16 v[20:23], v[118:121], v[82:85], v[20:23]
	v_mfma_f32_16x16x32_bf16 v[32:35], v[118:121], v[94:97], v[32:35]
	v_mfma_f32_16x16x32_bf16 v[40:43], v[118:121], v[102:105], v[40:43]
	v_mfma_f32_16x16x32_bf16 v[60:63], v[118:121], v[106:109], v[60:63]
	v_mfma_f32_16x16x32_bf16 v[56:59], v[76:79], v[90:93], v[56:59]
	v_mfma_f32_16x16x32_bf16 v[52:55], v[76:79], v[98:101], v[52:55]
	v_mfma_f32_16x16x32_bf16 v[48:51], v[76:79], v[72:75], v[48:51]
	v_mfma_f32_16x16x32_bf16 v[44:47], v[76:79], v[110:113], v[44:47]
	v_mfma_f32_16x16x32_bf16 v[12:15], v[68:71], v[90:93], v[12:15]
	v_mfma_f32_16x16x32_bf16 v[8:11], v[68:71], v[98:101], v[8:11]
	v_mfma_f32_16x16x32_bf16 v[4:7], v[68:71], v[72:75], v[4:7]
	v_mfma_f32_16x16x32_bf16 v[0:3], v[68:71], v[110:113], v[0:3]
	v_mfma_f32_16x16x32_bf16 v[16:19], v[114:117], v[90:93], v[16:19]
	v_mfma_f32_16x16x32_bf16 v[24:27], v[114:117], v[98:101], v[24:27]
	v_mfma_f32_16x16x32_bf16 v[28:31], v[114:117], v[72:75], v[28:31]
	v_mfma_f32_16x16x32_bf16 v[36:39], v[114:117], v[110:113], v[36:39]
	s_waitcnt vmcnt(0) lgkmcnt(0)
	v_mfma_f32_16x16x32_bf16 v[20:23], v[86:89], v[90:93], v[20:23]
	v_mfma_f32_16x16x32_bf16 v[32:35], v[86:89], v[98:101], v[32:35]
	v_mfma_f32_16x16x32_bf16 v[40:43], v[86:89], v[72:75], v[40:43]
	v_mfma_f32_16x16x32_bf16 v[60:63], v[86:89], v[110:113], v[60:63]
	s_cbranch_scc0 .LBB0_122
	v_and_b32_e32 v65, 63, v81
	s_ashr_i32 s2, s4, 7
	v_lshl_add_u32 v65, v65, 4, 0
	s_lshl_b32 s3, s2, 4
	v_lshl_add_u32 v66, s5, 14, v65
	s_addk_i32 s3, 0x4000
	ds_write_b128 v66, v[56:59]
	ds_write_b128 v66, v[52:55] offset:1024
	ds_write_b128 v66, v[48:51] offset:2048
	ds_write_b128 v66, v[44:47] offset:3072
	ds_write_b128 v66, v[12:15] offset:4096
	ds_write_b128 v66, v[8:11] offset:5120
	ds_write_b128 v66, v[4:7] offset:6144
	ds_write_b128 v66, v[0:3] offset:7168
	ds_write_b128 v66, v[16:19] offset:8192
	ds_write_b128 v66, v[24:27] offset:9216
	ds_write_b128 v66, v[28:31] offset:10240
	ds_write_b128 v66, v[36:39] offset:11264
	ds_write_b128 v66, v[20:23] offset:12288
	ds_write_b128 v66, v[32:35] offset:13312
	ds_write_b128 v66, v[40:43] offset:14336
	ds_write_b128 v66, v[60:63] offset:15360
	v_or_b32_e32 v0, s3, v80
	v_ashrrev_i32_e32 v1, 31, v0
	v_bfe_u32 v64, v81, 4, 2
	v_lshlrev_b64 v[2:3], 7, v[0:1]
	v_lshl_add_u64 v[2:3], s[8:9], 0, v[2:3]
	v_lshlrev_b32_e32 v128, 5, v64
	v_lshl_add_u64 v[6:7], v[2:3], 0, v[128:129]
	s_waitcnt lgkmcnt(0)
	s_barrier
	global_load_dwordx4 v[2:5], v[6:7], off
	s_nop 0
	global_load_dwordx4 v[6:9], v[6:7], off offset:16
	s_bfe_u32 s3, s4, 0x10006
	s_lshl_b32 s4, s3, 2
	s_add_i32 s4, s4, s2
	v_lshl_add_u32 v62, s4, 10, v65
	ds_read_b128 v[10:13], v62
	ds_read_b128 v[14:17], v62 offset:8192
	ds_read_b128 v[18:21], v62 offset:16384
	ds_read_b128 v[22:25], v62 offset:24576
	ds_read_b128 v[26:29], v62 offset:32768
	ds_read_b128 v[30:33], v62 offset:40960
	ds_read_b128 v[34:37], v62 offset:49152
	ds_read_b128 v[38:41], v62 offset:57344
	s_waitcnt lgkmcnt(0)
	v_pk_add_f32 v[10:11], v[10:11], 0 op_sel_hi:[1,0]
	v_pk_add_f32 v[12:13], v[12:13], 0 op_sel_hi:[1,0]
	v_pk_add_f32 v[10:11], v[10:11], v[18:19]
	v_pk_add_f32 v[12:13], v[12:13], v[20:21]
	v_add_u32_e32 v42, 0x10000, v62
	v_add_u32_e32 v46, 0x12000, v62
	v_add_u32_e32 v50, 0x14000, v62
	v_add_u32_e32 v54, 0x16000, v62
	v_add_u32_e32 v58, 0x18000, v62
	v_add_u32_e32 v63, 0x1a000, v62
	ds_read_b128 v[42:45], v42
	ds_read_b128 v[46:49], v46
	ds_read_b128 v[50:53], v50
	ds_read_b128 v[54:57], v54
	ds_read_b128 v[58:61], v58
	ds_read_b128 v[66:69], v63
	v_pk_add_f32 v[10:11], v[10:11], v[26:27]
	v_pk_add_f32 v[14:15], v[14:15], 0 op_sel_hi:[1,0]
	v_pk_add_f32 v[10:11], v[10:11], v[34:35]
	v_pk_add_f32 v[12:13], v[12:13], v[28:29]
	s_waitcnt lgkmcnt(0)
	v_pk_add_f32 v[10:11], v[10:11], v[42:43]
	v_pk_add_f32 v[16:17], v[16:17], 0 op_sel_hi:[1,0]
	v_pk_add_f32 v[10:11], v[10:11], v[50:51]
	v_pk_add_f32 v[14:15], v[14:15], v[22:23]
	v_pk_add_f32 v[10:11], v[10:11], v[58:59]
	v_pk_add_f32 v[12:13], v[12:13], v[36:37]
	v_pk_add_f32 v[16:17], v[16:17], v[24:25]
	v_pk_add_f32 v[14:15], v[14:15], v[30:31]
	v_pk_add_f32 v[12:13], v[12:13], v[44:45]
	v_pk_add_f32 v[16:17], v[16:17], v[32:33]
	v_pk_add_f32 v[14:15], v[14:15], v[38:39]
	v_pk_add_f32 v[12:13], v[12:13], v[52:53]
	v_pk_add_f32 v[16:17], v[16:17], v[40:41]
	v_pk_add_f32 v[14:15], v[14:15], v[46:47]
	v_pk_add_f32 v[12:13], v[12:13], v[60:61]
	v_pk_add_f32 v[16:17], v[16:17], v[48:49]
	v_pk_add_f32 v[14:15], v[14:15], v[54:55]
	v_lshlrev_b64 v[0:1], 12, v[0:1]
	s_and_b32 s0, s0, 0x700
	v_pk_add_f32 v[16:17], v[16:17], v[56:57]
	v_pk_add_f32 v[14:15], v[14:15], v[66:67]
	v_lshl_add_u64 v[0:1], s[6:7], 0, v[0:1]
	s_lshl_b32 s94, s0, 1
	v_pk_add_f32 v[16:17], v[16:17], v[68:69]
	v_lshl_add_u64 v[0:1], v[0:1], 0, s[94:95]
	s_waitcnt vmcnt(0)
	v_mov_b32_e32 v18, v2
	v_mov_b32_e32 v19, v6
	v_mov_b32_e32 v6, v3
	v_pk_add_f32 v[2:3], v[18:19], v[6:7]
	v_mov_b32_e32 v6, v4
	v_mov_b32_e32 v7, v8
	v_mov_b32_e32 v8, v5
	v_pk_add_f32 v[4:5], v[6:7], v[8:9]
	v_add_u32_e32 v6, 0x1e000, v62
	v_pk_add_f32 v[2:3], v[2:3], v[4:5]
	s_nop 0
	v_add_f32_e32 v18, v2, v3
	v_and_b32_e32 v3, 64, v214
	v_xor_b32_e32 v2, 16, v214
	v_add_u32_e32 v19, 64, v3
	v_cmp_lt_i32_e32 vcc, v2, v19
	s_nop 1
	v_cndmask_b32_e32 v2, v214, v2, vcc
	v_lshlrev_b32_e32 v2, 2, v2
	ds_bpermute_b32 v20, v2, v18
	v_add_u32_e32 v2, 0x1c000, v62
	ds_read_b128 v[2:5], v2
	ds_read_b128 v[6:9], v6
	s_waitcnt lgkmcnt(2)
	v_add_f32_e32 v18, v18, v20
	v_xor_b32_e32 v20, 32, v214
	v_cmp_lt_i32_e32 vcc, v20, v19
	s_waitcnt lgkmcnt(1)
	v_pk_add_f32 v[2:3], v[10:11], v[2:3]
	v_pk_add_f32 v[4:5], v[12:13], v[4:5]
	v_cndmask_b32_e32 v19, v214, v20, vcc
	v_lshlrev_b32_e32 v19, 2, v19
	ds_bpermute_b32 v19, v19, v18
	s_waitcnt lgkmcnt(1)
	v_pk_add_f32 v[6:7], v[14:15], v[6:7]
	v_pk_add_f32 v[8:9], v[16:17], v[8:9]
	s_waitcnt lgkmcnt(0)
	v_add_f32_e32 v10, v18, v19
	v_fmamk_f32 v10, v10, 0x3a000000, v190
	v_mul_f32_e32 v11, 0x4b800000, v10
	v_cmp_gt_f32_e32 vcc, s70, v10
	s_nop 1
	v_cndmask_b32_e32 v10, v10, v11, vcc
	v_rsq_f32_e32 v10, v10
	v_lshlrev_b32_e32 v11, 2, v64
	v_lshl_or_b32 v11, s3, 4, v11
	v_or_b32_e32 v11, s1, v11
	v_mul_f32_e32 v12, 0x45800000, v10
	v_cndmask_b32_e32 v10, v10, v12, vcc
	v_lshlrev_b32_e32 v128, 1, v11
	v_pk_mul_f32 v[4:5], v[4:5], v[10:11] op_sel_hi:[1,0]
	v_pk_mul_f32 v[2:3], v[2:3], v[10:11] op_sel_hi:[1,0]
	v_lshl_add_u64 v[0:1], v[0:1], 0, v[128:129]
	v_cvt_pk_bf16_f32 v2, v2, v3
	v_cvt_pk_bf16_f32 v3, v4, v5
	v_pk_mul_f32 v[4:5], v[6:7], v[10:11] op_sel_hi:[1,0]
	global_store_dwordx2 v[0:1], v[2:3], off
	v_pk_mul_f32 v[2:3], v[8:9], v[10:11] op_sel_hi:[1,0]
	v_cvt_pk_bf16_f32 v4, v4, v5
	s_nop 0
	v_cvt_pk_bf16_f32 v5, v2, v3
	global_store_dwordx2 v[0:1], v[4:5], off offset:256
	s_waitcnt lgkmcnt(0)
	s_barrier

.LBB0_178:
	s_add_u32 s16, s16, s14
	s_addc_u32 s17, s17, s15
	s_add_u32 s18, s20, s16
	s_addc_u32 s19, s21, s17
	v_cmp_gt_i64_e32 vcc, s[18:19], v[236:237]
	s_mov_b64 s[18:19], -1
	s_cbranch_vccnz .LBB0_173
	v_lshl_add_u32 v4, s24, 8, v2
	v_ashrrev_i32_e32 v5, 31, v4
	v_lshl_add_u32 v6, s25, 8, v2
	v_lshlrev_b64 v[4:5], 7, v[4:5]
	v_ashrrev_i32_e32 v7, 31, v6
	v_lshl_add_u64 v[4:5], v[0:1], 0, v[4:5]
	v_lshlrev_b64 v[6:7], 7, v[6:7]
	v_lshl_add_u64 v[6:7], v[0:1], 0, v[6:7]
	global_load_dwordx4 v[10:13], v[4:5], off
	global_load_dwordx4 v[14:17], v[4:5], off offset:16
	global_load_dwordx4 v[18:21], v[4:5], off offset:32
	global_load_dwordx4 v[22:25], v[4:5], off offset:48
	global_load_dwordx4 v[26:29], v[6:7], off
	global_load_dwordx4 v[30:33], v[6:7], off offset:16
	global_load_dwordx4 v[34:37], v[6:7], off offset:32
	global_load_dwordx4 v[38:41], v[6:7], off offset:48
	v_mov_b32_e32 v5, v129
	v_mov_b32_e32 v4, v129
	s_waitcnt vmcnt(0) lgkmcnt(0)
	v_pk_add_f32 v[6:7], v[12:13], v[16:17]
	v_pk_add_f32 v[10:11], v[10:11], v[14:15]
	v_pk_add_f32 v[12:13], v[20:21], v[24:25]
	v_pk_add_f32 v[14:15], v[18:19], v[22:23]
	v_pk_add_f32 v[16:17], v[28:29], v[32:33]
	v_pk_add_f32 v[18:19], v[26:27], v[30:31]
	v_pk_add_f32 v[20:21], v[36:37], v[40:41]
	v_pk_add_f32 v[22:23], v[34:35], v[38:39]
	v_pk_add_f32 v[6:7], v[6:7], v[12:13]
	v_pk_add_f32 v[10:11], v[10:11], v[14:15]
	v_pk_add_f32 v[12:13], v[16:17], v[20:21]
	v_pk_add_f32 v[14:15], v[18:19], v[22:23]
	v_add_f32_e32 v9, v10, v11
	v_add_f32_e32 v6, v6, v7
	v_add_f32_e32 v10, v14, v15
	v_add_f32_e32 v11, v12, v13
	v_add_f32_e32 v7, v9, v6
	v_add_f32_e32 v6, v10, v11
	s_nop 0
	v_mov_b32_dpp v5, v7 quad_perm:[1,0,3,2] row_mask:0xf bank_mask:0xf
	v_mov_b32_dpp v4, v6 quad_perm:[1,0,3,2] row_mask:0xf bank_mask:0xf
	s_and_saveexec_b64 s[18:19], s[2:3]
	s_cbranch_execz .LBB0_172
	v_add_f32_e32 v5, v7, v5
	v_fmamk_f32 v5, v5, 0x3a000000, v190
	v_mul_f32_e32 v7, 0x4b800000, v5
	v_cmp_gt_f32_e32 vcc, s70, v5
	s_nop 1
	v_cndmask_b32_e32 v5, v5, v7, vcc
	v_rsq_f32_e32 v5, v5
	s_nop 0
	v_mul_f32_e32 v7, 0x45800000, v5
	v_cndmask_b32_e32 v5, v5, v7, vcc
	s_andn2_b64 vcc, exec, s[4:5]
	ds_write_b32 v3, v5
	s_cbranch_vccnz .LBB0_172
	v_add_f32_e32 v4, v6, v4
	v_fmamk_f32 v4, v4, 0x3a000000, v190
	v_mul_f32_e32 v5, 0x4b800000, v4
	v_cmp_gt_f32_e32 vcc, s70, v4
	s_nop 1
	v_cndmask_b32_e32 v4, v4, v5, vcc
	v_rsq_f32_e32 v4, v4
	s_nop 0
	v_mul_f32_e32 v5, 0x45800000, v4
	v_cndmask_b32_e32 v4, v4, v5, vcc
	ds_write_b32 v3, v4 offset:1024
	s_branch .LBB0_172

.LBB0_192:
	s_add_u32 s30, s50, 0xffffff00
	s_addc_u32 s31, s51, -1
	s_ashr_i32 s23, s44, 3
	s_mul_hi_i32 s25, s23, 0x4200000
	s_mul_i32 s23, s23, 0x4200000
	s_add_u32 s23, s0, s23
	s_addc_u32 s25, s1, s25
	s_lshl_b32 s34, s44, 9
	s_and_b32 s34, s34, 0xe00
	s_add_u32 s23, s23, s34
	v_lshl_add_u32 v142, s48, 10, v150
	s_addc_u32 s25, s25, 0
	v_lshl_add_u32 v156, s14, 8, v148
	ds_read2_b32 v[158:159], v142 offset1:16
	ds_read2_b32 v[160:161], v142 offset0:32 offset1:48
	ds_read2_b32 v[146:147], v142 offset0:128 offset1:144
	ds_read2_b32 v[144:145], v142 offset0:160 offset1:176
	s_add_u32 s34, s23, s47
	s_addc_u32 s35, s25, 0
	v_ashrrev_i32_e32 v157, 31, v156
	v_lshl_add_u64 v[162:163], s[34:35], 0, v[128:129]
	v_lshlrev_b64 v[142:143], 12, v[156:157]
	s_waitcnt lgkmcnt(0)
	v_pk_mul_f32 v[152:153], v[124:125], v[158:159] op_sel_hi:[1,0]
	v_lshl_add_u64 v[142:143], v[162:163], 0, v[142:143]
	v_pk_mul_f32 v[154:155], v[126:127], v[158:159] op_sel_hi:[1,0]
	v_cvt_pk_bf16_f32 v152, v152, v153
	v_pk_mul_f32 v[164:165], v[122:123], v[158:159] op_sel_hi:[1,0]
	v_cvt_pk_bf16_f32 v153, v154, v155
	v_pk_mul_f32 v[166:167], v[120:121], v[158:159] op_sel_hi:[1,0]
	s_mov_b64 s[34:35], 0x90000
	v_cvt_pk_bf16_f32 v154, v166, v167
	v_cvt_pk_bf16_f32 v155, v164, v165
	global_store_dwordx4 v[142:143], v[152:155], off
	v_pk_mul_f32 v[164:165], v[90:91], v[158:159] op_sel_hi:[1,0]
	v_pk_mul_f32 v[166:167], v[88:89], v[158:159] op_sel_hi:[1,0]
	v_pk_mul_f32 v[152:153], v[92:93], v[158:159] op_sel_hi:[1,0]
	v_pk_mul_f32 v[154:155], v[94:95], v[158:159] op_sel_hi:[1,0]
	v_cvt_pk_bf16_f32 v152, v152, v153
	v_mov_b32_e32 v158, v159
	v_cvt_pk_bf16_f32 v153, v154, v155
	v_cvt_pk_bf16_f32 v154, v166, v167
	v_cvt_pk_bf16_f32 v155, v164, v165
	global_store_dwordx4 v[142:143], v[152:155], off offset:256
	v_pk_mul_f32 v[166:167], v[114:115], v[158:159] op_sel_hi:[1,0]
	v_pk_mul_f32 v[168:169], v[112:113], v[158:159] op_sel_hi:[1,0]
	v_or_b32_e32 v152, 16, v156
	v_ashrrev_i32_e32 v153, 31, v152
	v_lshlrev_b64 v[152:153], 12, v[152:153]
	v_lshl_add_u64 v[164:165], v[162:163], 0, v[152:153]
	v_pk_mul_f32 v[152:153], v[116:117], v[158:159] op_sel_hi:[1,0]
	v_pk_mul_f32 v[154:155], v[118:119], v[158:159] op_sel_hi:[1,0]
	v_cvt_pk_bf16_f32 v152, v152, v153
	s_nop 0
	v_cvt_pk_bf16_f32 v153, v154, v155
	v_cvt_pk_bf16_f32 v154, v168, v169
	v_cvt_pk_bf16_f32 v155, v166, v167
	global_store_dwordx4 v[164:165], v[152:155], off
	v_pk_mul_f32 v[166:167], v[82:83], v[158:159] op_sel_hi:[1,0]
	s_nop 0
	v_pk_mul_f32 v[152:153], v[84:85], v[158:159] op_sel_hi:[1,0]
	v_pk_mul_f32 v[154:155], v[86:87], v[158:159] op_sel_hi:[1,0]
	v_cvt_pk_bf16_f32 v152, v152, v153
	v_pk_mul_f32 v[158:159], v[80:81], v[158:159] op_sel_hi:[1,0]
	v_cvt_pk_bf16_f32 v153, v154, v155
	s_nop 0
	v_cvt_pk_bf16_f32 v154, v158, v159
	v_cvt_pk_bf16_f32 v155, v166, v167
	global_store_dwordx4 v[164:165], v[152:155], off offset:256
	v_pk_mul_f32 v[164:165], v[106:107], v[160:161] op_sel_hi:[1,0]
	v_pk_mul_f32 v[166:167], v[104:105], v[160:161] op_sel_hi:[1,0]
	v_or_b32_e32 v152, 32, v156
	v_ashrrev_i32_e32 v153, 31, v152
	v_lshlrev_b64 v[152:153], 12, v[152:153]
	v_lshl_add_u64 v[158:159], v[162:163], 0, v[152:153]
	v_pk_mul_f32 v[152:153], v[108:109], v[160:161] op_sel_hi:[1,0]
	v_pk_mul_f32 v[154:155], v[110:111], v[160:161] op_sel_hi:[1,0]
	v_cvt_pk_bf16_f32 v152, v152, v153
	s_nop 0
	v_cvt_pk_bf16_f32 v153, v154, v155
	v_cvt_pk_bf16_f32 v154, v166, v167
	v_cvt_pk_bf16_f32 v155, v164, v165
	global_store_dwordx4 v[158:159], v[152:155], off
	v_pk_mul_f32 v[164:165], v[74:75], v[160:161] op_sel_hi:[1,0]
	v_pk_mul_f32 v[166:167], v[72:73], v[160:161] op_sel_hi:[1,0]
	v_pk_mul_f32 v[152:153], v[76:77], v[160:161] op_sel_hi:[1,0]
	v_pk_mul_f32 v[154:155], v[78:79], v[160:161] op_sel_hi:[1,0]
	v_cvt_pk_bf16_f32 v152, v152, v153
	s_nop 0
	v_cvt_pk_bf16_f32 v153, v154, v155
	v_cvt_pk_bf16_f32 v154, v166, v167
	v_cvt_pk_bf16_f32 v155, v164, v165
	global_store_dwordx4 v[158:159], v[152:155], off offset:256
	v_mov_b32_e32 v158, v161
	v_pk_mul_f32 v[160:161], v[98:99], v[158:159] op_sel_hi:[1,0]
	v_or_b32_e32 v152, 48, v156
	v_ashrrev_i32_e32 v153, 31, v152
	v_lshlrev_b64 v[152:153], 12, v[152:153]
	v_lshl_add_u64 v[156:157], v[162:163], 0, v[152:153]
	v_pk_mul_f32 v[154:155], v[102:103], v[158:159] op_sel_hi:[1,0]
	v_pk_mul_f32 v[152:153], v[100:101], v[158:159] op_sel_hi:[1,0]
	v_pk_mul_f32 v[162:163], v[96:97], v[158:159] op_sel_hi:[1,0]
	v_cvt_pk_bf16_f32 v152, v152, v153
	v_cvt_pk_bf16_f32 v153, v154, v155
	s_nop 0
	v_cvt_pk_bf16_f32 v154, v162, v163
	v_cvt_pk_bf16_f32 v155, v160, v161
	global_store_dwordx4 v[156:157], v[152:155], off
	v_pk_mul_f32 v[160:161], v[66:67], v[158:159] op_sel_hi:[1,0]
	s_nop 0
	v_pk_mul_f32 v[154:155], v[70:71], v[158:159] op_sel_hi:[1,0]
	v_pk_mul_f32 v[152:153], v[68:69], v[158:159] op_sel_hi:[1,0]
	v_pk_mul_f32 v[158:159], v[64:65], v[158:159] op_sel_hi:[1,0]
	v_cvt_pk_bf16_f32 v152, v152, v153
	v_cvt_pk_bf16_f32 v153, v154, v155
	s_nop 0
	v_cvt_pk_bf16_f32 v154, v158, v159
	v_cvt_pk_bf16_f32 v155, v160, v161
	global_store_dwordx4 v[156:157], v[152:155], off offset:256
	v_pk_mul_f32 v[158:159], v[58:59], v[146:147] op_sel_hi:[1,0]
	v_pk_mul_f32 v[160:161], v[56:57], v[146:147] op_sel_hi:[1,0]
	v_pk_mul_f32 v[154:155], v[62:63], v[146:147] op_sel_hi:[1,0]
	v_pk_mul_f32 v[152:153], v[60:61], v[146:147] op_sel_hi:[1,0]
	v_lshl_add_u64 v[156:157], v[142:143], 0, s[76:77]
	v_cvt_pk_bf16_f32 v152, v152, v153
	v_cvt_pk_bf16_f32 v153, v154, v155
	v_cvt_pk_bf16_f32 v154, v160, v161
	v_cvt_pk_bf16_f32 v155, v158, v159
	v_add_co_u32_e32 v158, vcc, s72, v142
	v_pk_mul_f32 v[160:161], v[24:25], v[146:147] op_sel_hi:[1,0]
	s_nop 0
	v_addc_co_u32_e32 v159, vcc, 0, v143, vcc
	global_store_dwordx4 v[158:159], v[152:155], off
	v_pk_mul_f32 v[158:159], v[26:27], v[146:147] op_sel_hi:[1,0]
	s_nop 0
	v_pk_mul_f32 v[154:155], v[30:31], v[146:147] op_sel_hi:[1,0]
	v_pk_mul_f32 v[152:153], v[28:29], v[146:147] op_sel_hi:[1,0]
	v_mov_b32_e32 v146, v147
	v_cvt_pk_bf16_f32 v152, v152, v153
	v_cvt_pk_bf16_f32 v153, v154, v155
	v_cvt_pk_bf16_f32 v154, v160, v161
	v_cvt_pk_bf16_f32 v155, v158, v159
	global_store_dwordx4 v[156:157], v[152:155], off offset:256
	v_pk_mul_f32 v[158:159], v[50:51], v[146:147] op_sel_hi:[1,0]
	v_pk_mul_f32 v[160:161], v[48:49], v[146:147] op_sel_hi:[1,0]
	v_pk_mul_f32 v[154:155], v[54:55], v[146:147] op_sel_hi:[1,0]
	v_pk_mul_f32 v[152:153], v[52:53], v[146:147] op_sel_hi:[1,0]
	v_lshl_add_u64 v[156:157], v[142:143], 0, s[34:35]
	v_cvt_pk_bf16_f32 v152, v152, v153
	v_cvt_pk_bf16_f32 v153, v154, v155
	v_cvt_pk_bf16_f32 v154, v160, v161
	v_cvt_pk_bf16_f32 v155, v158, v159
	v_add_co_u32_e32 v158, vcc, s81, v142
	s_mov_b64 s[34:35], 0xa0000
	s_nop 0
	v_addc_co_u32_e32 v159, vcc, 0, v143, vcc
	global_store_dwordx4 v[158:159], v[152:155], off
	v_pk_mul_f32 v[158:159], v[18:19], v[146:147] op_sel_hi:[1,0]
	s_nop 0
	v_pk_mul_f32 v[154:155], v[22:23], v[146:147] op_sel_hi:[1,0]
	v_pk_mul_f32 v[152:153], v[20:21], v[146:147] op_sel_hi:[1,0]
	v_pk_mul_f32 v[146:147], v[16:17], v[146:147] op_sel_hi:[1,0]
	v_cvt_pk_bf16_f32 v152, v152, v153
	v_cvt_pk_bf16_f32 v153, v154, v155
	s_nop 0
	v_cvt_pk_bf16_f32 v154, v146, v147
	v_cvt_pk_bf16_f32 v155, v158, v159
	global_store_dwordx4 v[156:157], v[152:155], off offset:256
	v_pk_mul_f32 v[156:157], v[42:43], v[144:145] op_sel_hi:[1,0]
	v_pk_mul_f32 v[158:159], v[40:41], v[144:145] op_sel_hi:[1,0]
	v_pk_mul_f32 v[154:155], v[46:47], v[144:145] op_sel_hi:[1,0]
	v_pk_mul_f32 v[152:153], v[44:45], v[144:145] op_sel_hi:[1,0]
	v_lshl_add_u64 v[146:147], v[142:143], 0, s[34:35]
	v_cvt_pk_bf16_f32 v152, v152, v153
	v_cvt_pk_bf16_f32 v153, v154, v155
	v_cvt_pk_bf16_f32 v154, v158, v159
	v_cvt_pk_bf16_f32 v155, v156, v157
	v_add_co_u32_e32 v156, vcc, s82, v142
	v_pk_mul_f32 v[158:159], v[8:9], v[144:145] op_sel_hi:[1,0]
	s_nop 0
	v_addc_co_u32_e32 v157, vcc, 0, v143, vcc
	global_store_dwordx4 v[156:157], v[152:155], off
	v_pk_mul_f32 v[156:157], v[10:11], v[144:145] op_sel_hi:[1,0]
	s_mov_b64 s[34:35], 0xb0000
	v_pk_mul_f32 v[154:155], v[14:15], v[144:145] op_sel_hi:[1,0]
	v_pk_mul_f32 v[152:153], v[12:13], v[144:145] op_sel_hi:[1,0]
	s_nop 0
	v_cvt_pk_bf16_f32 v152, v152, v153
	v_cvt_pk_bf16_f32 v153, v154, v155
	v_cvt_pk_bf16_f32 v154, v158, v159
	v_cvt_pk_bf16_f32 v155, v156, v157
	global_store_dwordx4 v[146:147], v[152:155], off offset:256
	s_nop 1
	v_mov_b32_e32 v154, v145
	v_lshl_add_u64 v[152:153], v[142:143], 0, s[34:35]
	v_pk_mul_f32 v[144:145], v[36:37], v[154:155] op_sel_hi:[1,0]
	v_add_co_u32_e32 v142, vcc, s83, v142
	v_pk_mul_f32 v[146:147], v[38:39], v[154:155] op_sel_hi:[1,0]
	v_cvt_pk_bf16_f32 v144, v144, v145
	s_nop 0
	v_addc_co_u32_e32 v143, vcc, 0, v143, vcc
	v_cvt_pk_bf16_f32 v145, v146, v147
	v_pk_mul_f32 v[156:157], v[34:35], v[154:155] op_sel_hi:[1,0]
	v_pk_mul_f32 v[158:159], v[32:33], v[154:155] op_sel_hi:[1,0]
	s_andn2_b64 vcc, exec, s[4:5]
	v_cvt_pk_bf16_f32 v146, v158, v159
	v_cvt_pk_bf16_f32 v147, v156, v157
	global_store_dwordx4 v[142:143], v[144:147], off
	v_pk_mul_f32 v[142:143], v[4:5], v[154:155] op_sel_hi:[1,0]
	s_nop 0
	v_pk_mul_f32 v[144:145], v[6:7], v[154:155] op_sel_hi:[1,0]
	v_pk_mul_f32 v[146:147], v[2:3], v[154:155] op_sel_hi:[1,0]
	v_pk_mul_f32 v[154:155], v[0:1], v[154:155] op_sel_hi:[1,0]
	v_cvt_pk_bf16_f32 v142, v142, v143
	v_cvt_pk_bf16_f32 v143, v144, v145
	s_nop 0
	v_cvt_pk_bf16_f32 v144, v154, v155
	v_cvt_pk_bf16_f32 v145, v146, v147
	global_store_dwordx4 v[152:153], v[142:145], off offset:256
	s_cbranch_vccnz .LBB0_195
	s_andn2_b64 vcc, exec, s[16:17]
	s_cbranch_vccnz .LBB0_185
	s_barrier
	s_branch .LBB0_185

.LBB0_199:
	v_lshl_add_u64 v[68:69], v[66:67], 0, s[2:3]
	v_add_co_u32_e32 v78, vcc, s84, v68
	v_lshl_add_u64 v[126:127], v[64:65], 0, s[2:3]
	s_nop 0
	v_addc_co_u32_e32 v79, vcc, 0, v69, vcc
	v_add_co_u32_e32 v74, vcc, s85, v68
	s_mov_b32 s8, 0x4008000
	s_nop 0
	v_addc_co_u32_e32 v75, vcc, 0, v69, vcc
	v_add_co_u32_e32 v72, vcc, s88, v68
	s_mov_b32 s9, 0x4018000
	s_nop 0
	v_addc_co_u32_e32 v73, vcc, 0, v69, vcc
	v_add_co_u32_e32 v70, vcc, s89, v68
	s_add_u32 s2, s2, 0x100
	s_nop 0
	v_addc_co_u32_e32 v71, vcc, 0, v69, vcc
	v_add_co_u32_e32 v76, vcc, s8, v126
	s_mov_b32 s8, 0x4088000
	s_nop 0
	v_addc_co_u32_e32 v77, vcc, 0, v127, vcc
	global_load_dwordx4 v[82:85], v[76:77], off
	global_load_dwordx4 v[86:89], v[78:79], off
	global_load_dwordx4 v[90:93], v[78:79], off offset:64
	global_load_dwordx4 v[94:97], v[76:77], off offset:64
	global_load_dwordx4 v[98:101], v[74:75], off
	global_load_dwordx4 v[102:105], v[74:75], off offset:64
	global_load_dwordx4 v[106:109], v[72:73], off
	global_load_dwordx4 v[110:113], v[72:73], off offset:64
	global_load_dwordx4 v[114:117], v[70:71], off
	global_load_dwordx4 v[118:121], v[70:71], off offset:64
	v_add_co_u32_e32 v68, vcc, s9, v126
	s_addc_u32 s3, s3, 0
	s_nop 0
	v_addc_co_u32_e32 v69, vcc, 0, v127, vcc
	v_add_co_u32_e32 v138, vcc, s8, v126
	s_mov_b32 s8, 0x4098000
	s_nop 0
	v_addc_co_u32_e32 v139, vcc, 0, v127, vcc
	v_add_co_u32_e32 v126, vcc, s8, v126
	s_cmpk_eq_i32 s2, 0x200
	s_nop 0
	v_addc_co_u32_e32 v127, vcc, 0, v127, vcc
	s_waitcnt vmcnt(0) lgkmcnt(0)
	v_mfma_f32_16x16x32_bf16 v[56:59], v[82:85], v[86:89], v[56:59]
	v_mfma_f32_16x16x32_bf16 v[52:55], v[82:85], v[98:101], v[52:55]
	v_mfma_f32_16x16x32_bf16 v[48:51], v[82:85], v[106:109], v[48:51]
	v_mfma_f32_16x16x32_bf16 v[44:47], v[82:85], v[114:117], v[44:47]
	global_load_dwordx4 v[82:85], v[68:69], off
	global_load_dwordx4 v[122:125], v[68:69], off offset:64
	v_mfma_f32_16x16x32_bf16 v[56:59], v[94:97], v[90:93], v[56:59]
	v_mfma_f32_16x16x32_bf16 v[52:55], v[94:97], v[102:105], v[52:55]
	v_mfma_f32_16x16x32_bf16 v[48:51], v[94:97], v[110:113], v[48:51]
	v_mfma_f32_16x16x32_bf16 v[44:47], v[94:97], v[118:121], v[44:47]
	s_waitcnt vmcnt(0) lgkmcnt(0)
	v_mfma_f32_16x16x32_bf16 v[12:15], v[82:85], v[86:89], v[12:15]
	v_mfma_f32_16x16x32_bf16 v[8:11], v[82:85], v[98:101], v[8:11]
	v_mfma_f32_16x16x32_bf16 v[4:7], v[82:85], v[106:109], v[4:7]
	v_mfma_f32_16x16x32_bf16 v[0:3], v[82:85], v[114:117], v[0:3]
	global_load_dwordx4 v[82:85], v[138:139], off
	global_load_dwordx4 v[130:133], v[138:139], off offset:64
	global_load_dwordx4 v[134:137], v[126:127], off
	v_mfma_f32_16x16x32_bf16 v[12:15], v[122:125], v[90:93], v[12:15]
	v_mfma_f32_16x16x32_bf16 v[8:11], v[122:125], v[102:105], v[8:11]
	v_mfma_f32_16x16x32_bf16 v[4:7], v[122:125], v[110:113], v[4:7]
	v_mfma_f32_16x16x32_bf16 v[0:3], v[122:125], v[118:121], v[0:3]
	s_waitcnt vmcnt(0) lgkmcnt(0)
	v_mfma_f32_16x16x32_bf16 v[16:19], v[82:85], v[86:89], v[16:19]
	v_mfma_f32_16x16x32_bf16 v[24:27], v[82:85], v[98:101], v[24:27]
	v_mfma_f32_16x16x32_bf16 v[28:31], v[82:85], v[106:109], v[28:31]
	v_mfma_f32_16x16x32_bf16 v[36:39], v[82:85], v[114:117], v[36:39]
	global_load_dwordx4 v[82:85], v[126:127], off offset:64
	v_mfma_f32_16x16x32_bf16 v[20:23], v[134:137], v[86:89], v[20:23]
	global_load_dwordx4 v[86:89], v[76:77], off offset:128
	v_mfma_f32_16x16x32_bf16 v[32:35], v[134:137], v[98:101], v[32:35]
	v_mfma_f32_16x16x32_bf16 v[40:43], v[134:137], v[106:109], v[40:43]
	v_mfma_f32_16x16x32_bf16 v[60:63], v[134:137], v[114:117], v[60:63]
	v_mfma_f32_16x16x32_bf16 v[16:19], v[130:133], v[90:93], v[16:19]
	v_mfma_f32_16x16x32_bf16 v[24:27], v[130:133], v[102:105], v[24:27]
	v_mfma_f32_16x16x32_bf16 v[28:31], v[130:133], v[110:113], v[28:31]
	s_waitcnt vmcnt(0) lgkmcnt(0)
	v_mfma_f32_16x16x32_bf16 v[20:23], v[82:85], v[90:93], v[20:23]
	v_mfma_f32_16x16x32_bf16 v[32:35], v[82:85], v[102:105], v[32:35]
	v_mfma_f32_16x16x32_bf16 v[40:43], v[82:85], v[110:113], v[40:43]
	v_mfma_f32_16x16x32_bf16 v[60:63], v[82:85], v[118:121], v[60:63]
	global_load_dwordx4 v[82:85], v[78:79], off offset:128
	global_load_dwordx4 v[90:93], v[78:79], off offset:192
	s_nop 0
	global_load_dwordx4 v[76:79], v[76:77], off offset:192
	s_nop 0
	global_load_dwordx4 v[94:97], v[74:75], off offset:128
	global_load_dwordx4 v[98:101], v[74:75], off offset:192
	global_load_dwordx4 v[102:105], v[72:73], off offset:128
	s_nop 0
	global_load_dwordx4 v[72:75], v[72:73], off offset:192
	s_nop 0
	global_load_dwordx4 v[106:109], v[70:71], off offset:128
	global_load_dwordx4 v[110:113], v[70:71], off offset:192
	v_mfma_f32_16x16x32_bf16 v[36:39], v[130:133], v[118:121], v[36:39]
	s_waitcnt vmcnt(0) lgkmcnt(0)
	v_mfma_f32_16x16x32_bf16 v[56:59], v[86:89], v[82:85], v[56:59]
	v_mfma_f32_16x16x32_bf16 v[52:55], v[86:89], v[94:97], v[52:55]
	v_mfma_f32_16x16x32_bf16 v[48:51], v[86:89], v[102:105], v[48:51]
	v_mfma_f32_16x16x32_bf16 v[44:47], v[86:89], v[106:109], v[44:47]
	global_load_dwordx4 v[86:89], v[68:69], off offset:128
	s_nop 0
	global_load_dwordx4 v[68:71], v[68:69], off offset:192
	s_waitcnt vmcnt(0) lgkmcnt(0)
	v_mfma_f32_16x16x32_bf16 v[12:15], v[86:89], v[82:85], v[12:15]
	v_mfma_f32_16x16x32_bf16 v[8:11], v[86:89], v[94:97], v[8:11]
	v_mfma_f32_16x16x32_bf16 v[4:7], v[86:89], v[102:105], v[4:7]
	v_mfma_f32_16x16x32_bf16 v[0:3], v[86:89], v[106:109], v[0:3]
	global_load_dwordx4 v[86:89], v[138:139], off offset:128
	global_load_dwordx4 v[114:117], v[138:139], off offset:192
	global_load_dwordx4 v[118:121], v[126:127], off offset:128
	s_waitcnt vmcnt(0) lgkmcnt(0)
	v_mfma_f32_16x16x32_bf16 v[16:19], v[86:89], v[82:85], v[16:19]
	v_mfma_f32_16x16x32_bf16 v[24:27], v[86:89], v[94:97], v[24:27]
	v_mfma_f32_16x16x32_bf16 v[28:31], v[86:89], v[102:105], v[28:31]
	v_mfma_f32_16x16x32_bf16 v[36:39], v[86:89], v[106:109], v[36:39]
	global_load_dwordx4 v[86:89], v[126:127], off offset:192
	v_mfma_f32_16x16x32_bf16 v[20:23], v[118:121], v[82:85], v[20:23]
	v_mfma_f32_16x16x32_bf16 v[32:35], v[118:121], v[94:97], v[32:35]
	v_mfma_f32_16x16x32_bf16 v[40:43], v[118:121], v[102:105], v[40:43]
	v_mfma_f32_16x16x32_bf16 v[60:63], v[118:121], v[106:109], v[60:63]
	v_mfma_f32_16x16x32_bf16 v[56:59], v[76:79], v[90:93], v[56:59]
	v_mfma_f32_16x16x32_bf16 v[52:55], v[76:79], v[98:101], v[52:55]
	v_mfma_f32_16x16x32_bf16 v[48:51], v[76:79], v[72:75], v[48:51]
	v_mfma_f32_16x16x32_bf16 v[44:47], v[76:79], v[110:113], v[44:47]
	v_mfma_f32_16x16x32_bf16 v[12:15], v[68:71], v[90:93], v[12:15]
	v_mfma_f32_16x16x32_bf16 v[8:11], v[68:71], v[98:101], v[8:11]
	v_mfma_f32_16x16x32_bf16 v[4:7], v[68:71], v[72:75], v[4:7]
	v_mfma_f32_16x16x32_bf16 v[0:3], v[68:71], v[110:113], v[0:3]
	v_mfma_f32_16x16x32_bf16 v[16:19], v[114:117], v[90:93], v[16:19]
	v_mfma_f32_16x16x32_bf16 v[24:27], v[114:117], v[98:101], v[24:27]
	v_mfma_f32_16x16x32_bf16 v[28:31], v[114:117], v[72:75], v[28:31]
	v_mfma_f32_16x16x32_bf16 v[36:39], v[114:117], v[110:113], v[36:39]
	s_waitcnt vmcnt(0) lgkmcnt(0)
	v_mfma_f32_16x16x32_bf16 v[20:23], v[86:89], v[90:93], v[20:23]
	v_mfma_f32_16x16x32_bf16 v[32:35], v[86:89], v[98:101], v[32:35]
	v_mfma_f32_16x16x32_bf16 v[40:43], v[86:89], v[72:75], v[40:43]
	v_mfma_f32_16x16x32_bf16 v[60:63], v[86:89], v[110:113], v[60:63]
	s_cbranch_scc0 .LBB0_199
	v_and_b32_e32 v65, 63, v81
	s_ashr_i32 s2, s11, 7
	v_lshl_add_u32 v65, v65, 4, 0
	s_lshl_b32 s3, s2, 4
	v_lshl_add_u32 v66, s12, 14, v65
	s_addk_i32 s3, 0x4000
	ds_write_b128 v66, v[56:59]
	ds_write_b128 v66, v[52:55] offset:1024
	ds_write_b128 v66, v[48:51] offset:2048
	ds_write_b128 v66, v[44:47] offset:3072
	ds_write_b128 v66, v[12:15] offset:4096
	ds_write_b128 v66, v[8:11] offset:5120
	ds_write_b128 v66, v[4:7] offset:6144
	ds_write_b128 v66, v[0:3] offset:7168
	ds_write_b128 v66, v[16:19] offset:8192
	ds_write_b128 v66, v[24:27] offset:9216
	ds_write_b128 v66, v[28:31] offset:10240
	ds_write_b128 v66, v[36:39] offset:11264
	ds_write_b128 v66, v[20:23] offset:12288
	ds_write_b128 v66, v[32:35] offset:13312
	ds_write_b128 v66, v[40:43] offset:14336
	ds_write_b128 v66, v[60:63] offset:15360
	v_or_b32_e32 v0, s3, v80
	v_ashrrev_i32_e32 v1, 31, v0
	v_bfe_u32 v64, v81, 4, 2
	v_lshlrev_b64 v[2:3], 7, v[0:1]
	v_lshl_add_u64 v[2:3], s[6:7], 0, v[2:3]
	v_lshlrev_b32_e32 v128, 5, v64
	v_lshl_add_u64 v[6:7], v[2:3], 0, v[128:129]
	s_waitcnt lgkmcnt(0)
	s_barrier
	global_load_dwordx4 v[2:5], v[6:7], off
	s_nop 0
	global_load_dwordx4 v[6:9], v[6:7], off offset:16
	s_bfe_u32 s3, s11, 0x10006
	s_lshl_b32 s6, s3, 2
	s_add_i32 s6, s6, s2
	v_lshl_add_u32 v62, s6, 10, v65
	ds_read_b128 v[10:13], v62
	ds_read_b128 v[14:17], v62 offset:8192
	ds_read_b128 v[18:21], v62 offset:16384
	ds_read_b128 v[22:25], v62 offset:24576
	ds_read_b128 v[26:29], v62 offset:32768
	ds_read_b128 v[30:33], v62 offset:40960
	ds_read_b128 v[34:37], v62 offset:49152
	ds_read_b128 v[38:41], v62 offset:57344
	s_waitcnt lgkmcnt(0)
	v_pk_add_f32 v[10:11], v[10:11], 0 op_sel_hi:[1,0]
	v_pk_add_f32 v[12:13], v[12:13], 0 op_sel_hi:[1,0]
	v_pk_add_f32 v[10:11], v[10:11], v[18:19]
	v_pk_add_f32 v[12:13], v[12:13], v[20:21]
	v_add_u32_e32 v42, 0x10000, v62
	v_add_u32_e32 v46, 0x12000, v62
	v_add_u32_e32 v50, 0x14000, v62
	v_add_u32_e32 v54, 0x16000, v62
	v_add_u32_e32 v58, 0x18000, v62
	v_add_u32_e32 v63, 0x1a000, v62
	ds_read_b128 v[42:45], v42
	ds_read_b128 v[46:49], v46
	ds_read_b128 v[50:53], v50
	ds_read_b128 v[54:57], v54
	ds_read_b128 v[58:61], v58
	ds_read_b128 v[66:69], v63
	v_pk_add_f32 v[10:11], v[10:11], v[26:27]
	v_pk_add_f32 v[14:15], v[14:15], 0 op_sel_hi:[1,0]
	v_pk_add_f32 v[10:11], v[10:11], v[34:35]
	v_pk_add_f32 v[12:13], v[12:13], v[28:29]
	s_waitcnt lgkmcnt(0)
	v_pk_add_f32 v[10:11], v[10:11], v[42:43]
	v_pk_add_f32 v[16:17], v[16:17], 0 op_sel_hi:[1,0]
	v_pk_add_f32 v[10:11], v[10:11], v[50:51]
	v_pk_add_f32 v[14:15], v[14:15], v[22:23]
	v_pk_add_f32 v[10:11], v[10:11], v[58:59]
	v_pk_add_f32 v[12:13], v[12:13], v[36:37]
	s_ashr_i32 s2, s5, 5
	v_pk_add_f32 v[16:17], v[16:17], v[24:25]
	v_pk_add_f32 v[14:15], v[14:15], v[30:31]
	v_pk_add_f32 v[12:13], v[12:13], v[44:45]
	v_pk_add_f32 v[16:17], v[16:17], v[32:33]
	v_pk_add_f32 v[14:15], v[14:15], v[38:39]
	v_pk_add_f32 v[12:13], v[12:13], v[52:53]
	v_pk_add_f32 v[16:17], v[16:17], v[40:41]
	v_pk_add_f32 v[14:15], v[14:15], v[46:47]
	v_pk_add_f32 v[12:13], v[12:13], v[60:61]
	v_lshlrev_b64 v[0:1], 12, v[0:1]
	v_pk_add_f32 v[16:17], v[16:17], v[48:49]
	v_pk_add_f32 v[14:15], v[14:15], v[54:55]
	v_pk_add_f32 v[16:17], v[16:17], v[56:57]
	v_pk_add_f32 v[14:15], v[14:15], v[66:67]
	v_pk_add_f32 v[16:17], v[16:17], v[68:69]
	s_waitcnt vmcnt(0)
	v_mov_b32_e32 v18, v2
	v_mov_b32_e32 v19, v6
	v_mov_b32_e32 v6, v3
	v_pk_add_f32 v[2:3], v[18:19], v[6:7]
	v_mov_b32_e32 v6, v4
	v_mov_b32_e32 v7, v8
	v_mov_b32_e32 v8, v5
	v_pk_add_f32 v[4:5], v[6:7], v[8:9]
	v_add_u32_e32 v6, 0x1e000, v62
	v_pk_add_f32 v[2:3], v[2:3], v[4:5]
	s_nop 0
	v_add_f32_e32 v18, v2, v3
	v_and_b32_e32 v3, 64, v214
	v_xor_b32_e32 v2, 16, v214
	v_add_u32_e32 v19, 64, v3
	v_cmp_lt_i32_e32 vcc, v2, v19
	s_nop 1
	v_cndmask_b32_e32 v2, v214, v2, vcc
	v_lshlrev_b32_e32 v2, 2, v2
	ds_bpermute_b32 v20, v2, v18
	v_add_u32_e32 v2, 0x1c000, v62
	ds_read_b128 v[2:5], v2
	ds_read_b128 v[6:9], v6
	s_waitcnt lgkmcnt(2)
	v_add_f32_e32 v18, v18, v20
	v_xor_b32_e32 v20, 32, v214
	v_cmp_lt_i32_e32 vcc, v20, v19
	s_waitcnt lgkmcnt(1)
	v_pk_add_f32 v[2:3], v[10:11], v[2:3]
	v_pk_add_f32 v[4:5], v[12:13], v[4:5]
	v_cndmask_b32_e32 v19, v214, v20, vcc
	v_lshlrev_b32_e32 v19, 2, v19
	ds_bpermute_b32 v19, v19, v18
	s_waitcnt lgkmcnt(1)
	v_pk_add_f32 v[6:7], v[14:15], v[6:7]
	v_pk_add_f32 v[8:9], v[16:17], v[8:9]
	s_waitcnt lgkmcnt(0)
	v_add_f32_e32 v10, v18, v19
	v_fmamk_f32 v10, v10, 0x3a000000, v190
	v_mul_f32_e32 v11, 0x4b800000, v10
	v_cmp_gt_f32_e32 vcc, s70, v10
	s_nop 1
	v_cndmask_b32_e32 v10, v10, v11, vcc
	v_rsq_f32_e32 v10, v10
	v_lshlrev_b32_e32 v11, 2, v64
	v_lshl_or_b32 v11, s3, 4, v11
	s_mul_hi_i32 s3, s2, 0x4200000
	s_mul_i32 s2, s2, 0x4200000
	s_add_u32 s0, s0, s2
	s_addc_u32 s1, s1, s3
	v_mul_f32_e32 v12, 0x45800000, v10
	v_lshl_add_u64 v[0:1], s[0:1], 0, v[0:1]
	s_and_b32 s0, s4, 0x700
	v_or_b32_e32 v11, s10, v11
	v_cndmask_b32_e32 v10, v10, v12, vcc
	s_lshl_b32 s94, s0, 1
	v_lshl_add_u64 v[0:1], v[0:1], 0, s[94:95]
	v_lshlrev_b32_e32 v128, 1, v11
	v_pk_mul_f32 v[4:5], v[4:5], v[10:11] op_sel_hi:[1,0]
	v_pk_mul_f32 v[2:3], v[2:3], v[10:11] op_sel_hi:[1,0]
	v_lshl_add_u64 v[0:1], v[0:1], 0, v[128:129]
	v_cvt_pk_bf16_f32 v2, v2, v3
	v_cvt_pk_bf16_f32 v3, v4, v5
	v_pk_mul_f32 v[4:5], v[6:7], v[10:11] op_sel_hi:[1,0]
	global_store_dwordx2 v[0:1], v[2:3], off
	v_pk_mul_f32 v[2:3], v[8:9], v[10:11] op_sel_hi:[1,0]
	v_cvt_pk_bf16_f32 v4, v4, v5
	s_nop 0
	v_cvt_pk_bf16_f32 v5, v2, v3
	global_store_dwordx2 v[0:1], v[4:5], off offset:256
	s_waitcnt lgkmcnt(0)
	s_barrier

.LBB0_205:
	s_movk_i32 s0, 0xd000
	v_add_co_u32_e64 v80, s[38:39], s0, v76
	s_movk_i32 s0, 0xe000
	s_nop 0
	v_addc_co_u32_e64 v81, s[38:39], -1, v77, s[38:39]
	v_add_co_u32_e64 v84, s[38:39], s0, v76
	s_movk_i32 s0, 0xf000
	s_nop 0
	v_addc_co_u32_e64 v85, s[38:39], -1, v77, s[38:39]
	v_add_co_u32_e64 v98, s[38:39], s0, v76
	global_load_dwordx2 v[80:81], v[80:81], off
	s_nop 0
	v_addc_co_u32_e64 v99, s[38:39], -1, v77, s[38:39]
	global_load_dwordx2 v[84:85], v[84:85], off
	v_lshl_add_u64 v[156:157], v[6:7], 0, s[46:47]
	global_load_dwordx2 v[98:99], v[98:99], off
	s_add_u32 s46, s46, 0x4000
	global_load_dwordx4 v[94:97], v[74:75], off
	s_mov_b64 s[0:1], 0x200
	s_addc_u32 s47, s47, 0
	s_cmp_eq_u32 s46, 0x20000
	s_waitcnt vmcnt(0) lgkmcnt(0)
	v_lshlrev_b32_e32 v86, 16, v84
	v_and_b32_e32 v87, 0xffff0000, v84
	v_lshlrev_b32_e32 v100, 16, v98
	v_and_b32_e32 v101, 0xffff0000, v98
	v_lshlrev_b32_e32 v98, 16, v99
	v_and_b32_e32 v99, 0xffff0000, v99
	v_pk_mul_f32 v[126:127], v[96:97], v[98:99]
	global_load_dwordx2 v[98:99], v[76:77], off
	v_lshlrev_b32_e32 v82, 16, v80
	v_and_b32_e32 v83, 0xffff0000, v80
	v_lshlrev_b32_e32 v80, 16, v81
	v_and_b32_e32 v81, 0xffff0000, v81
	v_lshlrev_b32_e32 v84, 16, v85
	v_and_b32_e32 v85, 0xffff0000, v85
	v_pk_mul_f32 v[150:151], v[94:95], v[100:101]
	v_pk_mul_f32 v[80:81], v[96:97], v[80:81]
	v_pk_mul_f32 v[82:83], v[94:95], v[82:83]
	v_pk_mul_f32 v[84:85], v[96:97], v[84:85]
	v_pk_mul_f32 v[86:87], v[94:95], v[86:87]
	v_lshl_add_u64 v[76:77], v[76:77], 0, s[0:1]
	s_mov_b64 s[0:1], 0x400
	v_lshl_add_u64 v[74:75], v[74:75], 0, s[0:1]
	s_waitcnt vmcnt(0) lgkmcnt(0)
	v_lshlrev_b32_e32 v100, 16, v98
	v_and_b32_e32 v101, 0xffff0000, v98
	v_lshlrev_b32_e32 v98, 16, v99
	v_and_b32_e32 v99, 0xffff0000, v99
	v_pk_mul_f32 v[152:153], v[96:97], v[98:99]
	v_pk_mul_f32 v[154:155], v[94:95], v[100:101]
	global_load_dwordx4 v[94:97], v[156:157], off
	global_load_dwordx4 v[98:101], v[156:157], off offset:16
	global_load_dwordx4 v[102:105], v[156:157], off offset:32
	global_load_dwordx4 v[106:109], v[156:157], off offset:48
	global_load_dwordx4 v[110:113], v[156:157], off offset:64
	global_load_dwordx4 v[114:117], v[156:157], off offset:80
	global_load_dwordx4 v[118:121], v[156:157], off offset:96
	global_load_dwordx4 v[122:125], v[156:157], off offset:112
	global_load_dwordx4 v[130:133], v[156:157], off offset:128
	global_load_dwordx4 v[134:137], v[156:157], off offset:144
	global_load_dwordx4 v[138:141], v[156:157], off offset:160
	global_load_dwordx4 v[142:145], v[156:157], off offset:176
	global_load_dwordx4 v[146:149], v[156:157], off offset:192
	s_waitcnt vmcnt(0) lgkmcnt(0)
	v_pk_fma_f32 v[78:79], v[94:95], v[82:83], v[78:79] op_sel_hi:[1,0,1]
	v_pk_fma_f32 v[72:73], v[96:97], v[82:83], v[72:73] op_sel_hi:[1,0,1]
	v_pk_fma_f32 v[58:59], v[94:95], v[86:87], v[58:59] op_sel_hi:[1,0,1]
	v_pk_fma_f32 v[56:57], v[96:97], v[86:87], v[56:57] op_sel_hi:[1,0,1]
	v_pk_fma_f32 v[42:43], v[94:95], v[150:151], v[42:43] op_sel_hi:[1,0,1]
	v_pk_fma_f32 v[40:41], v[96:97], v[150:151], v[40:41] op_sel_hi:[1,0,1]
	v_pk_fma_f32 v[26:27], v[94:95], v[154:155], v[26:27] op_sel_hi:[1,0,1]
	v_pk_fma_f32 v[24:25], v[96:97], v[154:155], v[24:25] op_sel_hi:[1,0,1]
	global_load_dwordx4 v[94:97], v[156:157], off offset:208
	v_pk_fma_f32 v[70:71], v[98:99], v[82:83], v[70:71] op_sel_hi:[1,0,1]
	v_pk_fma_f32 v[68:69], v[100:101], v[82:83], v[68:69] op_sel_hi:[1,0,1]
	v_pk_fma_f32 v[54:55], v[98:99], v[86:87], v[54:55] op_sel_hi:[1,0,1]
	v_pk_fma_f32 v[52:53], v[100:101], v[86:87], v[52:53] op_sel_hi:[1,0,1]
	v_pk_fma_f32 v[38:39], v[98:99], v[150:151], v[38:39] op_sel_hi:[1,0,1]
	v_pk_fma_f32 v[36:37], v[100:101], v[150:151], v[36:37] op_sel_hi:[1,0,1]
	v_pk_fma_f32 v[22:23], v[98:99], v[154:155], v[22:23] op_sel_hi:[1,0,1]
	v_pk_fma_f32 v[20:21], v[100:101], v[154:155], v[20:21] op_sel_hi:[1,0,1]
	v_pk_fma_f32 v[70:71], v[82:83], v[114:115], v[70:71] op_sel:[1,0,0]
	v_pk_fma_f32 v[68:69], v[82:83], v[116:117], v[68:69] op_sel:[1,0,0]
	v_pk_fma_f32 v[54:55], v[114:115], v[86:87], v[54:55] op_sel:[0,1,0]
	v_pk_fma_f32 v[52:53], v[116:117], v[86:87], v[52:53] op_sel:[0,1,0]
	v_pk_fma_f32 v[38:39], v[114:115], v[150:151], v[38:39] op_sel:[0,1,0]
	v_pk_fma_f32 v[36:37], v[116:117], v[150:151], v[36:37] op_sel:[0,1,0]
	v_pk_fma_f32 v[22:23], v[114:115], v[154:155], v[22:23] op_sel:[0,1,0]
	v_pk_fma_f32 v[20:21], v[116:117], v[154:155], v[20:21] op_sel:[0,1,0]
	v_pk_fma_f32 v[70:71], v[80:81], v[134:135], v[70:71] op_sel_hi:[0,1,1]
	v_pk_fma_f32 v[68:69], v[80:81], v[136:137], v[68:69] op_sel_hi:[0,1,1]
	v_pk_fma_f32 v[54:55], v[84:85], v[134:135], v[54:55] op_sel_hi:[0,1,1]
	v_pk_fma_f32 v[52:53], v[84:85], v[136:137], v[52:53] op_sel_hi:[0,1,1]
	v_pk_fma_f32 v[38:39], v[126:127], v[134:135], v[38:39] op_sel_hi:[0,1,1]
	v_pk_fma_f32 v[36:37], v[126:127], v[136:137], v[36:37] op_sel_hi:[0,1,1]
	v_pk_fma_f32 v[22:23], v[152:153], v[134:135], v[22:23] op_sel_hi:[0,1,1]
	v_pk_fma_f32 v[20:21], v[152:153], v[136:137], v[20:21] op_sel_hi:[0,1,1]
	v_pk_fma_f32 v[66:67], v[102:103], v[82:83], v[66:67] op_sel_hi:[1,0,1]
	v_pk_fma_f32 v[64:65], v[104:105], v[82:83], v[64:65] op_sel_hi:[1,0,1]
	v_pk_fma_f32 v[50:51], v[102:103], v[86:87], v[50:51] op_sel_hi:[1,0,1]
	v_pk_fma_f32 v[48:49], v[104:105], v[86:87], v[48:49] op_sel_hi:[1,0,1]
	v_pk_fma_f32 v[34:35], v[102:103], v[150:151], v[34:35] op_sel_hi:[1,0,1]
	v_pk_fma_f32 v[32:33], v[104:105], v[150:151], v[32:33] op_sel_hi:[1,0,1]
	v_pk_fma_f32 v[18:19], v[102:103], v[154:155], v[18:19] op_sel_hi:[1,0,1]
	v_pk_fma_f32 v[12:13], v[104:105], v[154:155], v[12:13] op_sel_hi:[1,0,1]
	v_pk_fma_f32 v[66:67], v[82:83], v[118:119], v[66:67] op_sel:[1,0,0]
	v_pk_fma_f32 v[64:65], v[82:83], v[120:121], v[64:65] op_sel:[1,0,0]
	v_pk_fma_f32 v[50:51], v[86:87], v[118:119], v[50:51] op_sel:[1,0,0]
	v_pk_fma_f32 v[48:49], v[86:87], v[120:121], v[48:49] op_sel:[1,0,0]
	v_pk_fma_f32 v[34:35], v[118:119], v[150:151], v[34:35] op_sel:[0,1,0]
	v_pk_fma_f32 v[32:33], v[120:121], v[150:151], v[32:33] op_sel:[0,1,0]
	v_pk_fma_f32 v[18:19], v[118:119], v[154:155], v[18:19] op_sel:[0,1,0]
	v_pk_fma_f32 v[12:13], v[120:121], v[154:155], v[12:13] op_sel:[0,1,0]
	v_pk_fma_f32 v[66:67], v[80:81], v[138:139], v[66:67] op_sel_hi:[0,1,1]
	v_pk_fma_f32 v[64:65], v[80:81], v[140:141], v[64:65] op_sel_hi:[0,1,1]
	v_pk_fma_f32 v[50:51], v[84:85], v[138:139], v[50:51] op_sel_hi:[0,1,1]
	v_pk_fma_f32 v[48:49], v[84:85], v[140:141], v[48:49] op_sel_hi:[0,1,1]
	v_pk_fma_f32 v[34:35], v[126:127], v[138:139], v[34:35] op_sel_hi:[0,1,1]
	v_pk_fma_f32 v[32:33], v[126:127], v[140:141], v[32:33] op_sel_hi:[0,1,1]
	v_pk_fma_f32 v[18:19], v[152:153], v[138:139], v[18:19] op_sel_hi:[0,1,1]
	v_pk_fma_f32 v[12:13], v[152:153], v[140:141], v[12:13] op_sel_hi:[0,1,1]
	v_pk_fma_f32 v[62:63], v[106:107], v[82:83], v[62:63] op_sel_hi:[1,0,1]
	v_pk_fma_f32 v[60:61], v[108:109], v[82:83], v[60:61] op_sel_hi:[1,0,1]
	v_pk_fma_f32 v[46:47], v[106:107], v[86:87], v[46:47] op_sel_hi:[1,0,1]
	v_pk_fma_f32 v[44:45], v[108:109], v[86:87], v[44:45] op_sel_hi:[1,0,1]
	v_pk_fma_f32 v[30:31], v[106:107], v[150:151], v[30:31] op_sel_hi:[1,0,1]
	v_pk_fma_f32 v[28:29], v[108:109], v[150:151], v[28:29] op_sel_hi:[1,0,1]
	v_pk_fma_f32 v[16:17], v[106:107], v[154:155], v[16:17] op_sel_hi:[1,0,1]
	v_pk_fma_f32 v[14:15], v[108:109], v[154:155], v[14:15] op_sel_hi:[1,0,1]
	v_pk_fma_f32 v[78:79], v[110:111], v[82:83], v[78:79] op_sel:[0,1,0]
	v_pk_fma_f32 v[72:73], v[112:113], v[82:83], v[72:73] op_sel:[0,1,0]
	v_pk_fma_f32 v[58:59], v[110:111], v[86:87], v[58:59] op_sel:[0,1,0]
	v_pk_fma_f32 v[56:57], v[112:113], v[86:87], v[56:57] op_sel:[0,1,0]
	v_pk_fma_f32 v[42:43], v[110:111], v[150:151], v[42:43] op_sel:[0,1,0]
	v_pk_fma_f32 v[40:41], v[112:113], v[150:151], v[40:41] op_sel:[0,1,0]
	v_pk_fma_f32 v[26:27], v[110:111], v[154:155], v[26:27] op_sel:[0,1,0]
	v_pk_fma_f32 v[24:25], v[112:113], v[154:155], v[24:25] op_sel:[0,1,0]
	v_pk_fma_f32 v[62:63], v[82:83], v[122:123], v[62:63] op_sel:[1,0,0]
	v_pk_fma_f32 v[60:61], v[82:83], v[124:125], v[60:61] op_sel:[1,0,0]
	v_pk_fma_f32 v[46:47], v[86:87], v[122:123], v[46:47] op_sel:[1,0,0]
	v_pk_fma_f32 v[44:45], v[86:87], v[124:125], v[44:45] op_sel:[1,0,0]
	v_pk_fma_f32 v[30:31], v[150:151], v[122:123], v[30:31] op_sel:[1,0,0]
	v_pk_fma_f32 v[28:29], v[150:151], v[124:125], v[28:29] op_sel:[1,0,0]
	v_pk_fma_f32 v[16:17], v[122:123], v[154:155], v[16:17] op_sel:[0,1,0]
	v_pk_fma_f32 v[14:15], v[124:125], v[154:155], v[14:15] op_sel:[0,1,0]
	v_pk_fma_f32 v[78:79], v[80:81], v[130:131], v[78:79] op_sel_hi:[0,1,1]
	v_pk_fma_f32 v[72:73], v[80:81], v[132:133], v[72:73] op_sel_hi:[0,1,1]
	v_pk_fma_f32 v[58:59], v[84:85], v[130:131], v[58:59] op_sel_hi:[0,1,1]
	v_pk_fma_f32 v[56:57], v[84:85], v[132:133], v[56:57] op_sel_hi:[0,1,1]
	v_pk_fma_f32 v[42:43], v[126:127], v[130:131], v[42:43] op_sel_hi:[0,1,1]
	v_pk_fma_f32 v[40:41], v[126:127], v[132:133], v[40:41] op_sel_hi:[0,1,1]
	v_pk_fma_f32 v[26:27], v[152:153], v[130:131], v[26:27] op_sel_hi:[0,1,1]
	s_waitcnt vmcnt(0) lgkmcnt(0)
	v_pk_fma_f32 v[70:71], v[80:81], v[94:95], v[70:71] op_sel:[1,0,0]
	v_pk_fma_f32 v[68:69], v[80:81], v[96:97], v[68:69] op_sel:[1,0,0]
	v_pk_fma_f32 v[54:55], v[84:85], v[94:95], v[54:55] op_sel:[1,0,0]
	v_pk_fma_f32 v[52:53], v[84:85], v[96:97], v[52:53] op_sel:[1,0,0]
	v_pk_fma_f32 v[38:39], v[126:127], v[94:95], v[38:39] op_sel:[1,0,0]
	v_pk_fma_f32 v[36:37], v[126:127], v[96:97], v[36:37] op_sel:[1,0,0]
	v_pk_fma_f32 v[22:23], v[152:153], v[94:95], v[22:23] op_sel:[1,0,0]
	v_pk_fma_f32 v[20:21], v[152:153], v[96:97], v[20:21] op_sel:[1,0,0]
	global_load_dwordx4 v[94:97], v[156:157], off offset:224
	v_pk_fma_f32 v[24:25], v[152:153], v[132:133], v[24:25] op_sel_hi:[0,1,1]
	v_pk_fma_f32 v[62:63], v[80:81], v[142:143], v[62:63] op_sel_hi:[0,1,1]
	v_pk_fma_f32 v[60:61], v[80:81], v[144:145], v[60:61] op_sel_hi:[0,1,1]
	v_pk_fma_f32 v[46:47], v[84:85], v[142:143], v[46:47] op_sel_hi:[0,1,1]
	v_pk_fma_f32 v[44:45], v[84:85], v[144:145], v[44:45] op_sel_hi:[0,1,1]
	v_pk_fma_f32 v[30:31], v[126:127], v[142:143], v[30:31] op_sel_hi:[0,1,1]
	v_pk_fma_f32 v[28:29], v[126:127], v[144:145], v[28:29] op_sel_hi:[0,1,1]
	v_pk_fma_f32 v[16:17], v[152:153], v[142:143], v[16:17] op_sel_hi:[0,1,1]
	v_pk_fma_f32 v[14:15], v[152:153], v[144:145], v[14:15] op_sel_hi:[0,1,1]
	v_pk_fma_f32 v[78:79], v[80:81], v[146:147], v[78:79] op_sel:[1,0,0]
	v_pk_fma_f32 v[72:73], v[80:81], v[148:149], v[72:73] op_sel:[1,0,0]
	v_pk_fma_f32 v[58:59], v[84:85], v[146:147], v[58:59] op_sel:[1,0,0]
	v_pk_fma_f32 v[56:57], v[84:85], v[148:149], v[56:57] op_sel:[1,0,0]
	v_pk_fma_f32 v[42:43], v[126:127], v[146:147], v[42:43] op_sel:[1,0,0]
	v_pk_fma_f32 v[40:41], v[126:127], v[148:149], v[40:41] op_sel:[1,0,0]
	v_pk_fma_f32 v[26:27], v[152:153], v[146:147], v[26:27] op_sel:[1,0,0]
	v_pk_fma_f32 v[24:25], v[152:153], v[148:149], v[24:25] op_sel:[1,0,0]
	s_waitcnt vmcnt(0) lgkmcnt(0)
	v_pk_fma_f32 v[66:67], v[80:81], v[94:95], v[66:67] op_sel:[1,0,0]
	v_pk_fma_f32 v[64:65], v[80:81], v[96:97], v[64:65] op_sel:[1,0,0]
	v_pk_fma_f32 v[50:51], v[84:85], v[94:95], v[50:51] op_sel:[1,0,0]
	v_pk_fma_f32 v[48:49], v[84:85], v[96:97], v[48:49] op_sel:[1,0,0]
	v_pk_fma_f32 v[34:35], v[126:127], v[94:95], v[34:35] op_sel:[1,0,0]
	v_pk_fma_f32 v[32:33], v[126:127], v[96:97], v[32:33] op_sel:[1,0,0]
	v_pk_fma_f32 v[18:19], v[152:153], v[94:95], v[18:19] op_sel:[1,0,0]
	v_pk_fma_f32 v[12:13], v[152:153], v[96:97], v[12:13] op_sel:[1,0,0]
	global_load_dwordx4 v[94:97], v[156:157], off offset:240
	s_waitcnt vmcnt(0) lgkmcnt(0)
	v_pk_fma_f32 v[62:63], v[80:81], v[94:95], v[62:63] op_sel:[1,0,0]
	v_pk_fma_f32 v[60:61], v[80:81], v[96:97], v[60:61] op_sel:[1,0,0]
	v_pk_fma_f32 v[46:47], v[84:85], v[94:95], v[46:47] op_sel:[1,0,0]
	v_pk_fma_f32 v[44:45], v[84:85], v[96:97], v[44:45] op_sel:[1,0,0]
	v_pk_fma_f32 v[30:31], v[126:127], v[94:95], v[30:31] op_sel:[1,0,0]
	v_pk_fma_f32 v[28:29], v[126:127], v[96:97], v[28:29] op_sel:[1,0,0]
	v_pk_fma_f32 v[16:17], v[152:153], v[94:95], v[16:17] op_sel:[1,0,0]
	v_pk_fma_f32 v[14:15], v[152:153], v[96:97], v[14:15] op_sel:[1,0,0]
	s_cbranch_scc0 .LBB0_205
	s_ashr_i32 s43, s42, 31
	v_mov_b32_e32 v74, 0
	s_and_saveexec_b64 s[38:39], vcc
	s_cbranch_execz .LBB0_208
	s_lshl_b64 s[0:1], s[42:43], 7
	v_lshl_add_u64 v[74:75], v[0:1], 0, s[0:1]
	global_load_dword v74, v[74:75], off
.LBB0_208:
	s_or_b64 exec, exec, s[38:39]
	s_waitcnt vmcnt(0) lgkmcnt(0)
	ds_bpermute_b32 v75, v88, v74
	ds_bpermute_b32 v76, v88, v78
	ds_bpermute_b32 v80, v88, v72
	ds_bpermute_b32 v99, v88, v61
	s_waitcnt lgkmcnt(3)
	v_add_f32_e32 v74, v74, v75
	s_waitcnt lgkmcnt(2)
	v_add_f32_e32 v75, v78, v76
	ds_bpermute_b32 v76, v89, v74
	ds_bpermute_b32 v77, v89, v75
	ds_bpermute_b32 v78, v88, v79
	s_waitcnt lgkmcnt(4)
	v_add_f32_e32 v80, v72, v80
	s_waitcnt lgkmcnt(3)
	v_add_f32_e32 v61, v61, v99
	s_waitcnt lgkmcnt(2)
	v_add_f32_e32 v74, v74, v76
	s_waitcnt lgkmcnt(1)
	v_add_f32_e32 v75, v75, v77
	s_waitcnt lgkmcnt(0)
	v_add_f32_e32 v78, v79, v78
	ds_bpermute_b32 v76, v90, v74
	ds_bpermute_b32 v77, v90, v75
	ds_bpermute_b32 v79, v89, v78
	ds_bpermute_b32 v99, v89, v61
	s_waitcnt lgkmcnt(3)
	v_add_f32_e32 v74, v74, v76
	s_waitcnt lgkmcnt(2)
	v_add_f32_e32 v75, v75, v77
	s_waitcnt lgkmcnt(1)
	v_add_f32_e32 v72, v78, v79
	ds_bpermute_b32 v76, v91, v74
	ds_bpermute_b32 v77, v91, v75
	ds_bpermute_b32 v78, v90, v72
	ds_bpermute_b32 v79, v89, v80
	s_waitcnt lgkmcnt(4)
	v_add_f32_e32 v61, v61, v99
	s_waitcnt lgkmcnt(3)
	v_add_f32_e32 v74, v74, v76
	s_waitcnt lgkmcnt(2)
	v_add_f32_e32 v76, v75, v77
	s_waitcnt lgkmcnt(1)
	v_add_f32_e32 v78, v72, v78
	ds_bpermute_b32 v75, v92, v74
	ds_bpermute_b32 v77, v92, v76
	ds_bpermute_b32 v81, v91, v78
	s_waitcnt lgkmcnt(3)
	v_add_f32_e32 v79, v80, v79
	ds_bpermute_b32 v80, v90, v79
	s_waitcnt lgkmcnt(3)
	v_add_f32_e32 v75, v74, v75
	s_waitcnt lgkmcnt(2)
	v_add_f32_e32 v72, v76, v77
	ds_bpermute_b32 v74, v88, v73
	s_waitcnt lgkmcnt(2)
	v_add_f32_e32 v77, v78, v81
	ds_bpermute_b32 v78, v92, v77
	ds_bpermute_b32 v99, v90, v61
	ds_bpermute_b32 v76, v93, v75
	s_waitcnt lgkmcnt(3)
	v_add_f32_e32 v81, v73, v74
	ds_bpermute_b32 v82, v89, v81
	s_waitcnt lgkmcnt(3)
	v_add_f32_e32 v74, v77, v78
	v_add_f32_e32 v78, v79, v80
	ds_bpermute_b32 v79, v91, v78
	s_waitcnt lgkmcnt(3)
	v_add_f32_e32 v61, v61, v99
	s_waitcnt lgkmcnt(1)
	v_add_f32_e32 v80, v81, v82
	ds_bpermute_b32 v81, v90, v80
	ds_bpermute_b32 v82, v88, v70
	s_waitcnt lgkmcnt(2)
	v_add_f32_e32 v78, v78, v79
	ds_bpermute_b32 v79, v92, v78
	ds_bpermute_b32 v99, v91, v61
	s_waitcnt lgkmcnt(3)
	v_add_f32_e32 v80, v80, v81
	s_waitcnt lgkmcnt(2)
	v_add_f32_e32 v82, v70, v82
	ds_bpermute_b32 v81, v91, v80
	ds_bpermute_b32 v83, v89, v82
	s_waitcnt lgkmcnt(3)
	v_add_f32_e32 v70, v78, v79
	ds_bpermute_b32 v78, v88, v71
	s_waitcnt lgkmcnt(3)
	v_add_f32_e32 v99, v61, v99
	s_waitcnt lgkmcnt(2)
	v_add_f32_e32 v79, v80, v81
	s_waitcnt lgkmcnt(1)
	v_add_f32_e32 v81, v82, v83
	ds_bpermute_b32 v80, v92, v79
	s_waitcnt lgkmcnt(1)
	v_add_f32_e32 v83, v71, v78
	ds_bpermute_b32 v82, v90, v81
	ds_bpermute_b32 v84, v89, v83
	ds_bpermute_b32 v101, v92, v99
	s_waitcnt lgkmcnt(3)
	v_add_f32_e32 v78, v79, v80
	ds_bpermute_b32 v73, v93, v72
	s_waitcnt lgkmcnt(3)
	v_add_f32_e32 v80, v81, v82
	s_waitcnt lgkmcnt(2)
	v_add_f32_e32 v82, v83, v84
	ds_bpermute_b32 v81, v91, v80
	ds_bpermute_b32 v83, v90, v82
	ds_bpermute_b32 v84, v88, v68
	ds_bpermute_b32 v77, v93, v74
	ds_bpermute_b32 v71, v93, v70
	s_waitcnt lgkmcnt(4)
	v_add_f32_e32 v80, v80, v81
	s_waitcnt lgkmcnt(3)
	v_add_f32_e32 v82, v82, v83
	s_waitcnt lgkmcnt(2)
	v_add_f32_e32 v84, v68, v84
	ds_bpermute_b32 v81, v92, v80
	ds_bpermute_b32 v83, v91, v82
	ds_bpermute_b32 v85, v89, v84
	ds_bpermute_b32 v79, v93, v78
	s_waitcnt lgkmcnt(3)
	v_add_f32_e32 v68, v80, v81
	ds_bpermute_b32 v80, v88, v69
	s_waitcnt lgkmcnt(3)
	v_add_f32_e32 v81, v82, v83
	s_waitcnt lgkmcnt(2)
	v_add_f32_e32 v83, v84, v85
	ds_bpermute_b32 v82, v92, v81
	ds_bpermute_b32 v84, v90, v83
	s_waitcnt lgkmcnt(2)
	v_add_f32_e32 v85, v69, v80
	ds_bpermute_b32 v86, v89, v85
	ds_bpermute_b32 v69, v93, v68
	s_waitcnt lgkmcnt(3)
	v_add_f32_e32 v80, v81, v82
	s_waitcnt lgkmcnt(2)
	v_add_f32_e32 v82, v83, v84
	ds_bpermute_b32 v83, v91, v82
	s_waitcnt lgkmcnt(2)
	v_add_f32_e32 v84, v85, v86
	ds_bpermute_b32 v85, v90, v84
	ds_bpermute_b32 v86, v88, v66
	ds_bpermute_b32 v81, v93, v80
	s_waitcnt lgkmcnt(3)
	v_add_f32_e32 v82, v82, v83
	ds_bpermute_b32 v83, v92, v82
	s_waitcnt lgkmcnt(3)
	v_add_f32_e32 v84, v84, v85
	s_waitcnt lgkmcnt(2)
	v_add_f32_e32 v86, v66, v86
	ds_bpermute_b32 v85, v91, v84
	ds_bpermute_b32 v87, v89, v86
	s_waitcnt lgkmcnt(2)
	v_add_f32_e32 v66, v82, v83
	ds_bpermute_b32 v82, v88, v67
	s_waitcnt lgkmcnt(2)
	v_add_f32_e32 v83, v84, v85
	s_waitcnt lgkmcnt(1)
	v_add_f32_e32 v85, v86, v87
	ds_bpermute_b32 v84, v92, v83
	s_waitcnt lgkmcnt(1)
	v_add_f32_e32 v87, v67, v82
	ds_bpermute_b32 v86, v90, v85
	ds_bpermute_b32 v94, v89, v87
	ds_bpermute_b32 v67, v93, v66
	s_waitcnt lgkmcnt(3)
	v_add_f32_e32 v82, v83, v84
	ds_bpermute_b32 v83, v93, v82
	s_waitcnt lgkmcnt(3)
	v_add_f32_e32 v84, v85, v86
	s_waitcnt lgkmcnt(2)
	v_add_f32_e32 v86, v87, v94
	ds_bpermute_b32 v85, v91, v84
	ds_bpermute_b32 v87, v90, v86
	ds_bpermute_b32 v94, v88, v64
	s_waitcnt lgkmcnt(2)
	v_add_f32_e32 v84, v84, v85
	s_waitcnt lgkmcnt(1)
	v_add_f32_e32 v86, v86, v87
	s_waitcnt lgkmcnt(0)
	v_add_f32_e32 v94, v64, v94
	ds_bpermute_b32 v85, v92, v84
	ds_bpermute_b32 v87, v91, v86
	ds_bpermute_b32 v95, v89, v94
	s_waitcnt lgkmcnt(2)
	v_add_f32_e32 v64, v84, v85
	s_waitcnt lgkmcnt(1)
	v_add_f32_e32 v85, v86, v87
	s_waitcnt lgkmcnt(0)
	v_add_f32_e32 v87, v94, v95
	ds_bpermute_b32 v86, v88, v65
	ds_bpermute_b32 v94, v90, v87
	ds_bpermute_b32 v95, v88, v62
	ds_bpermute_b32 v96, v92, v85
	ds_bpermute_b32 v84, v93, v64
	s_waitcnt lgkmcnt(4)
	v_add_f32_e32 v65, v65, v86
	s_waitcnt lgkmcnt(3)
	v_add_f32_e32 v87, v87, v94
	s_waitcnt lgkmcnt(2)
	v_add_f32_e32 v94, v62, v95
	ds_bpermute_b32 v86, v89, v65
	ds_bpermute_b32 v95, v89, v94
	s_waitcnt lgkmcnt(3)
	v_add_f32_e32 v62, v85, v96
	ds_bpermute_b32 v97, v91, v87
	s_waitcnt lgkmcnt(2)
	v_add_f32_e32 v65, v65, v86
	s_waitcnt lgkmcnt(1)
	v_add_f32_e32 v85, v94, v95
	ds_bpermute_b32 v86, v90, v65
	ds_bpermute_b32 v94, v90, v85
	s_waitcnt lgkmcnt(2)
	v_add_f32_e32 v87, v87, v97
	ds_bpermute_b32 v96, v92, v87
	s_waitcnt lgkmcnt(2)
	v_add_f32_e32 v86, v65, v86
	s_waitcnt lgkmcnt(1)
	v_add_f32_e32 v94, v85, v94
	ds_bpermute_b32 v95, v91, v86
	ds_bpermute_b32 v97, v91, v94
	s_waitcnt lgkmcnt(2)
	v_add_f32_e32 v85, v87, v96
	ds_bpermute_b32 v65, v93, v62
	s_waitcnt lgkmcnt(2)
	v_add_f32_e32 v95, v86, v95
	s_waitcnt lgkmcnt(1)
	v_add_f32_e32 v96, v94, v97
	ds_bpermute_b32 v98, v92, v95
	ds_bpermute_b32 v97, v92, v96
	ds_bpermute_b32 v86, v93, v85
	s_waitcnt lgkmcnt(2)
	v_add_f32_e32 v87, v95, v98
	ds_bpermute_b32 v98, v88, v63
	s_waitcnt lgkmcnt(2)
	v_add_f32_e32 v95, v96, v97
	ds_bpermute_b32 v97, v88, v60
	ds_bpermute_b32 v94, v93, v87
	ds_bpermute_b32 v96, v93, v95
	s_waitcnt lgkmcnt(3)
	v_add_f32_e32 v63, v63, v98
	ds_bpermute_b32 v98, v89, v63
	s_waitcnt lgkmcnt(3)
	v_add_f32_e32 v60, v60, v97
	ds_bpermute_b32 v97, v89, v60
	s_waitcnt lgkmcnt(1)
	v_add_f32_e32 v63, v63, v98
	ds_bpermute_b32 v98, v90, v63
	s_waitcnt lgkmcnt(1)
	v_add_f32_e32 v60, v60, v97
	ds_bpermute_b32 v97, v90, v60
	s_waitcnt lgkmcnt(1)
	v_add_f32_e32 v63, v63, v98
	ds_bpermute_b32 v98, v91, v63
	s_waitcnt lgkmcnt(1)
	v_add_f32_e32 v60, v60, v97
	ds_bpermute_b32 v97, v91, v60
	s_waitcnt lgkmcnt(1)
	v_add_f32_e32 v63, v63, v98
	ds_bpermute_b32 v98, v92, v63
	s_waitcnt lgkmcnt(1)
	v_add_f32_e32 v97, v60, v97
	ds_bpermute_b32 v100, v92, v97
	s_waitcnt lgkmcnt(1)
	v_add_f32_e32 v60, v63, v98
	v_add_f32_e32 v98, v99, v101
	s_waitcnt lgkmcnt(0)
	v_add_f32_e32 v63, v97, v100
	ds_bpermute_b32 v61, v93, v60
	ds_bpermute_b32 v97, v93, v63
	ds_bpermute_b32 v99, v93, v98
	s_and_saveexec_b64 s[46:47], s[2:3]
	s_cbranch_execz .LBB0_210
	v_add_f32_e32 v72, v72, v73
	v_add_f32_e32 v70, v70, v71
	v_add_f32_e32 v71, v74, v77
	v_cndmask_b32_e64 v72, 0, v72, s[4:5]
	v_cndmask_b32_e64 v71, v72, v71, s[6:7]
	v_add_f32_e32 v68, v68, v69
	v_add_f32_e32 v69, v78, v79
	v_cndmask_b32_e64 v70, v71, v70, s[8:9]
	v_cndmask_b32_e64 v69, v70, v69, s[10:11]
	v_add_f32_e32 v66, v66, v67
	v_add_f32_e32 v67, v80, v81
	v_cndmask_b32_e64 v68, v69, v68, s[12:13]
	v_cndmask_b32_e64 v67, v68, v67, s[14:15]
	v_add_f32_e32 v62, v62, v65
	v_add_f32_e32 v65, v82, v83
	v_cndmask_b32_e64 v66, v67, v66, s[16:17]
	v_add_f32_e32 v64, v64, v84
	v_cndmask_b32_e64 v65, v66, v65, s[18:19]
	v_cndmask_b32_e64 v64, v65, v64, s[20:21]
	v_add_f32_e32 v85, v85, v86
	v_cndmask_b32_e64 v62, v64, v62, s[22:23]
	v_add_f32_e32 v87, v87, v94
	v_cndmask_b32_e64 v62, v62, v85, s[24:25]
	s_waitcnt lgkmcnt(2)
	v_add_f32_e32 v60, v60, v61
	v_add_f32_e32 v61, v95, v96
	v_cndmask_b32_e64 v62, v62, v87, s[26:27]
	v_cndmask_b32_e64 v61, v62, v61, s[28:29]
	v_cndmask_b32_e64 v60, v61, v60, s[30:31]
	global_load_dword v61, v[4:5], off
	v_add_f32_e32 v75, v75, v76
	v_fmamk_f32 v75, v75, 0x3a000000, v190
	v_cmp_gt_f32_e64 s[38:39], s70, v75
	v_mul_f32_e32 v76, 0x4b800000, v75
	s_waitcnt lgkmcnt(0)
	v_add_f32_e32 v63, v63, v97
	v_cndmask_b32_e64 v75, v75, v76, s[38:39]
	v_rsq_f32_e32 v75, v75
	v_cndmask_b32_e64 v60, v60, v63, s[34:35]
	s_mov_b32 s0, 0xbfb8aa3b
	v_mul_f32_e32 v76, 0x45800000, v75
	v_cndmask_b32_e64 v75, v75, v76, s[38:39]
	v_add_f32_e32 v76, v98, v99
	v_cndmask_b32_e64 v60, v60, v76, s[36:37]
	s_waitcnt vmcnt(0)
	v_fmac_f32_e32 v61, v75, v60
	v_mul_f32_e64 v60, |v61|, s0
	v_exp_f32_e32 v60, v60
	v_min_f32_e32 v62, 0, v61
	s_lshl_b64 s[0:1], s[42:43], 6
	v_add_f32_e32 v60, 1.0, v60
	v_log_f32_e32 v60, v60
	s_nop 0
	v_fmac_f32_e32 v62, 0xbf317218, v60
	v_lshl_add_u64 v[60:61], v[2:3], 0, s[0:1]
	global_store_dword v[60:61], v62, off
.LBB0_210:
	s_or_b64 exec, exec, s[46:47]
	s_or_b32 s46, s42, 1
	s_ashr_i32 s47, s46, 31
	v_mov_b32_e32 v60, 0
	s_and_saveexec_b64 s[38:39], vcc
	s_cbranch_execz .LBB0_212
	s_lshl_b64 s[0:1], s[46:47], 7
	s_waitcnt lgkmcnt(0)
	v_lshl_add_u64 v[60:61], v[0:1], 0, s[0:1]
	global_load_dword v60, v[60:61], off
.LBB0_212:
	s_or_b64 exec, exec, s[38:39]
	s_waitcnt vmcnt(0) lgkmcnt(0)
	ds_bpermute_b32 v61, v88, v60
	ds_bpermute_b32 v62, v88, v58
	ds_bpermute_b32 v63, v88, v59
	ds_bpermute_b32 v64, v88, v56
	ds_bpermute_b32 v77, v88, v45
	s_waitcnt lgkmcnt(4)
	v_add_f32_e32 v60, v60, v61
	s_waitcnt lgkmcnt(3)
	v_add_f32_e32 v58, v58, v62
	ds_bpermute_b32 v61, v89, v60
	ds_bpermute_b32 v62, v89, v58
	s_waitcnt lgkmcnt(4)
	v_add_f32_e32 v59, v59, v63
	ds_bpermute_b32 v63, v89, v59
	s_waitcnt lgkmcnt(4)
	v_add_f32_e32 v64, v56, v64
	s_waitcnt lgkmcnt(2)
	v_add_f32_e32 v60, v60, v61
	s_waitcnt lgkmcnt(1)
	v_add_f32_e32 v58, v58, v62
	ds_bpermute_b32 v61, v90, v60
	ds_bpermute_b32 v62, v90, v58
	s_waitcnt lgkmcnt(2)
	v_add_f32_e32 v56, v59, v63
	ds_bpermute_b32 v59, v90, v56
	ds_bpermute_b32 v63, v89, v64
	s_waitcnt lgkmcnt(3)
	v_add_f32_e32 v60, v60, v61
	s_waitcnt lgkmcnt(2)
	v_add_f32_e32 v58, v58, v62
	ds_bpermute_b32 v61, v91, v60
	ds_bpermute_b32 v62, v91, v58
	s_waitcnt lgkmcnt(3)
	v_add_f32_e32 v65, v56, v59
	ds_bpermute_b32 v66, v91, v65
	s_waitcnt lgkmcnt(3)
	v_add_f32_e32 v63, v64, v63
	s_waitcnt lgkmcnt(2)
	v_add_f32_e32 v60, v60, v61
	s_waitcnt lgkmcnt(1)
	v_add_f32_e32 v58, v58, v62
	ds_bpermute_b32 v61, v92, v60
	ds_bpermute_b32 v62, v92, v58
	ds_bpermute_b32 v64, v90, v63
	v_add_f32_e32 v45, v45, v77
	ds_bpermute_b32 v77, v89, v45
	s_waitcnt lgkmcnt(3)
	v_add_f32_e32 v59, v60, v61
	s_waitcnt lgkmcnt(2)
	v_add_f32_e32 v56, v58, v62
	ds_bpermute_b32 v58, v88, v57
	v_add_f32_e32 v61, v65, v66
	ds_bpermute_b32 v62, v92, v61
	s_waitcnt lgkmcnt(2)
	v_add_f32_e32 v45, v45, v77
	ds_bpermute_b32 v77, v90, v45
	s_waitcnt lgkmcnt(2)
	v_add_f32_e32 v65, v57, v58
	ds_bpermute_b32 v66, v89, v65
	s_waitcnt lgkmcnt(2)
	v_add_f32_e32 v58, v61, v62
	v_add_f32_e32 v62, v63, v64
	ds_bpermute_b32 v63, v91, v62
	s_waitcnt lgkmcnt(2)
	v_add_f32_e32 v45, v45, v77
	s_waitcnt lgkmcnt(1)
	v_add_f32_e32 v64, v65, v66
	ds_bpermute_b32 v65, v90, v64
	ds_bpermute_b32 v66, v88, v54
	s_waitcnt lgkmcnt(2)
	v_add_f32_e32 v62, v62, v63
	ds_bpermute_b32 v63, v92, v62
	ds_bpermute_b32 v77, v91, v45
	s_waitcnt lgkmcnt(3)
	v_add_f32_e32 v64, v64, v65
	s_waitcnt lgkmcnt(2)
	v_add_f32_e32 v66, v54, v66
	ds_bpermute_b32 v65, v91, v64
	ds_bpermute_b32 v67, v89, v66
	s_waitcnt lgkmcnt(3)
	v_add_f32_e32 v54, v62, v63
	ds_bpermute_b32 v62, v88, v55
	s_waitcnt lgkmcnt(3)
	v_add_f32_e32 v77, v45, v77
	s_waitcnt lgkmcnt(2)
	v_add_f32_e32 v63, v64, v65
	s_waitcnt lgkmcnt(1)
	v_add_f32_e32 v65, v66, v67
	ds_bpermute_b32 v64, v92, v63
	s_waitcnt lgkmcnt(1)
	v_add_f32_e32 v67, v55, v62
	ds_bpermute_b32 v66, v90, v65
	ds_bpermute_b32 v68, v89, v67
	ds_bpermute_b32 v79, v92, v77
	s_waitcnt lgkmcnt(3)
	v_add_f32_e32 v62, v63, v64
	ds_bpermute_b32 v60, v93, v59
	s_waitcnt lgkmcnt(3)
	v_add_f32_e32 v64, v65, v66
	s_waitcnt lgkmcnt(2)
	v_add_f32_e32 v66, v67, v68
	ds_bpermute_b32 v65, v91, v64
	ds_bpermute_b32 v67, v90, v66
	ds_bpermute_b32 v68, v88, v52
	ds_bpermute_b32 v57, v93, v56
	ds_bpermute_b32 v61, v93, v58
	s_waitcnt lgkmcnt(4)
	v_add_f32_e32 v64, v64, v65
	s_waitcnt lgkmcnt(3)
	v_add_f32_e32 v66, v66, v67
	s_waitcnt lgkmcnt(2)
	v_add_f32_e32 v68, v52, v68
	ds_bpermute_b32 v65, v92, v64
	ds_bpermute_b32 v67, v91, v66
	ds_bpermute_b32 v69, v89, v68
	ds_bpermute_b32 v55, v93, v54
	ds_bpermute_b32 v63, v93, v62
	s_waitcnt lgkmcnt(4)
	v_add_f32_e32 v52, v64, v65
	ds_bpermute_b32 v64, v88, v53
	s_waitcnt lgkmcnt(4)
	v_add_f32_e32 v65, v66, v67
	s_waitcnt lgkmcnt(3)
	v_add_f32_e32 v67, v68, v69
	ds_bpermute_b32 v66, v92, v65
	ds_bpermute_b32 v68, v90, v67
	s_waitcnt lgkmcnt(2)
	v_add_f32_e32 v69, v53, v64
	ds_bpermute_b32 v70, v89, v69
	ds_bpermute_b32 v53, v93, v52
	s_waitcnt lgkmcnt(3)
	v_add_f32_e32 v64, v65, v66
	s_waitcnt lgkmcnt(2)
	v_add_f32_e32 v66, v67, v68
	ds_bpermute_b32 v67, v91, v66
	s_waitcnt lgkmcnt(2)
	v_add_f32_e32 v68, v69, v70
	ds_bpermute_b32 v69, v90, v68
	ds_bpermute_b32 v70, v88, v50
	ds_bpermute_b32 v65, v93, v64
	s_waitcnt lgkmcnt(3)
	v_add_f32_e32 v66, v66, v67
	ds_bpermute_b32 v67, v92, v66
	s_waitcnt lgkmcnt(3)
	v_add_f32_e32 v68, v68, v69
	s_waitcnt lgkmcnt(2)
	v_add_f32_e32 v70, v50, v70
	ds_bpermute_b32 v69, v91, v68
	ds_bpermute_b32 v71, v89, v70
	s_waitcnt lgkmcnt(2)
	v_add_f32_e32 v50, v66, v67
	ds_bpermute_b32 v66, v88, v51
	s_waitcnt lgkmcnt(2)
	v_add_f32_e32 v67, v68, v69
	s_waitcnt lgkmcnt(1)
	v_add_f32_e32 v69, v70, v71
	ds_bpermute_b32 v68, v92, v67
	s_waitcnt lgkmcnt(1)
	v_add_f32_e32 v71, v51, v66
	ds_bpermute_b32 v70, v90, v69
	ds_bpermute_b32 v72, v89, v71
	ds_bpermute_b32 v51, v93, v50
	s_waitcnt lgkmcnt(3)
	v_add_f32_e32 v66, v67, v68
	ds_bpermute_b32 v67, v93, v66
	s_waitcnt lgkmcnt(3)
	v_add_f32_e32 v68, v69, v70
	s_waitcnt lgkmcnt(2)
	v_add_f32_e32 v70, v71, v72
	ds_bpermute_b32 v69, v91, v68
	ds_bpermute_b32 v71, v90, v70
	ds_bpermute_b32 v72, v88, v48
	s_waitcnt lgkmcnt(2)
	v_add_f32_e32 v68, v68, v69
	s_waitcnt lgkmcnt(1)
	v_add_f32_e32 v70, v70, v71
	s_waitcnt lgkmcnt(0)
	v_add_f32_e32 v72, v48, v72
	ds_bpermute_b32 v69, v92, v68
	ds_bpermute_b32 v71, v91, v70
	ds_bpermute_b32 v73, v89, v72
	s_waitcnt lgkmcnt(2)
	v_add_f32_e32 v48, v68, v69
	s_waitcnt lgkmcnt(1)
	v_add_f32_e32 v69, v70, v71
	s_waitcnt lgkmcnt(0)
	v_add_f32_e32 v71, v72, v73
	ds_bpermute_b32 v70, v88, v49
	ds_bpermute_b32 v72, v90, v71
	ds_bpermute_b32 v73, v88, v46
	ds_bpermute_b32 v74, v92, v69
	ds_bpermute_b32 v68, v93, v48
	s_waitcnt lgkmcnt(4)
	v_add_f32_e32 v49, v49, v70
	s_waitcnt lgkmcnt(3)
	v_add_f32_e32 v71, v71, v72
	s_waitcnt lgkmcnt(2)
	v_add_f32_e32 v72, v46, v73
	ds_bpermute_b32 v70, v89, v49
	ds_bpermute_b32 v73, v89, v72
	s_waitcnt lgkmcnt(3)
	v_add_f32_e32 v46, v69, v74
	ds_bpermute_b32 v75, v91, v71
	s_waitcnt lgkmcnt(2)
	v_add_f32_e32 v49, v49, v70
	s_waitcnt lgkmcnt(1)
	v_add_f32_e32 v69, v72, v73
	ds_bpermute_b32 v70, v90, v49
	ds_bpermute_b32 v72, v90, v69
	s_waitcnt lgkmcnt(2)
	v_add_f32_e32 v71, v71, v75
	ds_bpermute_b32 v74, v92, v71
	s_waitcnt lgkmcnt(2)
	v_add_f32_e32 v70, v49, v70
	s_waitcnt lgkmcnt(1)
	v_add_f32_e32 v72, v69, v72
	ds_bpermute_b32 v73, v91, v70
	ds_bpermute_b32 v75, v91, v72
	s_waitcnt lgkmcnt(2)
	v_add_f32_e32 v69, v71, v74
	ds_bpermute_b32 v49, v93, v46
	s_waitcnt lgkmcnt(2)
	v_add_f32_e32 v73, v70, v73
	s_waitcnt lgkmcnt(1)
	v_add_f32_e32 v74, v72, v75
	ds_bpermute_b32 v76, v92, v73
	ds_bpermute_b32 v75, v92, v74
	ds_bpermute_b32 v70, v93, v69
	s_waitcnt lgkmcnt(2)
	v_add_f32_e32 v71, v73, v76
	ds_bpermute_b32 v76, v88, v47
	s_waitcnt lgkmcnt(2)
	v_add_f32_e32 v73, v74, v75
	ds_bpermute_b32 v75, v88, v44
	ds_bpermute_b32 v72, v93, v71
	ds_bpermute_b32 v74, v93, v73
	s_waitcnt lgkmcnt(3)
	v_add_f32_e32 v47, v47, v76
	ds_bpermute_b32 v76, v89, v47
	s_waitcnt lgkmcnt(3)
	v_add_f32_e32 v44, v44, v75
	ds_bpermute_b32 v75, v89, v44
	s_waitcnt lgkmcnt(1)
	v_add_f32_e32 v47, v47, v76
	ds_bpermute_b32 v76, v90, v47
	s_waitcnt lgkmcnt(1)
	v_add_f32_e32 v44, v44, v75
	ds_bpermute_b32 v75, v90, v44
	s_waitcnt lgkmcnt(1)
	v_add_f32_e32 v47, v47, v76
	ds_bpermute_b32 v76, v91, v47
	s_waitcnt lgkmcnt(1)
	v_add_f32_e32 v44, v44, v75
	ds_bpermute_b32 v75, v91, v44
	s_waitcnt lgkmcnt(1)
	v_add_f32_e32 v47, v47, v76
	ds_bpermute_b32 v76, v92, v47
	s_waitcnt lgkmcnt(1)
	v_add_f32_e32 v75, v44, v75
	ds_bpermute_b32 v78, v92, v75
	s_waitcnt lgkmcnt(1)
	v_add_f32_e32 v44, v47, v76
	v_add_f32_e32 v76, v77, v79
	s_waitcnt lgkmcnt(0)
	v_add_f32_e32 v47, v75, v78
	ds_bpermute_b32 v45, v93, v44
	ds_bpermute_b32 v75, v93, v47
	ds_bpermute_b32 v77, v93, v76
	s_and_saveexec_b64 s[48:49], s[2:3]
	s_cbranch_execz .LBB0_214
	v_add_f32_e32 v56, v56, v57
	v_add_f32_e32 v54, v54, v55
	v_add_f32_e32 v55, v58, v61
	v_cndmask_b32_e64 v56, 0, v56, s[4:5]
	v_cndmask_b32_e64 v55, v56, v55, s[6:7]
	v_add_f32_e32 v52, v52, v53
	v_add_f32_e32 v53, v62, v63
	v_cndmask_b32_e64 v54, v55, v54, s[8:9]
	v_cndmask_b32_e64 v53, v54, v53, s[10:11]
	v_add_f32_e32 v50, v50, v51
	v_add_f32_e32 v51, v64, v65
	v_cndmask_b32_e64 v52, v53, v52, s[12:13]
	v_cndmask_b32_e64 v51, v52, v51, s[14:15]
	v_add_f32_e32 v46, v46, v49
	v_add_f32_e32 v49, v66, v67
	v_cndmask_b32_e64 v50, v51, v50, s[16:17]
	v_add_f32_e32 v48, v48, v68
	v_cndmask_b32_e64 v49, v50, v49, s[18:19]
	v_cndmask_b32_e64 v48, v49, v48, s[20:21]
	v_add_f32_e32 v69, v69, v70
	v_cndmask_b32_e64 v46, v48, v46, s[22:23]
	v_add_f32_e32 v71, v71, v72
	v_cndmask_b32_e64 v46, v46, v69, s[24:25]
	s_waitcnt lgkmcnt(2)
	v_add_f32_e32 v44, v44, v45
	v_add_f32_e32 v45, v73, v74
	v_cndmask_b32_e64 v46, v46, v71, s[26:27]
	v_cndmask_b32_e64 v45, v46, v45, s[28:29]
	v_cndmask_b32_e64 v44, v45, v44, s[30:31]
	global_load_dword v45, v[4:5], off
	v_add_f32_e32 v59, v59, v60
	v_fmamk_f32 v59, v59, 0x3a000000, v190
	v_cmp_gt_f32_e64 s[38:39], s70, v59
	v_mul_f32_e32 v60, 0x4b800000, v59
	s_waitcnt lgkmcnt(0)
	v_add_f32_e32 v47, v47, v75
	v_cndmask_b32_e64 v59, v59, v60, s[38:39]
	v_rsq_f32_e32 v59, v59
	v_cndmask_b32_e64 v44, v44, v47, s[34:35]
	s_mov_b32 s0, 0xbfb8aa3b
	v_mul_f32_e32 v60, 0x45800000, v59
	v_cndmask_b32_e64 v59, v59, v60, s[38:39]
	v_add_f32_e32 v60, v76, v77
	v_cndmask_b32_e64 v44, v44, v60, s[36:37]
	s_waitcnt vmcnt(0)
	v_fmac_f32_e32 v45, v59, v44
	v_mul_f32_e64 v44, |v45|, s0
	v_exp_f32_e32 v44, v44
	v_min_f32_e32 v46, 0, v45
	s_lshl_b64 s[0:1], s[46:47], 6
	v_add_f32_e32 v44, 1.0, v44
	v_log_f32_e32 v44, v44
	s_nop 0
	v_fmac_f32_e32 v46, 0xbf317218, v44
	v_lshl_add_u64 v[44:45], v[2:3], 0, s[0:1]
	global_store_dword v[44:45], v46, off
.LBB0_214:
	s_or_b64 exec, exec, s[48:49]
	s_or_b32 s46, s42, 2
	s_ashr_i32 s47, s46, 31
	v_mov_b32_e32 v44, 0
	s_and_saveexec_b64 s[38:39], vcc
	s_cbranch_execz .LBB0_216
	s_lshl_b64 s[0:1], s[46:47], 7
	s_waitcnt lgkmcnt(0)
	v_lshl_add_u64 v[44:45], v[0:1], 0, s[0:1]
	global_load_dword v44, v[44:45], off
.LBB0_216:
	s_or_b64 exec, exec, s[38:39]
	s_waitcnt vmcnt(0) lgkmcnt(0)
	ds_bpermute_b32 v45, v88, v44
	ds_bpermute_b32 v46, v88, v42
	ds_bpermute_b32 v47, v88, v43
	ds_bpermute_b32 v48, v88, v40
	ds_bpermute_b32 v61, v88, v29
	s_waitcnt lgkmcnt(4)
	v_add_f32_e32 v44, v44, v45
	s_waitcnt lgkmcnt(3)
	v_add_f32_e32 v42, v42, v46
	ds_bpermute_b32 v45, v89, v44
	ds_bpermute_b32 v46, v89, v42
	s_waitcnt lgkmcnt(4)
	v_add_f32_e32 v43, v43, v47
	ds_bpermute_b32 v47, v89, v43
	s_waitcnt lgkmcnt(4)
	v_add_f32_e32 v48, v40, v48
	s_waitcnt lgkmcnt(2)
	v_add_f32_e32 v44, v44, v45
	s_waitcnt lgkmcnt(1)
	v_add_f32_e32 v42, v42, v46
	ds_bpermute_b32 v45, v90, v44
	ds_bpermute_b32 v46, v90, v42
	s_waitcnt lgkmcnt(2)
	v_add_f32_e32 v40, v43, v47
	ds_bpermute_b32 v43, v90, v40
	ds_bpermute_b32 v47, v89, v48
	s_waitcnt lgkmcnt(3)
	v_add_f32_e32 v44, v44, v45
	s_waitcnt lgkmcnt(2)
	v_add_f32_e32 v42, v42, v46
	ds_bpermute_b32 v45, v91, v44
	ds_bpermute_b32 v46, v91, v42
	s_waitcnt lgkmcnt(3)
	v_add_f32_e32 v49, v40, v43
	ds_bpermute_b32 v50, v91, v49
	s_waitcnt lgkmcnt(3)
	v_add_f32_e32 v47, v48, v47
	s_waitcnt lgkmcnt(2)
	v_add_f32_e32 v44, v44, v45
	s_waitcnt lgkmcnt(1)
	v_add_f32_e32 v42, v42, v46
	ds_bpermute_b32 v45, v92, v44
	ds_bpermute_b32 v46, v92, v42
	ds_bpermute_b32 v48, v90, v47
	v_add_f32_e32 v29, v29, v61
	ds_bpermute_b32 v61, v89, v29
	s_waitcnt lgkmcnt(3)
	v_add_f32_e32 v43, v44, v45
	s_waitcnt lgkmcnt(2)
	v_add_f32_e32 v40, v42, v46
	ds_bpermute_b32 v42, v88, v41
	v_add_f32_e32 v45, v49, v50
	ds_bpermute_b32 v46, v92, v45
	s_waitcnt lgkmcnt(2)
	v_add_f32_e32 v29, v29, v61
	ds_bpermute_b32 v61, v90, v29
	s_waitcnt lgkmcnt(2)
	v_add_f32_e32 v49, v41, v42
	ds_bpermute_b32 v50, v89, v49
	s_waitcnt lgkmcnt(2)
	v_add_f32_e32 v42, v45, v46
	v_add_f32_e32 v46, v47, v48
	ds_bpermute_b32 v47, v91, v46
	s_waitcnt lgkmcnt(2)
	v_add_f32_e32 v29, v29, v61
	s_waitcnt lgkmcnt(1)
	v_add_f32_e32 v48, v49, v50
	ds_bpermute_b32 v49, v90, v48
	ds_bpermute_b32 v50, v88, v38
	s_waitcnt lgkmcnt(2)
	v_add_f32_e32 v46, v46, v47
	ds_bpermute_b32 v47, v92, v46
	ds_bpermute_b32 v61, v91, v29
	s_waitcnt lgkmcnt(3)
	v_add_f32_e32 v48, v48, v49
	s_waitcnt lgkmcnt(2)
	v_add_f32_e32 v50, v38, v50
	ds_bpermute_b32 v49, v91, v48
	ds_bpermute_b32 v51, v89, v50
	s_waitcnt lgkmcnt(3)
	v_add_f32_e32 v38, v46, v47
	ds_bpermute_b32 v46, v88, v39
	s_waitcnt lgkmcnt(3)
	v_add_f32_e32 v61, v29, v61
	s_waitcnt lgkmcnt(2)
	v_add_f32_e32 v47, v48, v49
	s_waitcnt lgkmcnt(1)
	v_add_f32_e32 v49, v50, v51
	ds_bpermute_b32 v48, v92, v47
	s_waitcnt lgkmcnt(1)
	v_add_f32_e32 v51, v39, v46
	ds_bpermute_b32 v50, v90, v49
	ds_bpermute_b32 v52, v89, v51
	ds_bpermute_b32 v63, v92, v61
	s_waitcnt lgkmcnt(3)
	v_add_f32_e32 v46, v47, v48
	ds_bpermute_b32 v44, v93, v43
	s_waitcnt lgkmcnt(3)
	v_add_f32_e32 v48, v49, v50
	s_waitcnt lgkmcnt(2)
	v_add_f32_e32 v50, v51, v52
	ds_bpermute_b32 v49, v91, v48
	ds_bpermute_b32 v51, v90, v50
	ds_bpermute_b32 v52, v88, v36
	ds_bpermute_b32 v41, v93, v40
	ds_bpermute_b32 v45, v93, v42
	s_waitcnt lgkmcnt(4)
	v_add_f32_e32 v48, v48, v49
	s_waitcnt lgkmcnt(3)
	v_add_f32_e32 v50, v50, v51
	s_waitcnt lgkmcnt(2)
	v_add_f32_e32 v52, v36, v52
	ds_bpermute_b32 v49, v92, v48
	ds_bpermute_b32 v51, v91, v50
	ds_bpermute_b32 v53, v89, v52
	ds_bpermute_b32 v39, v93, v38
	ds_bpermute_b32 v47, v93, v46
	s_waitcnt lgkmcnt(4)
	v_add_f32_e32 v36, v48, v49
	ds_bpermute_b32 v48, v88, v37
	s_waitcnt lgkmcnt(4)
	v_add_f32_e32 v49, v50, v51
	s_waitcnt lgkmcnt(3)
	v_add_f32_e32 v51, v52, v53
	ds_bpermute_b32 v50, v92, v49
	ds_bpermute_b32 v52, v90, v51
	s_waitcnt lgkmcnt(2)
	v_add_f32_e32 v53, v37, v48
	ds_bpermute_b32 v54, v89, v53
	ds_bpermute_b32 v37, v93, v36
	s_waitcnt lgkmcnt(3)
	v_add_f32_e32 v48, v49, v50
	s_waitcnt lgkmcnt(2)
	v_add_f32_e32 v50, v51, v52
	ds_bpermute_b32 v51, v91, v50
	s_waitcnt lgkmcnt(2)
	v_add_f32_e32 v52, v53, v54
	ds_bpermute_b32 v53, v90, v52
	ds_bpermute_b32 v54, v88, v34
	ds_bpermute_b32 v49, v93, v48
	s_waitcnt lgkmcnt(3)
	v_add_f32_e32 v50, v50, v51
	ds_bpermute_b32 v51, v92, v50
	s_waitcnt lgkmcnt(3)
	v_add_f32_e32 v52, v52, v53
	s_waitcnt lgkmcnt(2)
	v_add_f32_e32 v54, v34, v54
	ds_bpermute_b32 v53, v91, v52
	ds_bpermute_b32 v55, v89, v54
	s_waitcnt lgkmcnt(2)
	v_add_f32_e32 v34, v50, v51
	ds_bpermute_b32 v50, v88, v35
	s_waitcnt lgkmcnt(2)
	v_add_f32_e32 v51, v52, v53
	s_waitcnt lgkmcnt(1)
	v_add_f32_e32 v53, v54, v55
	ds_bpermute_b32 v52, v92, v51
	s_waitcnt lgkmcnt(1)
	v_add_f32_e32 v55, v35, v50
	ds_bpermute_b32 v54, v90, v53
	ds_bpermute_b32 v56, v89, v55
	ds_bpermute_b32 v35, v93, v34
	s_waitcnt lgkmcnt(3)
	v_add_f32_e32 v50, v51, v52
	ds_bpermute_b32 v51, v93, v50
	s_waitcnt lgkmcnt(3)
	v_add_f32_e32 v52, v53, v54
	s_waitcnt lgkmcnt(2)
	v_add_f32_e32 v54, v55, v56
	ds_bpermute_b32 v53, v91, v52
	ds_bpermute_b32 v55, v90, v54
	ds_bpermute_b32 v56, v88, v32
	s_waitcnt lgkmcnt(2)
	v_add_f32_e32 v52, v52, v53
	s_waitcnt lgkmcnt(1)
	v_add_f32_e32 v54, v54, v55
	s_waitcnt lgkmcnt(0)
	v_add_f32_e32 v56, v32, v56
	ds_bpermute_b32 v53, v92, v52
	ds_bpermute_b32 v55, v91, v54
	ds_bpermute_b32 v57, v89, v56
	s_waitcnt lgkmcnt(2)
	v_add_f32_e32 v32, v52, v53
	s_waitcnt lgkmcnt(1)
	v_add_f32_e32 v53, v54, v55
	s_waitcnt lgkmcnt(0)
	v_add_f32_e32 v55, v56, v57
	ds_bpermute_b32 v54, v88, v33
	ds_bpermute_b32 v56, v90, v55
	ds_bpermute_b32 v57, v88, v30
	ds_bpermute_b32 v58, v92, v53
	ds_bpermute_b32 v52, v93, v32
	s_waitcnt lgkmcnt(4)
	v_add_f32_e32 v33, v33, v54
	s_waitcnt lgkmcnt(3)
	v_add_f32_e32 v55, v55, v56
	s_waitcnt lgkmcnt(2)
	v_add_f32_e32 v56, v30, v57
	ds_bpermute_b32 v54, v89, v33
	ds_bpermute_b32 v57, v89, v56
	s_waitcnt lgkmcnt(3)
	v_add_f32_e32 v30, v53, v58
	ds_bpermute_b32 v59, v91, v55
	s_waitcnt lgkmcnt(2)
	v_add_f32_e32 v33, v33, v54
	s_waitcnt lgkmcnt(1)
	v_add_f32_e32 v53, v56, v57
	ds_bpermute_b32 v54, v90, v33
	ds_bpermute_b32 v56, v90, v53
	s_waitcnt lgkmcnt(2)
	v_add_f32_e32 v55, v55, v59
	ds_bpermute_b32 v58, v92, v55
	s_waitcnt lgkmcnt(2)
	v_add_f32_e32 v54, v33, v54
	s_waitcnt lgkmcnt(1)
	v_add_f32_e32 v56, v53, v56
	ds_bpermute_b32 v57, v91, v54
	ds_bpermute_b32 v59, v91, v56
	s_waitcnt lgkmcnt(2)
	v_add_f32_e32 v53, v55, v58
	ds_bpermute_b32 v33, v93, v30
	s_waitcnt lgkmcnt(2)
	v_add_f32_e32 v57, v54, v57
	s_waitcnt lgkmcnt(1)
	v_add_f32_e32 v58, v56, v59
	ds_bpermute_b32 v60, v92, v57
	ds_bpermute_b32 v59, v92, v58
	ds_bpermute_b32 v54, v93, v53
	s_waitcnt lgkmcnt(2)
	v_add_f32_e32 v55, v57, v60
	ds_bpermute_b32 v60, v88, v31
	s_waitcnt lgkmcnt(2)
	v_add_f32_e32 v57, v58, v59
	ds_bpermute_b32 v59, v88, v28
	ds_bpermute_b32 v56, v93, v55
	ds_bpermute_b32 v58, v93, v57
	s_waitcnt lgkmcnt(3)
	v_add_f32_e32 v31, v31, v60
	ds_bpermute_b32 v60, v89, v31
	s_waitcnt lgkmcnt(3)
	v_add_f32_e32 v28, v28, v59
	ds_bpermute_b32 v59, v89, v28
	s_waitcnt lgkmcnt(1)
	v_add_f32_e32 v31, v31, v60
	ds_bpermute_b32 v60, v90, v31
	s_waitcnt lgkmcnt(1)
	v_add_f32_e32 v28, v28, v59
	ds_bpermute_b32 v59, v90, v28
	s_waitcnt lgkmcnt(1)
	v_add_f32_e32 v31, v31, v60
	ds_bpermute_b32 v60, v91, v31
	s_waitcnt lgkmcnt(1)
	v_add_f32_e32 v28, v28, v59
	ds_bpermute_b32 v59, v91, v28
	s_waitcnt lgkmcnt(1)
	v_add_f32_e32 v31, v31, v60
	ds_bpermute_b32 v60, v92, v31
	s_waitcnt lgkmcnt(1)
	v_add_f32_e32 v59, v28, v59
	ds_bpermute_b32 v62, v92, v59
	s_waitcnt lgkmcnt(1)
	v_add_f32_e32 v28, v31, v60
	v_add_f32_e32 v60, v61, v63
	s_waitcnt lgkmcnt(0)
	v_add_f32_e32 v31, v59, v62
	ds_bpermute_b32 v29, v93, v28
	ds_bpermute_b32 v59, v93, v31
	ds_bpermute_b32 v61, v93, v60
	s_and_saveexec_b64 s[48:49], s[2:3]
	s_cbranch_execz .LBB0_218
	v_add_f32_e32 v40, v40, v41
	v_add_f32_e32 v38, v38, v39
	v_add_f32_e32 v39, v42, v45
	v_cndmask_b32_e64 v40, 0, v40, s[4:5]
	v_cndmask_b32_e64 v39, v40, v39, s[6:7]
	v_add_f32_e32 v36, v36, v37
	v_add_f32_e32 v37, v46, v47
	v_cndmask_b32_e64 v38, v39, v38, s[8:9]
	v_cndmask_b32_e64 v37, v38, v37, s[10:11]
	v_add_f32_e32 v34, v34, v35
	v_add_f32_e32 v35, v48, v49
	v_cndmask_b32_e64 v36, v37, v36, s[12:13]
	v_cndmask_b32_e64 v35, v36, v35, s[14:15]
	v_add_f32_e32 v30, v30, v33
	v_add_f32_e32 v33, v50, v51
	v_cndmask_b32_e64 v34, v35, v34, s[16:17]
	v_add_f32_e32 v32, v32, v52
	v_cndmask_b32_e64 v33, v34, v33, s[18:19]
	v_cndmask_b32_e64 v32, v33, v32, s[20:21]
	v_add_f32_e32 v53, v53, v54
	v_cndmask_b32_e64 v30, v32, v30, s[22:23]
	v_add_f32_e32 v55, v55, v56
	v_cndmask_b32_e64 v30, v30, v53, s[24:25]
	s_waitcnt lgkmcnt(2)
	v_add_f32_e32 v28, v28, v29
	v_add_f32_e32 v29, v57, v58
	v_cndmask_b32_e64 v30, v30, v55, s[26:27]
	v_cndmask_b32_e64 v29, v30, v29, s[28:29]
	v_cndmask_b32_e64 v28, v29, v28, s[30:31]
	global_load_dword v29, v[4:5], off
	v_add_f32_e32 v43, v43, v44
	v_fmamk_f32 v43, v43, 0x3a000000, v190
	v_cmp_gt_f32_e64 s[38:39], s70, v43
	v_mul_f32_e32 v44, 0x4b800000, v43
	s_waitcnt lgkmcnt(0)
	v_add_f32_e32 v31, v31, v59
	v_cndmask_b32_e64 v43, v43, v44, s[38:39]
	v_rsq_f32_e32 v43, v43
	v_cndmask_b32_e64 v28, v28, v31, s[34:35]
	s_mov_b32 s0, 0xbfb8aa3b
	v_mul_f32_e32 v44, 0x45800000, v43
	v_cndmask_b32_e64 v43, v43, v44, s[38:39]
	v_add_f32_e32 v44, v60, v61
	v_cndmask_b32_e64 v28, v28, v44, s[36:37]
	s_waitcnt vmcnt(0)
	v_fmac_f32_e32 v29, v43, v28
	v_mul_f32_e64 v28, |v29|, s0
	v_exp_f32_e32 v28, v28
	v_min_f32_e32 v30, 0, v29
	s_lshl_b64 s[0:1], s[46:47], 6
	v_add_f32_e32 v28, 1.0, v28
	v_log_f32_e32 v28, v28
	s_nop 0
	v_fmac_f32_e32 v30, 0xbf317218, v28
	v_lshl_add_u64 v[28:29], v[2:3], 0, s[0:1]
	global_store_dword v[28:29], v30, off
.LBB0_218:
	s_or_b64 exec, exec, s[48:49]
	s_or_b32 s46, s42, 3
	s_ashr_i32 s47, s46, 31
	v_mov_b32_e32 v28, 0
	s_and_saveexec_b64 s[38:39], vcc
	s_cbranch_execz .LBB0_220
	s_lshl_b64 s[0:1], s[46:47], 7
	s_waitcnt lgkmcnt(0)
	v_lshl_add_u64 v[28:29], v[0:1], 0, s[0:1]
	global_load_dword v28, v[28:29], off
.LBB0_220:
	s_or_b64 exec, exec, s[38:39]
	s_waitcnt vmcnt(0) lgkmcnt(0)
	ds_bpermute_b32 v29, v88, v28
	ds_bpermute_b32 v30, v88, v26
	ds_bpermute_b32 v31, v88, v27
	ds_bpermute_b32 v32, v88, v24
	ds_bpermute_b32 v45, v88, v15
	s_waitcnt lgkmcnt(4)
	v_add_f32_e32 v28, v28, v29
	s_waitcnt lgkmcnt(3)
	v_add_f32_e32 v26, v26, v30
	ds_bpermute_b32 v29, v89, v28
	ds_bpermute_b32 v30, v89, v26
	s_waitcnt lgkmcnt(4)
	v_add_f32_e32 v27, v27, v31
	ds_bpermute_b32 v31, v89, v27
	s_waitcnt lgkmcnt(4)
	v_add_f32_e32 v32, v24, v32
	s_waitcnt lgkmcnt(2)
	v_add_f32_e32 v28, v28, v29
	s_waitcnt lgkmcnt(1)
	v_add_f32_e32 v26, v26, v30
	ds_bpermute_b32 v29, v90, v28
	ds_bpermute_b32 v30, v90, v26
	s_waitcnt lgkmcnt(2)
	v_add_f32_e32 v24, v27, v31
	ds_bpermute_b32 v27, v90, v24
	ds_bpermute_b32 v31, v89, v32
	s_waitcnt lgkmcnt(3)
	v_add_f32_e32 v28, v28, v29
	s_waitcnt lgkmcnt(2)
	v_add_f32_e32 v26, v26, v30
	ds_bpermute_b32 v29, v91, v28
	ds_bpermute_b32 v30, v91, v26
	s_waitcnt lgkmcnt(3)
	v_add_f32_e32 v33, v24, v27
	ds_bpermute_b32 v34, v91, v33
	s_waitcnt lgkmcnt(3)
	v_add_f32_e32 v31, v32, v31
	s_waitcnt lgkmcnt(2)
	v_add_f32_e32 v28, v28, v29
	s_waitcnt lgkmcnt(1)
	v_add_f32_e32 v26, v26, v30
	ds_bpermute_b32 v29, v92, v28
	ds_bpermute_b32 v30, v92, v26
	ds_bpermute_b32 v32, v90, v31
	v_add_f32_e32 v15, v15, v45
	ds_bpermute_b32 v45, v89, v15
	s_waitcnt lgkmcnt(3)
	v_add_f32_e32 v27, v28, v29
	s_waitcnt lgkmcnt(2)
	v_add_f32_e32 v24, v26, v30
	ds_bpermute_b32 v26, v88, v25
	v_add_f32_e32 v29, v33, v34
	ds_bpermute_b32 v30, v92, v29
	s_waitcnt lgkmcnt(2)
	v_add_f32_e32 v15, v15, v45
	ds_bpermute_b32 v45, v90, v15
	s_waitcnt lgkmcnt(2)
	v_add_f32_e32 v33, v25, v26
	ds_bpermute_b32 v34, v89, v33
	s_waitcnt lgkmcnt(2)
	v_add_f32_e32 v26, v29, v30
	v_add_f32_e32 v30, v31, v32
	ds_bpermute_b32 v31, v91, v30
	s_waitcnt lgkmcnt(2)
	v_add_f32_e32 v15, v15, v45
	s_waitcnt lgkmcnt(1)
	v_add_f32_e32 v32, v33, v34
	ds_bpermute_b32 v33, v90, v32
	ds_bpermute_b32 v34, v88, v22
	s_waitcnt lgkmcnt(2)
	v_add_f32_e32 v30, v30, v31
	ds_bpermute_b32 v31, v92, v30
	ds_bpermute_b32 v45, v91, v15
	s_waitcnt lgkmcnt(3)
	v_add_f32_e32 v32, v32, v33
	s_waitcnt lgkmcnt(2)
	v_add_f32_e32 v34, v22, v34
	ds_bpermute_b32 v33, v91, v32
	ds_bpermute_b32 v35, v89, v34
	s_waitcnt lgkmcnt(3)
	v_add_f32_e32 v22, v30, v31
	ds_bpermute_b32 v30, v88, v23
	s_waitcnt lgkmcnt(3)
	v_add_f32_e32 v45, v15, v45
	s_waitcnt lgkmcnt(2)
	v_add_f32_e32 v31, v32, v33
	s_waitcnt lgkmcnt(1)
	v_add_f32_e32 v33, v34, v35
	ds_bpermute_b32 v32, v92, v31
	s_waitcnt lgkmcnt(1)
	v_add_f32_e32 v35, v23, v30
	ds_bpermute_b32 v34, v90, v33
	ds_bpermute_b32 v36, v89, v35
	ds_bpermute_b32 v47, v92, v45
	s_waitcnt lgkmcnt(3)
	v_add_f32_e32 v30, v31, v32
	ds_bpermute_b32 v28, v93, v27
	s_waitcnt lgkmcnt(3)
	v_add_f32_e32 v32, v33, v34
	s_waitcnt lgkmcnt(2)
	v_add_f32_e32 v34, v35, v36
	ds_bpermute_b32 v33, v91, v32
	ds_bpermute_b32 v35, v90, v34
	ds_bpermute_b32 v36, v88, v20
	ds_bpermute_b32 v25, v93, v24
	ds_bpermute_b32 v29, v93, v26
	s_waitcnt lgkmcnt(4)
	v_add_f32_e32 v32, v32, v33
	s_waitcnt lgkmcnt(3)
	v_add_f32_e32 v34, v34, v35
	s_waitcnt lgkmcnt(2)
	v_add_f32_e32 v36, v20, v36
	ds_bpermute_b32 v33, v92, v32
	ds_bpermute_b32 v35, v91, v34
	ds_bpermute_b32 v37, v89, v36
	ds_bpermute_b32 v23, v93, v22
	ds_bpermute_b32 v31, v93, v30
	s_waitcnt lgkmcnt(4)
	v_add_f32_e32 v20, v32, v33
	ds_bpermute_b32 v32, v88, v21
	s_waitcnt lgkmcnt(4)
	v_add_f32_e32 v33, v34, v35
	s_waitcnt lgkmcnt(3)
	v_add_f32_e32 v35, v36, v37
	ds_bpermute_b32 v34, v92, v33
	ds_bpermute_b32 v36, v90, v35
	s_waitcnt lgkmcnt(2)
	v_add_f32_e32 v37, v21, v32
	ds_bpermute_b32 v38, v89, v37
	ds_bpermute_b32 v21, v93, v20
	s_waitcnt lgkmcnt(3)
	v_add_f32_e32 v32, v33, v34
	s_waitcnt lgkmcnt(2)
	v_add_f32_e32 v34, v35, v36
	ds_bpermute_b32 v35, v91, v34
	s_waitcnt lgkmcnt(2)
	v_add_f32_e32 v36, v37, v38
	ds_bpermute_b32 v37, v90, v36
	ds_bpermute_b32 v38, v88, v18
	ds_bpermute_b32 v33, v93, v32
	s_waitcnt lgkmcnt(3)
	v_add_f32_e32 v34, v34, v35
	ds_bpermute_b32 v35, v92, v34
	s_waitcnt lgkmcnt(3)
	v_add_f32_e32 v36, v36, v37
	s_waitcnt lgkmcnt(2)
	v_add_f32_e32 v38, v18, v38
	ds_bpermute_b32 v37, v91, v36
	ds_bpermute_b32 v39, v89, v38
	s_waitcnt lgkmcnt(2)
	v_add_f32_e32 v18, v34, v35
	ds_bpermute_b32 v34, v88, v19
	s_waitcnt lgkmcnt(2)
	v_add_f32_e32 v35, v36, v37
	s_waitcnt lgkmcnt(1)
	v_add_f32_e32 v37, v38, v39
	ds_bpermute_b32 v36, v92, v35
	s_waitcnt lgkmcnt(1)
	v_add_f32_e32 v39, v19, v34
	ds_bpermute_b32 v38, v90, v37
	ds_bpermute_b32 v40, v89, v39
	ds_bpermute_b32 v19, v93, v18
	s_waitcnt lgkmcnt(3)
	v_add_f32_e32 v34, v35, v36
	ds_bpermute_b32 v35, v93, v34
	s_waitcnt lgkmcnt(3)
	v_add_f32_e32 v36, v37, v38
	s_waitcnt lgkmcnt(2)
	v_add_f32_e32 v38, v39, v40
	ds_bpermute_b32 v37, v91, v36
	ds_bpermute_b32 v39, v90, v38
	ds_bpermute_b32 v40, v88, v12
	s_waitcnt lgkmcnt(2)
	v_add_f32_e32 v36, v36, v37
	s_waitcnt lgkmcnt(1)
	v_add_f32_e32 v38, v38, v39
	ds_bpermute_b32 v37, v92, v36
	ds_bpermute_b32 v39, v91, v38
	s_waitcnt lgkmcnt(2)
	v_add_f32_e32 v40, v12, v40
	ds_bpermute_b32 v41, v89, v40
	s_waitcnt lgkmcnt(2)
	v_add_f32_e32 v12, v36, v37
	s_waitcnt lgkmcnt(1)
	v_add_f32_e32 v37, v38, v39
	ds_bpermute_b32 v38, v88, v13
	s_waitcnt lgkmcnt(1)
	v_add_f32_e32 v39, v40, v41
	ds_bpermute_b32 v41, v88, v16
	ds_bpermute_b32 v40, v90, v39
	ds_bpermute_b32 v42, v92, v37
	s_waitcnt lgkmcnt(3)
	v_add_f32_e32 v13, v13, v38
	ds_bpermute_b32 v38, v89, v13
	s_waitcnt lgkmcnt(3)
	v_add_f32_e32 v16, v16, v41
	s_waitcnt lgkmcnt(2)
	v_add_f32_e32 v39, v39, v40
	ds_bpermute_b32 v40, v89, v16
	ds_bpermute_b32 v41, v91, v39
	s_waitcnt lgkmcnt(2)
	v_add_f32_e32 v38, v13, v38
	ds_bpermute_b32 v43, v90, v38
	v_add_f32_e32 v13, v37, v42
	s_waitcnt lgkmcnt(2)
	v_add_f32_e32 v16, v16, v40
	ds_bpermute_b32 v37, v90, v16
	s_waitcnt lgkmcnt(2)
	v_add_f32_e32 v39, v39, v41
	s_waitcnt lgkmcnt(1)
	v_add_f32_e32 v38, v38, v43
	ds_bpermute_b32 v40, v91, v38
	ds_bpermute_b32 v41, v92, v39
	s_waitcnt lgkmcnt(2)
	v_add_f32_e32 v42, v16, v37
	ds_bpermute_b32 v43, v91, v42
	ds_bpermute_b32 v36, v93, v12
	s_waitcnt lgkmcnt(3)
	v_add_f32_e32 v40, v38, v40
	ds_bpermute_b32 v44, v92, v40
	s_waitcnt lgkmcnt(3)
	v_add_f32_e32 v37, v39, v41
	s_waitcnt lgkmcnt(2)
	v_add_f32_e32 v41, v42, v43
	ds_bpermute_b32 v43, v88, v17
	ds_bpermute_b32 v42, v92, v41
	s_waitcnt lgkmcnt(2)
	v_add_f32_e32 v39, v40, v44
	ds_bpermute_b32 v44, v88, v14
	ds_bpermute_b32 v16, v93, v13
	s_waitcnt lgkmcnt(3)
	v_add_f32_e32 v17, v17, v43
	ds_bpermute_b32 v43, v89, v17
	s_waitcnt lgkmcnt(3)
	v_add_f32_e32 v41, v41, v42
	s_waitcnt lgkmcnt(2)
	v_add_f32_e32 v14, v14, v44
	ds_bpermute_b32 v44, v89, v14
	ds_bpermute_b32 v38, v93, v37
	s_waitcnt lgkmcnt(2)
	v_add_f32_e32 v17, v17, v43
	ds_bpermute_b32 v43, v90, v17
	ds_bpermute_b32 v40, v93, v39
	s_waitcnt lgkmcnt(3)
	v_add_f32_e32 v14, v14, v44
	ds_bpermute_b32 v44, v90, v14
	ds_bpermute_b32 v42, v93, v41
	s_waitcnt lgkmcnt(3)
	v_add_f32_e32 v17, v17, v43
	ds_bpermute_b32 v43, v91, v17
	s_waitcnt lgkmcnt(2)
	v_add_f32_e32 v14, v14, v44
	ds_bpermute_b32 v44, v91, v14
	s_waitcnt lgkmcnt(1)
	v_add_f32_e32 v17, v17, v43
	ds_bpermute_b32 v43, v92, v17
	s_waitcnt lgkmcnt(1)
	v_add_f32_e32 v44, v14, v44
	ds_bpermute_b32 v46, v92, v44
	s_waitcnt lgkmcnt(1)
	v_add_f32_e32 v14, v17, v43
	ds_bpermute_b32 v15, v93, v14
	s_waitcnt lgkmcnt(1)
	v_add_f32_e32 v17, v44, v46
	v_add_f32_e32 v44, v45, v47
	ds_bpermute_b32 v43, v93, v17
	ds_bpermute_b32 v45, v93, v44
	s_and_saveexec_b64 s[48:49], s[2:3]
	s_cbranch_execz .LBB0_203
	v_add_f32_e32 v24, v24, v25
	v_add_f32_e32 v22, v22, v23
	v_add_f32_e32 v23, v26, v29
	v_cndmask_b32_e64 v24, 0, v24, s[4:5]
	v_cndmask_b32_e64 v23, v24, v23, s[6:7]
	v_add_f32_e32 v20, v20, v21
	v_add_f32_e32 v21, v30, v31
	v_cndmask_b32_e64 v22, v23, v22, s[8:9]
	v_cndmask_b32_e64 v21, v22, v21, s[10:11]
	v_add_f32_e32 v18, v18, v19
	v_add_f32_e32 v19, v32, v33
	v_cndmask_b32_e64 v20, v21, v20, s[12:13]
	v_cndmask_b32_e64 v19, v20, v19, s[14:15]
	v_add_f32_e32 v13, v13, v16
	v_add_f32_e32 v16, v34, v35
	v_cndmask_b32_e64 v18, v19, v18, s[16:17]
	v_add_f32_e32 v12, v12, v36
	v_cndmask_b32_e64 v16, v18, v16, s[18:19]
	v_cndmask_b32_e64 v12, v16, v12, s[20:21]
	v_cndmask_b32_e64 v12, v12, v13, s[22:23]
	global_load_dword v13, v[4:5], off
	v_add_f32_e32 v27, v27, v28
	v_fmamk_f32 v27, v27, 0x3a000000, v190
	v_cmp_gt_f32_e64 s[38:39], s70, v27
	v_mul_f32_e32 v28, 0x4b800000, v27
	v_add_f32_e32 v37, v37, v38
	v_cndmask_b32_e64 v27, v27, v28, s[38:39]
	v_rsq_f32_e32 v27, v27
	v_add_f32_e32 v39, v39, v40
	v_cndmask_b32_e64 v12, v12, v37, s[24:25]
	s_waitcnt lgkmcnt(0)
	v_add_f32_e32 v14, v14, v15
	v_add_f32_e32 v15, v41, v42
	v_cndmask_b32_e64 v12, v12, v39, s[26:27]
	v_cndmask_b32_e64 v12, v12, v15, s[28:29]
	v_mul_f32_e32 v28, 0x45800000, v27
	v_add_f32_e32 v17, v17, v43
	v_cndmask_b32_e64 v12, v12, v14, s[30:31]
	v_cndmask_b32_e64 v27, v27, v28, s[38:39]
	v_add_f32_e32 v28, v44, v45
	v_cndmask_b32_e64 v12, v12, v17, s[34:35]
	v_cndmask_b32_e64 v12, v12, v28, s[36:37]
	s_mov_b32 s0, 0xbfb8aa3b
	s_waitcnt vmcnt(0)
	v_fmac_f32_e32 v13, v27, v12
	v_mul_f32_e64 v12, |v13|, s0
	v_exp_f32_e32 v12, v12
	v_min_f32_e32 v14, 0, v13
	s_lshl_b64 s[0:1], s[46:47], 6
	v_add_f32_e32 v12, 1.0, v12
	v_log_f32_e32 v12, v12
	s_nop 0
	v_fmac_f32_e32 v14, 0xbf317218, v12
	v_lshl_add_u64 v[12:13], v[2:3], 0, s[0:1]
	global_store_dword v[12:13], v14, off
	s_branch .LBB0_203

.LBB0_268:
	global_load_dwordx4 v[2:5], v[0:1], off
	global_load_dwordx4 v[6:9], v[0:1], off offset:16
	global_load_dwordx4 v[34:37], v[0:1], off offset:32
	global_load_dwordx4 v[38:41], v[0:1], off offset:48
	s_add_i32 s0, s0, s2
	s_cmpk_lt_i32 s0, 0x4040
	s_waitcnt vmcnt(0) lgkmcnt(0)
	v_and_b32_e32 v14, 0xffff0000, v2
	v_lshlrev_b32_e32 v13, 16, v2
	v_lshlrev_b32_e32 v29, 16, v34
	v_and_b32_e32 v30, 0xffff0000, v34
	v_lshlrev_b32_e32 v31, 16, v35
	v_and_b32_e32 v32, 0xffff0000, v35
	v_lshlrev_b32_e32 v33, 16, v36
	v_and_b32_e32 v34, 0xffff0000, v36
	v_lshlrev_b32_e32 v35, 16, v37
	v_and_b32_e32 v36, 0xffff0000, v37
	v_mul_f32_e32 v37, v14, v14
	v_lshlrev_b32_e32 v15, 16, v3
	v_fmac_f32_e32 v37, v13, v13
	v_and_b32_e32 v16, 0xffff0000, v3
	v_fmac_f32_e32 v37, v15, v15
	v_lshlrev_b32_e32 v17, 16, v4
	v_fmac_f32_e32 v37, v16, v16
	v_and_b32_e32 v18, 0xffff0000, v4
	v_fmac_f32_e32 v37, v17, v17
	v_lshlrev_b32_e32 v19, 16, v5
	v_fmac_f32_e32 v37, v18, v18
	v_and_b32_e32 v20, 0xffff0000, v5
	v_fmac_f32_e32 v37, v19, v19
	v_lshlrev_b32_e32 v21, 16, v6
	v_fmac_f32_e32 v37, v20, v20
	v_and_b32_e32 v22, 0xffff0000, v6
	v_fmac_f32_e32 v37, v21, v21
	v_lshlrev_b32_e32 v23, 16, v7
	v_fmac_f32_e32 v37, v22, v22
	v_and_b32_e32 v24, 0xffff0000, v7
	v_fmac_f32_e32 v37, v23, v23
	v_lshlrev_b32_e32 v25, 16, v8
	v_fmac_f32_e32 v37, v24, v24
	v_and_b32_e32 v26, 0xffff0000, v8
	v_fmac_f32_e32 v37, v25, v25
	v_lshlrev_b32_e32 v27, 16, v9
	v_fmac_f32_e32 v37, v26, v26
	v_and_b32_e32 v28, 0xffff0000, v9
	v_fmac_f32_e32 v37, v27, v27
	v_fmac_f32_e32 v37, v28, v28
	v_fmac_f32_e32 v37, v29, v29
	v_fmac_f32_e32 v37, v30, v30
	v_fmac_f32_e32 v37, v31, v31
	v_fmac_f32_e32 v37, v32, v32
	v_fmac_f32_e32 v37, v33, v33
	v_fmac_f32_e32 v37, v34, v34
	v_and_b32_e32 v2, 0xffff0000, v38
	v_lshlrev_b32_e32 v3, 16, v38
	v_fmac_f32_e32 v37, v35, v35
	v_and_b32_e32 v4, 0xffff0000, v39
	v_lshlrev_b32_e32 v5, 16, v39
	v_pk_mul_f32 v[38:39], v[2:3], v[2:3]
	v_fmac_f32_e32 v37, v36, v36
	v_add_f32_e32 v37, v39, v37
	v_and_b32_e32 v6, 0xffff0000, v40
	v_lshlrev_b32_e32 v7, 16, v40
	v_and_b32_e32 v8, 0xffff0000, v41
	v_lshlrev_b32_e32 v9, 16, v41
	v_pk_mul_f32 v[40:41], v[4:5], v[4:5]
	v_add_f32_e32 v37, v38, v37
	v_add_f32_e32 v37, v41, v37
	v_pk_mul_f32 v[42:43], v[6:7], v[6:7]
	v_add_f32_e32 v37, v40, v37
	v_add_f32_e32 v37, v43, v37
	v_pk_mul_f32 v[44:45], v[8:9], v[8:9]
	v_add_f32_e32 v37, v42, v37
	v_add_f32_e32 v37, v45, v37
	v_add_f32_e32 v37, v44, v37
	ds_bpermute_b32 v38, v11, v37
	s_waitcnt lgkmcnt(0)
	v_add_f32_e32 v37, v37, v38
	ds_bpermute_b32 v38, v12, v37
	s_waitcnt lgkmcnt(0)
	v_add_f32_e32 v37, v37, v38
	v_fmamk_f32 v37, v37, 0x3c000000, v190
	v_mul_f32_e32 v38, 0x4b800000, v37
	v_cmp_gt_f32_e32 vcc, s70, v37
	s_nop 1
	v_cndmask_b32_e32 v37, v37, v38, vcc
	v_rsq_f32_e32 v37, v37
	s_nop 0
	v_mul_f32_e32 v38, 0x45800000, v37
	v_cndmask_b32_e32 v37, v37, v38, vcc
	v_mul_f32_e32 v13, v37, v13
	v_mul_f32_e32 v14, v37, v14
	v_mul_f32_e32 v15, v37, v15
	v_mul_f32_e32 v16, v37, v16
	v_mul_f32_e32 v17, v37, v17
	v_mul_f32_e32 v18, v37, v18
	v_mul_f32_e32 v19, v37, v19
	v_mul_f32_e32 v20, v37, v20
	v_mul_f32_e32 v38, v37, v3
	v_mul_f32_e32 v39, v37, v2
	v_mul_f32_e32 v40, v37, v5
	v_mul_f32_e32 v41, v37, v4
	v_cvt_pk_bf16_f32 v2, v13, v14
	v_cvt_pk_bf16_f32 v3, v15, v16
	v_cvt_pk_bf16_f32 v4, v17, v18
	v_cvt_pk_bf16_f32 v5, v19, v20
	v_mul_f32_e32 v21, v37, v21
	v_mul_f32_e32 v22, v37, v22
	v_mul_f32_e32 v23, v37, v23
	v_mul_f32_e32 v24, v37, v24
	v_mul_f32_e32 v25, v37, v25
	v_mul_f32_e32 v26, v37, v26
	v_mul_f32_e32 v27, v37, v27
	v_mul_f32_e32 v28, v37, v28
	global_store_dwordx4 v[0:1], v[2:5], off
	v_mul_f32_e32 v29, v37, v29
	v_mul_f32_e32 v30, v37, v30
	v_cvt_pk_bf16_f32 v2, v21, v22
	v_cvt_pk_bf16_f32 v3, v23, v24
	v_cvt_pk_bf16_f32 v4, v25, v26
	v_cvt_pk_bf16_f32 v5, v27, v28
	v_mul_f32_e32 v31, v37, v31
	v_mul_f32_e32 v32, v37, v32
	v_mul_f32_e32 v33, v37, v33
	v_mul_f32_e32 v34, v37, v34
	v_mul_f32_e32 v35, v37, v35
	v_mul_f32_e32 v36, v37, v36
	global_store_dwordx4 v[0:1], v[2:5], off offset:16
	v_mul_f32_e32 v7, v37, v7
	v_mul_f32_e32 v6, v37, v6
	v_cvt_pk_bf16_f32 v2, v29, v30
	v_cvt_pk_bf16_f32 v3, v31, v32
	v_cvt_pk_bf16_f32 v4, v33, v34
	v_cvt_pk_bf16_f32 v5, v35, v36
	v_mul_f32_e32 v9, v37, v9
	v_mul_f32_e32 v8, v37, v8
	global_store_dwordx4 v[0:1], v[2:5], off offset:32
	s_nop 1
	v_cvt_pk_bf16_f32 v2, v38, v39
	v_cvt_pk_bf16_f32 v3, v40, v41
	v_cvt_pk_bf16_f32 v4, v7, v6
	v_cvt_pk_bf16_f32 v5, v9, v8
	global_store_dwordx4 v[0:1], v[2:5], off offset:48
	v_lshl_add_u64 v[0:1], v[0:1], 0, s[8:9]
	s_cbranch_scc1 .LBB0_268
.LBB0_269:
	s_cmp_gt_i32 s6, 63
	s_cbranch_scc1 .LBB0_410
	s_and_b32 s0, s6, 15
	s_ashr_i32 s7, s6, 4
	s_lshl_b32 s0, s0, 2
	s_add_u32 s0, s4, s0
	s_addc_u32 s1, s5, 0
	s_movk_i32 s8, 0x41
	s_add_u32 s2, s0, 0x3f6d0000
	v_mov_b32_e32 v11, 0x1010
	v_mad_u32_u24 v6, v10, s8, 3
	v_mov_b32_e32 v7, v129
	s_addc_u32 s3, s1, 0
	v_mad_i64_i32 v[6:7], s[0:1], s7, v11, v[6:7]
	v_lshlrev_b64 v[6:7], 6, v[6:7]
	v_lshl_add_u64 v[12:13], s[2:3], 0, v[6:7]
	v_mad_u32_u24 v6, v10, s8, 4
	v_mov_b32_e32 v7, v129
	v_mad_i64_i32 v[6:7], s[0:1], s7, v11, v[6:7]
	v_lshlrev_b64 v[6:7], 6, v[6:7]
	v_lshl_add_u64 v[14:15], s[2:3], 0, v[6:7]
	v_mad_u32_u24 v6, v10, s8, 5
	v_mov_b32_e32 v7, v129
	v_mad_i64_i32 v[6:7], s[0:1], s7, v11, v[6:7]
	v_lshlrev_b64 v[6:7], 6, v[6:7]
	v_lshl_add_u64 v[16:17], s[2:3], 0, v[6:7]
	v_mad_u32_u24 v6, v10, s8, 6
	v_mov_b32_e32 v7, v129
	v_mad_i64_i32 v[6:7], s[0:1], s7, v11, v[6:7]
	v_mul_u32_u24_e32 v128, 0x41, v10
	v_mad_u32_u24 v2, v10, s8, 1
	v_mov_b32_e32 v3, v129
	v_mad_u32_u24 v4, v10, s8, 2
	v_mov_b32_e32 v5, v129
	v_lshlrev_b64 v[6:7], 6, v[6:7]
	v_mad_i64_i32 v[0:1], s[0:1], s7, v11, v[128:129]
	v_mad_i64_i32 v[2:3], s[0:1], s7, v11, v[2:3]
	v_mad_i64_i32 v[4:5], s[0:1], s7, v11, v[4:5]
	v_lshl_add_u64 v[18:19], s[2:3], 0, v[6:7]
	v_mad_u32_u24 v6, v10, s8, 7
	v_mov_b32_e32 v7, v129
	v_lshlrev_b64 v[0:1], 6, v[0:1]
	v_lshlrev_b64 v[2:3], 6, v[2:3]
	v_lshlrev_b64 v[4:5], 6, v[4:5]
	v_mad_i64_i32 v[6:7], s[0:1], s7, v11, v[6:7]
	v_lshl_add_u64 v[0:1], s[2:3], 0, v[0:1]
	v_lshl_add_u64 v[2:3], s[2:3], 0, v[2:3]
	v_lshl_add_u64 v[4:5], s[2:3], 0, v[4:5]
	v_lshlrev_b64 v[6:7], 6, v[6:7]
	v_lshl_add_u64 v[20:21], s[2:3], 0, v[6:7]
	global_load_dword v8, v[0:1], off
	global_load_dword v9, v[2:3], off
	global_load_dword v6, v[4:5], off
	global_load_dword v7, v[12:13], off
	s_nop 0
	global_load_dword v4, v[14:15], off
	global_load_dword v5, v[16:17], off
	global_load_dword v2, v[18:19], off
	global_load_dword v3, v[20:21], off
	v_mad_u32_u24 v18, v10, s8, 12
	v_mov_b32_e32 v19, v129
	v_mad_i64_i32 v[18:19], s[0:1], s7, v11, v[18:19]
	v_lshlrev_b64 v[18:19], 6, v[18:19]
	v_lshl_add_u64 v[24:25], s[2:3], 0, v[18:19]
	v_mad_u32_u24 v18, v10, s8, 13
	v_mov_b32_e32 v19, v129
	v_mad_i64_i32 v[18:19], s[0:1], s7, v11, v[18:19]
	v_lshlrev_b64 v[18:19], 6, v[18:19]
	v_lshl_add_u64 v[26:27], s[2:3], 0, v[18:19]
	v_mad_u32_u24 v18, v10, s8, 14
	v_mov_b32_e32 v19, v129
	v_mad_i64_i32 v[18:19], s[0:1], s7, v11, v[18:19]
	v_mad_u32_u24 v0, v10, s8, 8
	v_mov_b32_e32 v1, v129
	v_mad_u32_u24 v12, v10, s8, 9
	v_mov_b32_e32 v13, v129
	v_mad_u32_u24 v14, v10, s8, 10
	v_mov_b32_e32 v15, v129
	v_mad_u32_u24 v16, v10, s8, 11
	v_mov_b32_e32 v17, v129
	v_lshlrev_b64 v[18:19], 6, v[18:19]
	v_mad_i64_i32 v[0:1], s[0:1], s7, v11, v[0:1]
	v_mad_i64_i32 v[12:13], s[0:1], s7, v11, v[12:13]
	v_mad_i64_i32 v[14:15], s[0:1], s7, v11, v[14:15]
	v_mad_i64_i32 v[16:17], s[0:1], s7, v11, v[16:17]
	v_lshl_add_u64 v[28:29], s[2:3], 0, v[18:19]
	v_mad_u32_u24 v18, v10, s8, 15
	v_mov_b32_e32 v19, v129
	v_lshlrev_b64 v[0:1], 6, v[0:1]
	v_lshlrev_b64 v[12:13], 6, v[12:13]
	v_lshlrev_b64 v[14:15], 6, v[14:15]
	v_lshlrev_b64 v[16:17], 6, v[16:17]
	v_mad_i64_i32 v[18:19], s[0:1], s7, v11, v[18:19]
	v_lshl_add_u64 v[0:1], s[2:3], 0, v[0:1]
	v_lshl_add_u64 v[12:13], s[2:3], 0, v[12:13]
	v_lshl_add_u64 v[14:15], s[2:3], 0, v[14:15]
	v_lshl_add_u64 v[16:17], s[2:3], 0, v[16:17]
	v_lshlrev_b64 v[18:19], 6, v[18:19]
	v_lshl_add_u64 v[30:31], s[2:3], 0, v[18:19]
	global_load_dword v21, v[0:1], off
	global_load_dword v22, v[12:13], off
	global_load_dword v18, v[14:15], off
	global_load_dword v19, v[16:17], off
	s_nop 0
	global_load_dword v15, v[24:25], off
	global_load_dword v16, v[26:27], off
	global_load_dword v13, v[28:29], off
	global_load_dword v14, v[30:31], off
	v_mad_u32_u24 v0, v10, s8, 16
	v_mov_b32_e32 v1, v129
	v_mad_i64_i32 v[0:1], s[0:1], s7, v11, v[0:1]
	v_lshlrev_b64 v[0:1], 6, v[0:1]
	v_lshl_add_u64 v[0:1], s[2:3], 0, v[0:1]
	global_load_dword v12, v[0:1], off
	s_mul_hi_i32 s9, s7, 0x1010
	s_mul_i32 s8, s7, 0x1010
	v_cmp_ne_u32_e32 vcc, 63, v10
	v_mov_b32_e32 v11, 0
	v_mov_b32_e32 v17, 0
	s_and_saveexec_b64 s[10:11], vcc
	s_cbranch_execz .LBB0_272
	v_add_u32_e32 v0, 17, v128
	v_mov_b32_e32 v1, v129
	v_lshl_add_u64 v[0:1], s[8:9], 0, v[0:1]
	v_lshlrev_b64 v[0:1], 6, v[0:1]
	v_lshl_add_u64 v[0:1], s[2:3], 0, v[0:1]
	global_load_dword v17, v[0:1], off
.LBB0_272:
	s_or_b64 exec, exec, s[10:11]
	s_and_saveexec_b64 s[10:11], vcc
	s_cbranch_execz .LBB0_274
	v_add_u32_e32 v0, 18, v128
	v_mov_b32_e32 v1, v129
	v_lshl_add_u64 v[0:1], s[8:9], 0, v[0:1]
	v_lshlrev_b64 v[0:1], 6, v[0:1]
	v_lshl_add_u64 v[0:1], s[2:3], 0, v[0:1]
	global_load_dword v11, v[0:1], off
.LBB0_274:
	s_or_b64 exec, exec, s[10:11]
	v_mov_b32_e32 v20, 0
	v_mov_b32_e32 v23, 0
	s_and_saveexec_b64 s[10:11], vcc
	s_cbranch_execz .LBB0_276
	v_add_u32_e32 v0, 19, v128
	v_mov_b32_e32 v1, v129
	v_lshl_add_u64 v[0:1], s[8:9], 0, v[0:1]
	v_lshlrev_b64 v[0:1], 6, v[0:1]
	v_lshl_add_u64 v[0:1], s[2:3], 0, v[0:1]
	global_load_dword v23, v[0:1], off
.LBB0_276:
	s_or_b64 exec, exec, s[10:11]
	s_and_saveexec_b64 s[10:11], vcc
	s_cbranch_execz .LBB0_278
	v_add_u32_e32 v0, 20, v128
	v_mov_b32_e32 v1, v129
	v_lshl_add_u64 v[0:1], s[8:9], 0, v[0:1]
	v_lshlrev_b64 v[0:1], 6, v[0:1]
	v_lshl_add_u64 v[0:1], s[2:3], 0, v[0:1]
	global_load_dword v20, v[0:1], off
.LBB0_278:
	s_or_b64 exec, exec, s[10:11]
	v_mov_b32_e32 v24, 0
	v_mov_b32_e32 v25, 0
	s_and_saveexec_b64 s[10:11], vcc
	s_cbranch_execz .LBB0_280
	v_add_u32_e32 v0, 21, v128
	v_mov_b32_e32 v1, v129
	v_lshl_add_u64 v[0:1], s[8:9], 0, v[0:1]
	v_lshlrev_b64 v[0:1], 6, v[0:1]
	v_lshl_add_u64 v[0:1], s[2:3], 0, v[0:1]
	global_load_dword v25, v[0:1], off
.LBB0_280:
	s_or_b64 exec, exec, s[10:11]
	s_and_saveexec_b64 s[10:11], vcc
	s_cbranch_execz .LBB0_282
	v_add_u32_e32 v0, 22, v128
	v_mov_b32_e32 v1, v129
	v_lshl_add_u64 v[0:1], s[8:9], 0, v[0:1]
	v_lshlrev_b64 v[0:1], 6, v[0:1]
	v_lshl_add_u64 v[0:1], s[2:3], 0, v[0:1]
	global_load_dword v24, v[0:1], off
.LBB0_282:
	s_or_b64 exec, exec, s[10:11]
	v_mov_b32_e32 v26, 0
	v_mov_b32_e32 v27, 0
	s_and_saveexec_b64 s[10:11], vcc
	s_cbranch_execz .LBB0_284
	v_add_u32_e32 v0, 23, v128
	v_mov_b32_e32 v1, v129
	v_lshl_add_u64 v[0:1], s[8:9], 0, v[0:1]
	v_lshlrev_b64 v[0:1], 6, v[0:1]
	v_lshl_add_u64 v[0:1], s[2:3], 0, v[0:1]
	global_load_dword v27, v[0:1], off
.LBB0_284:
	s_or_b64 exec, exec, s[10:11]
	s_and_saveexec_b64 s[10:11], vcc
	s_cbranch_execz .LBB0_286
	v_add_u32_e32 v0, 24, v128
	v_mov_b32_e32 v1, v129
	v_lshl_add_u64 v[0:1], s[8:9], 0, v[0:1]
	v_lshlrev_b64 v[0:1], 6, v[0:1]
	v_lshl_add_u64 v[0:1], s[2:3], 0, v[0:1]
	global_load_dword v26, v[0:1], off
.LBB0_286:
	s_or_b64 exec, exec, s[10:11]
	v_mov_b32_e32 v28, 0
	v_mov_b32_e32 v29, 0
	s_and_saveexec_b64 s[10:11], vcc
	s_cbranch_execz .LBB0_288
	v_add_u32_e32 v0, 25, v128
	v_mov_b32_e32 v1, v129
	v_lshl_add_u64 v[0:1], s[8:9], 0, v[0:1]
	v_lshlrev_b64 v[0:1], 6, v[0:1]
	v_lshl_add_u64 v[0:1], s[2:3], 0, v[0:1]
	global_load_dword v29, v[0:1], off
.LBB0_288:
	s_or_b64 exec, exec, s[10:11]
	s_and_saveexec_b64 s[10:11], vcc
	s_cbranch_execz .LBB0_290
	v_add_u32_e32 v0, 26, v128
	v_mov_b32_e32 v1, v129
	v_lshl_add_u64 v[0:1], s[8:9], 0, v[0:1]
	v_lshlrev_b64 v[0:1], 6, v[0:1]
	v_lshl_add_u64 v[0:1], s[2:3], 0, v[0:1]
	global_load_dword v28, v[0:1], off
.LBB0_290:
	s_or_b64 exec, exec, s[10:11]
	v_mov_b32_e32 v30, 0
	v_mov_b32_e32 v31, 0
	s_and_saveexec_b64 s[10:11], vcc
	s_cbranch_execz .LBB0_292
	v_add_u32_e32 v0, 27, v128
	v_mov_b32_e32 v1, v129
	v_lshl_add_u64 v[0:1], s[8:9], 0, v[0:1]
	v_lshlrev_b64 v[0:1], 6, v[0:1]
	v_lshl_add_u64 v[0:1], s[2:3], 0, v[0:1]
	global_load_dword v31, v[0:1], off
.LBB0_292:
	s_or_b64 exec, exec, s[10:11]
	s_and_saveexec_b64 s[10:11], vcc
	s_cbranch_execz .LBB0_294
	v_add_u32_e32 v0, 28, v128
	v_mov_b32_e32 v1, v129
	v_lshl_add_u64 v[0:1], s[8:9], 0, v[0:1]
	v_lshlrev_b64 v[0:1], 6, v[0:1]
	v_lshl_add_u64 v[0:1], s[2:3], 0, v[0:1]
	global_load_dword v30, v[0:1], off
.LBB0_294:
	s_or_b64 exec, exec, s[10:11]
	v_mov_b32_e32 v32, 0
	v_mov_b32_e32 v33, 0
	s_and_saveexec_b64 s[10:11], vcc
	s_cbranch_execz .LBB0_296
	v_add_u32_e32 v0, 29, v128
	v_mov_b32_e32 v1, v129
	v_lshl_add_u64 v[0:1], s[8:9], 0, v[0:1]
	v_lshlrev_b64 v[0:1], 6, v[0:1]
	v_lshl_add_u64 v[0:1], s[2:3], 0, v[0:1]
	global_load_dword v33, v[0:1], off
.LBB0_296:
	s_or_b64 exec, exec, s[10:11]
	s_and_saveexec_b64 s[10:11], vcc
	s_cbranch_execz .LBB0_298
	v_add_u32_e32 v0, 30, v128
	v_mov_b32_e32 v1, v129
	v_lshl_add_u64 v[0:1], s[8:9], 0, v[0:1]
	v_lshlrev_b64 v[0:1], 6, v[0:1]
	v_lshl_add_u64 v[0:1], s[2:3], 0, v[0:1]
	global_load_dword v32, v[0:1], off
.LBB0_298:
	s_or_b64 exec, exec, s[10:11]
	v_mov_b32_e32 v34, 0
	v_mov_b32_e32 v35, 0
	s_and_saveexec_b64 s[10:11], vcc
	s_cbranch_execz .LBB0_300
	v_add_u32_e32 v0, 31, v128
	v_mov_b32_e32 v1, v129
	v_lshl_add_u64 v[0:1], s[8:9], 0, v[0:1]
	v_lshlrev_b64 v[0:1], 6, v[0:1]
	v_lshl_add_u64 v[0:1], s[2:3], 0, v[0:1]
	global_load_dword v35, v[0:1], off
.LBB0_300:
	s_or_b64 exec, exec, s[10:11]
	s_and_saveexec_b64 s[10:11], vcc
	s_cbranch_execz .LBB0_302
	v_add_u32_e32 v0, 32, v128
	v_mov_b32_e32 v1, v129
	v_lshl_add_u64 v[0:1], s[8:9], 0, v[0:1]
	v_lshlrev_b64 v[0:1], 6, v[0:1]
	v_lshl_add_u64 v[0:1], s[2:3], 0, v[0:1]
	global_load_dword v34, v[0:1], off
.LBB0_302:
	s_or_b64 exec, exec, s[10:11]
	v_mov_b32_e32 v36, 0
	v_mov_b32_e32 v37, 0
	s_and_saveexec_b64 s[10:11], vcc
	s_cbranch_execz .LBB0_304
	v_add_u32_e32 v0, 33, v128
	v_mov_b32_e32 v1, v129
	v_lshl_add_u64 v[0:1], s[8:9], 0, v[0:1]
	v_lshlrev_b64 v[0:1], 6, v[0:1]
	v_lshl_add_u64 v[0:1], s[2:3], 0, v[0:1]
	global_load_dword v37, v[0:1], off
.LBB0_304:
	s_or_b64 exec, exec, s[10:11]
	s_and_saveexec_b64 s[10:11], vcc
	s_cbranch_execz .LBB0_306
	v_add_u32_e32 v0, 34, v128
	v_mov_b32_e32 v1, v129
	v_lshl_add_u64 v[0:1], s[8:9], 0, v[0:1]
	v_lshlrev_b64 v[0:1], 6, v[0:1]
	v_lshl_add_u64 v[0:1], s[2:3], 0, v[0:1]
	global_load_dword v36, v[0:1], off
.LBB0_306:
	s_or_b64 exec, exec, s[10:11]
	v_mov_b32_e32 v38, 0
	v_mov_b32_e32 v39, 0
	s_and_saveexec_b64 s[10:11], vcc
	s_cbranch_execz .LBB0_308
	v_add_u32_e32 v0, 35, v128
	v_mov_b32_e32 v1, v129
	v_lshl_add_u64 v[0:1], s[8:9], 0, v[0:1]
	v_lshlrev_b64 v[0:1], 6, v[0:1]
	v_lshl_add_u64 v[0:1], s[2:3], 0, v[0:1]
	global_load_dword v39, v[0:1], off
.LBB0_308:
	s_or_b64 exec, exec, s[10:11]
	s_and_saveexec_b64 s[10:11], vcc
	s_cbranch_execz .LBB0_310
	v_add_u32_e32 v0, 36, v128
	v_mov_b32_e32 v1, v129
	v_lshl_add_u64 v[0:1], s[8:9], 0, v[0:1]
	v_lshlrev_b64 v[0:1], 6, v[0:1]
	v_lshl_add_u64 v[0:1], s[2:3], 0, v[0:1]
	global_load_dword v38, v[0:1], off
.LBB0_310:
	s_or_b64 exec, exec, s[10:11]
	v_mov_b32_e32 v40, 0
	v_mov_b32_e32 v41, 0
	s_and_saveexec_b64 s[10:11], vcc
	s_cbranch_execz .LBB0_312
	v_add_u32_e32 v0, 37, v128
	v_mov_b32_e32 v1, v129
	v_lshl_add_u64 v[0:1], s[8:9], 0, v[0:1]
	v_lshlrev_b64 v[0:1], 6, v[0:1]
	v_lshl_add_u64 v[0:1], s[2:3], 0, v[0:1]
	global_load_dword v41, v[0:1], off
.LBB0_312:
	s_or_b64 exec, exec, s[10:11]
	s_and_saveexec_b64 s[10:11], vcc
	s_cbranch_execz .LBB0_314
	v_add_u32_e32 v0, 38, v128
	v_mov_b32_e32 v1, v129
	v_lshl_add_u64 v[0:1], s[8:9], 0, v[0:1]
	v_lshlrev_b64 v[0:1], 6, v[0:1]
	v_lshl_add_u64 v[0:1], s[2:3], 0, v[0:1]
	global_load_dword v40, v[0:1], off
.LBB0_314:
	s_or_b64 exec, exec, s[10:11]
	v_mov_b32_e32 v42, 0
	v_mov_b32_e32 v43, 0
	s_and_saveexec_b64 s[10:11], vcc
	s_cbranch_execz .LBB0_316
	v_add_u32_e32 v0, 39, v128
	v_mov_b32_e32 v1, v129
	v_lshl_add_u64 v[0:1], s[8:9], 0, v[0:1]
	v_lshlrev_b64 v[0:1], 6, v[0:1]
	v_lshl_add_u64 v[0:1], s[2:3], 0, v[0:1]
	global_load_dword v43, v[0:1], off
.LBB0_316:
	s_or_b64 exec, exec, s[10:11]
	s_and_saveexec_b64 s[10:11], vcc
	s_cbranch_execz .LBB0_318
	v_add_u32_e32 v0, 40, v128
	v_mov_b32_e32 v1, v129
	v_lshl_add_u64 v[0:1], s[8:9], 0, v[0:1]
	v_lshlrev_b64 v[0:1], 6, v[0:1]
	v_lshl_add_u64 v[0:1], s[2:3], 0, v[0:1]
	global_load_dword v42, v[0:1], off
.LBB0_318:
	s_or_b64 exec, exec, s[10:11]
	v_mov_b32_e32 v44, 0
	v_mov_b32_e32 v45, 0
	s_and_saveexec_b64 s[10:11], vcc
	s_cbranch_execz .LBB0_320
	v_add_u32_e32 v0, 41, v128
	v_mov_b32_e32 v1, v129
	v_lshl_add_u64 v[0:1], s[8:9], 0, v[0:1]
	v_lshlrev_b64 v[0:1], 6, v[0:1]
	v_lshl_add_u64 v[0:1], s[2:3], 0, v[0:1]
	global_load_dword v45, v[0:1], off
.LBB0_320:
	s_or_b64 exec, exec, s[10:11]
	s_and_saveexec_b64 s[10:11], vcc
	s_cbranch_execz .LBB0_322
	v_add_u32_e32 v0, 42, v128
	v_mov_b32_e32 v1, v129
	v_lshl_add_u64 v[0:1], s[8:9], 0, v[0:1]
	v_lshlrev_b64 v[0:1], 6, v[0:1]
	v_lshl_add_u64 v[0:1], s[2:3], 0, v[0:1]
	global_load_dword v44, v[0:1], off
.LBB0_322:
	s_or_b64 exec, exec, s[10:11]
	v_mov_b32_e32 v46, 0
	v_mov_b32_e32 v47, 0
	s_and_saveexec_b64 s[10:11], vcc
	s_cbranch_execz .LBB0_324
	v_add_u32_e32 v0, 43, v128
	v_mov_b32_e32 v1, v129
	v_lshl_add_u64 v[0:1], s[8:9], 0, v[0:1]
	v_lshlrev_b64 v[0:1], 6, v[0:1]
	v_lshl_add_u64 v[0:1], s[2:3], 0, v[0:1]
	global_load_dword v47, v[0:1], off
.LBB0_324:
	s_or_b64 exec, exec, s[10:11]
	s_and_saveexec_b64 s[10:11], vcc
	s_cbranch_execz .LBB0_326
	v_add_u32_e32 v0, 44, v128
	v_mov_b32_e32 v1, v129
	v_lshl_add_u64 v[0:1], s[8:9], 0, v[0:1]
	v_lshlrev_b64 v[0:1], 6, v[0:1]
	v_lshl_add_u64 v[0:1], s[2:3], 0, v[0:1]
	global_load_dword v46, v[0:1], off
.LBB0_326:
	s_or_b64 exec, exec, s[10:11]
	v_mov_b32_e32 v48, 0
	v_mov_b32_e32 v49, 0
	s_and_saveexec_b64 s[10:11], vcc
	s_cbranch_execz .LBB0_328
	v_add_u32_e32 v0, 45, v128
	v_mov_b32_e32 v1, v129
	v_lshl_add_u64 v[0:1], s[8:9], 0, v[0:1]
	v_lshlrev_b64 v[0:1], 6, v[0:1]
	v_lshl_add_u64 v[0:1], s[2:3], 0, v[0:1]
	global_load_dword v49, v[0:1], off
.LBB0_328:
	s_or_b64 exec, exec, s[10:11]
	s_and_saveexec_b64 s[10:11], vcc
	s_cbranch_execz .LBB0_330
	v_add_u32_e32 v0, 46, v128
	v_mov_b32_e32 v1, v129
	v_lshl_add_u64 v[0:1], s[8:9], 0, v[0:1]
	v_lshlrev_b64 v[0:1], 6, v[0:1]
	v_lshl_add_u64 v[0:1], s[2:3], 0, v[0:1]
	global_load_dword v48, v[0:1], off
.LBB0_330:
	s_or_b64 exec, exec, s[10:11]
	v_mov_b32_e32 v50, 0
	v_mov_b32_e32 v51, 0
	s_and_saveexec_b64 s[10:11], vcc
	s_cbranch_execz .LBB0_332
	v_add_u32_e32 v0, 47, v128
	v_mov_b32_e32 v1, v129
	v_lshl_add_u64 v[0:1], s[8:9], 0, v[0:1]
	v_lshlrev_b64 v[0:1], 6, v[0:1]
	v_lshl_add_u64 v[0:1], s[2:3], 0, v[0:1]
	global_load_dword v51, v[0:1], off
.LBB0_332:
	s_or_b64 exec, exec, s[10:11]
	s_and_saveexec_b64 s[10:11], vcc
	s_cbranch_execz .LBB0_334
	v_add_u32_e32 v0, 48, v128
	v_mov_b32_e32 v1, v129
	v_lshl_add_u64 v[0:1], s[8:9], 0, v[0:1]
	v_lshlrev_b64 v[0:1], 6, v[0:1]
	v_lshl_add_u64 v[0:1], s[2:3], 0, v[0:1]
	global_load_dword v50, v[0:1], off
.LBB0_334:
	s_or_b64 exec, exec, s[10:11]
	v_mov_b32_e32 v52, 0
	v_mov_b32_e32 v53, 0
	s_and_saveexec_b64 s[10:11], vcc
	s_cbranch_execz .LBB0_336
	v_add_u32_e32 v0, 49, v128
	v_mov_b32_e32 v1, v129
	v_lshl_add_u64 v[0:1], s[8:9], 0, v[0:1]
	v_lshlrev_b64 v[0:1], 6, v[0:1]
	v_lshl_add_u64 v[0:1], s[2:3], 0, v[0:1]
	global_load_dword v53, v[0:1], off
.LBB0_336:
	s_or_b64 exec, exec, s[10:11]
	s_and_saveexec_b64 s[10:11], vcc
	s_cbranch_execz .LBB0_338
	v_add_u32_e32 v0, 50, v128
	v_mov_b32_e32 v1, v129
	v_lshl_add_u64 v[0:1], s[8:9], 0, v[0:1]
	v_lshlrev_b64 v[0:1], 6, v[0:1]
	v_lshl_add_u64 v[0:1], s[2:3], 0, v[0:1]
	global_load_dword v52, v[0:1], off
.LBB0_338:
	s_or_b64 exec, exec, s[10:11]
	v_mov_b32_e32 v54, 0
	v_mov_b32_e32 v56, 0
	s_and_saveexec_b64 s[10:11], vcc
	s_cbranch_execz .LBB0_340
	v_add_u32_e32 v0, 51, v128
	v_mov_b32_e32 v1, v129
	v_lshl_add_u64 v[0:1], s[8:9], 0, v[0:1]
	v_lshlrev_b64 v[0:1], 6, v[0:1]
	v_lshl_add_u64 v[0:1], s[2:3], 0, v[0:1]
	global_load_dword v56, v[0:1], off
.LBB0_340:
	s_or_b64 exec, exec, s[10:11]
	s_and_saveexec_b64 s[10:11], vcc
	s_cbranch_execz .LBB0_342
	v_add_u32_e32 v0, 52, v128
	v_mov_b32_e32 v1, v129
	v_lshl_add_u64 v[0:1], s[8:9], 0, v[0:1]
	v_lshlrev_b64 v[0:1], 6, v[0:1]
	v_lshl_add_u64 v[0:1], s[2:3], 0, v[0:1]
	global_load_dword v54, v[0:1], off
.LBB0_342:
	s_or_b64 exec, exec, s[10:11]
	v_mov_b32_e32 v55, 0
	v_mov_b32_e32 v57, 0
	s_and_saveexec_b64 s[10:11], vcc
	s_cbranch_execz .LBB0_344
	v_add_u32_e32 v0, 53, v128
	v_mov_b32_e32 v1, v129
	v_lshl_add_u64 v[0:1], s[8:9], 0, v[0:1]
	v_lshlrev_b64 v[0:1], 6, v[0:1]
	v_lshl_add_u64 v[0:1], s[2:3], 0, v[0:1]
	global_load_dword v57, v[0:1], off
.LBB0_344:
	s_or_b64 exec, exec, s[10:11]
	s_and_saveexec_b64 s[10:11], vcc
	s_cbranch_execz .LBB0_346
	v_add_u32_e32 v0, 54, v128
	v_mov_b32_e32 v1, v129
	v_lshl_add_u64 v[0:1], s[8:9], 0, v[0:1]
	v_lshlrev_b64 v[0:1], 6, v[0:1]
	v_lshl_add_u64 v[0:1], s[2:3], 0, v[0:1]
	global_load_dword v55, v[0:1], off
.LBB0_346:
	s_or_b64 exec, exec, s[10:11]
	v_mov_b32_e32 v58, 0
	v_mov_b32_e32 v59, 0
	s_and_saveexec_b64 s[10:11], vcc
	s_cbranch_execz .LBB0_348
	v_add_u32_e32 v0, 55, v128
	v_mov_b32_e32 v1, v129
	v_lshl_add_u64 v[0:1], s[8:9], 0, v[0:1]
	v_lshlrev_b64 v[0:1], 6, v[0:1]
	v_lshl_add_u64 v[0:1], s[2:3], 0, v[0:1]
	global_load_dword v59, v[0:1], off
.LBB0_348:
	s_or_b64 exec, exec, s[10:11]
	s_and_saveexec_b64 s[10:11], vcc
	s_cbranch_execz .LBB0_350
	v_add_u32_e32 v0, 56, v128
	v_mov_b32_e32 v1, v129
	v_lshl_add_u64 v[0:1], s[8:9], 0, v[0:1]
	v_lshlrev_b64 v[0:1], 6, v[0:1]
	v_lshl_add_u64 v[0:1], s[2:3], 0, v[0:1]
	global_load_dword v58, v[0:1], off
.LBB0_350:
	s_or_b64 exec, exec, s[10:11]
	v_mov_b32_e32 v60, 0
	v_mov_b32_e32 v61, 0
	s_and_saveexec_b64 s[10:11], vcc
	s_cbranch_execz .LBB0_352
	v_add_u32_e32 v0, 57, v128
	v_mov_b32_e32 v1, v129
	v_lshl_add_u64 v[0:1], s[8:9], 0, v[0:1]
	v_lshlrev_b64 v[0:1], 6, v[0:1]
	v_lshl_add_u64 v[0:1], s[2:3], 0, v[0:1]
	global_load_dword v61, v[0:1], off
.LBB0_352:
	s_or_b64 exec, exec, s[10:11]
	s_and_saveexec_b64 s[10:11], vcc
	s_cbranch_execz .LBB0_354
	v_add_u32_e32 v0, 58, v128
	v_mov_b32_e32 v1, v129
	v_lshl_add_u64 v[0:1], s[8:9], 0, v[0:1]
	v_lshlrev_b64 v[0:1], 6, v[0:1]
	v_lshl_add_u64 v[0:1], s[2:3], 0, v[0:1]
	global_load_dword v60, v[0:1], off
.LBB0_354:
	s_or_b64 exec, exec, s[10:11]
	v_mov_b32_e32 v62, 0
	v_mov_b32_e32 v63, 0
	s_and_saveexec_b64 s[10:11], vcc
	s_cbranch_execz .LBB0_356
	v_add_u32_e32 v0, 59, v128
	v_mov_b32_e32 v1, v129
	v_lshl_add_u64 v[0:1], s[8:9], 0, v[0:1]
	v_lshlrev_b64 v[0:1], 6, v[0:1]
	v_lshl_add_u64 v[0:1], s[2:3], 0, v[0:1]
	global_load_dword v63, v[0:1], off
.LBB0_356:
	s_or_b64 exec, exec, s[10:11]
	s_and_saveexec_b64 s[10:11], vcc
	s_cbranch_execz .LBB0_358
	v_add_u32_e32 v0, 60, v128
	v_mov_b32_e32 v1, v129
	v_lshl_add_u64 v[0:1], s[8:9], 0, v[0:1]
	v_lshlrev_b64 v[0:1], 6, v[0:1]
	v_lshl_add_u64 v[0:1], s[2:3], 0, v[0:1]
	global_load_dword v62, v[0:1], off
.LBB0_358:
	s_or_b64 exec, exec, s[10:11]
	v_mov_b32_e32 v64, 0
	v_mov_b32_e32 v65, 0
	s_and_saveexec_b64 s[10:11], vcc
	s_cbranch_execz .LBB0_360
	v_add_u32_e32 v0, 61, v128
	v_mov_b32_e32 v1, v129
	v_lshl_add_u64 v[0:1], s[8:9], 0, v[0:1]
	v_lshlrev_b64 v[0:1], 6, v[0:1]
	v_lshl_add_u64 v[0:1], s[2:3], 0, v[0:1]
	global_load_dword v65, v[0:1], off
.LBB0_360:
	s_or_b64 exec, exec, s[10:11]
	s_and_saveexec_b64 s[10:11], vcc
	s_cbranch_execz .LBB0_362
	v_add_u32_e32 v0, 62, v128
	v_mov_b32_e32 v1, v129
	v_lshl_add_u64 v[0:1], s[8:9], 0, v[0:1]
	v_lshlrev_b64 v[0:1], 6, v[0:1]
	v_lshl_add_u64 v[0:1], s[2:3], 0, v[0:1]
	global_load_dword v64, v[0:1], off
.LBB0_362:
	s_or_b64 exec, exec, s[10:11]
	v_mov_b32_e32 v66, 0
	v_mov_b32_e32 v67, 0
	s_and_saveexec_b64 s[10:11], vcc
	s_cbranch_execz .LBB0_364
	v_add_u32_e32 v0, 63, v128
	v_mov_b32_e32 v1, v129
	v_lshl_add_u64 v[0:1], s[8:9], 0, v[0:1]
	v_lshlrev_b64 v[0:1], 6, v[0:1]
	v_lshl_add_u64 v[0:1], s[2:3], 0, v[0:1]
	global_load_dword v67, v[0:1], off
.LBB0_364:
	s_or_b64 exec, exec, s[10:11]
	s_and_saveexec_b64 s[10:11], vcc
	s_cbranch_execz .LBB0_366
	v_add_u32_e32 v0, 64, v128
	v_mov_b32_e32 v1, v129
	v_lshl_add_u64 v[0:1], s[8:9], 0, v[0:1]
	v_lshlrev_b64 v[0:1], 6, v[0:1]
	v_lshl_add_u64 v[0:1], s[2:3], 0, v[0:1]
	global_load_dword v66, v[0:1], off
.LBB0_366:
	s_or_b64 exec, exec, s[10:11]
	s_waitcnt vmcnt(0) lgkmcnt(0)
	v_add_f32_e32 v0, 0, v8
	v_add_f32_e32 v0, v0, v9
	v_add_f32_e32 v0, v0, v6
	v_add_f32_e32 v0, v0, v7
	v_add_f32_e32 v0, v0, v4
	v_add_f32_e32 v0, v0, v5
	v_add_f32_e32 v0, v0, v2
	v_add_f32_e32 v0, v0, v3
	v_add_f32_e32 v0, v0, v21
	v_add_f32_e32 v0, v0, v22
	v_add_f32_e32 v0, v0, v18
	v_add_f32_e32 v0, v0, v19
	v_add_f32_e32 v0, v0, v15
	v_add_f32_e32 v0, v0, v16
	v_add_f32_e32 v0, v0, v13
	v_add_f32_e32 v0, v0, v14
	v_add_f32_e32 v0, v0, v12
	v_add_f32_e32 v0, v0, v17
	v_add_f32_e32 v0, v0, v11
	v_add_f32_e32 v0, v0, v23
	v_add_f32_e32 v0, v0, v20
	v_add_f32_e32 v0, v0, v25
	v_add_f32_e32 v0, v0, v24
	v_add_f32_e32 v0, v0, v27
	v_add_f32_e32 v0, v0, v26
	v_add_f32_e32 v0, v0, v29
	v_add_f32_e32 v0, v0, v28
	v_add_f32_e32 v0, v0, v31
	v_add_f32_e32 v0, v0, v30
	v_add_f32_e32 v0, v0, v33
	v_add_f32_e32 v0, v0, v32
	v_add_f32_e32 v0, v0, v35
	v_add_f32_e32 v0, v0, v34
	v_add_f32_e32 v0, v0, v37
	v_add_f32_e32 v0, v0, v36
	v_add_f32_e32 v0, v0, v39
	v_add_f32_e32 v0, v0, v38
	v_add_f32_e32 v0, v0, v41
	v_add_f32_e32 v0, v0, v40
	v_add_f32_e32 v0, v0, v43
	v_add_f32_e32 v0, v0, v42
	v_add_f32_e32 v0, v0, v45
	v_add_f32_e32 v0, v0, v44
	v_add_f32_e32 v0, v0, v47
	v_add_f32_e32 v0, v0, v46
	v_add_f32_e32 v0, v0, v49
	v_add_f32_e32 v0, v0, v48
	v_add_f32_e32 v0, v0, v51
	v_add_f32_e32 v0, v0, v50
	v_add_f32_e32 v0, v0, v53
	v_add_f32_e32 v0, v0, v52
	v_add_f32_e32 v0, v0, v56
	v_add_f32_e32 v0, v0, v54
	v_add_f32_e32 v0, v0, v57
	v_add_f32_e32 v0, v0, v55
	v_add_f32_e32 v0, v0, v59
	v_add_f32_e32 v0, v0, v58
	v_add_f32_e32 v0, v0, v61
	v_add_f32_e32 v0, v0, v60
	v_add_f32_e32 v0, v0, v63
	v_add_f32_e32 v0, v0, v62
	v_add_f32_e32 v0, v0, v65
	v_and_b32_e32 v68, 64, v214
	v_add_u32_e32 v1, -1, v214
	v_add_f32_e32 v0, v0, v64
	v_cmp_lt_i32_e64 s[2:3], v1, v68
	v_add_f32_e32 v0, v0, v67
	v_add_f32_e32 v0, v0, v66
	v_cndmask_b32_e64 v1, v1, v214, s[2:3]
	v_lshlrev_b32_e32 v1, 2, v1
	ds_bpermute_b32 v1, v1, v0
	v_cmp_eq_u32_e64 s[2:3], 0, v10
	v_add_u32_e32 v69, -2, v214
	s_mul_i32 s1, s6, 0x4400
	s_mul_hi_i32 s0, s6, 0x4400
	s_waitcnt lgkmcnt(0)
	v_add_f32_e32 v1, v0, v1
	v_cndmask_b32_e64 v1, v1, v0, s[2:3]
	v_cmp_lt_i32_e64 s[2:3], v69, v68
	s_add_u32 s1, s4, s1
	s_addc_u32 s0, s5, s0
	v_cndmask_b32_e64 v69, v69, v214, s[2:3]
	v_lshlrev_b32_e32 v69, 2, v69
	ds_bpermute_b32 v69, v69, v1
	v_cmp_gt_u32_e64 s[2:3], 2, v10
	s_add_u32 s6, s1, 0x3f7d4000
	s_addc_u32 s7, s0, 0
	v_lshlrev_b32_e32 v70, 2, v10
	s_waitcnt lgkmcnt(0)
	v_add_f32_e32 v69, v1, v69
	v_cndmask_b32_e64 v1, v69, v1, s[2:3]
	v_add_u32_e32 v69, -4, v214
	v_cmp_lt_i32_e64 s[2:3], v69, v68
	v_mov_b32_e32 v71, v129
	v_lshl_add_u64 v[70:71], s[6:7], 0, v[70:71]
	v_cndmask_b32_e64 v69, v69, v214, s[2:3]
	v_lshlrev_b32_e32 v69, 2, v69
	ds_bpermute_b32 v69, v69, v1
	v_cmp_gt_u32_e64 s[2:3], 4, v10
	global_store_dword v[70:71], v213, off
	v_mov_b32_e32 v71, v129
	s_waitcnt lgkmcnt(0)
	v_add_f32_e32 v69, v1, v69
	v_cndmask_b32_e64 v1, v69, v1, s[2:3]
	v_add_u32_e32 v69, -8, v214
	v_cmp_lt_i32_e64 s[2:3], v69, v68
	s_nop 1
	v_cndmask_b32_e64 v69, v69, v214, s[2:3]
	v_lshlrev_b32_e32 v69, 2, v69
	ds_bpermute_b32 v69, v69, v1
	v_cmp_gt_u32_e64 s[2:3], 8, v10
	s_waitcnt lgkmcnt(0)
	v_add_f32_e32 v69, v1, v69
	v_cndmask_b32_e64 v1, v69, v1, s[2:3]
	v_add_u32_e32 v69, -16, v214
	v_cmp_lt_i32_e64 s[2:3], v69, v68
	s_nop 1
	v_cndmask_b32_e64 v69, v69, v214, s[2:3]
	v_lshlrev_b32_e32 v69, 2, v69
	ds_bpermute_b32 v69, v69, v1
	v_cmp_gt_u32_e64 s[2:3], 16, v10
	s_waitcnt lgkmcnt(0)
	v_add_f32_e32 v69, v1, v69
	v_cndmask_b32_e64 v1, v69, v1, s[2:3]
	v_subrev_u32_e32 v69, 32, v214
	v_cmp_lt_i32_e64 s[2:3], v69, v68
	s_nop 1
	v_cndmask_b32_e64 v68, v69, v214, s[2:3]
	v_lshlrev_b32_e32 v68, 2, v68
	ds_bpermute_b32 v68, v68, v1
	v_sub_u32_e32 v69, 0xef, v10
	v_lshrrev_b32_e32 v72, 6, v69
	v_or_b32_e32 v69, 64, v10
	v_lshlrev_b32_e32 v70, 2, v69
	v_lshl_add_u64 v[70:71], s[6:7], 0, v[70:71]
	global_store_dword v[70:71], v213, off
	v_or_b32_e32 v69, 0xc0, v10
	v_or_b32_e32 v70, 0x80, v10
	v_cmp_lt_u32_e64 s[2:3], 2, v72
	v_cmp_lt_u32_e64 s[4:5], 1, v72
	s_and_saveexec_b64 s[8:9], s[4:5]
	s_cbranch_execz .LBB0_368
	v_lshlrev_b32_e32 v70, 2, v70
	v_mov_b32_e32 v71, v129
	v_lshl_add_u64 v[70:71], s[6:7], 0, v[70:71]
	global_store_dword v[70:71], v213, off
.LBB0_368:
	s_or_b64 exec, exec, s[8:9]
	s_and_saveexec_b64 s[4:5], s[2:3]
	s_cbranch_execz .LBB0_370
	v_lshlrev_b32_e32 v70, 2, v69
	v_mov_b32_e32 v71, v129
	v_lshl_add_u64 v[70:71], s[6:7], 0, v[70:71]
	global_store_dword v[70:71], v213, off
.LBB0_370:
	s_or_b64 exec, exec, s[4:5]
	s_waitcnt lgkmcnt(0)
	v_add_f32_e32 v68, v1, v68
	v_cmp_gt_u32_e64 s[2:3], 32, v10
	s_mov_b32 s0, 0xc13504f3
	v_lshlrev_b32_e32 v128, 2, v128
	v_cndmask_b32_e64 v1, v68, v1, s[2:3]
	v_sub_f32_e32 v10, v1, v0
	v_add_f32_e32 v8, v8, v10
	v_add_f32_e32 v9, v9, v8
	v_add_f32_e32 v6, v6, v9
	v_add_f32_e32 v7, v7, v6
	v_pk_mul_f32 v[70:71], v[6:7], s[0:1] op_sel_hi:[1,0]
	v_add_f32_e32 v6, v4, v7
	v_add_f32_e32 v7, v5, v6
	v_add_f32_e32 v2, v2, v7
	v_add_f32_e32 v3, v3, v2
	v_lshl_add_u64 v[0:1], s[6:7], 0, v[128:129]
	v_pk_mul_f32 v[4:5], v[6:7], s[0:1] op_sel_hi:[1,0]
	v_pk_mul_f32 v[6:7], v[2:3], s[0:1] op_sel_hi:[1,0]
	global_store_dwordx4 v[0:1], v[4:7], off offset:976
	v_pk_mul_f32 v[68:69], v[8:9], s[0:1] op_sel_hi:[1,0]
	global_store_dwordx4 v[0:1], v[68:71], off offset:960
	v_add_f32_e32 v4, v21, v3
	v_add_f32_e32 v5, v22, v4
	v_add_f32_e32 v6, v18, v5
	v_add_f32_e32 v7, v19, v6
	v_pk_mul_f32 v[2:3], v[4:5], s[0:1] op_sel_hi:[1,0]
	v_pk_mul_f32 v[4:5], v[6:7], s[0:1] op_sel_hi:[1,0]
	global_store_dwordx4 v[0:1], v[2:5], off offset:992
	s_nop 1
	v_add_f32_e32 v4, v15, v7
	v_add_f32_e32 v5, v16, v4
	v_add_f32_e32 v6, v13, v5
	v_add_f32_e32 v7, v14, v6
	v_pk_mul_f32 v[2:3], v[4:5], s[0:1] op_sel_hi:[1,0]
	v_pk_mul_f32 v[4:5], v[6:7], s[0:1] op_sel_hi:[1,0]
	global_store_dwordx4 v[0:1], v[2:5], off offset:1008
	s_nop 1
	v_add_f32_e32 v2, v12, v7
	v_mul_f32_e32 v3, 0xc13504f3, v2
	v_add_f32_e32 v2, v17, v2
	global_store_dword v[0:1], v3, off offset:1024
	s_and_saveexec_b64 s[2:3], vcc
	s_cbranch_execnz .LBB0_422
	s_or_b64 exec, exec, s[2:3]
	v_add_f32_e32 v2, v11, v2
	s_and_saveexec_b64 s[2:3], vcc
	s_cbranch_execnz .LBB0_423

.LBB0_408:
	v_add_f32_e32 v3, v55, v2
	v_add_f32_e32 v4, v59, v3
	v_add_f32_e32 v6, v58, v4
	v_add_f32_e32 v7, v61, v6
	v_mul_f32_e32 v2, 0xc13504f3, v3
	v_mul_f32_e32 v3, 0xc13504f3, v4
	v_pk_mul_f32 v[4:5], v[6:7], s[0:1] op_sel_hi:[1,0]
	global_store_dwordx4 v[0:1], v[2:5], off offset:1176
	s_nop 1
	v_add_f32_e32 v4, v60, v7
	v_add_f32_e32 v5, v63, v4
	v_add_f32_e32 v6, v62, v5
	v_add_f32_e32 v7, v65, v6
	v_pk_mul_f32 v[2:3], v[4:5], s[0:1] op_sel_hi:[1,0]
	v_pk_mul_f32 v[4:5], v[6:7], s[0:1] op_sel_hi:[1,0]
	global_store_dwordx4 v[0:1], v[2:5], off offset:1192
	s_nop 1
	v_add_f32_e32 v4, v64, v7
	v_add_f32_e32 v5, v67, v4
	v_pk_mul_f32 v[2:3], v[4:5], s[0:1] op_sel_hi:[1,0]
	v_add_f32_e32 v4, v66, v5
	v_mul_f32_e32 v4, 0xc13504f3, v4
	global_store_dwordx3 v[0:1], v[2:4], off offset:1208

.LBB0_422:
	v_mul_f32_e32 v3, 0xc13504f3, v2
	global_store_dword v[0:1], v3, off offset:1028
	s_or_b64 exec, exec, s[2:3]
	v_add_f32_e32 v2, v11, v2
	s_and_saveexec_b64 s[2:3], vcc
	s_cbranch_execz .LBB0_372
.LBB0_423:
	v_mul_f32_e32 v3, 0xc13504f3, v2
	global_store_dword v[0:1], v3, off offset:1032
	s_or_b64 exec, exec, s[2:3]
	v_add_f32_e32 v2, v23, v2
	s_and_saveexec_b64 s[2:3], vcc
	s_cbranch_execz .LBB0_373
.LBB0_424:
	v_mul_f32_e32 v3, 0xc13504f3, v2
	global_store_dword v[0:1], v3, off offset:1036
	s_or_b64 exec, exec, s[2:3]
	v_add_f32_e32 v2, v20, v2
	s_and_saveexec_b64 s[2:3], vcc
	s_cbranch_execz .LBB0_374
.LBB0_425:
	v_mul_f32_e32 v3, 0xc13504f3, v2
	global_store_dword v[0:1], v3, off offset:1040
	s_or_b64 exec, exec, s[2:3]
	v_add_f32_e32 v2, v25, v2
	s_and_saveexec_b64 s[2:3], vcc
	s_cbranch_execz .LBB0_375
.LBB0_426:
	v_mul_f32_e32 v3, 0xc13504f3, v2
	global_store_dword v[0:1], v3, off offset:1044
	s_or_b64 exec, exec, s[2:3]
	v_add_f32_e32 v2, v24, v2
	s_and_saveexec_b64 s[2:3], vcc
	s_cbranch_execz .LBB0_376
.LBB0_427:
	v_mul_f32_e32 v3, 0xc13504f3, v2
	global_store_dword v[0:1], v3, off offset:1048
	s_or_b64 exec, exec, s[2:3]
	v_add_f32_e32 v2, v27, v2
	s_and_saveexec_b64 s[2:3], vcc
	s_cbranch_execz .LBB0_377
.LBB0_428:
	v_mul_f32_e32 v3, 0xc13504f3, v2
	global_store_dword v[0:1], v3, off offset:1052
	s_or_b64 exec, exec, s[2:3]
	v_add_f32_e32 v2, v26, v2
	s_and_saveexec_b64 s[2:3], vcc
	s_cbranch_execz .LBB0_378
.LBB0_429:
	v_mul_f32_e32 v3, 0xc13504f3, v2
	global_store_dword v[0:1], v3, off offset:1056
	s_or_b64 exec, exec, s[2:3]
	v_add_f32_e32 v2, v29, v2
	s_and_saveexec_b64 s[2:3], vcc
	s_cbranch_execz .LBB0_379
.LBB0_430:
	v_mul_f32_e32 v3, 0xc13504f3, v2
	global_store_dword v[0:1], v3, off offset:1060
	s_or_b64 exec, exec, s[2:3]
	v_add_f32_e32 v2, v28, v2
	s_and_saveexec_b64 s[2:3], vcc
	s_cbranch_execz .LBB0_380
.LBB0_431:
	v_mul_f32_e32 v3, 0xc13504f3, v2
	global_store_dword v[0:1], v3, off offset:1064
	s_or_b64 exec, exec, s[2:3]
	v_add_f32_e32 v2, v31, v2
	s_and_saveexec_b64 s[2:3], vcc
	s_cbranch_execz .LBB0_381
.LBB0_432:
	v_mul_f32_e32 v3, 0xc13504f3, v2
	global_store_dword v[0:1], v3, off offset:1068
	s_or_b64 exec, exec, s[2:3]
	v_add_f32_e32 v2, v30, v2
	s_and_saveexec_b64 s[2:3], vcc
	s_cbranch_execz .LBB0_382
.LBB0_433:
	v_mul_f32_e32 v3, 0xc13504f3, v2
	global_store_dword v[0:1], v3, off offset:1072
	s_or_b64 exec, exec, s[2:3]
	v_add_f32_e32 v2, v33, v2
	s_and_saveexec_b64 s[2:3], vcc
	s_cbranch_execz .LBB0_383
.LBB0_434:
	v_mul_f32_e32 v3, 0xc13504f3, v2
	global_store_dword v[0:1], v3, off offset:1076
	s_or_b64 exec, exec, s[2:3]
	v_add_f32_e32 v2, v32, v2
	s_and_saveexec_b64 s[2:3], vcc
	s_cbranch_execz .LBB0_384
.LBB0_435:
	v_mul_f32_e32 v3, 0xc13504f3, v2
	global_store_dword v[0:1], v3, off offset:1080
	s_or_b64 exec, exec, s[2:3]
	v_add_f32_e32 v2, v35, v2
	s_and_saveexec_b64 s[2:3], vcc
	s_cbranch_execz .LBB0_385
.LBB0_436:
	v_mul_f32_e32 v3, 0xc13504f3, v2
	global_store_dword v[0:1], v3, off offset:1084
	s_or_b64 exec, exec, s[2:3]
	v_add_f32_e32 v2, v34, v2
	s_and_saveexec_b64 s[2:3], vcc
	s_cbranch_execz .LBB0_386
.LBB0_437:
	v_mul_f32_e32 v3, 0xc13504f3, v2
	global_store_dword v[0:1], v3, off offset:1088
	s_or_b64 exec, exec, s[2:3]
	v_add_f32_e32 v2, v37, v2
	s_and_saveexec_b64 s[2:3], vcc
	s_cbranch_execz .LBB0_387
.LBB0_438:
	v_mul_f32_e32 v3, 0xc13504f3, v2
	global_store_dword v[0:1], v3, off offset:1092
	s_or_b64 exec, exec, s[2:3]
	v_add_f32_e32 v2, v36, v2
	s_and_saveexec_b64 s[2:3], vcc
	s_cbranch_execz .LBB0_388
.LBB0_439:
	v_mul_f32_e32 v3, 0xc13504f3, v2
	global_store_dword v[0:1], v3, off offset:1096
	s_or_b64 exec, exec, s[2:3]
	v_add_f32_e32 v2, v39, v2
	s_and_saveexec_b64 s[2:3], vcc
	s_cbranch_execz .LBB0_389
.LBB0_440:
	v_mul_f32_e32 v3, 0xc13504f3, v2
	global_store_dword v[0:1], v3, off offset:1100
	s_or_b64 exec, exec, s[2:3]
	v_add_f32_e32 v2, v38, v2
	s_and_saveexec_b64 s[2:3], vcc
	s_cbranch_execz .LBB0_390
.LBB0_441:
	v_mul_f32_e32 v3, 0xc13504f3, v2
	global_store_dword v[0:1], v3, off offset:1104
	s_or_b64 exec, exec, s[2:3]
	v_add_f32_e32 v2, v41, v2
	s_and_saveexec_b64 s[2:3], vcc
	s_cbranch_execz .LBB0_391
.LBB0_442:
	v_mul_f32_e32 v3, 0xc13504f3, v2
	global_store_dword v[0:1], v3, off offset:1108
	s_or_b64 exec, exec, s[2:3]
	v_add_f32_e32 v2, v40, v2
	s_and_saveexec_b64 s[2:3], vcc
	s_cbranch_execz .LBB0_392
.LBB0_443:
	v_mul_f32_e32 v3, 0xc13504f3, v2
	global_store_dword v[0:1], v3, off offset:1112
	s_or_b64 exec, exec, s[2:3]
	v_add_f32_e32 v2, v43, v2
	s_and_saveexec_b64 s[2:3], vcc
	s_cbranch_execz .LBB0_393
.LBB0_444:
	v_mul_f32_e32 v3, 0xc13504f3, v2
	global_store_dword v[0:1], v3, off offset:1116
	s_or_b64 exec, exec, s[2:3]
	v_add_f32_e32 v2, v42, v2
	s_and_saveexec_b64 s[2:3], vcc
	s_cbranch_execz .LBB0_394
.LBB0_445:
	v_mul_f32_e32 v3, 0xc13504f3, v2
	global_store_dword v[0:1], v3, off offset:1120
	s_or_b64 exec, exec, s[2:3]
	v_add_f32_e32 v2, v45, v2
	s_and_saveexec_b64 s[2:3], vcc
	s_cbranch_execz .LBB0_395
.LBB0_446:
	v_mul_f32_e32 v3, 0xc13504f3, v2
	global_store_dword v[0:1], v3, off offset:1124
	s_or_b64 exec, exec, s[2:3]
	v_add_f32_e32 v2, v44, v2
	s_and_saveexec_b64 s[2:3], vcc
	s_cbranch_execz .LBB0_396
.LBB0_447:
	v_mul_f32_e32 v3, 0xc13504f3, v2
	global_store_dword v[0:1], v3, off offset:1128
	s_or_b64 exec, exec, s[2:3]
	v_add_f32_e32 v2, v47, v2
	s_and_saveexec_b64 s[2:3], vcc
	s_cbranch_execz .LBB0_397
.LBB0_448:
	v_mul_f32_e32 v3, 0xc13504f3, v2
	global_store_dword v[0:1], v3, off offset:1132
	s_or_b64 exec, exec, s[2:3]
	v_add_f32_e32 v2, v46, v2
	s_and_saveexec_b64 s[2:3], vcc
	s_cbranch_execz .LBB0_398
.LBB0_449:
	v_mul_f32_e32 v3, 0xc13504f3, v2
	global_store_dword v[0:1], v3, off offset:1136
	s_or_b64 exec, exec, s[2:3]
	v_add_f32_e32 v2, v49, v2
	s_and_saveexec_b64 s[2:3], vcc
	s_cbranch_execz .LBB0_399
.LBB0_450:
	v_mul_f32_e32 v3, 0xc13504f3, v2
	global_store_dword v[0:1], v3, off offset:1140
	s_or_b64 exec, exec, s[2:3]
	v_add_f32_e32 v2, v48, v2
	s_and_saveexec_b64 s[2:3], vcc
	s_cbranch_execz .LBB0_400
.LBB0_451:
	v_mul_f32_e32 v3, 0xc13504f3, v2
	global_store_dword v[0:1], v3, off offset:1144
	s_or_b64 exec, exec, s[2:3]
	v_add_f32_e32 v2, v51, v2
	s_and_saveexec_b64 s[2:3], vcc
	s_cbranch_execz .LBB0_401
.LBB0_452:
	v_mul_f32_e32 v3, 0xc13504f3, v2
	global_store_dword v[0:1], v3, off offset:1148
	s_or_b64 exec, exec, s[2:3]
	v_add_f32_e32 v2, v50, v2
	s_and_saveexec_b64 s[2:3], vcc
	s_cbranch_execz .LBB0_402
.LBB0_453:
	v_mul_f32_e32 v3, 0xc13504f3, v2
	global_store_dword v[0:1], v3, off offset:1152
	s_or_b64 exec, exec, s[2:3]
	v_add_f32_e32 v2, v53, v2
	s_and_saveexec_b64 s[2:3], vcc
	s_cbranch_execz .LBB0_403
.LBB0_454:
	v_mul_f32_e32 v3, 0xc13504f3, v2
	global_store_dword v[0:1], v3, off offset:1156
	s_or_b64 exec, exec, s[2:3]
	v_add_f32_e32 v2, v52, v2
	s_and_saveexec_b64 s[2:3], vcc
	s_cbranch_execz .LBB0_404
.LBB0_455:
	v_mul_f32_e32 v3, 0xc13504f3, v2
	global_store_dword v[0:1], v3, off offset:1160
	s_or_b64 exec, exec, s[2:3]
	v_add_f32_e32 v2, v56, v2
	s_and_saveexec_b64 s[2:3], vcc
	s_cbranch_execz .LBB0_405
.LBB0_456:
	v_mul_f32_e32 v3, 0xc13504f3, v2
	global_store_dword v[0:1], v3, off offset:1164
	s_or_b64 exec, exec, s[2:3]
	v_add_f32_e32 v2, v54, v2
	s_and_saveexec_b64 s[2:3], vcc
	s_cbranch_execz .LBB0_406
.LBB0_457:
	v_mul_f32_e32 v3, 0xc13504f3, v2
	global_store_dword v[0:1], v3, off offset:1168
	s_or_b64 exec, exec, s[2:3]
	v_add_f32_e32 v2, v57, v2
	s_and_saveexec_b64 s[2:3], vcc
	s_cbranch_execz .LBB0_407
.LBB0_458:
	v_mul_f32_e32 v3, 0xc13504f3, v2
	global_store_dword v[0:1], v3, off offset:1172
	s_or_b64 exec, exec, s[2:3]
	s_and_saveexec_b64 s[2:3], vcc
	s_cbranch_execnz .LBB0_408
	s_branch .LBB0_409

.LBB0_492:
	v_mov_b32_e32 v0, v210
	s_movk_i32 s0, 0x80
	s_waitcnt lgkmcnt(0)
	s_load_dwordx2 s[2:3], s[74:75], 0x98
	s_waitcnt lgkmcnt(0)
	s_load_dwordx2 s[8:9], s[74:75], 0x68
	s_waitcnt lgkmcnt(0)
	s_load_dwordx2 s[6:7], s[74:75], 64
	s_waitcnt lgkmcnt(0)
	s_nop 0
	v_cmp_gt_i32_e32 vcc, s0, v0
	s_and_saveexec_b64 s[4:5], vcc
	s_cbranch_execz .LBB0_494
	s_lshl_b32 s94, s86, 7
	s_lshl_b64 s[0:1], s[94:95], 2
	s_add_u32 s0, s8, s0
	v_ashrrev_i32_e32 v1, 31, v0
	s_addc_u32 s1, s9, s1
	v_lshlrev_b64 v[2:3], 2, v[0:1]
	v_lshl_add_u64 v[4:5], s[0:1], 0, v[2:3]
	v_lshl_add_u64 v[2:3], s[6:7], 0, v[2:3]
	global_load_dword v1, v[4:5], off
	s_nop 0
	global_load_dword v2, v[2:3], off
	v_lshl_add_u32 v0, v0, 2, 0
	v_add_u32_e32 v0, 0x10a40, v0
	s_waitcnt vmcnt(0) lgkmcnt(0)
	v_mul_f32_e32 v1, v1, v2
	ds_write_b32 v0, v1

.LBB0_497:
	s_mov_b32 s0, 0x78787879
	v_mul_hi_i32 v2, v0, s0
	v_lshrrev_b32_e32 v3, 31, v2
	v_ashrrev_i32_e32 v2, 3, v2
	v_add_u32_e32 v2, v2, v3
	s_movk_i32 s0, 0xffef
	v_mad_u64_u32 v[4:5], s[0:1], v2, s0, v[0:1]
	v_mov_b32_e32 v6, 3
	v_cmp_lt_i32_e32 vcc, 0, v4
	s_and_saveexec_b64 s[8:9], vcc
	s_cbranch_execz .LBB0_496
	v_readlane_b32 s0, v255, 10
	v_readlane_b32 s1, v255, 11
	v_lshlrev_b32_e32 v5, 8, v4
	v_cmp_ne_u32_e32 vcc, 0, v4
	v_mov_b64_e32 v[6:7], s[0:1]
	s_movk_i32 s0, 0x4400
	v_mad_i64_i32 v[2:3], s[0:1], v2, s0, v[6:7]
	v_mov_b32_e32 v6, 0xf0
	v_cndmask_b32_e32 v6, v6, v5, vcc
	v_ashrrev_i32_e32 v7, 31, v6
	v_lshl_add_u64 v[6:7], v[6:7], 2, v[2:3]
	global_load_dword v5, v[6:7], off
	v_mov_b32_e32 v6, 3
	v_lshl_or_b32 v4, v4, 2, 3
	s_mov_b64 s[10:11], 0
	s_waitcnt vmcnt(0) lgkmcnt(0)
	v_sub_f32_e32 v5, v5, v1
.LBB0_499:
	v_add_u32_e32 v7, v4, v6
	v_lshrrev_b32_e32 v7, 1, v7
	v_lshlrev_b32_e32 v128, 6, v7
	v_lshl_add_u64 v[8:9], v[128:129], 2, v[2:3]
	global_load_dword v8, v[8:9], off offset:252
	v_add_u32_e32 v9, 1, v7
	s_waitcnt vmcnt(0) lgkmcnt(0)
	v_cmp_nge_f32_e32 vcc, v8, v5
	s_nop 1
	v_cndmask_b32_e32 v4, v7, v4, vcc
	v_cndmask_b32_e32 v6, v6, v9, vcc
	v_cmp_ge_i32_e32 vcc, v6, v4
	s_or_b64 s[10:11], vcc, s[10:11]
	s_andn2_b64 exec, exec, s[10:11]
	s_cbranch_execnz .LBB0_499
	s_or_b64 exec, exec, s[10:11]
	s_branch .LBB0_496

.LBB0_506:
	s_or_b64 exec, exec, s[4:5]
	s_add_u32 s72, s2, 0x2f0d0000
	v_readlane_b32 s0, v255, 1
	s_addc_u32 s85, s3, 0
	s_waitcnt lgkmcnt(0)
	v_mov_b32_e32 v0, s0
	s_ashr_i32 s0, s6, 31
	s_lshr_b32 s0, s0, 26
	s_add_i32 s0, s6, s0
	s_ashr_i32 s4, s0, 6
	s_and_b32 s0, s6, 63
	s_mul_i32 s7, s0, 0x44
	s_sub_i32 s1, 16, s4
	s_add_i32 s7, s7, 0
	s_lshl_b32 s4, s4, 2
	s_sub_i32 s4, s7, s4
	s_add_i32 s4, s4, 0x10e40
	s_barrier
	ds_read_b32 v35, v0
	v_mov_b32_e32 v0, s4
	s_waitcnt lgkmcnt(0)
	s_barrier
	ds_read_b32 v0, v0
	s_bfe_u32 s5, s6, 0x20004
	s_lshl_b32 s4, s6, 7
	s_mul_i32 s5, s5, 0x808000
	s_and_b32 s4, s4, 0x780
	s_or_b32 s4, s5, s4
	v_mov_b32_e32 v32, v210
	s_add_i32 s76, s4, 0xfff88000
	s_waitcnt lgkmcnt(0)
	v_readfirstlane_b32 s68, v0
	v_lshrrev_b32_e32 v1, 2, v32
	v_lshlrev_b32_e32 v0, 11, v32
	v_and_b32_e32 v1, 8, v1
	s_mov_b32 s4, 0xf800
	s_ashr_i32 s77, s76, 31
	v_and_or_b32 v0, v0, s4, v1
	s_lshl_b64 s[4:5], s[76:77], 1
	v_readfirstlane_b32 s6, v32
	s_add_u32 s7, s72, s4
	s_addc_u32 s8, s85, s5
	s_lshl_b32 s4, s6, 10
	s_and_b32 s4, s4, 0xffff0000
	s_lshl_b32 s5, s1, 19
	s_add_i32 s94, s4, s5
	s_lshl_b64 s[4:5], s[94:95], 1
	s_add_u32 s4, s7, s4
	s_addc_u32 s5, s8, s5
	v_lshlrev_b32_e32 v128, 1, v0
	v_lshl_add_u64 v[0:1], s[4:5], 0, v[128:129]
	s_mov_b64 s[4:5], 0x8400000
	v_lshl_add_u64 v[2:3], v[0:1], 0, s[4:5]
	s_mov_b32 s4, 0x8400000
	s_lshl_b32 s94, s68, 17
	v_lshlrev_b32_e32 v34, 3, v32
	v_add_co_u32_e32 v0, vcc, s4, v0
	s_lshl_b64 s[4:5], s[94:95], 1
	v_ashrrev_i32_e32 v33, 4, v32
	v_and_b32_e32 v34, 0x78, v34
	s_add_u32 s4, s7, s4
	v_addc_co_u32_e32 v1, vcc, 0, v1, vcc
	v_lshl_or_b32 v128, v33, 11, v34
	s_addc_u32 s5, s8, s5
	global_load_dwordx4 v[24:27], v[2:3], off offset:32
	global_load_dwordx4 v[20:23], v[2:3], off offset:64
	global_load_dwordx4 v[16:19], v[2:3], off offset:96
	global_load_dwordx4 v[12:15], v[2:3], off offset:128
	global_load_dwordx4 v[8:11], v[2:3], off offset:160
	global_load_dwordx4 v[4:7], v[2:3], off offset:192
	global_load_dwordx4 v[28:31], v[0:1], off
	s_nop 0
	global_load_dwordx4 v[0:3], v[2:3], off offset:224
	v_lshl_add_u64 v[36:37], v[128:129], 1, s[4:5]
	v_add_co_u32_e32 v38, vcc, 0x4200000, v36
	s_cmp_lt_u32 s6, 64
	s_nop 0
	v_addc_co_u32_e32 v39, vcc, 0, v37, vcc
	v_add_co_u32_e32 v40, vcc, 0x4220000, v36
	global_load_dwordx4 v[130:133], v[38:39], off
	global_load_dwordx4 v[134:137], v[36:37], off
	v_addc_co_u32_e32 v41, vcc, 0, v37, vcc
	v_add_co_u32_e32 v36, vcc, 0x20000, v36
	v_readfirstlane_b32 s93, v35
	s_nop 0
	v_addc_co_u32_e32 v37, vcc, 0, v37, vcc
	global_load_dwordx4 v[138:141], v[40:41], off
	global_load_dwordx4 v[142:145], v[36:37], off
	v_and_b32_e32 v35, 63, v32
	s_cselect_b64 s[4:5], -1, 0
	s_cmp_gt_u32 s6, 63
	v_mov_b32_e32 v219, 0
	s_cbranch_scc1 .LBB0_508
	s_mul_i32 s6, s0, 0x4400
	v_readlane_b32 s8, v255, 10
	v_readlane_b32 s9, v255, 11
	s_add_u32 s8, s8, s6
	s_addc_u32 s9, s9, 0
	s_lshl_b32 s94, s68, 6
	s_lshl_b64 s[6:7], s[94:95], 2
	s_add_u32 s6, s8, s6
	s_addc_u32 s7, s9, s7
	v_lshlrev_b32_e32 v128, 2, v35
	v_lshl_add_u64 v[36:37], s[6:7], 0, v[128:129]
	global_load_dword v219, v[36:37], off

.LBB0_518:
	v_mov_b32_e32 v220, v210
	s_lshr_b32 s1, s89, 6
	v_ashrrev_i32_e32 v32, 4, v220
	v_and_b32_e32 v2, 0xfffff0, v32
	v_lshlrev_b32_e32 v3, 1, v32
	v_lshlrev_b32_e32 v0, 3, v220
	v_and_or_b32 v2, v3, 8, v2
	v_and_b32_e32 v1, 0x78, v0
	v_lshrrev_b32_e32 v2, 1, v2
	v_bfe_u32 v0, v0, 5, 2
	v_lshrrev_b32_e32 v3, 1, v32
	v_or_b32_e32 v0, v2, v0
	v_and_b32_e32 v2, 3, v32
	v_lshlrev_b32_e32 v34, 1, v1
	v_and_or_b32 v2, v3, 4, v2
	v_and_b32_e32 v3, 48, v34
	s_or_b32 s97, s1, 3
	v_lshl_or_b32 v2, v2, 6, v3
	s_sub_i32 s74, s97, s68
	v_lshl_or_b32 v0, v0, 9, v2
	v_readfirstlane_b32 s92, v220
	v_and_b32_e32 v221, 63, v220
	s_add_i32 s81, s74, 1
	v_lshl_or_b32 v128, v32, 11, v1
	v_add_u32_e32 v234, 0, v0
	ds_write_b128 v234, v[130:133]
	ds_write_b128 v234, v[138:141] offset:8192
	s_cmp_gt_i32 s81, 1
	s_cselect_b64 s[66:67], -1, 0
	s_cmp_lt_i32 s81, 2
	s_cbranch_scc1 .LBB0_521
	s_ashr_i32 s77, s76, 31
	s_lshl_b64 s[4:5], s[76:77], 1
	s_add_u32 s1, s72, s4
	s_addc_u32 s6, s85, s5
	s_lshl_b32 s4, s68, 17
	s_add_i32 s94, s4, 0x20000
	s_lshl_b64 s[4:5], s[94:95], 1
	s_add_u32 s4, s1, s4
	s_addc_u32 s5, s6, s5
	v_lshl_add_u64 v[0:1], v[128:129], 1, s[4:5]
	v_add_co_u32_e32 v2, vcc, 0x4200000, v0
	s_cmp_gt_u32 s92, 63
	s_nop 0
	v_addc_co_u32_e32 v3, vcc, 0, v1, vcc
	v_add_co_u32_e32 v4, vcc, 0x4220000, v0
	global_load_dwordx4 v[130:133], v[2:3], off
	global_load_dwordx4 v[134:137], v[0:1], off
	v_addc_co_u32_e32 v5, vcc, 0, v1, vcc
	v_add_co_u32_e32 v0, vcc, 0x20000, v0
	s_nop 1
	v_addc_co_u32_e32 v1, vcc, 0, v1, vcc
	global_load_dwordx4 v[138:141], v[4:5], off
	global_load_dwordx4 v[142:145], v[0:1], off
	s_cbranch_scc1 .LBB0_521
	s_mul_i32 s94, s0, 0x1100
	s_lshl_b64 s[4:5], s[94:95], 2
	v_readlane_b32 s6, v255, 10
	v_readlane_b32 s7, v255, 11
	s_add_u32 s1, s6, s4
	s_addc_u32 s6, s7, s5
	s_lshl_b32 s4, s68, 6
	s_add_i32 s94, s4, 64
	s_lshl_b64 s[4:5], s[94:95], 2
	s_add_u32 s4, s1, s4
	s_addc_u32 s5, s6, s5
	v_lshlrev_b32_e32 v0, 2, v221
	v_mov_b32_e32 v1, v129
	v_lshl_add_u64 v[0:1], s[4:5], 0, v[0:1]
	global_load_dword v219, v[0:1], off

.LBB0_526:
	s_cmp_eq_u32 s81, 2
	s_cbranch_scc1 .LBB0_529
	s_ashr_i32 s77, s76, 31
	s_lshl_b64 s[8:9], s[76:77], 1
	s_add_u32 s10, s72, s8
	s_addc_u32 s11, s85, s9
	s_lshl_b32 s8, s68, 17
	s_add_i32 s94, s8, 0x40000
	s_lshl_b64 s[8:9], s[94:95], 1
	s_add_u32 s8, s10, s8
	s_addc_u32 s9, s11, s9
	v_lshl_add_u64 v[34:35], v[128:129], 1, s[8:9]
	v_add_co_u32_e32 v36, vcc, 0x4200000, v34
	s_nop 1
	v_addc_co_u32_e32 v37, vcc, 0, v35, vcc
	v_add_co_u32_e32 v38, vcc, 0x4220000, v34
	global_load_dwordx4 v[130:133], v[36:37], off
	global_load_dwordx4 v[134:137], v[34:35], off
	v_addc_co_u32_e32 v39, vcc, 0, v35, vcc
	v_add_co_u32_e32 v34, vcc, 0x20000, v34
	s_nop 1
	v_addc_co_u32_e32 v35, vcc, 0, v35, vcc
	global_load_dwordx4 v[138:141], v[38:39], off
	global_load_dwordx4 v[142:145], v[34:35], off
	s_andn2_b64 vcc, exec, s[6:7]
	s_cbranch_vccnz .LBB0_529
	s_mul_i32 s94, s0, 0x1100
	s_lshl_b64 s[6:7], s[94:95], 2
	v_readlane_b32 s8, v255, 10
	v_readlane_b32 s9, v255, 11
	s_add_u32 s8, s8, s6
	s_addc_u32 s9, s9, s7
	s_add_i32 s94, s69, 0x80
	s_lshl_b64 s[6:7], s[94:95], 2
	s_add_u32 s6, s8, s6
	s_addc_u32 s7, s9, s7
	v_lshlrev_b32_e32 v34, 2, v221
	v_mov_b32_e32 v35, v129
	v_lshl_add_u64 v[34:35], s[6:7], 0, v[34:35]
	global_load_dword v219, v[34:35], off

.LBB0_535:
	s_add_i32 s10, s0, -1
	s_cmp_lt_i32 s10, s81
	s_cselect_b64 s[72:73], -1, 0
	s_cmp_ge_i32 s10, s81
	s_cbranch_scc1 .LBB0_538
	s_add_i32 s94, s70, 0xfffe0000
	s_lshl_b64 s[10:11], s[94:95], 1
	s_add_u32 s10, s77, s10
	s_addc_u32 s11, s96, s11
	v_lshl_add_u64 v[66:67], v[128:129], 1, s[10:11]
	v_add_co_u32_e32 v100, vcc, 0x4200000, v66
	s_nop 1
	v_addc_co_u32_e32 v101, vcc, 0, v67, vcc
	v_add_co_u32_e32 v102, vcc, 0x4220000, v66
	global_load_dwordx4 v[130:133], v[100:101], off
	global_load_dwordx4 v[134:137], v[66:67], off
	v_addc_co_u32_e32 v103, vcc, 0, v67, vcc
	v_add_co_u32_e32 v66, vcc, 0x20000, v66
	s_nop 1
	v_addc_co_u32_e32 v67, vcc, 0, v67, vcc
	global_load_dwordx4 v[138:141], v[102:103], off
	global_load_dwordx4 v[142:145], v[66:67], off
	s_and_b64 vcc, exec, s[6:7]
	s_cbranch_vccnz .LBB0_538
	s_add_i32 s94, s85, 1
	v_lshl_add_u64 v[66:67], s[94:95], 2, v[196:197]
	global_load_dword v219, v[66:67], off

.LBB0_547:
	s_cmp_ge_i32 s0, s81
	s_cbranch_scc1 .LBB0_550
	s_mov_b32 s71, s95
	s_lshl_b64 s[10:11], s[70:71], 1
	s_add_u32 s10, s77, s10
	s_addc_u32 s11, s96, s11
	v_lshl_add_u64 v[138:139], v[128:129], 1, s[10:11]
	v_add_co_u32_e32 v130, vcc, 0x4200000, v138
	s_nop 1
	v_addc_co_u32_e32 v131, vcc, 0, v139, vcc
	v_add_co_u32_e32 v140, vcc, 0x4220000, v138
	global_load_dwordx4 v[130:133], v[130:131], off
	s_nop 0
	global_load_dwordx4 v[134:137], v[138:139], off
	v_addc_co_u32_e32 v141, vcc, 0, v139, vcc
	v_add_co_u32_e32 v142, vcc, 0x20000, v138
	s_nop 1
	v_addc_co_u32_e32 v143, vcc, 0, v139, vcc
	global_load_dwordx4 v[138:141], v[140:141], off
	s_nop 0
	global_load_dwordx4 v[142:145], v[142:143], off
	s_and_b64 vcc, exec, s[6:7]
	s_cbranch_vccnz .LBB0_550
	s_add_i32 s94, s85, 0x41
	v_lshl_add_u64 v[180:181], s[94:95], 2, v[196:197]
	global_load_dword v219, v[180:181], off

.LBB0_559:
	s_ashr_i32 s81, s80, 31
	s_lshl_b64 s[6:7], s[80:81], 1
	s_add_u32 s0, s72, s6
	s_addc_u32 s6, s85, s7
	s_lshl_b32 s94, s84, 17
	s_lshl_b64 s[8:9], s[94:95], 1
	s_add_u32 s8, s0, s8
	s_addc_u32 s9, s6, s9
	v_lshl_add_u64 v[96:97], v[128:129], 1, s[8:9]
	v_add_co_u32_e32 v98, vcc, 0x4200000, v96
	s_cmp_lt_u32 s92, 64
	s_nop 0
	v_addc_co_u32_e32 v99, vcc, 0, v97, vcc
	v_add_co_u32_e32 v100, vcc, 0x4220000, v96
	s_waitcnt vmcnt(0)
	global_load_dwordx4 v[130:133], v[98:99], off
	global_load_dwordx4 v[134:137], v[96:97], off
	v_addc_co_u32_e32 v101, vcc, 0, v97, vcc
	v_add_co_u32_e32 v96, vcc, 0x20000, v96
	s_cselect_b64 s[66:67], -1, 0
	s_nop 0
	v_addc_co_u32_e32 v97, vcc, 0, v97, vcc
	global_load_dwordx4 v[138:141], v[100:101], off
	global_load_dwordx4 v[142:145], v[96:97], off
	s_cmp_gt_u32 s92, 63
	s_cbranch_scc1 .LBB0_561
	s_mul_i32 s94, s91, 0x1100
	s_lshl_b64 s[8:9], s[94:95], 2
	v_readlane_b32 s10, v255, 10
	v_readlane_b32 s11, v255, 11
	s_add_u32 s7, s10, s8
	s_addc_u32 s10, s11, s9
	s_lshl_b32 s94, s84, 6
	s_lshl_b64 s[8:9], s[94:95], 2
	s_add_u32 s8, s7, s8
	s_addc_u32 s9, s10, s9
	v_mov_b32_e32 v195, v129
	v_lshl_add_u64 v[96:97], s[8:9], 0, v[194:195]
	global_load_dword v219, v[96:97], off
.LBB0_561:
	s_add_i32 s33, s33, s83
	s_lshl_b32 s94, s33, 11
	s_lshl_b64 s[8:9], s[94:95], 1
	s_add_u32 s8, s0, s8
	v_lshlrev_b32_e32 v96, 12, v222
	s_addc_u32 s9, s6, s9
	v_lshl_or_b32 v128, v223, 4, v96
	v_lshl_add_u64 v[96:97], s[8:9], 0, v[128:129]
	s_mov_b64 s[6:7], 0x8400000
	s_mov_b32 s0, 0x8400000
	v_lshl_add_u64 v[98:99], v[96:97], 0, s[6:7]
	v_add_co_u32_e32 v96, vcc, s0, v96
	s_nop 1
	v_addc_co_u32_e32 v97, vcc, 0, v97, vcc
	global_load_dwordx4 v[120:123], v[98:99], off offset:32
	global_load_dwordx4 v[116:119], v[98:99], off offset:64
	global_load_dwordx4 v[112:115], v[98:99], off offset:96
	global_load_dwordx4 v[108:111], v[98:99], off offset:128
	global_load_dwordx4 v[104:107], v[98:99], off offset:160
	global_load_dwordx4 v[100:103], v[98:99], off offset:192
	global_load_dwordx4 v[124:127], v[96:97], off
	s_nop 0
	global_load_dwordx4 v[96:99], v[98:99], off offset:224
	v_add_f32_e32 v128, 0, v215
	v_add_f32_e32 v128, v188, v128
	v_add_f32_e32 v128, v253, v128
	v_add_f32_e32 v128, v212, v128
	v_add_f32_e32 v128, v252, v128
	v_add_f32_e32 v128, v254, v128
	v_add_f32_e32 v128, v250, v128
	v_add_f32_e32 v128, v251, v128
	v_add_f32_e32 v128, v247, v128
	v_add_f32_e32 v128, v249, v128
	v_add_f32_e32 v128, v246, v128
	v_add_f32_e32 v128, v248, v128
	v_exp_f32_e32 v154, v208
	v_add_f32_e32 v128, v243, v128
	v_exp_f32_e32 v155, v209
	v_add_f32_e32 v128, v245, v128
	v_exp_f32_e32 v156, v206
	v_add_f32_e32 v128, v242, v128
	v_exp_f32_e32 v157, v207
	v_add_f32_e32 v128, v244, v128
	v_exp_f32_e32 v158, v204
	v_add_f32_e32 v128, v154, v128
	v_exp_f32_e32 v159, v205
	v_add_f32_e32 v128, v155, v128
	v_exp_f32_e32 v160, v202
	v_add_f32_e32 v128, v156, v128
	v_exp_f32_e32 v161, v203
	v_add_f32_e32 v128, v157, v128
	v_exp_f32_e32 v162, v200
	v_add_f32_e32 v128, v158, v128
	v_exp_f32_e32 v163, v201
	v_add_f32_e32 v128, v159, v128
	v_exp_f32_e32 v164, v198
	v_add_f32_e32 v128, v160, v128
	v_exp_f32_e32 v165, v199
	v_add_f32_e32 v128, v161, v128
	v_exp_f32_e32 v166, v180
	v_add_f32_e32 v128, v162, v128
	v_exp_f32_e32 v167, v181
	v_add_f32_e32 v128, v163, v128
	v_exp_f32_e32 v168, v178
	v_add_f32_e32 v128, v164, v128
	v_exp_f32_e32 v169, v179
	v_add_f32_e32 v128, v165, v128
	v_add_f32_e32 v128, v166, v128
	v_add_f32_e32 v128, v167, v128
	v_add_f32_e32 v128, v168, v128
	v_add_f32_e32 v128, v169, v128
	v_mov_b32_e32 v146, v128
	s_nop 1
	v_permlane32_swap_b32_e32 v128, v146
	v_add_f32_e32 v128, v128, v146
	v_fmac_f32_e32 v128, v237, v236
	v_cvt_pk_bf16_f32 v146, v215, v188
	v_cvt_pk_bf16_f32 v147, v253, v212
	v_cvt_pk_bf16_f32 v148, v252, v254
	v_cvt_pk_bf16_f32 v149, v250, v251
	v_cvt_pk_bf16_f32 v150, v247, v249
	v_cvt_pk_bf16_f32 v151, v246, v248
	v_cvt_pk_bf16_f32 v152, v243, v245
	v_cvt_pk_bf16_f32 v153, v242, v244
	v_cvt_pk_bf16_f32 v154, v154, v155
	v_cvt_pk_bf16_f32 v155, v156, v157
	v_cvt_pk_bf16_f32 v156, v158, v159
	v_cvt_pk_bf16_f32 v157, v160, v161
	v_cvt_pk_bf16_f32 v158, v162, v163
	v_cvt_pk_bf16_f32 v159, v164, v165
	v_cvt_pk_bf16_f32 v160, v166, v167
	v_cvt_pk_bf16_f32 v161, v168, v169
	s_nop 0
	v_permlane32_swap_b32_e32 v146, v148
	v_permlane32_swap_b32_e32 v147, v149
	v_permlane32_swap_b32_e32 v150, v152
	v_permlane32_swap_b32_e32 v151, v153
	v_permlane32_swap_b32_e32 v154, v156
	v_permlane32_swap_b32_e32 v155, v157
	v_permlane32_swap_b32_e32 v158, v160
	v_permlane32_swap_b32_e32 v159, v161
	ds_read_b64_tr_b16 v[162:163], v228 offset:0
	ds_read_b64_tr_b16 v[164:165], v228 offset:0x800
	ds_read_b64_tr_b16 v[166:167], v228 offset:0x1000
	ds_read_b64_tr_b16 v[168:169], v228 offset:0x1800
	ds_read_b64_tr_b16 v[170:171], v228 offset:0x2000
	ds_read_b64_tr_b16 v[172:173], v228 offset:0x2800
	ds_read_b64_tr_b16 v[174:175], v228 offset:0x3000
	ds_read_b64_tr_b16 v[176:177], v228 offset:0x3800
	s_waitcnt lgkmcnt(0)
	s_nop 0
	v_mfma_f32_32x32x16_bf16 v[48:63], v[146:149], v[162:165], v[48:63]
	ds_read_b64_tr_b16 v[162:163], v228 offset:0x200
	ds_read_b64_tr_b16 v[164:165], v228 offset:0xa00
	v_mfma_f32_32x32x16_bf16 v[48:63], v[150:153], v[166:169], v[48:63]
	ds_read_b64_tr_b16 v[166:167], v228 offset:0x1200
	ds_read_b64_tr_b16 v[168:169], v228 offset:0x1a00
	v_mfma_f32_32x32x16_bf16 v[48:63], v[154:157], v[170:173], v[48:63]
	ds_read_b64_tr_b16 v[170:171], v228 offset:0x2200
	ds_read_b64_tr_b16 v[172:173], v228 offset:0x2a00
	ds_read_b64_tr_b16 v[178:179], v228 offset:0x3200
	ds_read_b64_tr_b16 v[180:181], v228 offset:0x3a00
	s_waitcnt lgkmcnt(0)
	v_mfma_f32_32x32x16_bf16 v[48:63], v[158:161], v[174:177], v[48:63]
	v_mfma_f32_32x32x16_bf16 v[32:47], v[146:149], v[162:165], v[32:47]
	ds_read_b64_tr_b16 v[162:163], v228 offset:0x400
	ds_read_b64_tr_b16 v[164:165], v228 offset:0xc00
	v_mfma_f32_32x32x16_bf16 v[32:47], v[150:153], v[166:169], v[32:47]
	ds_read_b64_tr_b16 v[166:167], v228 offset:0x1400
	ds_read_b64_tr_b16 v[168:169], v228 offset:0x1c00
	v_mfma_f32_32x32x16_bf16 v[32:47], v[154:157], v[170:173], v[32:47]
	ds_read_b64_tr_b16 v[170:171], v228 offset:0x2400
	ds_read_b64_tr_b16 v[172:173], v228 offset:0x2c00
	ds_read_b64_tr_b16 v[174:175], v228 offset:0x3400
	ds_read_b64_tr_b16 v[176:177], v228 offset:0x3c00
	s_waitcnt lgkmcnt(0)
	v_mfma_f32_32x32x16_bf16 v[32:47], v[158:161], v[178:181], v[32:47]
	v_mfma_f32_32x32x16_bf16 v[16:31], v[146:149], v[162:165], v[16:31]
	ds_read_b64_tr_b16 v[162:163], v228 offset:0x600
	ds_read_b64_tr_b16 v[164:165], v228 offset:0xe00
	v_mfma_f32_32x32x16_bf16 v[16:31], v[150:153], v[166:169], v[16:31]
	ds_read_b64_tr_b16 v[166:167], v228 offset:0x1600
	ds_read_b64_tr_b16 v[168:169], v228 offset:0x1e00
	v_mfma_f32_32x32x16_bf16 v[16:31], v[154:157], v[170:173], v[16:31]
	ds_read_b64_tr_b16 v[170:171], v228 offset:0x2600
	ds_read_b64_tr_b16 v[172:173], v228 offset:0x2e00
	ds_read_b64_tr_b16 v[178:179], v228 offset:0x3600
	ds_read_b64_tr_b16 v[180:181], v228 offset:0x3e00
	s_waitcnt lgkmcnt(0)
	v_mfma_f32_32x32x16_bf16 v[16:31], v[158:161], v[174:177], v[16:31]
	v_mfma_f32_32x32x16_bf16 v[0:15], v[146:149], v[162:165], v[0:15]
	s_andn2_b64 vcc, exec, s[4:5]
	v_mfma_f32_32x32x16_bf16 v[0:15], v[150:153], v[166:169], v[0:15]
	v_mfma_f32_32x32x16_bf16 v[0:15], v[154:157], v[170:173], v[0:15]
	v_mfma_f32_32x32x16_bf16 v[0:15], v[158:161], v[178:181], v[0:15]
	s_cbranch_vccnz .LBB0_569
	s_lshl_b32 s0, s97, 6
	s_or_b32 s4, s0, 63
	s_cmp_le_i32 s4, s1
	v_mov_b64_e32 v[242:243], 0x1ff
	v_mov_b64_e32 v[236:237], 0x5ff
	v_mov_b64_e32 v[244:245], v[186:187]
	s_cbranch_scc1 .LBB0_564
	v_subrev_u32_e32 v146, s0, v227
	v_cmp_gt_i32_e64 s[62:63], 26, v146
	v_cmp_gt_i32_e64 s[64:65], 27, v146
	v_cmp_gt_i32_e64 s[60:61], 25, v146
	s_and_b64 s[62:63], s[64:65], s[62:63]
	v_cmp_gt_i32_e64 s[58:59], 24, v146
	s_and_b64 s[60:61], s[62:63], s[60:61]
	v_cmp_gt_i32_e64 s[56:57], 19, v146
	s_and_b64 s[58:59], s[60:61], s[58:59]
	v_cmp_gt_i32_e64 s[54:55], 18, v146
	s_and_b64 s[56:57], s[58:59], s[56:57]
	v_cmp_gt_i32_e64 s[52:53], 17, v146
	s_and_b64 s[54:55], s[56:57], s[54:55]
	v_cmp_gt_i32_e64 s[50:51], 16, v146
	s_and_b64 s[52:53], s[54:55], s[52:53]
	v_cmp_gt_i32_e64 s[48:49], 11, v146
	s_and_b64 s[50:51], s[52:53], s[50:51]
	v_cmp_gt_i32_e64 s[46:47], 10, v146
	s_and_b64 s[48:49], s[50:51], s[48:49]
	v_cmp_gt_i32_e64 s[44:45], 9, v146
	s_and_b64 s[46:47], s[48:49], s[46:47]
	v_cmp_gt_i32_e64 s[42:43], 8, v146
	s_and_b64 s[44:45], s[46:47], s[44:45]
	v_cmp_gt_i32_e64 s[40:41], 3, v146
	s_and_b64 s[42:43], s[44:45], s[42:43]
	v_cmp_gt_i32_e64 s[38:39], 2, v146
	s_and_b64 s[40:41], s[42:43], s[40:41]
	v_cmp_gt_i32_e64 s[36:37], 1, v146
	s_and_b64 s[38:39], s[40:41], s[38:39]
	v_cmp_gt_i32_e64 s[34:35], 0, v146
	s_and_b64 s[36:37], s[38:39], s[36:37]
	s_and_b64 s[34:35], s[36:37], s[34:35]
	v_cmp_gt_i32_e64 s[30:31], 58, v146
	v_cndmask_b32_e64 v64, v64, v213, s[34:35]
	v_cmp_gt_i32_e64 s[34:35], 59, v146
	v_cmp_gt_i32_e64 s[28:29], 57, v146
	s_and_b64 s[30:31], s[34:35], s[30:31]
	v_cmp_gt_i32_e64 s[26:27], 56, v146
	s_and_b64 s[28:29], s[30:31], s[28:29]
	v_cmp_gt_i32_e64 s[24:25], 51, v146
	s_and_b64 s[26:27], s[28:29], s[26:27]
	v_cmp_gt_i32_e64 s[22:23], 50, v146
	s_and_b64 s[24:25], s[26:27], s[24:25]
	v_cmp_gt_i32_e64 s[20:21], 49, v146
	s_and_b64 s[22:23], s[24:25], s[22:23]
	v_cmp_gt_i32_e64 s[18:19], 48, v146
	s_and_b64 s[20:21], s[22:23], s[20:21]
	v_cmp_gt_i32_e64 s[16:17], 43, v146
	s_and_b64 s[18:19], s[20:21], s[18:19]
	v_cmp_gt_i32_e64 s[14:15], 42, v146
	s_and_b64 s[16:17], s[18:19], s[16:17]
	v_cmp_gt_i32_e64 s[12:13], 41, v146
	s_and_b64 s[14:15], s[16:17], s[14:15]
	v_cmp_gt_i32_e64 s[10:11], 40, v146
	s_and_b64 s[12:13], s[14:15], s[12:13]
	v_cmp_gt_i32_e64 s[8:9], 35, v146
	s_and_b64 s[10:11], s[12:13], s[10:11]
	v_cmp_gt_i32_e64 s[6:7], 34, v146
	s_and_b64 s[8:9], s[10:11], s[8:9]
	v_cmp_gt_i32_e64 s[4:5], 33, v146
	s_and_b64 s[6:7], s[8:9], s[6:7]
	v_cmp_gt_i32_e32 vcc, 32, v146
	s_and_b64 s[4:5], s[6:7], s[4:5]
	s_and_b64 vcc, s[4:5], vcc
	v_cndmask_b32_e64 v79, v79, v213, s[64:65]
	v_cndmask_b32_e64 v78, v78, v213, s[62:63]
	s_mov_b32 s62, s86
	v_cndmask_b32_e64 v77, v77, v213, s[60:61]
	v_cndmask_b32_e64 v76, v76, v213, s[58:59]
	v_cndmask_b32_e64 v75, v75, v213, s[56:57]
	v_cndmask_b32_e64 v74, v74, v213, s[54:55]
	v_cndmask_b32_e64 v73, v73, v213, s[52:53]
	v_cndmask_b32_e64 v72, v72, v213, s[50:51]
	v_cndmask_b32_e64 v71, v71, v213, s[48:49]
	v_cndmask_b32_e64 v70, v70, v213, s[46:47]
	v_cndmask_b32_e64 v69, v69, v213, s[44:45]
	v_cndmask_b32_e64 v68, v68, v213, s[42:43]
	v_cndmask_b32_e64 v67, v67, v213, s[40:41]
	v_cndmask_b32_e64 v66, v66, v213, s[38:39]
	v_cndmask_b32_e64 v65, v65, v213, s[36:37]
	v_cndmask_b32_e64 v95, v95, v213, s[34:35]
	v_cndmask_b32_e64 v94, v94, v213, s[30:31]
	v_cndmask_b32_e64 v93, v93, v213, s[28:29]
	v_cndmask_b32_e64 v92, v92, v213, s[26:27]
	v_cndmask_b32_e64 v91, v91, v213, s[24:25]
	v_cndmask_b32_e64 v90, v90, v213, s[22:23]
	v_cndmask_b32_e64 v89, v89, v213, s[20:21]
	v_cndmask_b32_e64 v88, v88, v213, s[18:19]
	v_cndmask_b32_e64 v87, v87, v213, s[16:17]
	v_cndmask_b32_e64 v86, v86, v213, s[14:15]
	v_cndmask_b32_e64 v85, v85, v213, s[12:13]
	v_cndmask_b32_e64 v84, v84, v213, s[10:11]
	v_cndmask_b32_e64 v83, v83, v213, s[8:9]
	v_cndmask_b32_e64 v82, v82, v213, s[6:7]
	v_cndmask_b32_e64 v81, v81, v213, s[4:5]
	v_cndmask_b32_e32 v80, v80, v213, vcc

.LBB0_572:
	v_cmp_gt_u32_e32 vcc, 32, v221
	s_and_saveexec_b64 s[4:5], vcc
	ds_write_b32 v226, v128
	s_or_b64 exec, exec, s[4:5]
	s_ashr_i32 s77, s76, 31
	s_lshl_b64 s[4:5], s[76:77], 1
	s_add_u32 s4, s73, s4
	s_waitcnt lgkmcnt(0)
	s_addc_u32 s5, s82, s5
	s_lshl_b32 s94, s1, 11
	ds_read_b128 v[68:71], v225 offset:64
	ds_read_b128 v[64:67], v225 offset:96
	s_lshl_b64 s[0:1], s[94:95], 1
	s_add_u32 s6, s4, s0
	s_addc_u32 s7, s5, s1
	v_lshl_or_b32 v72, v223, 13, v222
	s_cmp_gt_i32 s89, 0
	v_and_b32_e32 v82, 1, v220
	s_cselect_b64 s[8:9], -1, 0
	s_cmp_lt_i32 s89, 1
	v_lshlrev_b32_e32 v128, 1, v72
	v_cmp_eq_u32_e64 s[4:5], 0, v82
	s_cbranch_scc1 .LBB0_640
	ds_read2_b32 v[78:79], v225 offset1:3
	ds_read2_b32 v[80:81], v225 offset0:1 offset1:2
	ds_read_b128 v[72:75], v225 offset:32
	v_lshl_add_u64 v[76:77], s[6:7], 0, v[128:129]
	s_waitcnt lgkmcnt(2)
	v_rcp_f32_e32 v78, v78
	s_nop 0
	v_mul_f32_e32 v48, v48, v78
	ds_bpermute_b32 v83, v218, v48
	s_and_saveexec_b64 s[10:11], s[4:5]
	s_cbranch_execz .LBB0_577
	s_waitcnt lgkmcnt(0)
	v_cvt_pk_bf16_f32 v48, v48, v83
	global_store_dword v[76:77], v48, off
.LBB0_577:
	s_or_b64 exec, exec, s[10:11]
	v_mul_f32_e32 v32, v32, v78
	ds_bpermute_b32 v48, v218, v32
	s_and_saveexec_b64 s[10:11], s[4:5]
	s_cbranch_execz .LBB0_579
	s_waitcnt lgkmcnt(0)
	v_cvt_pk_bf16_f32 v32, v32, v48
	global_store_dword v[76:77], v32, off offset:64
.LBB0_579:
	s_or_b64 exec, exec, s[10:11]
	v_mul_f32_e32 v16, v16, v78
	ds_bpermute_b32 v32, v218, v16
	s_and_saveexec_b64 s[10:11], s[4:5]
	s_cbranch_execz .LBB0_581
	s_waitcnt lgkmcnt(0)
	v_cvt_pk_bf16_f32 v16, v16, v32
	global_store_dword v[76:77], v16, off offset:128
.LBB0_581:
	s_or_b64 exec, exec, s[10:11]
	v_mul_f32_e32 v0, v0, v78
	ds_bpermute_b32 v16, v218, v0
	s_and_saveexec_b64 s[10:11], s[4:5]
	s_cbranch_execz .LBB0_583
	s_waitcnt lgkmcnt(0)
	v_cvt_pk_bf16_f32 v0, v0, v16
	global_store_dword v[76:77], v0, off offset:192
.LBB0_583:
	s_or_b64 exec, exec, s[10:11]
	s_waitcnt lgkmcnt(0)
	v_rcp_f32_e32 v0, v80
	s_nop 0
	v_mul_f32_e32 v16, v49, v0
	ds_bpermute_b32 v32, v218, v16
	s_and_saveexec_b64 s[10:11], s[4:5]
	s_cbranch_execz .LBB0_585
	v_add_co_u32_e32 v48, vcc, 0x1000, v76
	s_waitcnt lgkmcnt(0)
	v_cvt_pk_bf16_f32 v16, v16, v32
	s_nop 0
	v_addc_co_u32_e32 v49, vcc, 0, v77, vcc
	global_store_dword v[48:49], v16, off
.LBB0_585:
	s_or_b64 exec, exec, s[10:11]
	v_mul_f32_e32 v16, v33, v0
	s_waitcnt lgkmcnt(0)
	ds_bpermute_b32 v32, v218, v16
	s_and_saveexec_b64 s[10:11], s[4:5]
	s_cbranch_execz .LBB0_587
	s_waitcnt lgkmcnt(0)
	v_cvt_pk_bf16_f32 v16, v16, v32
	v_add_co_u32_e32 v32, vcc, 0x1000, v76
	s_nop 1
	v_addc_co_u32_e32 v33, vcc, 0, v77, vcc
	global_store_dword v[32:33], v16, off offset:64
.LBB0_587:
	s_or_b64 exec, exec, s[10:11]
	v_mul_f32_e32 v16, v17, v0
	ds_bpermute_b32 v17, v218, v16
	s_and_saveexec_b64 s[10:11], s[4:5]
	s_cbranch_execz .LBB0_589
	s_waitcnt lgkmcnt(0)
	v_cvt_pk_bf16_f32 v32, v16, v17
	v_add_co_u32_e32 v16, vcc, 0x1000, v76
	s_nop 1
	v_addc_co_u32_e32 v17, vcc, 0, v77, vcc
	global_store_dword v[16:17], v32, off offset:128
.LBB0_589:
	s_or_b64 exec, exec, s[10:11]
	v_mul_f32_e32 v0, v1, v0
	ds_bpermute_b32 v1, v218, v0
	s_and_saveexec_b64 s[10:11], s[4:5]
	s_cbranch_execz .LBB0_591
	s_waitcnt lgkmcnt(0)
	v_cvt_pk_bf16_f32 v16, v0, v1
	v_add_co_u32_e32 v0, vcc, 0x1000, v76
	s_nop 1
	v_addc_co_u32_e32 v1, vcc, 0, v77, vcc
	global_store_dword v[0:1], v16, off offset:192
.LBB0_591:
	s_or_b64 exec, exec, s[10:11]
	v_rcp_f32_e32 v0, v81
	s_waitcnt lgkmcnt(0)
	v_mul_f32_e32 v1, v50, v0
	ds_bpermute_b32 v16, v218, v1
	s_and_saveexec_b64 s[10:11], s[4:5]
	s_cbranch_execz .LBB0_593
	s_waitcnt lgkmcnt(0)
	v_cvt_pk_bf16_f32 v1, v1, v16
	v_add_co_u32_e32 v16, vcc, 0x2000, v76
	s_nop 1
	v_addc_co_u32_e32 v17, vcc, 0, v77, vcc
	global_store_dword v[16:17], v1, off
.LBB0_593:
	s_or_b64 exec, exec, s[10:11]
	v_mul_f32_e32 v1, v34, v0
	s_waitcnt lgkmcnt(0)
	ds_bpermute_b32 v16, v218, v1
	s_and_saveexec_b64 s[10:11], s[4:5]
	s_cbranch_execz .LBB0_595
	s_waitcnt lgkmcnt(0)
	v_cvt_pk_bf16_f32 v1, v1, v16
	v_add_co_u32_e32 v16, vcc, 0x2000, v76
	s_nop 1
	v_addc_co_u32_e32 v17, vcc, 0, v77, vcc
	global_store_dword v[16:17], v1, off offset:64
.LBB0_595:
	s_or_b64 exec, exec, s[10:11]
	v_mul_f32_e32 v1, v18, v0
	s_waitcnt lgkmcnt(0)
	ds_bpermute_b32 v16, v218, v1
	s_and_saveexec_b64 s[10:11], s[4:5]
	s_cbranch_execz .LBB0_597
	s_waitcnt lgkmcnt(0)
	v_cvt_pk_bf16_f32 v1, v1, v16
	v_add_co_u32_e32 v16, vcc, 0x2000, v76
	s_nop 1
	v_addc_co_u32_e32 v17, vcc, 0, v77, vcc
	global_store_dword v[16:17], v1, off offset:128
.LBB0_597:
	s_or_b64 exec, exec, s[10:11]
	v_mul_f32_e32 v0, v2, v0
	ds_bpermute_b32 v1, v218, v0
	s_and_saveexec_b64 s[10:11], s[4:5]
	s_cbranch_execz .LBB0_599
	s_waitcnt lgkmcnt(0)
	v_cvt_pk_bf16_f32 v2, v0, v1
	v_add_co_u32_e32 v0, vcc, 0x2000, v76
	s_nop 1
	v_addc_co_u32_e32 v1, vcc, 0, v77, vcc
	global_store_dword v[0:1], v2, off offset:192
.LBB0_599:
	s_or_b64 exec, exec, s[10:11]
	v_rcp_f32_e32 v0, v79
	s_waitcnt lgkmcnt(0)
	v_mul_f32_e32 v1, v51, v0
	ds_bpermute_b32 v2, v218, v1
	s_and_saveexec_b64 s[10:11], s[4:5]
	s_cbranch_execz .LBB0_601
	v_add_co_u32_e32 v16, vcc, 0x3000, v76
	s_waitcnt lgkmcnt(0)
	v_cvt_pk_bf16_f32 v1, v1, v2
	s_nop 0
	v_addc_co_u32_e32 v17, vcc, 0, v77, vcc
	global_store_dword v[16:17], v1, off
.LBB0_601:
	s_or_b64 exec, exec, s[10:11]
	v_mul_f32_e32 v1, v35, v0
	s_waitcnt lgkmcnt(0)
	ds_bpermute_b32 v2, v218, v1
	s_and_saveexec_b64 s[10:11], s[4:5]
	s_cbranch_execz .LBB0_603
	v_add_co_u32_e32 v16, vcc, 0x3000, v76
	s_waitcnt lgkmcnt(0)
	v_cvt_pk_bf16_f32 v1, v1, v2
	s_nop 0
	v_addc_co_u32_e32 v17, vcc, 0, v77, vcc
	global_store_dword v[16:17], v1, off offset:64
.LBB0_603:
	s_or_b64 exec, exec, s[10:11]
	v_mul_f32_e32 v1, v19, v0
	s_waitcnt lgkmcnt(0)
	ds_bpermute_b32 v2, v218, v1
	s_and_saveexec_b64 s[10:11], s[4:5]
	s_cbranch_execz .LBB0_605
	v_add_co_u32_e32 v16, vcc, 0x3000, v76
	s_waitcnt lgkmcnt(0)
	v_cvt_pk_bf16_f32 v1, v1, v2
	s_nop 0
	v_addc_co_u32_e32 v17, vcc, 0, v77, vcc
	global_store_dword v[16:17], v1, off offset:128
.LBB0_605:
	s_or_b64 exec, exec, s[10:11]
	v_mul_f32_e32 v0, v3, v0
	ds_bpermute_b32 v1, v218, v0
	s_and_saveexec_b64 s[10:11], s[4:5]
	s_cbranch_execz .LBB0_607
	s_waitcnt lgkmcnt(0)
	v_cvt_pk_bf16_f32 v2, v0, v1
	v_add_co_u32_e32 v0, vcc, 0x3000, v76
	s_nop 1
	v_addc_co_u32_e32 v1, vcc, 0, v77, vcc
	global_store_dword v[0:1], v2, off offset:192
.LBB0_607:
	s_or_b64 exec, exec, s[10:11]
	v_rcp_f32_e32 v0, v72
	s_waitcnt lgkmcnt(0)
	v_mul_f32_e32 v1, v52, v0
	ds_bpermute_b32 v2, v218, v1
	s_and_saveexec_b64 s[10:11], s[4:5]
	s_cbranch_execz .LBB0_609
	s_waitcnt lgkmcnt(0)
	v_cvt_pk_bf16_f32 v1, v1, v2
	v_add_co_u32_e32 v2, vcc, 0x8000, v76
	s_nop 1
	v_addc_co_u32_e32 v3, vcc, 0, v77, vcc
	global_store_dword v[2:3], v1, off
.LBB0_609:
	s_or_b64 exec, exec, s[10:11]
	v_mul_f32_e32 v1, v36, v0
	s_waitcnt lgkmcnt(0)
	ds_bpermute_b32 v2, v218, v1
	s_and_saveexec_b64 s[10:11], s[4:5]
	s_cbranch_execz .LBB0_611
	s_waitcnt lgkmcnt(0)
	v_cvt_pk_bf16_f32 v1, v1, v2
	v_add_co_u32_e32 v2, vcc, 0x8000, v76
	s_nop 1
	v_addc_co_u32_e32 v3, vcc, 0, v77, vcc
	global_store_dword v[2:3], v1, off offset:64
.LBB0_611:
	s_or_b64 exec, exec, s[10:11]
	v_mul_f32_e32 v1, v20, v0
	s_waitcnt lgkmcnt(0)
	ds_bpermute_b32 v2, v218, v1
	s_and_saveexec_b64 s[10:11], s[4:5]
	s_cbranch_execz .LBB0_613
	s_waitcnt lgkmcnt(0)
	v_cvt_pk_bf16_f32 v1, v1, v2
	v_add_co_u32_e32 v2, vcc, 0x8000, v76
	s_nop 1
	v_addc_co_u32_e32 v3, vcc, 0, v77, vcc
	global_store_dword v[2:3], v1, off offset:128
.LBB0_613:
	s_or_b64 exec, exec, s[10:11]
	v_mul_f32_e32 v0, v4, v0
	ds_bpermute_b32 v1, v218, v0
	s_and_saveexec_b64 s[10:11], s[4:5]
	s_cbranch_execz .LBB0_615
	s_waitcnt lgkmcnt(0)
	v_cvt_pk_bf16_f32 v2, v0, v1
	v_add_co_u32_e32 v0, vcc, 0x8000, v76
	s_nop 1
	v_addc_co_u32_e32 v1, vcc, 0, v77, vcc
	global_store_dword v[0:1], v2, off offset:192
.LBB0_615:
	s_or_b64 exec, exec, s[10:11]
	v_rcp_f32_e32 v0, v73
	s_waitcnt lgkmcnt(0)
	v_mul_f32_e32 v1, v53, v0
	ds_bpermute_b32 v2, v218, v1
	s_and_saveexec_b64 s[10:11], s[4:5]
	s_cbranch_execz .LBB0_617
	s_waitcnt lgkmcnt(0)
	v_cvt_pk_bf16_f32 v1, v1, v2
	v_add_co_u32_e32 v2, vcc, 0x9000, v76
	s_nop 1
	v_addc_co_u32_e32 v3, vcc, 0, v77, vcc
	global_store_dword v[2:3], v1, off
.LBB0_617:
	s_or_b64 exec, exec, s[10:11]
	v_mul_f32_e32 v1, v37, v0
	s_waitcnt lgkmcnt(0)
	ds_bpermute_b32 v2, v218, v1
	s_and_saveexec_b64 s[10:11], s[4:5]
	s_cbranch_execz .LBB0_619
	s_waitcnt lgkmcnt(0)
	v_cvt_pk_bf16_f32 v1, v1, v2
	v_add_co_u32_e32 v2, vcc, 0x9000, v76
	s_nop 1
	v_addc_co_u32_e32 v3, vcc, 0, v77, vcc
	global_store_dword v[2:3], v1, off offset:64
.LBB0_619:
	s_or_b64 exec, exec, s[10:11]
	v_mul_f32_e32 v1, v21, v0
	s_waitcnt lgkmcnt(0)
	ds_bpermute_b32 v2, v218, v1
	s_and_saveexec_b64 s[10:11], s[4:5]
	s_cbranch_execz .LBB0_621
	s_waitcnt lgkmcnt(0)
	v_cvt_pk_bf16_f32 v1, v1, v2
	v_add_co_u32_e32 v2, vcc, 0x9000, v76
	s_nop 1
	v_addc_co_u32_e32 v3, vcc, 0, v77, vcc
	global_store_dword v[2:3], v1, off offset:128
.LBB0_621:
	s_or_b64 exec, exec, s[10:11]
	v_mul_f32_e32 v0, v5, v0
	ds_bpermute_b32 v1, v218, v0
	s_and_saveexec_b64 s[10:11], s[4:5]
	s_cbranch_execz .LBB0_623
	s_waitcnt lgkmcnt(0)
	v_cvt_pk_bf16_f32 v2, v0, v1
	v_add_co_u32_e32 v0, vcc, 0x9000, v76
	s_nop 1
	v_addc_co_u32_e32 v1, vcc, 0, v77, vcc
	global_store_dword v[0:1], v2, off offset:192
.LBB0_623:
	s_or_b64 exec, exec, s[10:11]
	v_rcp_f32_e32 v0, v74
	s_waitcnt lgkmcnt(0)
	v_mul_f32_e32 v1, v54, v0
	ds_bpermute_b32 v2, v218, v1
	s_and_saveexec_b64 s[10:11], s[4:5]
	s_cbranch_execz .LBB0_625
	s_waitcnt lgkmcnt(0)
	v_cvt_pk_bf16_f32 v1, v1, v2
	v_add_co_u32_e32 v2, vcc, 0xa000, v76
	s_nop 1
	v_addc_co_u32_e32 v3, vcc, 0, v77, vcc
	global_store_dword v[2:3], v1, off
.LBB0_625:
	s_or_b64 exec, exec, s[10:11]
	v_mul_f32_e32 v1, v38, v0
	s_waitcnt lgkmcnt(0)
	ds_bpermute_b32 v2, v218, v1
	s_and_saveexec_b64 s[10:11], s[4:5]
	s_cbranch_execz .LBB0_627
	s_waitcnt lgkmcnt(0)
	v_cvt_pk_bf16_f32 v1, v1, v2
	v_add_co_u32_e32 v2, vcc, 0xa000, v76
	s_nop 1
	v_addc_co_u32_e32 v3, vcc, 0, v77, vcc
	global_store_dword v[2:3], v1, off offset:64
.LBB0_627:
	s_or_b64 exec, exec, s[10:11]
	v_mul_f32_e32 v1, v22, v0
	s_waitcnt lgkmcnt(0)
	ds_bpermute_b32 v2, v218, v1
	s_and_saveexec_b64 s[10:11], s[4:5]
	s_cbranch_execz .LBB0_629
	s_waitcnt lgkmcnt(0)
	v_cvt_pk_bf16_f32 v1, v1, v2
	v_add_co_u32_e32 v2, vcc, 0xa000, v76
	s_nop 1
	v_addc_co_u32_e32 v3, vcc, 0, v77, vcc
	global_store_dword v[2:3], v1, off offset:128
.LBB0_629:
	s_or_b64 exec, exec, s[10:11]
	v_mul_f32_e32 v0, v6, v0
	ds_bpermute_b32 v1, v218, v0
	s_and_saveexec_b64 s[10:11], s[4:5]
	s_cbranch_execz .LBB0_631
	s_waitcnt lgkmcnt(0)
	v_cvt_pk_bf16_f32 v2, v0, v1
	v_add_co_u32_e32 v0, vcc, 0xa000, v76
	s_nop 1
	v_addc_co_u32_e32 v1, vcc, 0, v77, vcc
	global_store_dword v[0:1], v2, off offset:192
.LBB0_631:
	s_or_b64 exec, exec, s[10:11]
	v_rcp_f32_e32 v0, v75
	s_waitcnt lgkmcnt(0)
	v_mul_f32_e32 v1, v55, v0
	ds_bpermute_b32 v2, v218, v1
	s_and_saveexec_b64 s[10:11], s[4:5]
	s_cbranch_execz .LBB0_633
	s_waitcnt lgkmcnt(0)
	v_cvt_pk_bf16_f32 v1, v1, v2
	v_add_co_u32_e32 v2, vcc, 0xb000, v76
	s_nop 1
	v_addc_co_u32_e32 v3, vcc, 0, v77, vcc
	global_store_dword v[2:3], v1, off
.LBB0_633:
	s_or_b64 exec, exec, s[10:11]
	v_mul_f32_e32 v1, v39, v0
	s_waitcnt lgkmcnt(0)
	ds_bpermute_b32 v2, v218, v1
	s_and_saveexec_b64 s[10:11], s[4:5]
	s_cbranch_execz .LBB0_635
	s_waitcnt lgkmcnt(0)
	v_cvt_pk_bf16_f32 v1, v1, v2
	v_add_co_u32_e32 v2, vcc, 0xb000, v76
	s_nop 1
	v_addc_co_u32_e32 v3, vcc, 0, v77, vcc
	global_store_dword v[2:3], v1, off offset:64
.LBB0_635:
	s_or_b64 exec, exec, s[10:11]
	v_mul_f32_e32 v1, v23, v0
	s_waitcnt lgkmcnt(0)
	ds_bpermute_b32 v2, v218, v1
	s_and_saveexec_b64 s[10:11], s[4:5]
	s_cbranch_execz .LBB0_637
	s_waitcnt lgkmcnt(0)
	v_cvt_pk_bf16_f32 v1, v1, v2
	v_add_co_u32_e32 v2, vcc, 0xb000, v76
	s_nop 1
	v_addc_co_u32_e32 v3, vcc, 0, v77, vcc
	global_store_dword v[2:3], v1, off offset:128
.LBB0_637:
	s_or_b64 exec, exec, s[10:11]
	v_mul_f32_e32 v0, v7, v0
	ds_bpermute_b32 v1, v218, v0
	s_and_saveexec_b64 s[10:11], s[4:5]
	s_cbranch_execz .LBB0_639
	s_waitcnt lgkmcnt(0)
	v_cvt_pk_bf16_f32 v2, v0, v1
	v_add_co_u32_e32 v0, vcc, 0xb000, v76
	s_nop 1
	v_addc_co_u32_e32 v1, vcc, 0, v77, vcc
	global_store_dword v[0:1], v2, off offset:192

.LBB0_640:
	s_cmp_eq_u32 s88, 7
	s_cselect_b64 s[0:1], -1, 0
	s_or_b64 s[0:1], s[8:9], s[0:1]
	s_andn2_b64 vcc, exec, s[0:1]
	s_cbranch_vccnz .LBB0_706
	s_waitcnt lgkmcnt(0)
	v_rcp_f32_e32 v2, v68
	v_cmp_eq_u32_e64 s[4:5], 0, v82
	v_lshl_add_u64 v[0:1], s[6:7], 0, v[128:129]
	v_mul_f32_e32 v3, v56, v2
	ds_bpermute_b32 v4, v218, v3
	s_and_saveexec_b64 s[6:7], s[4:5]
	s_cbranch_execz .LBB0_643
	s_waitcnt lgkmcnt(0)
	v_cvt_pk_bf16_f32 v3, v3, v4
	v_add_co_u32_e32 v4, vcc, 0x10000, v0
	s_nop 1
	v_addc_co_u32_e32 v5, vcc, 0, v1, vcc
	global_store_dword v[4:5], v3, off
.LBB0_643:
	s_or_b64 exec, exec, s[6:7]
	v_mul_f32_e32 v3, v40, v2
	s_waitcnt lgkmcnt(0)
	ds_bpermute_b32 v4, v218, v3
	s_and_saveexec_b64 s[6:7], s[4:5]
	s_cbranch_execz .LBB0_645
	s_waitcnt lgkmcnt(0)
	v_cvt_pk_bf16_f32 v3, v3, v4
	v_add_co_u32_e32 v4, vcc, 0x10000, v0
	s_nop 1
	v_addc_co_u32_e32 v5, vcc, 0, v1, vcc
	global_store_dword v[4:5], v3, off offset:64
.LBB0_645:
	s_or_b64 exec, exec, s[6:7]
	v_mul_f32_e32 v3, v24, v2
	s_waitcnt lgkmcnt(0)
	ds_bpermute_b32 v4, v218, v3
	s_and_saveexec_b64 s[6:7], s[4:5]
	s_cbranch_execz .LBB0_647
	s_waitcnt lgkmcnt(0)
	v_cvt_pk_bf16_f32 v3, v3, v4
	v_add_co_u32_e32 v4, vcc, 0x10000, v0
	s_nop 1
	v_addc_co_u32_e32 v5, vcc, 0, v1, vcc
	global_store_dword v[4:5], v3, off offset:128
.LBB0_647:
	s_or_b64 exec, exec, s[6:7]
	v_mul_f32_e32 v2, v8, v2
	ds_bpermute_b32 v3, v218, v2
	s_and_saveexec_b64 s[6:7], s[4:5]
	s_cbranch_execz .LBB0_649
	s_waitcnt lgkmcnt(0)
	v_cvt_pk_bf16_f32 v4, v2, v3
	v_add_co_u32_e32 v2, vcc, 0x10000, v0
	s_nop 1
	v_addc_co_u32_e32 v3, vcc, 0, v1, vcc
	global_store_dword v[2:3], v4, off offset:192
.LBB0_649:
	s_or_b64 exec, exec, s[6:7]
	v_rcp_f32_e32 v2, v69
	s_waitcnt lgkmcnt(0)
	v_mul_f32_e32 v3, v57, v2
	ds_bpermute_b32 v4, v218, v3
	s_and_saveexec_b64 s[6:7], s[4:5]
	s_cbranch_execz .LBB0_651
	s_waitcnt lgkmcnt(0)
	v_cvt_pk_bf16_f32 v3, v3, v4
	v_add_co_u32_e32 v4, vcc, 0x11000, v0
	s_nop 1
	v_addc_co_u32_e32 v5, vcc, 0, v1, vcc
	global_store_dword v[4:5], v3, off
.LBB0_651:
	s_or_b64 exec, exec, s[6:7]
	v_mul_f32_e32 v3, v41, v2
	s_waitcnt lgkmcnt(0)
	ds_bpermute_b32 v4, v218, v3
	s_and_saveexec_b64 s[6:7], s[4:5]
	s_cbranch_execz .LBB0_653
	s_waitcnt lgkmcnt(0)
	v_cvt_pk_bf16_f32 v3, v3, v4
	v_add_co_u32_e32 v4, vcc, 0x11000, v0
	s_nop 1
	v_addc_co_u32_e32 v5, vcc, 0, v1, vcc
	global_store_dword v[4:5], v3, off offset:64
.LBB0_653:
	s_or_b64 exec, exec, s[6:7]
	v_mul_f32_e32 v3, v25, v2
	s_waitcnt lgkmcnt(0)
	ds_bpermute_b32 v4, v218, v3
	s_and_saveexec_b64 s[6:7], s[4:5]
	s_cbranch_execz .LBB0_655
	s_waitcnt lgkmcnt(0)
	v_cvt_pk_bf16_f32 v3, v3, v4
	v_add_co_u32_e32 v4, vcc, 0x11000, v0
	s_nop 1
	v_addc_co_u32_e32 v5, vcc, 0, v1, vcc
	global_store_dword v[4:5], v3, off offset:128
.LBB0_655:
	s_or_b64 exec, exec, s[6:7]
	v_mul_f32_e32 v2, v9, v2
	ds_bpermute_b32 v3, v218, v2
	s_and_saveexec_b64 s[6:7], s[4:5]
	s_cbranch_execz .LBB0_657
	s_waitcnt lgkmcnt(0)
	v_cvt_pk_bf16_f32 v4, v2, v3
	v_add_co_u32_e32 v2, vcc, 0x11000, v0
	s_nop 1
	v_addc_co_u32_e32 v3, vcc, 0, v1, vcc
	global_store_dword v[2:3], v4, off offset:192
.LBB0_657:
	s_or_b64 exec, exec, s[6:7]
	v_rcp_f32_e32 v2, v70
	s_waitcnt lgkmcnt(0)
	v_mul_f32_e32 v3, v58, v2
	ds_bpermute_b32 v4, v218, v3
	s_and_saveexec_b64 s[6:7], s[4:5]
	s_cbranch_execz .LBB0_659
	s_waitcnt lgkmcnt(0)
	v_cvt_pk_bf16_f32 v3, v3, v4
	v_add_co_u32_e32 v4, vcc, 0x12000, v0
	s_nop 1
	v_addc_co_u32_e32 v5, vcc, 0, v1, vcc
	global_store_dword v[4:5], v3, off
.LBB0_659:
	s_or_b64 exec, exec, s[6:7]
	v_mul_f32_e32 v3, v42, v2
	s_waitcnt lgkmcnt(0)
	ds_bpermute_b32 v4, v218, v3
	s_and_saveexec_b64 s[6:7], s[4:5]
	s_cbranch_execz .LBB0_661
	s_waitcnt lgkmcnt(0)
	v_cvt_pk_bf16_f32 v3, v3, v4
	v_add_co_u32_e32 v4, vcc, 0x12000, v0
	s_nop 1
	v_addc_co_u32_e32 v5, vcc, 0, v1, vcc
	global_store_dword v[4:5], v3, off offset:64
.LBB0_661:
	s_or_b64 exec, exec, s[6:7]
	v_mul_f32_e32 v3, v26, v2
	s_waitcnt lgkmcnt(0)
	ds_bpermute_b32 v4, v218, v3
	s_and_saveexec_b64 s[6:7], s[4:5]
	s_cbranch_execz .LBB0_663
	s_waitcnt lgkmcnt(0)
	v_cvt_pk_bf16_f32 v3, v3, v4
	v_add_co_u32_e32 v4, vcc, 0x12000, v0
	s_nop 1
	v_addc_co_u32_e32 v5, vcc, 0, v1, vcc
	global_store_dword v[4:5], v3, off offset:128
.LBB0_663:
	s_or_b64 exec, exec, s[6:7]
	v_mul_f32_e32 v2, v10, v2
	ds_bpermute_b32 v3, v218, v2
	s_and_saveexec_b64 s[6:7], s[4:5]
	s_cbranch_execz .LBB0_665
	s_waitcnt lgkmcnt(0)
	v_cvt_pk_bf16_f32 v4, v2, v3
	v_add_co_u32_e32 v2, vcc, 0x12000, v0
	s_nop 1
	v_addc_co_u32_e32 v3, vcc, 0, v1, vcc
	global_store_dword v[2:3], v4, off offset:192
.LBB0_665:
	s_or_b64 exec, exec, s[6:7]
	v_rcp_f32_e32 v2, v71
	s_waitcnt lgkmcnt(0)
	v_mul_f32_e32 v3, v59, v2
	ds_bpermute_b32 v4, v218, v3
	s_and_saveexec_b64 s[6:7], s[4:5]
	s_cbranch_execz .LBB0_667
	s_waitcnt lgkmcnt(0)
	v_cvt_pk_bf16_f32 v3, v3, v4
	v_add_co_u32_e32 v4, vcc, 0x13000, v0
	s_nop 1
	v_addc_co_u32_e32 v5, vcc, 0, v1, vcc
	global_store_dword v[4:5], v3, off
.LBB0_667:
	s_or_b64 exec, exec, s[6:7]
	v_mul_f32_e32 v3, v43, v2
	s_waitcnt lgkmcnt(0)
	ds_bpermute_b32 v4, v218, v3
	s_and_saveexec_b64 s[6:7], s[4:5]
	s_cbranch_execz .LBB0_669
	s_waitcnt lgkmcnt(0)
	v_cvt_pk_bf16_f32 v3, v3, v4
	v_add_co_u32_e32 v4, vcc, 0x13000, v0
	s_nop 1
	v_addc_co_u32_e32 v5, vcc, 0, v1, vcc
	global_store_dword v[4:5], v3, off offset:64
.LBB0_669:
	s_or_b64 exec, exec, s[6:7]
	v_mul_f32_e32 v3, v27, v2
	s_waitcnt lgkmcnt(0)
	ds_bpermute_b32 v4, v218, v3
	s_and_saveexec_b64 s[6:7], s[4:5]
	s_cbranch_execz .LBB0_671
	s_waitcnt lgkmcnt(0)
	v_cvt_pk_bf16_f32 v3, v3, v4
	v_add_co_u32_e32 v4, vcc, 0x13000, v0
	s_nop 1
	v_addc_co_u32_e32 v5, vcc, 0, v1, vcc
	global_store_dword v[4:5], v3, off offset:128
.LBB0_671:
	s_or_b64 exec, exec, s[6:7]
	v_mul_f32_e32 v2, v11, v2
	ds_bpermute_b32 v3, v218, v2
	s_and_saveexec_b64 s[6:7], s[4:5]
	s_cbranch_execz .LBB0_673
	s_waitcnt lgkmcnt(0)
	v_cvt_pk_bf16_f32 v4, v2, v3
	v_add_co_u32_e32 v2, vcc, 0x13000, v0
	s_nop 1
	v_addc_co_u32_e32 v3, vcc, 0, v1, vcc
	global_store_dword v[2:3], v4, off offset:192
.LBB0_673:
	s_or_b64 exec, exec, s[6:7]
	v_rcp_f32_e32 v2, v64
	s_waitcnt lgkmcnt(0)
	v_mul_f32_e32 v3, v60, v2
	ds_bpermute_b32 v4, v218, v3
	s_and_saveexec_b64 s[6:7], s[4:5]
	s_cbranch_execz .LBB0_675
	s_waitcnt lgkmcnt(0)
	v_cvt_pk_bf16_f32 v3, v3, v4
	v_add_co_u32_e32 v4, vcc, 0x18000, v0
	s_nop 1
	v_addc_co_u32_e32 v5, vcc, 0, v1, vcc
	global_store_dword v[4:5], v3, off
.LBB0_675:
	s_or_b64 exec, exec, s[6:7]
	v_mul_f32_e32 v3, v44, v2
	s_waitcnt lgkmcnt(0)
	ds_bpermute_b32 v4, v218, v3
	s_and_saveexec_b64 s[6:7], s[4:5]
	s_cbranch_execz .LBB0_677
	s_waitcnt lgkmcnt(0)
	v_cvt_pk_bf16_f32 v3, v3, v4
	v_add_co_u32_e32 v4, vcc, 0x18000, v0
	s_nop 1
	v_addc_co_u32_e32 v5, vcc, 0, v1, vcc
	global_store_dword v[4:5], v3, off offset:64
.LBB0_677:
	s_or_b64 exec, exec, s[6:7]
	v_mul_f32_e32 v3, v28, v2
	s_waitcnt lgkmcnt(0)
	ds_bpermute_b32 v4, v218, v3
	s_and_saveexec_b64 s[6:7], s[4:5]
	s_cbranch_execz .LBB0_679
	s_waitcnt lgkmcnt(0)
	v_cvt_pk_bf16_f32 v3, v3, v4
	v_add_co_u32_e32 v4, vcc, 0x18000, v0
	s_nop 1
	v_addc_co_u32_e32 v5, vcc, 0, v1, vcc
	global_store_dword v[4:5], v3, off offset:128
.LBB0_679:
	s_or_b64 exec, exec, s[6:7]
	v_mul_f32_e32 v2, v12, v2
	ds_bpermute_b32 v3, v218, v2
	s_and_saveexec_b64 s[6:7], s[4:5]
	s_cbranch_execz .LBB0_681
	s_waitcnt lgkmcnt(0)
	v_cvt_pk_bf16_f32 v4, v2, v3
	v_add_co_u32_e32 v2, vcc, 0x18000, v0
	s_nop 1
	v_addc_co_u32_e32 v3, vcc, 0, v1, vcc
	global_store_dword v[2:3], v4, off offset:192
.LBB0_681:
	s_or_b64 exec, exec, s[6:7]
	v_rcp_f32_e32 v2, v65
	s_waitcnt lgkmcnt(0)
	v_mul_f32_e32 v3, v61, v2
	ds_bpermute_b32 v4, v218, v3
	s_and_saveexec_b64 s[6:7], s[4:5]
	s_cbranch_execz .LBB0_683
	s_waitcnt lgkmcnt(0)
	v_cvt_pk_bf16_f32 v3, v3, v4
	v_add_co_u32_e32 v4, vcc, 0x19000, v0
	s_nop 1
	v_addc_co_u32_e32 v5, vcc, 0, v1, vcc
	global_store_dword v[4:5], v3, off
.LBB0_683:
	s_or_b64 exec, exec, s[6:7]
	v_mul_f32_e32 v3, v45, v2
	s_waitcnt lgkmcnt(0)
	ds_bpermute_b32 v4, v218, v3
	s_and_saveexec_b64 s[6:7], s[4:5]
	s_cbranch_execz .LBB0_685
	s_waitcnt lgkmcnt(0)
	v_cvt_pk_bf16_f32 v3, v3, v4
	v_add_co_u32_e32 v4, vcc, 0x19000, v0
	s_nop 1
	v_addc_co_u32_e32 v5, vcc, 0, v1, vcc
	global_store_dword v[4:5], v3, off offset:64
.LBB0_685:
	s_or_b64 exec, exec, s[6:7]
	v_mul_f32_e32 v3, v29, v2
	s_waitcnt lgkmcnt(0)
	ds_bpermute_b32 v4, v218, v3
	s_and_saveexec_b64 s[6:7], s[4:5]
	s_cbranch_execz .LBB0_687
	s_waitcnt lgkmcnt(0)
	v_cvt_pk_bf16_f32 v3, v3, v4
	v_add_co_u32_e32 v4, vcc, 0x19000, v0
	s_nop 1
	v_addc_co_u32_e32 v5, vcc, 0, v1, vcc
	global_store_dword v[4:5], v3, off offset:128
.LBB0_687:
	s_or_b64 exec, exec, s[6:7]
	v_mul_f32_e32 v2, v13, v2
	ds_bpermute_b32 v3, v218, v2
	s_and_saveexec_b64 s[6:7], s[4:5]
	s_cbranch_execz .LBB0_689
	s_waitcnt lgkmcnt(0)
	v_cvt_pk_bf16_f32 v4, v2, v3
	v_add_co_u32_e32 v2, vcc, 0x19000, v0
	s_nop 1
	v_addc_co_u32_e32 v3, vcc, 0, v1, vcc
	global_store_dword v[2:3], v4, off offset:192
.LBB0_689:
	s_or_b64 exec, exec, s[6:7]
	v_rcp_f32_e32 v2, v66
	s_waitcnt lgkmcnt(0)
	v_mul_f32_e32 v3, v62, v2
	ds_bpermute_b32 v4, v218, v3
	s_and_saveexec_b64 s[6:7], s[4:5]
	s_cbranch_execz .LBB0_691
	s_waitcnt lgkmcnt(0)
	v_cvt_pk_bf16_f32 v3, v3, v4
	v_add_co_u32_e32 v4, vcc, 0x1a000, v0
	s_nop 1
	v_addc_co_u32_e32 v5, vcc, 0, v1, vcc
	global_store_dword v[4:5], v3, off
.LBB0_691:
	s_or_b64 exec, exec, s[6:7]
	v_mul_f32_e32 v3, v46, v2
	s_waitcnt lgkmcnt(0)
	ds_bpermute_b32 v4, v218, v3
	s_and_saveexec_b64 s[6:7], s[4:5]
	s_cbranch_execz .LBB0_693
	s_waitcnt lgkmcnt(0)
	v_cvt_pk_bf16_f32 v3, v3, v4
	v_add_co_u32_e32 v4, vcc, 0x1a000, v0
	s_nop 1
	v_addc_co_u32_e32 v5, vcc, 0, v1, vcc
	global_store_dword v[4:5], v3, off offset:64
.LBB0_693:
	s_or_b64 exec, exec, s[6:7]
	v_mul_f32_e32 v3, v30, v2
	s_waitcnt lgkmcnt(0)
	ds_bpermute_b32 v4, v218, v3
	s_and_saveexec_b64 s[6:7], s[4:5]
	s_cbranch_execz .LBB0_695
	s_waitcnt lgkmcnt(0)
	v_cvt_pk_bf16_f32 v3, v3, v4
	v_add_co_u32_e32 v4, vcc, 0x1a000, v0
	s_nop 1
	v_addc_co_u32_e32 v5, vcc, 0, v1, vcc
	global_store_dword v[4:5], v3, off offset:128
.LBB0_695:
	s_or_b64 exec, exec, s[6:7]
	v_mul_f32_e32 v2, v14, v2
	ds_bpermute_b32 v3, v218, v2
	s_and_saveexec_b64 s[6:7], s[4:5]
	s_cbranch_execz .LBB0_697
	s_waitcnt lgkmcnt(0)
	v_cvt_pk_bf16_f32 v4, v2, v3
	v_add_co_u32_e32 v2, vcc, 0x1a000, v0
	s_nop 1
	v_addc_co_u32_e32 v3, vcc, 0, v1, vcc
	global_store_dword v[2:3], v4, off offset:192
.LBB0_697:
	s_or_b64 exec, exec, s[6:7]
	v_rcp_f32_e32 v2, v67
	s_waitcnt lgkmcnt(0)
	v_mul_f32_e32 v3, v63, v2
	ds_bpermute_b32 v4, v218, v3
	s_and_saveexec_b64 s[6:7], s[4:5]
	s_cbranch_execz .LBB0_699
	s_waitcnt lgkmcnt(0)
	v_cvt_pk_bf16_f32 v3, v3, v4
	v_add_co_u32_e32 v4, vcc, 0x1b000, v0
	s_nop 1
	v_addc_co_u32_e32 v5, vcc, 0, v1, vcc
	global_store_dword v[4:5], v3, off
.LBB0_699:
	s_or_b64 exec, exec, s[6:7]
	v_mul_f32_e32 v3, v47, v2
	s_waitcnt lgkmcnt(0)
	ds_bpermute_b32 v4, v218, v3
	s_and_saveexec_b64 s[6:7], s[4:5]
	s_cbranch_execz .LBB0_701
	s_waitcnt lgkmcnt(0)
	v_cvt_pk_bf16_f32 v3, v3, v4
	v_add_co_u32_e32 v4, vcc, 0x1b000, v0
	s_nop 1
	v_addc_co_u32_e32 v5, vcc, 0, v1, vcc
	global_store_dword v[4:5], v3, off offset:64
.LBB0_701:
	s_or_b64 exec, exec, s[6:7]
	v_mul_f32_e32 v3, v31, v2
	s_waitcnt lgkmcnt(0)
	ds_bpermute_b32 v4, v218, v3
	s_and_saveexec_b64 s[6:7], s[4:5]
	s_cbranch_execz .LBB0_703
	s_waitcnt lgkmcnt(0)
	v_cvt_pk_bf16_f32 v3, v3, v4
	v_add_co_u32_e32 v4, vcc, 0x1b000, v0
	s_nop 1
	v_addc_co_u32_e32 v5, vcc, 0, v1, vcc
	global_store_dword v[4:5], v3, off offset:128
.LBB0_703:
	s_or_b64 exec, exec, s[6:7]
	v_mul_f32_e32 v2, v15, v2
	ds_bpermute_b32 v3, v218, v2
	s_and_saveexec_b64 s[6:7], s[4:5]
	s_cbranch_execz .LBB0_705
	v_add_co_u32_e32 v0, vcc, 0x1b000, v0
	s_waitcnt lgkmcnt(0)
	v_cvt_pk_bf16_f32 v2, v2, v3
	s_nop 0
	v_addc_co_u32_e32 v1, vcc, 0, v1, vcc
	global_store_dword v[0:1], v2, off offset:192

.LBB0_775:
	v_lshl_add_u32 v220, s26, 8, v156
	v_lshl_or_b32 v221, s24, 8, v158
	s_lshl_b32 s94, s24, 2
	s_add_i32 s94, s94, s44
	s_lshl_b32 s94, s94, 2
	v_lshlrev_b32_e32 v218, 12, v220
	v_lshl_add_u32 v218, v221, 1, v218
	v_lshlrev_b32_e32 v219, 7, v220
	v_add_u32_e32 v219, s94, v219
	s_mov_b32 s24, s8
	s_mov_b32 s25, s9
	global_load_dwordx4 v[130:133], v218, s[24:25]
	global_load_dwordx4 v[134:137], v218, s[24:25] offset:256
	s_add_u32 s24, s24, 0x10000
	s_addc_u32 s25, s25, 0
	global_load_dwordx4 v[148:151], v218, s[24:25]
	global_load_dwordx4 v[152:155], v218, s[24:25] offset:256
	s_add_u32 s24, s24, 0x10000
	s_addc_u32 s25, s25, 0
	global_load_dwordx4 v[160:163], v218, s[24:25]
	global_load_dwordx4 v[164:167], v218, s[24:25] offset:256
	s_add_u32 s24, s24, 0x10000
	s_addc_u32 s25, s25, 0
	global_load_dwordx4 v[168:171], v218, s[24:25]
	global_load_dwordx4 v[172:175], v218, s[24:25] offset:256
	s_add_u32 s24, s24, 0x50000
	s_addc_u32 s25, s25, 0
	global_load_dwordx4 v[176:179], v218, s[24:25]
	global_load_dwordx4 v[180:183], v218, s[24:25] offset:256
	s_add_u32 s24, s24, 0x10000
	s_addc_u32 s25, s25, 0
	global_load_dwordx4 v[192:195], v218, s[24:25]
	global_load_dwordx4 v[196:199], v218, s[24:25] offset:256
	s_add_u32 s24, s24, 0x10000
	s_addc_u32 s25, s25, 0
	global_load_dwordx4 v[200:203], v218, s[24:25]
	global_load_dwordx4 v[204:207], v218, s[24:25] offset:256
	s_mov_b32 s24, s8
	s_mov_b32 s25, s9
	s_waitcnt vmcnt(12)
	v_and_b32_e32 v220, 0xffff0000, v130
	v_lshlrev_b32_e32 v130, 16, v130
	v_and_b32_e32 v221, 0xffff0000, v131
	v_lshlrev_b32_e32 v131, 16, v131
	v_and_b32_e32 v222, 0xffff0000, v132
	v_lshlrev_b32_e32 v132, 16, v132
	v_and_b32_e32 v223, 0xffff0000, v133
	v_lshlrev_b32_e32 v133, 16, v133
	v_add_f32_e32 v124, v124, v130
	v_add_f32_e32 v125, v125, v220
	v_add_f32_e32 v126, v126, v131
	v_add_f32_e32 v127, v127, v221
	v_add_f32_e32 v120, v120, v132
	v_add_f32_e32 v121, v121, v222
	v_add_f32_e32 v122, v122, v133
	v_add_f32_e32 v123, v123, v223
	v_cvt_pk_bf16_f32 v130, v124, v125
	v_cvt_pk_bf16_f32 v131, v126, v127
	v_cvt_pk_bf16_f32 v132, v120, v121
	v_cvt_pk_bf16_f32 v133, v122, v123
	v_and_b32_e32 v220, 0xffff0000, v134
	v_lshlrev_b32_e32 v134, 16, v134
	v_and_b32_e32 v221, 0xffff0000, v135
	v_lshlrev_b32_e32 v135, 16, v135
	v_and_b32_e32 v222, 0xffff0000, v136
	v_lshlrev_b32_e32 v136, 16, v136
	v_and_b32_e32 v223, 0xffff0000, v137
	v_lshlrev_b32_e32 v137, 16, v137
	v_add_f32_e32 v116, v116, v134
	v_add_f32_e32 v117, v117, v220
	v_add_f32_e32 v118, v118, v135
	v_add_f32_e32 v119, v119, v221
	v_add_f32_e32 v112, v112, v136
	v_add_f32_e32 v113, v113, v222
	v_add_f32_e32 v114, v114, v137
	v_add_f32_e32 v115, v115, v223
	v_cvt_pk_bf16_f32 v134, v116, v117
	v_cvt_pk_bf16_f32 v135, v118, v119
	v_cvt_pk_bf16_f32 v136, v112, v113
	v_cvt_pk_bf16_f32 v137, v114, v115
	global_store_dwordx4 v218, v[130:133], s[24:25]
	global_store_dwordx4 v218, v[134:137], s[24:25] offset:256
	v_mul_f32_e32 v220, v112, v112
	v_mul_f32_e32 v221, v120, v120
	v_fmac_f32_e32 v220, v113, v113
	v_fmac_f32_e32 v221, v121, v121
	v_fmac_f32_e32 v220, v114, v114
	v_fmac_f32_e32 v221, v122, v122
	v_fmac_f32_e32 v220, v115, v115
	v_fmac_f32_e32 v221, v123, v123
	v_fmac_f32_e32 v220, v116, v116
	v_fmac_f32_e32 v221, v124, v124
	v_fmac_f32_e32 v220, v117, v117
	v_fmac_f32_e32 v221, v125, v125
	v_fmac_f32_e32 v220, v118, v118
	v_fmac_f32_e32 v221, v126, v126
	v_fmac_f32_e32 v220, v119, v119
	v_fmac_f32_e32 v221, v127, v127
	v_add_f32_e32 v112, v220, v221
	s_add_u32 s24, s24, 0xb0000
	s_addc_u32 s25, s25, 0
	global_load_dwordx4 v[130:133], v218, s[24:25]
	global_load_dwordx4 v[134:137], v218, s[24:25] offset:256
	s_mov_b32 s24, s8
	s_mov_b32 s25, s9
	s_waitcnt vmcnt(14)
	v_and_b32_e32 v220, 0xffff0000, v148
	v_lshlrev_b32_e32 v148, 16, v148
	v_and_b32_e32 v221, 0xffff0000, v149
	v_lshlrev_b32_e32 v149, 16, v149
	v_and_b32_e32 v222, 0xffff0000, v150
	v_lshlrev_b32_e32 v150, 16, v150
	v_and_b32_e32 v223, 0xffff0000, v151
	v_lshlrev_b32_e32 v151, 16, v151
	v_add_f32_e32 v108, v108, v148
	v_add_f32_e32 v109, v109, v220
	v_add_f32_e32 v110, v110, v149
	v_add_f32_e32 v111, v111, v221
	v_add_f32_e32 v104, v104, v150
	v_add_f32_e32 v105, v105, v222
	v_add_f32_e32 v106, v106, v151
	v_add_f32_e32 v107, v107, v223
	v_cvt_pk_bf16_f32 v148, v108, v109
	v_cvt_pk_bf16_f32 v149, v110, v111
	v_cvt_pk_bf16_f32 v150, v104, v105
	v_cvt_pk_bf16_f32 v151, v106, v107
	v_and_b32_e32 v220, 0xffff0000, v152
	v_lshlrev_b32_e32 v152, 16, v152
	v_and_b32_e32 v221, 0xffff0000, v153
	v_lshlrev_b32_e32 v153, 16, v153
	v_and_b32_e32 v222, 0xffff0000, v154
	v_lshlrev_b32_e32 v154, 16, v154
	v_and_b32_e32 v223, 0xffff0000, v155
	v_lshlrev_b32_e32 v155, 16, v155
	v_add_f32_e32 v100, v100, v152
	v_add_f32_e32 v101, v101, v220
	v_add_f32_e32 v102, v102, v153
	v_add_f32_e32 v103, v103, v221
	v_add_f32_e32 v96, v96, v154
	v_add_f32_e32 v97, v97, v222
	v_add_f32_e32 v98, v98, v155
	v_add_f32_e32 v99, v99, v223
	v_cvt_pk_bf16_f32 v152, v100, v101
	v_cvt_pk_bf16_f32 v153, v102, v103
	v_cvt_pk_bf16_f32 v154, v96, v97
	v_cvt_pk_bf16_f32 v155, v98, v99
	s_add_u32 s24, s24, 0x10000
	s_addc_u32 s25, s25, 0
	global_store_dwordx4 v218, v[148:151], s[24:25]
	global_store_dwordx4 v218, v[152:155], s[24:25] offset:256
	v_mul_f32_e32 v220, v96, v96
	v_mul_f32_e32 v221, v104, v104
	v_fmac_f32_e32 v220, v97, v97
	v_fmac_f32_e32 v221, v105, v105
	v_fmac_f32_e32 v220, v98, v98
	v_fmac_f32_e32 v221, v106, v106
	v_fmac_f32_e32 v220, v99, v99
	v_fmac_f32_e32 v221, v107, v107
	v_fmac_f32_e32 v220, v100, v100
	v_fmac_f32_e32 v221, v108, v108
	v_fmac_f32_e32 v220, v101, v101
	v_fmac_f32_e32 v221, v109, v109
	v_fmac_f32_e32 v220, v102, v102
	v_fmac_f32_e32 v221, v110, v110
	v_fmac_f32_e32 v220, v103, v103
	v_fmac_f32_e32 v221, v111, v111
	v_add_f32_e32 v96, v220, v221
	s_waitcnt vmcnt(14)
	v_and_b32_e32 v220, 0xffff0000, v160
	v_lshlrev_b32_e32 v160, 16, v160
	v_and_b32_e32 v221, 0xffff0000, v161
	v_lshlrev_b32_e32 v161, 16, v161
	v_and_b32_e32 v222, 0xffff0000, v162
	v_lshlrev_b32_e32 v162, 16, v162
	v_and_b32_e32 v223, 0xffff0000, v163
	v_lshlrev_b32_e32 v163, 16, v163
	v_add_f32_e32 v92, v92, v160
	v_add_f32_e32 v93, v93, v220
	v_add_f32_e32 v94, v94, v161
	v_add_f32_e32 v95, v95, v221
	v_add_f32_e32 v88, v88, v162
	v_add_f32_e32 v89, v89, v222
	v_add_f32_e32 v90, v90, v163
	v_add_f32_e32 v91, v91, v223
	v_cvt_pk_bf16_f32 v160, v92, v93
	v_cvt_pk_bf16_f32 v161, v94, v95
	v_cvt_pk_bf16_f32 v162, v88, v89
	v_cvt_pk_bf16_f32 v163, v90, v91
	v_and_b32_e32 v220, 0xffff0000, v164
	v_lshlrev_b32_e32 v164, 16, v164
	v_and_b32_e32 v221, 0xffff0000, v165
	v_lshlrev_b32_e32 v165, 16, v165
	v_and_b32_e32 v222, 0xffff0000, v166
	v_lshlrev_b32_e32 v166, 16, v166
	v_and_b32_e32 v223, 0xffff0000, v167
	v_lshlrev_b32_e32 v167, 16, v167
	v_add_f32_e32 v84, v84, v164
	v_add_f32_e32 v85, v85, v220
	v_add_f32_e32 v86, v86, v165
	v_add_f32_e32 v87, v87, v221
	v_add_f32_e32 v80, v80, v166
	v_add_f32_e32 v81, v81, v222
	v_add_f32_e32 v82, v82, v167
	v_add_f32_e32 v83, v83, v223
	v_cvt_pk_bf16_f32 v164, v84, v85
	v_cvt_pk_bf16_f32 v165, v86, v87
	v_cvt_pk_bf16_f32 v166, v80, v81
	v_cvt_pk_bf16_f32 v167, v82, v83
	s_add_u32 s24, s24, 0x10000
	s_addc_u32 s25, s25, 0
	global_store_dwordx4 v218, v[160:163], s[24:25]
	global_store_dwordx4 v218, v[164:167], s[24:25] offset:256
	v_mul_f32_e32 v220, v80, v80
	v_mul_f32_e32 v221, v88, v88
	v_fmac_f32_e32 v220, v81, v81
	v_fmac_f32_e32 v221, v89, v89
	v_fmac_f32_e32 v220, v82, v82
	v_fmac_f32_e32 v221, v90, v90
	v_fmac_f32_e32 v220, v83, v83
	v_fmac_f32_e32 v221, v91, v91
	v_fmac_f32_e32 v220, v84, v84
	v_fmac_f32_e32 v221, v92, v92
	v_fmac_f32_e32 v220, v85, v85
	v_fmac_f32_e32 v221, v93, v93
	v_fmac_f32_e32 v220, v86, v86
	v_fmac_f32_e32 v221, v94, v94
	v_fmac_f32_e32 v220, v87, v87
	v_fmac_f32_e32 v221, v95, v95
	v_add_f32_e32 v80, v220, v221
	s_waitcnt vmcnt(14)
	v_and_b32_e32 v220, 0xffff0000, v168
	v_lshlrev_b32_e32 v168, 16, v168
	v_and_b32_e32 v221, 0xffff0000, v169
	v_lshlrev_b32_e32 v169, 16, v169
	v_and_b32_e32 v222, 0xffff0000, v170
	v_lshlrev_b32_e32 v170, 16, v170
	v_and_b32_e32 v223, 0xffff0000, v171
	v_lshlrev_b32_e32 v171, 16, v171
	v_add_f32_e32 v76, v76, v168
	v_add_f32_e32 v77, v77, v220
	v_add_f32_e32 v78, v78, v169
	v_add_f32_e32 v79, v79, v221
	v_add_f32_e32 v72, v72, v170
	v_add_f32_e32 v73, v73, v222
	v_add_f32_e32 v74, v74, v171
	v_add_f32_e32 v75, v75, v223
	v_cvt_pk_bf16_f32 v168, v76, v77
	v_cvt_pk_bf16_f32 v169, v78, v79
	v_cvt_pk_bf16_f32 v170, v72, v73
	v_cvt_pk_bf16_f32 v171, v74, v75
	v_and_b32_e32 v220, 0xffff0000, v172
	v_lshlrev_b32_e32 v172, 16, v172
	v_and_b32_e32 v221, 0xffff0000, v173
	v_lshlrev_b32_e32 v173, 16, v173
	v_and_b32_e32 v222, 0xffff0000, v174
	v_lshlrev_b32_e32 v174, 16, v174
	v_and_b32_e32 v223, 0xffff0000, v175
	v_lshlrev_b32_e32 v175, 16, v175
	v_add_f32_e32 v68, v68, v172
	v_add_f32_e32 v69, v69, v220
	v_add_f32_e32 v70, v70, v173
	v_add_f32_e32 v71, v71, v221
	v_add_f32_e32 v64, v64, v174
	v_add_f32_e32 v65, v65, v222
	v_add_f32_e32 v66, v66, v175
	v_add_f32_e32 v67, v67, v223
	v_cvt_pk_bf16_f32 v172, v68, v69
	v_cvt_pk_bf16_f32 v173, v70, v71
	v_cvt_pk_bf16_f32 v174, v64, v65
	v_cvt_pk_bf16_f32 v175, v66, v67
	s_add_u32 s24, s24, 0x10000
	s_addc_u32 s25, s25, 0
	global_store_dwordx4 v218, v[168:171], s[24:25]
	global_store_dwordx4 v218, v[172:175], s[24:25] offset:256
	v_mul_f32_e32 v220, v64, v64
	v_mul_f32_e32 v221, v72, v72
	v_fmac_f32_e32 v220, v65, v65
	v_fmac_f32_e32 v221, v73, v73
	v_fmac_f32_e32 v220, v66, v66
	v_fmac_f32_e32 v221, v74, v74
	v_fmac_f32_e32 v220, v67, v67
	v_fmac_f32_e32 v221, v75, v75
	v_fmac_f32_e32 v220, v68, v68
	v_fmac_f32_e32 v221, v76, v76
	v_fmac_f32_e32 v220, v69, v69
	v_fmac_f32_e32 v221, v77, v77
	v_fmac_f32_e32 v220, v70, v70
	v_fmac_f32_e32 v221, v78, v78
	v_fmac_f32_e32 v220, v71, v71
	v_fmac_f32_e32 v221, v79, v79
	v_add_f32_e32 v64, v220, v221
	s_waitcnt vmcnt(14)
	v_and_b32_e32 v220, 0xffff0000, v176
	v_lshlrev_b32_e32 v176, 16, v176
	v_and_b32_e32 v221, 0xffff0000, v177
	v_lshlrev_b32_e32 v177, 16, v177
	v_and_b32_e32 v222, 0xffff0000, v178
	v_lshlrev_b32_e32 v178, 16, v178
	v_and_b32_e32 v223, 0xffff0000, v179
	v_lshlrev_b32_e32 v179, 16, v179
	v_add_f32_e32 v60, v60, v176
	v_add_f32_e32 v61, v61, v220
	v_add_f32_e32 v62, v62, v177
	v_add_f32_e32 v63, v63, v221
	v_add_f32_e32 v56, v56, v178
	v_add_f32_e32 v57, v57, v222
	v_add_f32_e32 v58, v58, v179
	v_add_f32_e32 v59, v59, v223
	v_cvt_pk_bf16_f32 v176, v60, v61
	v_cvt_pk_bf16_f32 v177, v62, v63
	v_cvt_pk_bf16_f32 v178, v56, v57
	v_cvt_pk_bf16_f32 v179, v58, v59
	v_and_b32_e32 v220, 0xffff0000, v180
	v_lshlrev_b32_e32 v180, 16, v180
	v_and_b32_e32 v221, 0xffff0000, v181
	v_lshlrev_b32_e32 v181, 16, v181
	v_and_b32_e32 v222, 0xffff0000, v182
	v_lshlrev_b32_e32 v182, 16, v182
	v_and_b32_e32 v223, 0xffff0000, v183
	v_lshlrev_b32_e32 v183, 16, v183
	v_add_f32_e32 v52, v52, v180
	v_add_f32_e32 v53, v53, v220
	v_add_f32_e32 v54, v54, v181
	v_add_f32_e32 v55, v55, v221
	v_add_f32_e32 v48, v48, v182
	v_add_f32_e32 v49, v49, v222
	v_add_f32_e32 v50, v50, v183
	v_add_f32_e32 v51, v51, v223
	v_cvt_pk_bf16_f32 v180, v52, v53
	v_cvt_pk_bf16_f32 v181, v54, v55
	v_cvt_pk_bf16_f32 v182, v48, v49
	v_cvt_pk_bf16_f32 v183, v50, v51
	s_add_u32 s24, s24, 0x50000
	s_addc_u32 s25, s25, 0
	global_store_dwordx4 v218, v[176:179], s[24:25]
	global_store_dwordx4 v218, v[180:183], s[24:25] offset:256
	v_mul_f32_e32 v220, v48, v48
	v_mul_f32_e32 v221, v56, v56
	v_fmac_f32_e32 v220, v49, v49
	v_fmac_f32_e32 v221, v57, v57
	v_fmac_f32_e32 v220, v50, v50
	v_fmac_f32_e32 v221, v58, v58
	v_fmac_f32_e32 v220, v51, v51
	v_fmac_f32_e32 v221, v59, v59
	v_fmac_f32_e32 v220, v52, v52
	v_fmac_f32_e32 v221, v60, v60
	v_fmac_f32_e32 v220, v53, v53
	v_fmac_f32_e32 v221, v61, v61
	v_fmac_f32_e32 v220, v54, v54
	v_fmac_f32_e32 v221, v62, v62
	v_fmac_f32_e32 v220, v55, v55
	v_fmac_f32_e32 v221, v63, v63
	v_add_f32_e32 v48, v220, v221
	s_waitcnt vmcnt(14)
	v_and_b32_e32 v220, 0xffff0000, v192
	v_lshlrev_b32_e32 v192, 16, v192
	v_and_b32_e32 v221, 0xffff0000, v193
	v_lshlrev_b32_e32 v193, 16, v193
	v_and_b32_e32 v222, 0xffff0000, v194
	v_lshlrev_b32_e32 v194, 16, v194
	v_and_b32_e32 v223, 0xffff0000, v195
	v_lshlrev_b32_e32 v195, 16, v195
	v_add_f32_e32 v44, v44, v192
	v_add_f32_e32 v45, v45, v220
	v_add_f32_e32 v46, v46, v193
	v_add_f32_e32 v47, v47, v221
	v_add_f32_e32 v40, v40, v194
	v_add_f32_e32 v41, v41, v222
	v_add_f32_e32 v42, v42, v195
	v_add_f32_e32 v43, v43, v223
	v_cvt_pk_bf16_f32 v192, v44, v45
	v_cvt_pk_bf16_f32 v193, v46, v47
	v_cvt_pk_bf16_f32 v194, v40, v41
	v_cvt_pk_bf16_f32 v195, v42, v43
	v_and_b32_e32 v220, 0xffff0000, v196
	v_lshlrev_b32_e32 v196, 16, v196
	v_and_b32_e32 v221, 0xffff0000, v197
	v_lshlrev_b32_e32 v197, 16, v197
	v_and_b32_e32 v222, 0xffff0000, v198
	v_lshlrev_b32_e32 v198, 16, v198
	v_and_b32_e32 v223, 0xffff0000, v199
	v_lshlrev_b32_e32 v199, 16, v199
	v_add_f32_e32 v36, v36, v196
	v_add_f32_e32 v37, v37, v220
	v_add_f32_e32 v38, v38, v197
	v_add_f32_e32 v39, v39, v221
	v_add_f32_e32 v32, v32, v198
	v_add_f32_e32 v33, v33, v222
	v_add_f32_e32 v34, v34, v199
	v_add_f32_e32 v35, v35, v223
	v_cvt_pk_bf16_f32 v196, v36, v37
	v_cvt_pk_bf16_f32 v197, v38, v39
	v_cvt_pk_bf16_f32 v198, v32, v33
	v_cvt_pk_bf16_f32 v199, v34, v35
	s_add_u32 s24, s24, 0x10000
	s_addc_u32 s25, s25, 0
	global_store_dwordx4 v218, v[192:195], s[24:25]
	global_store_dwordx4 v218, v[196:199], s[24:25] offset:256
	v_mul_f32_e32 v220, v32, v32
	v_mul_f32_e32 v221, v40, v40
	v_fmac_f32_e32 v220, v33, v33
	v_fmac_f32_e32 v221, v41, v41
	v_fmac_f32_e32 v220, v34, v34
	v_fmac_f32_e32 v221, v42, v42
	v_fmac_f32_e32 v220, v35, v35
	v_fmac_f32_e32 v221, v43, v43
	v_fmac_f32_e32 v220, v36, v36
	v_fmac_f32_e32 v221, v44, v44
	v_fmac_f32_e32 v220, v37, v37
	v_fmac_f32_e32 v221, v45, v45
	v_fmac_f32_e32 v220, v38, v38
	v_fmac_f32_e32 v221, v46, v46
	v_fmac_f32_e32 v220, v39, v39
	v_fmac_f32_e32 v221, v47, v47
	v_add_f32_e32 v32, v220, v221
	s_waitcnt vmcnt(14)
	v_and_b32_e32 v220, 0xffff0000, v200
	v_lshlrev_b32_e32 v200, 16, v200
	v_and_b32_e32 v221, 0xffff0000, v201
	v_lshlrev_b32_e32 v201, 16, v201
	v_and_b32_e32 v222, 0xffff0000, v202
	v_lshlrev_b32_e32 v202, 16, v202
	v_and_b32_e32 v223, 0xffff0000, v203
	v_lshlrev_b32_e32 v203, 16, v203
	v_add_f32_e32 v28, v28, v200
	v_add_f32_e32 v29, v29, v220
	v_add_f32_e32 v30, v30, v201
	v_add_f32_e32 v31, v31, v221
	v_add_f32_e32 v24, v24, v202
	v_add_f32_e32 v25, v25, v222
	v_add_f32_e32 v26, v26, v203
	v_add_f32_e32 v27, v27, v223
	v_cvt_pk_bf16_f32 v200, v28, v29
	v_cvt_pk_bf16_f32 v201, v30, v31
	v_cvt_pk_bf16_f32 v202, v24, v25
	v_cvt_pk_bf16_f32 v203, v26, v27
	v_and_b32_e32 v220, 0xffff0000, v204
	v_lshlrev_b32_e32 v204, 16, v204
	v_and_b32_e32 v221, 0xffff0000, v205
	v_lshlrev_b32_e32 v205, 16, v205
	v_and_b32_e32 v222, 0xffff0000, v206
	v_lshlrev_b32_e32 v206, 16, v206
	v_and_b32_e32 v223, 0xffff0000, v207
	v_lshlrev_b32_e32 v207, 16, v207
	v_add_f32_e32 v20, v20, v204
	v_add_f32_e32 v21, v21, v220
	v_add_f32_e32 v22, v22, v205
	v_add_f32_e32 v23, v23, v221
	v_add_f32_e32 v16, v16, v206
	v_add_f32_e32 v17, v17, v222
	v_add_f32_e32 v18, v18, v207
	v_add_f32_e32 v19, v19, v223
	v_cvt_pk_bf16_f32 v204, v20, v21
	v_cvt_pk_bf16_f32 v205, v22, v23
	v_cvt_pk_bf16_f32 v206, v16, v17
	v_cvt_pk_bf16_f32 v207, v18, v19
	s_add_u32 s24, s24, 0x10000
	s_addc_u32 s25, s25, 0
	global_store_dwordx4 v218, v[200:203], s[24:25]
	global_store_dwordx4 v218, v[204:207], s[24:25] offset:256
	v_mul_f32_e32 v220, v16, v16
	v_mul_f32_e32 v221, v24, v24
	v_fmac_f32_e32 v220, v17, v17
	v_fmac_f32_e32 v221, v25, v25
	v_fmac_f32_e32 v220, v18, v18
	v_fmac_f32_e32 v221, v26, v26
	v_fmac_f32_e32 v220, v19, v19
	v_fmac_f32_e32 v221, v27, v27
	v_fmac_f32_e32 v220, v20, v20
	v_fmac_f32_e32 v221, v28, v28
	v_fmac_f32_e32 v220, v21, v21
	v_fmac_f32_e32 v221, v29, v29
	v_fmac_f32_e32 v220, v22, v22
	v_fmac_f32_e32 v221, v30, v30
	v_fmac_f32_e32 v220, v23, v23
	v_fmac_f32_e32 v221, v31, v31
	v_add_f32_e32 v16, v220, v221
	s_waitcnt vmcnt(12)
	v_and_b32_e32 v220, 0xffff0000, v130
	v_lshlrev_b32_e32 v130, 16, v130
	v_and_b32_e32 v221, 0xffff0000, v131
	v_lshlrev_b32_e32 v131, 16, v131
	v_and_b32_e32 v222, 0xffff0000, v132
	v_lshlrev_b32_e32 v132, 16, v132
	v_and_b32_e32 v223, 0xffff0000, v133
	v_lshlrev_b32_e32 v133, 16, v133
	v_add_f32_e32 v12, v12, v130
	v_add_f32_e32 v13, v13, v220
	v_add_f32_e32 v14, v14, v131
	v_add_f32_e32 v15, v15, v221
	v_add_f32_e32 v8, v8, v132
	v_add_f32_e32 v9, v9, v222
	v_add_f32_e32 v10, v10, v133
	v_add_f32_e32 v11, v11, v223
	v_cvt_pk_bf16_f32 v130, v12, v13
	v_cvt_pk_bf16_f32 v131, v14, v15
	v_cvt_pk_bf16_f32 v132, v8, v9
	v_cvt_pk_bf16_f32 v133, v10, v11
	v_and_b32_e32 v220, 0xffff0000, v134
	v_lshlrev_b32_e32 v134, 16, v134
	v_and_b32_e32 v221, 0xffff0000, v135
	v_lshlrev_b32_e32 v135, 16, v135
	v_and_b32_e32 v222, 0xffff0000, v136
	v_lshlrev_b32_e32 v136, 16, v136
	v_and_b32_e32 v223, 0xffff0000, v137
	v_lshlrev_b32_e32 v137, 16, v137
	v_add_f32_e32 v4, v4, v134
	v_add_f32_e32 v5, v5, v220
	v_add_f32_e32 v6, v6, v135
	v_add_f32_e32 v7, v7, v221
	v_add_f32_e32 v0, v0, v136
	v_add_f32_e32 v1, v1, v222
	v_add_f32_e32 v2, v2, v137
	v_add_f32_e32 v3, v3, v223
	v_cvt_pk_bf16_f32 v134, v4, v5
	v_cvt_pk_bf16_f32 v135, v6, v7
	v_cvt_pk_bf16_f32 v136, v0, v1
	v_cvt_pk_bf16_f32 v137, v2, v3
	s_add_u32 s24, s24, 0x10000
	s_addc_u32 s25, s25, 0
	global_store_dwordx4 v218, v[130:133], s[24:25]
	global_store_dwordx4 v218, v[134:137], s[24:25] offset:256
	v_mul_f32_e32 v220, v0, v0
	v_mul_f32_e32 v221, v8, v8
	v_fmac_f32_e32 v220, v1, v1
	v_fmac_f32_e32 v221, v9, v9
	v_fmac_f32_e32 v220, v2, v2
	v_fmac_f32_e32 v221, v10, v10
	v_fmac_f32_e32 v220, v3, v3
	v_fmac_f32_e32 v221, v11, v11
	v_fmac_f32_e32 v220, v4, v4
	v_fmac_f32_e32 v221, v12, v12
	v_fmac_f32_e32 v220, v5, v5
	v_fmac_f32_e32 v221, v13, v13
	v_fmac_f32_e32 v220, v6, v6
	v_fmac_f32_e32 v221, v14, v14
	v_fmac_f32_e32 v220, v7, v7
	v_fmac_f32_e32 v221, v15, v15
	v_add_f32_e32 v0, v220, v221
	v_xor_b32_e32 v222, 16, v214
	v_xor_b32_e32 v223, 32, v214
	v_lshlrev_b32_e32 v222, 2, v222
	v_lshlrev_b32_e32 v223, 2, v223
	ds_bpermute_b32 v113, v222, v112
	ds_bpermute_b32 v97, v222, v96
	ds_bpermute_b32 v81, v222, v80
	ds_bpermute_b32 v65, v222, v64
	ds_bpermute_b32 v49, v222, v48
	ds_bpermute_b32 v33, v222, v32
	ds_bpermute_b32 v17, v222, v16
	ds_bpermute_b32 v1, v222, v0
	s_waitcnt lgkmcnt(0)
	v_add_f32_e32 v112, v112, v113
	v_add_f32_e32 v96, v96, v97
	v_add_f32_e32 v80, v80, v81
	v_add_f32_e32 v64, v64, v65
	v_add_f32_e32 v48, v48, v49
	v_add_f32_e32 v32, v32, v33
	v_add_f32_e32 v16, v16, v17
	v_add_f32_e32 v0, v0, v1
	ds_bpermute_b32 v113, v223, v112
	ds_bpermute_b32 v97, v223, v96
	ds_bpermute_b32 v81, v223, v80
	ds_bpermute_b32 v65, v223, v64
	ds_bpermute_b32 v49, v223, v48
	ds_bpermute_b32 v33, v223, v32
	ds_bpermute_b32 v17, v223, v16
	ds_bpermute_b32 v1, v223, v0
	s_waitcnt lgkmcnt(0)
	v_add_f32_e32 v112, v112, v113
	v_add_f32_e32 v96, v96, v97
	v_add_f32_e32 v80, v80, v81
	v_add_f32_e32 v64, v64, v65
	v_add_f32_e32 v48, v48, v49
	v_add_f32_e32 v32, v32, v33
	v_add_f32_e32 v16, v16, v17
	v_add_f32_e32 v0, v0, v1
	s_mov_b32 s24, s6
	s_mov_b32 s25, s7
	s_and_saveexec_b64 s[26:27], s[2:3]
	global_store_dword v219, v112, s[24:25]
	global_store_dword v219, v96, s[24:25] offset:2048
	s_add_u32 s24, s24, 0x1000
	s_addc_u32 s25, s25, 0
	global_store_dword v219, v80, s[24:25]
	global_store_dword v219, v64, s[24:25] offset:2048
	s_add_u32 s24, s24, 0x3000
	s_addc_u32 s25, s25, 0
	global_store_dword v219, v48, s[24:25]
	global_store_dword v219, v32, s[24:25] offset:2048
	s_add_u32 s24, s24, 0x1000
	s_addc_u32 s25, s25, 0
	global_store_dword v219, v16, s[24:25]
	global_store_dword v219, v0, s[24:25] offset:2048
	s_or_b64 exec, exec, s[26:27]
	s_andn2_b64 vcc, exec, s[4:5]
	s_mov_b64 s[4:5], -1
	s_cbranch_vccnz .LBB0_764
	s_andn2_b64 vcc, exec, s[12:13]
	s_cbranch_vccnz .LBB0_763
	s_barrier
	s_branch .LBB0_763

.LBB0_797:
	v_lshl_add_u64 v[68:69], v[66:67], 0, s[10:11]
	s_mov_b32 s5, 0x3f5d0000
	v_add_co_u32_e32 v78, vcc, s5, v68
	s_mov_b32 s12, 0x3f5e0000
	s_nop 0
	v_addc_co_u32_e32 v79, vcc, 0, v69, vcc
	v_add_co_u32_e32 v74, vcc, s12, v68
	s_mov_b32 s13, 0x3f5f0000
	s_nop 0
	v_addc_co_u32_e32 v75, vcc, 0, v69, vcc
	v_add_co_u32_e32 v72, vcc, s13, v68
	s_mov_b32 s14, 0x3f600000
	s_nop 0
	v_addc_co_u32_e32 v73, vcc, 0, v69, vcc
	v_add_co_u32_e32 v70, vcc, s14, v68
	v_lshl_add_u64 v[126:127], v[64:65], 0, s[10:11]
	s_mov_b32 s15, 0x6008000
	v_addc_co_u32_e32 v71, vcc, 0, v69, vcc
	v_add_co_u32_e32 v76, vcc, s15, v126
	s_mov_b32 s16, 0x6018000
	s_nop 0
	v_addc_co_u32_e32 v77, vcc, 0, v127, vcc
	global_load_dwordx4 v[82:85], v[76:77], off
	global_load_dwordx4 v[86:89], v[78:79], off
	global_load_dwordx4 v[90:93], v[78:79], off offset:64
	global_load_dwordx4 v[94:97], v[76:77], off offset:64
	global_load_dwordx4 v[98:101], v[74:75], off
	global_load_dwordx4 v[102:105], v[74:75], off offset:64
	global_load_dwordx4 v[106:109], v[72:73], off
	global_load_dwordx4 v[110:113], v[72:73], off offset:64
	global_load_dwordx4 v[114:117], v[70:71], off
	global_load_dwordx4 v[118:121], v[70:71], off offset:64
	v_add_co_u32_e32 v68, vcc, s16, v126
	s_mov_b32 s5, 0x6088000
	s_nop 0
	v_addc_co_u32_e32 v69, vcc, 0, v127, vcc
	v_add_co_u32_e32 v138, vcc, s5, v126
	s_mov_b32 s5, 0x6098000
	s_nop 0
	v_addc_co_u32_e32 v139, vcc, 0, v127, vcc
	v_add_co_u32_e32 v126, vcc, s5, v126
	s_add_u32 s10, s10, 0x100
	s_nop 0
	v_addc_co_u32_e32 v127, vcc, 0, v127, vcc
	s_addc_u32 s11, s11, 0
	s_cmpk_eq_i32 s10, 0x200
	s_waitcnt vmcnt(0) lgkmcnt(0)
	v_mfma_f32_16x16x32_bf16 v[56:59], v[82:85], v[86:89], v[56:59]
	v_mfma_f32_16x16x32_bf16 v[52:55], v[82:85], v[98:101], v[52:55]
	v_mfma_f32_16x16x32_bf16 v[48:51], v[82:85], v[106:109], v[48:51]
	v_mfma_f32_16x16x32_bf16 v[44:47], v[82:85], v[114:117], v[44:47]
	global_load_dwordx4 v[82:85], v[68:69], off
	global_load_dwordx4 v[122:125], v[68:69], off offset:64
	v_mfma_f32_16x16x32_bf16 v[56:59], v[94:97], v[90:93], v[56:59]
	v_mfma_f32_16x16x32_bf16 v[52:55], v[94:97], v[102:105], v[52:55]
	v_mfma_f32_16x16x32_bf16 v[48:51], v[94:97], v[110:113], v[48:51]
	v_mfma_f32_16x16x32_bf16 v[44:47], v[94:97], v[118:121], v[44:47]
	s_waitcnt vmcnt(0) lgkmcnt(0)
	v_mfma_f32_16x16x32_bf16 v[12:15], v[82:85], v[86:89], v[12:15]
	v_mfma_f32_16x16x32_bf16 v[8:11], v[82:85], v[98:101], v[8:11]
	v_mfma_f32_16x16x32_bf16 v[4:7], v[82:85], v[106:109], v[4:7]
	v_mfma_f32_16x16x32_bf16 v[0:3], v[82:85], v[114:117], v[0:3]
	global_load_dwordx4 v[82:85], v[138:139], off
	global_load_dwordx4 v[130:133], v[138:139], off offset:64
	global_load_dwordx4 v[134:137], v[126:127], off
	v_mfma_f32_16x16x32_bf16 v[12:15], v[122:125], v[90:93], v[12:15]
	v_mfma_f32_16x16x32_bf16 v[8:11], v[122:125], v[102:105], v[8:11]
	v_mfma_f32_16x16x32_bf16 v[4:7], v[122:125], v[110:113], v[4:7]
	v_mfma_f32_16x16x32_bf16 v[0:3], v[122:125], v[118:121], v[0:3]
	s_waitcnt vmcnt(0) lgkmcnt(0)
	v_mfma_f32_16x16x32_bf16 v[16:19], v[82:85], v[86:89], v[16:19]
	v_mfma_f32_16x16x32_bf16 v[24:27], v[82:85], v[98:101], v[24:27]
	v_mfma_f32_16x16x32_bf16 v[28:31], v[82:85], v[106:109], v[28:31]
	v_mfma_f32_16x16x32_bf16 v[36:39], v[82:85], v[114:117], v[36:39]
	global_load_dwordx4 v[82:85], v[126:127], off offset:64
	v_mfma_f32_16x16x32_bf16 v[20:23], v[134:137], v[86:89], v[20:23]
	global_load_dwordx4 v[86:89], v[76:77], off offset:128
	v_mfma_f32_16x16x32_bf16 v[32:35], v[134:137], v[98:101], v[32:35]
	v_mfma_f32_16x16x32_bf16 v[40:43], v[134:137], v[106:109], v[40:43]
	v_mfma_f32_16x16x32_bf16 v[60:63], v[134:137], v[114:117], v[60:63]
	v_mfma_f32_16x16x32_bf16 v[16:19], v[130:133], v[90:93], v[16:19]
	v_mfma_f32_16x16x32_bf16 v[24:27], v[130:133], v[102:105], v[24:27]
	v_mfma_f32_16x16x32_bf16 v[28:31], v[130:133], v[110:113], v[28:31]
	s_waitcnt vmcnt(0) lgkmcnt(0)
	v_mfma_f32_16x16x32_bf16 v[20:23], v[82:85], v[90:93], v[20:23]
	v_mfma_f32_16x16x32_bf16 v[32:35], v[82:85], v[102:105], v[32:35]
	v_mfma_f32_16x16x32_bf16 v[40:43], v[82:85], v[110:113], v[40:43]
	v_mfma_f32_16x16x32_bf16 v[60:63], v[82:85], v[118:121], v[60:63]
	global_load_dwordx4 v[82:85], v[78:79], off offset:128
	global_load_dwordx4 v[90:93], v[78:79], off offset:192
	s_nop 0
	global_load_dwordx4 v[76:79], v[76:77], off offset:192
	s_nop 0
	global_load_dwordx4 v[94:97], v[74:75], off offset:128
	global_load_dwordx4 v[98:101], v[74:75], off offset:192
	global_load_dwordx4 v[102:105], v[72:73], off offset:128
	s_nop 0
	global_load_dwordx4 v[72:75], v[72:73], off offset:192
	s_nop 0
	global_load_dwordx4 v[106:109], v[70:71], off offset:128
	global_load_dwordx4 v[110:113], v[70:71], off offset:192
	v_mfma_f32_16x16x32_bf16 v[36:39], v[130:133], v[118:121], v[36:39]
	s_waitcnt vmcnt(0) lgkmcnt(0)
	v_mfma_f32_16x16x32_bf16 v[56:59], v[86:89], v[82:85], v[56:59]
	v_mfma_f32_16x16x32_bf16 v[52:55], v[86:89], v[94:97], v[52:55]
	v_mfma_f32_16x16x32_bf16 v[48:51], v[86:89], v[102:105], v[48:51]
	v_mfma_f32_16x16x32_bf16 v[44:47], v[86:89], v[106:109], v[44:47]
	global_load_dwordx4 v[86:89], v[68:69], off offset:128
	s_nop 0
	global_load_dwordx4 v[68:71], v[68:69], off offset:192
	s_waitcnt vmcnt(0) lgkmcnt(0)
	v_mfma_f32_16x16x32_bf16 v[12:15], v[86:89], v[82:85], v[12:15]
	v_mfma_f32_16x16x32_bf16 v[8:11], v[86:89], v[94:97], v[8:11]
	v_mfma_f32_16x16x32_bf16 v[4:7], v[86:89], v[102:105], v[4:7]
	v_mfma_f32_16x16x32_bf16 v[0:3], v[86:89], v[106:109], v[0:3]
	global_load_dwordx4 v[86:89], v[138:139], off offset:128
	global_load_dwordx4 v[114:117], v[138:139], off offset:192
	global_load_dwordx4 v[118:121], v[126:127], off offset:128
	s_waitcnt vmcnt(0) lgkmcnt(0)
	v_mfma_f32_16x16x32_bf16 v[16:19], v[86:89], v[82:85], v[16:19]
	v_mfma_f32_16x16x32_bf16 v[24:27], v[86:89], v[94:97], v[24:27]
	v_mfma_f32_16x16x32_bf16 v[28:31], v[86:89], v[102:105], v[28:31]
	v_mfma_f32_16x16x32_bf16 v[36:39], v[86:89], v[106:109], v[36:39]
	global_load_dwordx4 v[86:89], v[126:127], off offset:192
	v_mfma_f32_16x16x32_bf16 v[20:23], v[118:121], v[82:85], v[20:23]
	v_mfma_f32_16x16x32_bf16 v[32:35], v[118:121], v[94:97], v[32:35]
	v_mfma_f32_16x16x32_bf16 v[40:43], v[118:121], v[102:105], v[40:43]
	v_mfma_f32_16x16x32_bf16 v[60:63], v[118:121], v[106:109], v[60:63]
	v_mfma_f32_16x16x32_bf16 v[56:59], v[76:79], v[90:93], v[56:59]
	v_mfma_f32_16x16x32_bf16 v[52:55], v[76:79], v[98:101], v[52:55]
	v_mfma_f32_16x16x32_bf16 v[48:51], v[76:79], v[72:75], v[48:51]
	v_mfma_f32_16x16x32_bf16 v[44:47], v[76:79], v[110:113], v[44:47]
	v_mfma_f32_16x16x32_bf16 v[12:15], v[68:71], v[90:93], v[12:15]
	v_mfma_f32_16x16x32_bf16 v[8:11], v[68:71], v[98:101], v[8:11]
	v_mfma_f32_16x16x32_bf16 v[4:7], v[68:71], v[72:75], v[4:7]
	v_mfma_f32_16x16x32_bf16 v[0:3], v[68:71], v[110:113], v[0:3]
	v_mfma_f32_16x16x32_bf16 v[16:19], v[114:117], v[90:93], v[16:19]
	v_mfma_f32_16x16x32_bf16 v[24:27], v[114:117], v[98:101], v[24:27]
	v_mfma_f32_16x16x32_bf16 v[28:31], v[114:117], v[72:75], v[28:31]
	v_mfma_f32_16x16x32_bf16 v[36:39], v[114:117], v[110:113], v[36:39]
	s_waitcnt vmcnt(0) lgkmcnt(0)
	v_mfma_f32_16x16x32_bf16 v[20:23], v[86:89], v[90:93], v[20:23]
	v_mfma_f32_16x16x32_bf16 v[32:35], v[86:89], v[98:101], v[32:35]
	v_mfma_f32_16x16x32_bf16 v[40:43], v[86:89], v[72:75], v[40:43]
	v_mfma_f32_16x16x32_bf16 v[60:63], v[86:89], v[110:113], v[60:63]
	s_cbranch_scc0 .LBB0_797
	v_and_b32_e32 v65, 63, v81
	v_lshl_add_u32 v66, v65, 4, 0
	s_ashr_i32 s10, s0, 7
	v_bfe_u32 v64, v81, 4, 2
	v_lshl_add_u32 v67, s3, 14, v66
	s_lshl_b32 s5, s10, 4
	ds_write_b128 v67, v[56:59]
	ds_write_b128 v67, v[52:55] offset:1024
	ds_write_b128 v67, v[48:51] offset:2048
	ds_write_b128 v67, v[44:47] offset:3072
	ds_write_b128 v67, v[12:15] offset:4096
	ds_write_b128 v67, v[8:11] offset:5120
	ds_write_b128 v67, v[4:7] offset:6144
	ds_write_b128 v67, v[0:3] offset:7168
	ds_write_b128 v67, v[16:19] offset:8192
	ds_write_b128 v67, v[24:27] offset:9216
	ds_write_b128 v67, v[28:31] offset:10240
	ds_write_b128 v67, v[36:39] offset:11264
	ds_write_b128 v67, v[20:23] offset:12288
	ds_write_b128 v67, v[32:35] offset:13312
	ds_write_b128 v67, v[40:43] offset:14336
	ds_write_b128 v67, v[60:63] offset:15360
	s_bfe_u32 s3, s0, 0x10006
	s_addk_i32 s5, 0x4000
	v_lshlrev_b32_e32 v1, 2, v64
	v_or_b32_e32 v0, s5, v80
	v_lshl_or_b32 v1, s3, 4, v1
	v_or_b32_e32 v4, s1, v1
	v_ashrrev_i32_e32 v1, 31, v0
	v_lshlrev_b64 v[2:3], 12, v[0:1]
	s_ashr_i32 s5, s4, 31
	v_lshl_add_u64 v[2:3], s[8:9], 0, v[2:3]
	v_lshl_add_u64 v[2:3], s[4:5], 1, v[2:3]
	v_lshlrev_b32_e32 v128, 1, v4
	v_lshl_add_u64 v[14:15], v[2:3], 0, v[128:129]
	s_waitcnt lgkmcnt(0)
	s_barrier
	global_load_dwordx2 v[16:17], v[14:15], off
	global_load_dwordx2 v[18:19], v[14:15], off offset:256
	s_lshl_b32 s1, s3, 2
	s_add_i32 s1, s1, s10
	v_lshl_add_u32 v28, s1, 10, v66
	ds_read_b128 v[2:5], v28
	ds_read_b128 v[6:9], v28 offset:8192
	ds_read_b128 v[10:13], v28 offset:16384
	v_cmp_gt_u32_e32 vcc, 16, v65
	s_waitcnt lgkmcnt(0)
	v_pk_add_f32 v[20:21], v[4:5], 0 op_sel_hi:[1,0]
	v_pk_add_f32 v[22:23], v[2:3], 0 op_sel_hi:[1,0]
	ds_read_b128 v[2:5], v28 offset:24576
	v_pk_add_f32 v[24:25], v[8:9], 0 op_sel_hi:[1,0]
	v_pk_add_f32 v[26:27], v[6:7], 0 op_sel_hi:[1,0]
	ds_read_b128 v[6:9], v28 offset:32768
	v_pk_add_f32 v[22:23], v[22:23], v[10:11]
	s_waitcnt lgkmcnt(0)
	v_pk_add_f32 v[24:25], v[24:25], v[4:5]
	v_pk_add_f32 v[26:27], v[26:27], v[2:3]
	ds_read_b128 v[2:5], v28 offset:49152
	v_pk_add_f32 v[20:21], v[20:21], v[12:13]
	ds_read_b128 v[10:13], v28 offset:40960
	v_pk_add_f32 v[22:23], v[22:23], v[6:7]
	v_pk_add_f32 v[20:21], v[20:21], v[8:9]
	ds_read_b128 v[6:9], v28 offset:57344
	s_waitcnt lgkmcnt(0)
	v_pk_add_f32 v[22:23], v[22:23], v[2:3]
	v_add_u32_e32 v2, 0x10000, v28
	v_pk_add_f32 v[20:21], v[20:21], v[4:5]
	ds_read_b128 v[2:5], v2
	v_pk_add_f32 v[10:11], v[26:27], v[10:11]
	v_pk_add_f32 v[12:13], v[24:25], v[12:13]
	v_pk_add_f32 v[10:11], v[10:11], v[6:7]
	v_add_u32_e32 v6, 0x12000, v28
	v_pk_add_f32 v[12:13], v[12:13], v[8:9]
	ds_read_b128 v[6:9], v6
	s_waitcnt lgkmcnt(0)
	v_pk_add_f32 v[22:23], v[22:23], v[2:3]
	v_add_u32_e32 v2, 0x14000, v28
	v_pk_add_f32 v[20:21], v[20:21], v[4:5]
	ds_read_b128 v[2:5], v2
	v_pk_add_f32 v[10:11], v[10:11], v[6:7]
	v_add_u32_e32 v6, 0x16000, v28
	v_pk_add_f32 v[12:13], v[12:13], v[8:9]
	ds_read_b128 v[6:9], v6
	s_waitcnt lgkmcnt(0)
	v_pk_add_f32 v[22:23], v[22:23], v[2:3]
	v_add_u32_e32 v2, 0x18000, v28
	v_pk_add_f32 v[20:21], v[20:21], v[4:5]
	ds_read_b128 v[2:5], v2
	v_pk_add_f32 v[26:27], v[10:11], v[6:7]
	v_add_u32_e32 v6, 0x1a000, v28
	v_pk_add_f32 v[24:25], v[12:13], v[8:9]
	ds_read_b128 v[6:9], v6
	s_waitcnt lgkmcnt(0)
	v_pk_add_f32 v[22:23], v[22:23], v[2:3]
	v_add_u32_e32 v2, 0x1c000, v28
	v_add_u32_e32 v10, 0x1e000, v28
	v_pk_add_f32 v[20:21], v[20:21], v[4:5]
	ds_read_b128 v[2:5], v2
	ds_read_b128 v[10:13], v10
	v_pk_add_f32 v[6:7], v[26:27], v[6:7]
	v_pk_add_f32 v[8:9], v[24:25], v[8:9]
	s_waitcnt lgkmcnt(0)
	v_pk_add_f32 v[2:3], v[22:23], v[2:3]
	v_pk_add_f32 v[6:7], v[6:7], v[10:11]
	v_pk_add_f32 v[4:5], v[20:21], v[4:5]
	v_pk_add_f32 v[8:9], v[8:9], v[12:13]
	s_waitcnt vmcnt(0)
	v_lshlrev_b32_e32 v10, 16, v16
	v_and_b32_e32 v11, 0xffff0000, v16
	v_pk_add_f32 v[2:3], v[2:3], v[10:11]
	v_lshlrev_b32_e32 v10, 16, v18
	v_and_b32_e32 v11, 0xffff0000, v18
	v_lshlrev_b32_e32 v12, 16, v17
	v_and_b32_e32 v13, 0xffff0000, v17
	v_pk_add_f32 v[6:7], v[6:7], v[10:11]
	v_pk_add_f32 v[4:5], v[4:5], v[12:13]
	v_lshlrev_b32_e32 v12, 16, v19
	v_and_b32_e32 v13, 0xffff0000, v19
	v_mul_f32_e32 v10, v6, v6
	v_mul_f32_e32 v11, v7, v7
	v_pk_add_f32 v[8:9], v[8:9], v[12:13]
	v_fmac_f32_e32 v10, v2, v2
	v_fmac_f32_e32 v11, v3, v3
	v_add_f32_e32 v10, v10, v11
	v_mul_f32_e32 v11, v8, v8
	v_fmac_f32_e32 v11, v4, v4
	v_add_f32_e32 v10, v11, v10
	v_mul_f32_e32 v11, v9, v9
	v_fmac_f32_e32 v11, v5, v5
	v_add_f32_e32 v10, v11, v10
	ds_bpermute_b32 v11, v216, v10
	v_cvt_pk_bf16_f32 v2, v2, v3
	v_cvt_pk_bf16_f32 v3, v4, v5
	global_store_dwordx2 v[14:15], v[2:3], off
	v_cvt_pk_bf16_f32 v2, v6, v7
	s_waitcnt lgkmcnt(0)
	v_add_f32_e32 v4, v10, v11
	ds_bpermute_b32 v5, v217, v4
	v_cvt_pk_bf16_f32 v3, v8, v9
	global_store_dwordx2 v[14:15], v[2:3], off offset:256
	s_waitcnt lgkmcnt(0)
	v_add_f32_e32 v2, v4, v5
	s_and_saveexec_b64 s[4:5], vcc
	s_and_b32 s1, s0, 0xffffffc0
	s_add_i32 s1, s1, 0
	v_lshl_add_u32 v3, v80, 2, s1
	v_add_u32_e32 v3, 0x20100, v3
	ds_write_b32 v3, v2
	s_or_b64 exec, exec, s[4:5]
	v_or_b32_e32 v3, s3, v64
	v_cmp_eq_u32_e32 vcc, 0, v3
	s_waitcnt lgkmcnt(0)
	s_barrier
	s_and_saveexec_b64 s[4:5], vcc
	s_cbranch_execz .LBB0_802
	s_andn2_b32 s0, s0, 63
	s_add_i32 s0, s0, 0
	s_add_i32 s0, s0, 0x20100
	v_lshl_add_u32 v3, v80, 2, s0
	ds_read_b32 v3, v3 offset:64
	v_lshlrev_b64 v[0:1], 7, v[0:1]
	v_lshl_add_u64 v[0:1], s[6:7], 0, v[0:1]
	s_ashr_i32 s3, s2, 31
	v_lshl_add_u64 v[0:1], s[2:3], 2, v[0:1]
	s_waitcnt lgkmcnt(0)
	v_add_f32_e32 v2, v2, v3
	global_store_dword v[0:1], v2, off

.LBB0_859:
	s_add_u32 s24, s24, s22
	s_addc_u32 s25, s25, s23
	s_add_u32 s26, s0, s24
	s_addc_u32 s27, s1, s25
	v_cmp_gt_i64_e32 vcc, s[26:27], v[236:237]
	s_mov_b64 s[26:27], -1
	s_cbranch_vccnz .LBB0_854
	v_lshl_add_u32 v4, s21, 8, v2
	v_ashrrev_i32_e32 v5, 31, v4
	v_lshl_add_u32 v6, s29, 8, v2
	v_lshlrev_b64 v[4:5], 7, v[4:5]
	v_ashrrev_i32_e32 v7, 31, v6
	v_lshl_add_u64 v[4:5], v[0:1], 0, v[4:5]
	v_lshlrev_b64 v[6:7], 7, v[6:7]
	v_lshl_add_u64 v[6:7], v[0:1], 0, v[6:7]
	global_load_dwordx4 v[10:13], v[4:5], off
	global_load_dwordx4 v[14:17], v[4:5], off offset:16
	global_load_dwordx4 v[18:21], v[4:5], off offset:32
	global_load_dwordx4 v[22:25], v[4:5], off offset:48
	global_load_dwordx4 v[26:29], v[6:7], off
	global_load_dwordx4 v[30:33], v[6:7], off offset:16
	global_load_dwordx4 v[34:37], v[6:7], off offset:32
	global_load_dwordx4 v[38:41], v[6:7], off offset:48
	v_mov_b32_e32 v5, v129
	v_mov_b32_e32 v4, v129
	s_waitcnt vmcnt(0) lgkmcnt(0)
	v_pk_add_f32 v[6:7], v[12:13], v[16:17]
	v_pk_add_f32 v[10:11], v[10:11], v[14:15]
	v_pk_add_f32 v[12:13], v[20:21], v[24:25]
	v_pk_add_f32 v[14:15], v[18:19], v[22:23]
	v_pk_add_f32 v[16:17], v[28:29], v[32:33]
	v_pk_add_f32 v[18:19], v[26:27], v[30:31]
	v_pk_add_f32 v[20:21], v[36:37], v[40:41]
	v_pk_add_f32 v[22:23], v[34:35], v[38:39]
	v_pk_add_f32 v[6:7], v[6:7], v[12:13]
	v_pk_add_f32 v[10:11], v[10:11], v[14:15]
	v_pk_add_f32 v[12:13], v[16:17], v[20:21]
	v_pk_add_f32 v[14:15], v[18:19], v[22:23]
	v_add_f32_e32 v9, v10, v11
	v_add_f32_e32 v6, v6, v7
	v_add_f32_e32 v10, v14, v15
	v_add_f32_e32 v11, v12, v13
	v_add_f32_e32 v7, v9, v6
	v_add_f32_e32 v6, v10, v11
	s_nop 0
	v_mov_b32_dpp v5, v7 quad_perm:[1,0,3,2] row_mask:0xf bank_mask:0xf
	v_mov_b32_dpp v4, v6 quad_perm:[1,0,3,2] row_mask:0xf bank_mask:0xf
	s_and_saveexec_b64 s[26:27], s[2:3]
	s_cbranch_execz .LBB0_853
	v_add_f32_e32 v5, v7, v5
	v_fmamk_f32 v5, v5, 0x3a000000, v190
	v_mul_f32_e32 v7, 0x4b800000, v5
	v_cmp_gt_f32_e32 vcc, s70, v5
	s_nop 1
	v_cndmask_b32_e32 v5, v5, v7, vcc
	v_rsq_f32_e32 v5, v5
	s_nop 0
	v_mul_f32_e32 v7, 0x45800000, v5
	v_cndmask_b32_e32 v5, v5, v7, vcc
	s_andn2_b64 vcc, exec, s[4:5]
	ds_write_b32 v3, v5
	s_cbranch_vccnz .LBB0_853
	v_add_f32_e32 v4, v6, v4
	v_fmamk_f32 v4, v4, 0x3a000000, v190
	v_mul_f32_e32 v5, 0x4b800000, v4
	v_cmp_gt_f32_e32 vcc, s70, v4
	s_nop 1
	v_cndmask_b32_e32 v4, v4, v5, vcc
	v_rsq_f32_e32 v4, v4
	s_nop 0
	v_mul_f32_e32 v5, 0x45800000, v4
	v_cndmask_b32_e32 v4, v4, v5, vcc
	ds_write_b32 v3, v4 offset:1024
	s_branch .LBB0_853

.LBB0_878:
	s_lshl_b32 s29, s18, 7
	s_add_i32 s94, s29, 0xfffffc00
	v_lshlrev_b64 v[160:161], 12, v[158:159]
	v_lshl_add_u64 v[160:161], s[8:9], 0, v[160:161]
	s_lshl_b64 s[38:39], s[94:95], 1
	v_lshl_add_u64 v[160:161], v[160:161], 0, s[38:39]
	s_lshl_b32 s94, s47, 1
	v_lshl_add_u64 v[160:161], v[160:161], 0, s[94:95]
	s_waitcnt lgkmcnt(0)
	v_mul_f32_e32 v166, v154, v154
	v_pk_mul_f32 v[168:169], v[126:127], v[94:95]
	v_pk_mul_f32 v[170:171], v[124:125], v[92:93]
	v_pk_mul_f32 v[172:173], v[122:123], v[90:91]
	v_pk_mul_f32 v[174:175], v[120:121], v[88:89]
	v_lshl_add_u64 v[160:161], v[160:161], 0, v[128:129]
	v_pk_mul_f32 v[168:169], v[168:169], v[166:167] op_sel_hi:[1,0]
	v_pk_mul_f32 v[170:171], v[170:171], v[166:167] op_sel_hi:[1,0]
	v_pk_mul_f32 v[172:173], v[172:173], v[166:167] op_sel_hi:[1,0]
	v_pk_mul_f32 v[174:175], v[174:175], v[166:167] op_sel_hi:[1,0]
	v_cvt_pk_bf16_f32 v166, v170, v171
	v_cvt_pk_bf16_f32 v167, v168, v169
	v_pk_mul_f32 v[176:177], v[112:113], v[80:81]
	v_cvt_pk_bf16_f32 v168, v174, v175
	v_cvt_pk_bf16_f32 v169, v172, v173
	global_store_dwordx4 v[160:161], v[166:169], off
	v_pk_mul_f32 v[172:173], v[116:117], v[84:85]
	v_pk_mul_f32 v[174:175], v[114:115], v[82:83]
	v_lshlrev_b64 v[166:167], 12, v[156:157]
	v_lshl_add_u64 v[166:167], s[8:9], 0, v[166:167]
	v_lshl_add_u64 v[166:167], v[166:167], 0, s[38:39]
	v_lshl_add_u64 v[166:167], v[166:167], 0, s[94:95]
	v_lshl_add_u64 v[170:171], v[166:167], 0, v[128:129]
	v_mul_f32_e32 v166, v155, v155
	v_pk_mul_f32 v[168:169], v[118:119], v[86:87]
	v_pk_mul_f32 v[172:173], v[172:173], v[166:167] op_sel_hi:[1,0]
	v_pk_mul_f32 v[168:169], v[168:169], v[166:167] op_sel_hi:[1,0]
	v_pk_mul_f32 v[174:175], v[174:175], v[166:167] op_sel_hi:[1,0]
	v_pk_mul_f32 v[176:177], v[176:177], v[166:167] op_sel_hi:[1,0]
	v_cvt_pk_bf16_f32 v166, v172, v173
	v_cvt_pk_bf16_f32 v167, v168, v169
	v_pk_mul_f32 v[172:173], v[108:109], v[76:77]
	v_cvt_pk_bf16_f32 v168, v176, v177
	v_cvt_pk_bf16_f32 v169, v174, v175
	global_store_dwordx4 v[170:171], v[166:169], off
	v_pk_mul_f32 v[174:175], v[106:107], v[74:75]
	v_pk_mul_f32 v[176:177], v[104:105], v[72:73]
	v_lshlrev_b64 v[166:167], 12, v[152:153]
	v_lshl_add_u64 v[166:167], s[8:9], 0, v[166:167]
	v_lshl_add_u64 v[166:167], v[166:167], 0, s[38:39]
	v_lshl_add_u64 v[166:167], v[166:167], 0, s[94:95]
	v_lshl_add_u64 v[170:171], v[166:167], 0, v[128:129]
	v_mul_f32_e32 v166, v148, v148
	v_pk_mul_f32 v[168:169], v[110:111], v[78:79]
	v_pk_mul_f32 v[172:173], v[172:173], v[166:167] op_sel_hi:[1,0]
	v_pk_mul_f32 v[168:169], v[168:169], v[166:167] op_sel_hi:[1,0]
	v_pk_mul_f32 v[174:175], v[174:175], v[166:167] op_sel_hi:[1,0]
	v_pk_mul_f32 v[176:177], v[176:177], v[166:167] op_sel_hi:[1,0]
	v_cvt_pk_bf16_f32 v166, v172, v173
	v_cvt_pk_bf16_f32 v167, v168, v169
	v_pk_mul_f32 v[172:173], v[100:101], v[68:69]
	v_cvt_pk_bf16_f32 v168, v176, v177
	v_cvt_pk_bf16_f32 v169, v174, v175
	global_store_dwordx4 v[170:171], v[166:169], off
	v_pk_mul_f32 v[174:175], v[98:99], v[66:67]
	v_pk_mul_f32 v[176:177], v[96:97], v[64:65]
	v_lshlrev_b64 v[166:167], 12, v[150:151]
	v_lshl_add_u64 v[166:167], s[8:9], 0, v[166:167]
	v_lshl_add_u64 v[166:167], v[166:167], 0, s[38:39]
	v_lshl_add_u64 v[166:167], v[166:167], 0, s[94:95]
	v_lshl_add_u64 v[170:171], v[166:167], 0, v[128:129]
	v_mul_f32_e32 v166, v149, v149
	v_pk_mul_f32 v[168:169], v[102:103], v[70:71]
	v_pk_mul_f32 v[172:173], v[172:173], v[166:167] op_sel_hi:[1,0]
	v_pk_mul_f32 v[168:169], v[168:169], v[166:167] op_sel_hi:[1,0]
	v_pk_mul_f32 v[174:175], v[174:175], v[166:167] op_sel_hi:[1,0]
	v_pk_mul_f32 v[176:177], v[176:177], v[166:167] op_sel_hi:[1,0]
	v_cvt_pk_bf16_f32 v166, v172, v173
	v_cvt_pk_bf16_f32 v167, v168, v169
	v_pk_mul_f32 v[172:173], v[58:59], v[26:27]
	v_cvt_pk_bf16_f32 v168, v176, v177
	v_cvt_pk_bf16_f32 v169, v174, v175
	global_store_dwordx4 v[170:171], v[166:169], off
	v_pk_mul_f32 v[170:171], v[60:61], v[28:29]
	v_pk_mul_f32 v[174:175], v[56:57], v[24:25]
	v_mul_f32_e32 v166, v146, v146
	v_pk_mul_f32 v[168:169], v[62:63], v[30:31]
	v_pk_mul_f32 v[170:171], v[170:171], v[166:167] op_sel_hi:[1,0]
	v_pk_mul_f32 v[168:169], v[168:169], v[166:167] op_sel_hi:[1,0]
	v_pk_mul_f32 v[172:173], v[172:173], v[166:167] op_sel_hi:[1,0]
	v_pk_mul_f32 v[174:175], v[174:175], v[166:167] op_sel_hi:[1,0]
	v_cvt_pk_bf16_f32 v166, v170, v171
	v_add_co_u32_e32 v170, vcc, s72, v160
	v_cvt_pk_bf16_f32 v167, v168, v169
	v_cvt_pk_bf16_f32 v168, v174, v175
	v_cvt_pk_bf16_f32 v169, v172, v173
	v_pk_mul_f32 v[172:173], v[50:51], v[18:19]
	s_nop 0
	v_addc_co_u32_e32 v171, vcc, 0, v161, vcc
	global_store_dwordx4 v[170:171], v[166:169], off
	v_pk_mul_f32 v[170:171], v[52:53], v[20:21]
	v_pk_mul_f32 v[174:175], v[48:49], v[16:17]
	v_mul_f32_e32 v166, v147, v147
	v_pk_mul_f32 v[168:169], v[54:55], v[22:23]
	v_pk_mul_f32 v[170:171], v[170:171], v[166:167] op_sel_hi:[1,0]
	v_pk_mul_f32 v[168:169], v[168:169], v[166:167] op_sel_hi:[1,0]
	v_pk_mul_f32 v[172:173], v[172:173], v[166:167] op_sel_hi:[1,0]
	v_pk_mul_f32 v[174:175], v[174:175], v[166:167] op_sel_hi:[1,0]
	v_cvt_pk_bf16_f32 v166, v170, v171
	v_add_co_u32_e32 v170, vcc, s81, v160
	v_cvt_pk_bf16_f32 v167, v168, v169
	v_cvt_pk_bf16_f32 v168, v174, v175
	v_cvt_pk_bf16_f32 v169, v172, v173
	v_pk_mul_f32 v[172:173], v[42:43], v[10:11]
	s_nop 0
	v_addc_co_u32_e32 v171, vcc, 0, v161, vcc
	global_store_dwordx4 v[170:171], v[166:169], off
	v_pk_mul_f32 v[170:171], v[44:45], v[12:13]
	v_pk_mul_f32 v[174:175], v[40:41], v[8:9]
	v_mul_f32_e32 v166, v144, v144
	v_pk_mul_f32 v[168:169], v[46:47], v[14:15]
	v_pk_mul_f32 v[170:171], v[170:171], v[166:167] op_sel_hi:[1,0]
	v_pk_mul_f32 v[168:169], v[168:169], v[166:167] op_sel_hi:[1,0]
	v_pk_mul_f32 v[172:173], v[172:173], v[166:167] op_sel_hi:[1,0]
	v_pk_mul_f32 v[174:175], v[174:175], v[166:167] op_sel_hi:[1,0]
	v_cvt_pk_bf16_f32 v166, v170, v171
	v_add_co_u32_e32 v170, vcc, s82, v160
	v_cvt_pk_bf16_f32 v167, v168, v169
	v_cvt_pk_bf16_f32 v168, v174, v175
	v_cvt_pk_bf16_f32 v169, v172, v173
	v_pk_mul_f32 v[172:173], v[34:35], v[2:3]
	s_nop 0
	v_addc_co_u32_e32 v171, vcc, 0, v161, vcc
	global_store_dwordx4 v[170:171], v[166:169], off
	v_add_co_u32_e32 v160, vcc, 0xb0000, v160
	s_nop 0
	v_mul_f32_e32 v166, v145, v145
	v_pk_mul_f32 v[168:169], v[38:39], v[6:7]
	v_pk_mul_f32 v[170:171], v[36:37], v[4:5]
	v_pk_mul_f32 v[168:169], v[168:169], v[166:167] op_sel_hi:[1,0]
	v_pk_mul_f32 v[174:175], v[32:33], v[0:1]
	v_addc_co_u32_e32 v161, vcc, 0, v161, vcc
	v_pk_mul_f32 v[170:171], v[170:171], v[166:167] op_sel_hi:[1,0]
	v_pk_mul_f32 v[172:173], v[172:173], v[166:167] op_sel_hi:[1,0]
	v_pk_mul_f32 v[174:175], v[174:175], v[166:167] op_sel_hi:[1,0]
	v_cvt_pk_bf16_f32 v166, v170, v171
	v_cvt_pk_bf16_f32 v167, v168, v169
	s_nop 0
	v_cvt_pk_bf16_f32 v168, v174, v175
	v_cvt_pk_bf16_f32 v169, v172, v173
	global_store_dwordx4 v[160:161], v[166:169], off
	s_cbranch_execnz .LBB0_875
.LBB0_879:
	s_lshl_b32 s38, s18, 8
	s_ashr_i32 s39, s38, 31
	v_lshlrev_b64 v[158:159], 12, v[158:159]
	v_lshl_add_u64 v[158:159], s[6:7], 0, v[158:159]
	s_lshl_b64 s[38:39], s[38:39], 1
	v_lshl_add_u64 v[158:159], v[158:159], 0, s[38:39]
	s_lshl_b32 s94, s47, 1
	v_lshl_add_u64 v[158:159], v[158:159], 0, s[94:95]
	s_waitcnt lgkmcnt(0)
	v_pk_mul_f32 v[166:167], v[124:125], v[154:155] op_sel_hi:[1,0]
	v_lshl_add_u64 v[158:159], v[158:159], 0, v[128:129]
	v_pk_mul_f32 v[160:161], v[126:127], v[154:155] op_sel_hi:[1,0]
	v_pk_mul_f32 v[168:169], v[120:121], v[154:155] op_sel_hi:[1,0]
	v_cvt_pk_bf16_f32 v166, v166, v167
	v_cvt_pk_bf16_f32 v167, v160, v161
	v_lshlrev_b64 v[156:157], 12, v[156:157]
	v_pk_mul_f32 v[170:171], v[122:123], v[154:155] op_sel_hi:[1,0]
	v_cvt_pk_bf16_f32 v168, v168, v169
	v_lshl_add_u64 v[156:157], s[6:7], 0, v[156:157]
	v_cvt_pk_bf16_f32 v169, v170, v171
	global_store_dwordx4 v[158:159], v[166:169], off
	v_lshl_add_u64 v[156:157], v[156:157], 0, s[38:39]
	v_pk_mul_f32 v[160:161], v[94:95], v[154:155] op_sel_hi:[1,0]
	v_pk_mul_f32 v[166:167], v[92:93], v[154:155] op_sel_hi:[1,0]
	v_pk_mul_f32 v[168:169], v[88:89], v[154:155] op_sel_hi:[1,0]
	v_cvt_pk_bf16_f32 v166, v166, v167
	v_pk_mul_f32 v[170:171], v[90:91], v[154:155] op_sel_hi:[1,0]
	v_cvt_pk_bf16_f32 v167, v160, v161
	v_cvt_pk_bf16_f32 v168, v168, v169
	v_lshl_add_u64 v[156:157], v[156:157], 0, s[94:95]
	v_cvt_pk_bf16_f32 v169, v170, v171
	global_store_dwordx4 v[158:159], v[166:169], off offset:256
	v_lshl_add_u64 v[160:161], v[156:157], 0, v[128:129]
	v_lshlrev_b64 v[152:153], 12, v[152:153]
	v_mov_b32_e32 v166, v155
	v_pk_mul_f32 v[156:157], v[118:119], v[166:167] op_sel_hi:[1,0]
	v_pk_mul_f32 v[154:155], v[116:117], v[166:167] op_sel_hi:[1,0]
	v_pk_mul_f32 v[168:169], v[114:115], v[166:167] op_sel_hi:[1,0]
	v_pk_mul_f32 v[170:171], v[112:113], v[166:167] op_sel_hi:[1,0]
	v_cvt_pk_bf16_f32 v154, v154, v155
	v_cvt_pk_bf16_f32 v155, v156, v157
	v_lshl_add_u64 v[152:153], s[6:7], 0, v[152:153]
	v_cvt_pk_bf16_f32 v156, v170, v171
	v_cvt_pk_bf16_f32 v157, v168, v169
	global_store_dwordx4 v[160:161], v[154:157], off
	v_lshl_add_u64 v[152:153], v[152:153], 0, s[38:39]
	v_pk_mul_f32 v[168:169], v[82:83], v[166:167] op_sel_hi:[1,0]
	v_pk_mul_f32 v[156:157], v[86:87], v[166:167] op_sel_hi:[1,0]
	v_pk_mul_f32 v[154:155], v[84:85], v[166:167] op_sel_hi:[1,0]
	v_pk_mul_f32 v[166:167], v[80:81], v[166:167] op_sel_hi:[1,0]
	v_cvt_pk_bf16_f32 v154, v154, v155
	v_cvt_pk_bf16_f32 v155, v156, v157
	v_lshl_add_u64 v[152:153], v[152:153], 0, s[94:95]
	v_cvt_pk_bf16_f32 v156, v166, v167
	v_cvt_pk_bf16_f32 v157, v168, v169
	global_store_dwordx4 v[160:161], v[154:157], off offset:256
	v_lshlrev_b64 v[150:151], 12, v[150:151]
	v_lshl_add_u64 v[150:151], s[6:7], 0, v[150:151]
	v_lshl_add_u64 v[156:157], v[152:153], 0, v[128:129]
	v_pk_mul_f32 v[152:153], v[108:109], v[148:149] op_sel_hi:[1,0]
	v_pk_mul_f32 v[154:155], v[110:111], v[148:149] op_sel_hi:[1,0]
	v_cvt_pk_bf16_f32 v152, v152, v153
	v_pk_mul_f32 v[160:161], v[106:107], v[148:149] op_sel_hi:[1,0]
	v_cvt_pk_bf16_f32 v153, v154, v155
	v_pk_mul_f32 v[166:167], v[104:105], v[148:149] op_sel_hi:[1,0]
	v_lshl_add_u64 v[150:151], v[150:151], 0, s[38:39]
	v_cvt_pk_bf16_f32 v154, v166, v167
	v_cvt_pk_bf16_f32 v155, v160, v161
	global_store_dwordx4 v[156:157], v[152:155], off
	v_lshl_add_u64 v[150:151], v[150:151], 0, s[94:95]
	v_pk_mul_f32 v[160:161], v[74:75], v[148:149] op_sel_hi:[1,0]
	v_pk_mul_f32 v[152:153], v[76:77], v[148:149] op_sel_hi:[1,0]
	v_pk_mul_f32 v[154:155], v[78:79], v[148:149] op_sel_hi:[1,0]
	v_cvt_pk_bf16_f32 v152, v152, v153
	v_pk_mul_f32 v[166:167], v[72:73], v[148:149] op_sel_hi:[1,0]
	v_cvt_pk_bf16_f32 v153, v154, v155
	s_mov_b64 s[38:39], 0x90000
	v_cvt_pk_bf16_f32 v154, v166, v167
	v_cvt_pk_bf16_f32 v155, v160, v161
	global_store_dwordx4 v[156:157], v[152:155], off offset:256
	s_nop 1
	v_lshl_add_u64 v[152:153], v[150:151], 0, v[128:129]
	v_mov_b32_e32 v128, v149
	v_pk_mul_f32 v[150:151], v[102:103], v[128:129] op_sel_hi:[1,0]
	v_pk_mul_f32 v[148:149], v[100:101], v[128:129] op_sel_hi:[1,0]
	v_pk_mul_f32 v[154:155], v[98:99], v[128:129] op_sel_hi:[1,0]
	v_pk_mul_f32 v[156:157], v[96:97], v[128:129] op_sel_hi:[1,0]
	v_cvt_pk_bf16_f32 v148, v148, v149
	v_cvt_pk_bf16_f32 v149, v150, v151
	s_nop 0
	v_cvt_pk_bf16_f32 v150, v156, v157
	v_cvt_pk_bf16_f32 v151, v154, v155
	global_store_dwordx4 v[152:153], v[148:151], off
	v_pk_mul_f32 v[154:155], v[66:67], v[128:129] op_sel_hi:[1,0]
	v_pk_mul_f32 v[156:157], v[64:65], v[128:129] op_sel_hi:[1,0]
	v_pk_mul_f32 v[150:151], v[70:71], v[128:129] op_sel_hi:[1,0]
	v_pk_mul_f32 v[148:149], v[68:69], v[128:129] op_sel_hi:[1,0]
	v_mov_b32_e32 v128, v147
	v_cvt_pk_bf16_f32 v148, v148, v149
	v_cvt_pk_bf16_f32 v149, v150, v151
	v_cvt_pk_bf16_f32 v150, v156, v157
	v_cvt_pk_bf16_f32 v151, v154, v155
	global_store_dwordx4 v[152:153], v[148:151], off offset:256
	v_pk_mul_f32 v[154:155], v[58:59], v[146:147] op_sel_hi:[1,0]
	v_pk_mul_f32 v[156:157], v[56:57], v[146:147] op_sel_hi:[1,0]
	v_pk_mul_f32 v[150:151], v[62:63], v[146:147] op_sel_hi:[1,0]
	v_pk_mul_f32 v[148:149], v[60:61], v[146:147] op_sel_hi:[1,0]
	v_lshl_add_u64 v[152:153], v[158:159], 0, s[76:77]
	v_cvt_pk_bf16_f32 v148, v148, v149
	v_cvt_pk_bf16_f32 v149, v150, v151
	v_cvt_pk_bf16_f32 v150, v156, v157
	v_cvt_pk_bf16_f32 v151, v154, v155
	v_add_co_u32_e32 v154, vcc, s72, v158
	v_pk_mul_f32 v[156:157], v[24:25], v[146:147] op_sel_hi:[1,0]
	s_nop 0
	v_addc_co_u32_e32 v155, vcc, 0, v159, vcc
	global_store_dwordx4 v[154:155], v[148:151], off
	v_pk_mul_f32 v[154:155], v[26:27], v[146:147] op_sel_hi:[1,0]
	s_nop 0
	v_pk_mul_f32 v[148:149], v[28:29], v[146:147] op_sel_hi:[1,0]
	v_pk_mul_f32 v[150:151], v[30:31], v[146:147] op_sel_hi:[1,0]
	v_cvt_pk_bf16_f32 v148, v148, v149
	v_pk_mul_f32 v[146:147], v[52:53], v[128:129] op_sel_hi:[1,0]
	v_cvt_pk_bf16_f32 v149, v150, v151
	v_cvt_pk_bf16_f32 v150, v156, v157
	v_cvt_pk_bf16_f32 v151, v154, v155
	global_store_dwordx4 v[152:153], v[148:151], off offset:256
	v_pk_mul_f32 v[152:153], v[50:51], v[128:129] op_sel_hi:[1,0]
	v_pk_mul_f32 v[154:155], v[48:49], v[128:129] op_sel_hi:[1,0]
	v_pk_mul_f32 v[148:149], v[54:55], v[128:129] op_sel_hi:[1,0]
	v_cvt_pk_bf16_f32 v146, v146, v147
	v_lshl_add_u64 v[150:151], v[158:159], 0, s[38:39]
	v_cvt_pk_bf16_f32 v147, v148, v149
	v_cvt_pk_bf16_f32 v148, v154, v155
	v_cvt_pk_bf16_f32 v149, v152, v153
	v_add_co_u32_e32 v152, vcc, s81, v158
	v_pk_mul_f32 v[154:155], v[16:17], v[128:129] op_sel_hi:[1,0]
	s_nop 0
	v_addc_co_u32_e32 v153, vcc, 0, v159, vcc
	global_store_dwordx4 v[152:153], v[146:149], off
	v_pk_mul_f32 v[152:153], v[18:19], v[128:129] op_sel_hi:[1,0]
	s_mov_b64 s[38:39], 0xa0000
	v_pk_mul_f32 v[148:149], v[22:23], v[128:129] op_sel_hi:[1,0]
	v_pk_mul_f32 v[146:147], v[20:21], v[128:129] op_sel_hi:[1,0]
	v_mov_b32_e32 v128, v145
	v_cvt_pk_bf16_f32 v146, v146, v147
	v_cvt_pk_bf16_f32 v147, v148, v149
	v_cvt_pk_bf16_f32 v148, v154, v155
	v_cvt_pk_bf16_f32 v149, v152, v153
	global_store_dwordx4 v[150:151], v[146:149], off offset:256
	v_pk_mul_f32 v[152:153], v[42:43], v[144:145] op_sel_hi:[1,0]
	v_pk_mul_f32 v[154:155], v[40:41], v[144:145] op_sel_hi:[1,0]
	v_pk_mul_f32 v[148:149], v[46:47], v[144:145] op_sel_hi:[1,0]
	v_pk_mul_f32 v[146:147], v[44:45], v[144:145] op_sel_hi:[1,0]
	v_lshl_add_u64 v[150:151], v[158:159], 0, s[38:39]
	v_cvt_pk_bf16_f32 v146, v146, v147
	v_cvt_pk_bf16_f32 v147, v148, v149
	v_cvt_pk_bf16_f32 v148, v154, v155
	v_cvt_pk_bf16_f32 v149, v152, v153
	v_add_co_u32_e32 v152, vcc, s82, v158
	v_pk_mul_f32 v[154:155], v[8:9], v[144:145] op_sel_hi:[1,0]
	s_nop 0
	v_addc_co_u32_e32 v153, vcc, 0, v159, vcc
	global_store_dwordx4 v[152:153], v[146:149], off
	v_pk_mul_f32 v[152:153], v[10:11], v[144:145] op_sel_hi:[1,0]
	s_mov_b64 s[38:39], 0xb0000
	v_pk_mul_f32 v[146:147], v[12:13], v[144:145] op_sel_hi:[1,0]
	v_pk_mul_f32 v[148:149], v[14:15], v[144:145] op_sel_hi:[1,0]
	v_cvt_pk_bf16_f32 v146, v146, v147
	v_pk_mul_f32 v[144:145], v[36:37], v[128:129] op_sel_hi:[1,0]
	v_cvt_pk_bf16_f32 v147, v148, v149
	v_cvt_pk_bf16_f32 v148, v154, v155
	v_cvt_pk_bf16_f32 v149, v152, v153
	global_store_dwordx4 v[150:151], v[146:149], off offset:256
	v_pk_mul_f32 v[150:151], v[34:35], v[128:129] op_sel_hi:[1,0]
	v_pk_mul_f32 v[152:153], v[32:33], v[128:129] op_sel_hi:[1,0]
	v_pk_mul_f32 v[146:147], v[38:39], v[128:129] op_sel_hi:[1,0]
	v_cvt_pk_bf16_f32 v144, v144, v145
	v_lshl_add_u64 v[148:149], v[158:159], 0, s[38:39]
	v_cvt_pk_bf16_f32 v145, v146, v147
	v_cvt_pk_bf16_f32 v146, v152, v153
	v_cvt_pk_bf16_f32 v147, v150, v151
	v_add_co_u32_e32 v150, vcc, s83, v158
	v_pk_mul_f32 v[152:153], v[0:1], v[128:129] op_sel_hi:[1,0]
	s_nop 0
	v_addc_co_u32_e32 v151, vcc, 0, v159, vcc
	global_store_dwordx4 v[150:151], v[144:147], off
	v_pk_mul_f32 v[150:151], v[2:3], v[128:129] op_sel_hi:[1,0]
	s_nop 0
	v_pk_mul_f32 v[146:147], v[6:7], v[128:129] op_sel_hi:[1,0]
	v_pk_mul_f32 v[144:145], v[4:5], v[128:129] op_sel_hi:[1,0]
	s_nop 0
	v_cvt_pk_bf16_f32 v144, v144, v145
	v_cvt_pk_bf16_f32 v145, v146, v147
	v_cvt_pk_bf16_f32 v146, v152, v153
	v_cvt_pk_bf16_f32 v147, v150, v151
	global_store_dwordx4 v[148:149], v[144:147], off offset:256
	s_add_u32 s38, s52, 0xffffff00
	s_addc_u32 s39, s53, -1
	s_andn2_b64 vcc, exec, s[4:5]
	s_cbranch_vccz .LBB0_876

.LBB0_884:
	v_lshl_add_u64 v[68:69], v[66:67], 0, s[4:5]
	v_add_co_u32_e32 v78, vcc, s84, v68
	v_lshl_add_u64 v[126:127], v[64:65], 0, s[4:5]
	s_nop 0
	v_addc_co_u32_e32 v79, vcc, 0, v69, vcc
	v_add_co_u32_e32 v74, vcc, s85, v68
	s_mov_b32 s12, 0x8000
	s_nop 0
	v_addc_co_u32_e32 v75, vcc, 0, v69, vcc
	v_add_co_u32_e32 v72, vcc, s88, v68
	s_mov_b32 s13, 0x18000
	s_nop 0
	v_addc_co_u32_e32 v73, vcc, 0, v69, vcc
	v_add_co_u32_e32 v70, vcc, s89, v68
	s_add_u32 s4, s4, 0x100
	s_nop 0
	v_addc_co_u32_e32 v71, vcc, 0, v69, vcc
	v_add_co_u32_e32 v76, vcc, s12, v126
	s_mov_b32 s12, 0x88000
	s_nop 0
	v_addc_co_u32_e32 v77, vcc, 0, v127, vcc
	global_load_dwordx4 v[82:85], v[76:77], off
	global_load_dwordx4 v[86:89], v[78:79], off
	global_load_dwordx4 v[90:93], v[78:79], off offset:64
	global_load_dwordx4 v[94:97], v[76:77], off offset:64
	global_load_dwordx4 v[98:101], v[74:75], off
	global_load_dwordx4 v[102:105], v[74:75], off offset:64
	global_load_dwordx4 v[106:109], v[72:73], off
	global_load_dwordx4 v[110:113], v[72:73], off offset:64
	global_load_dwordx4 v[114:117], v[70:71], off
	global_load_dwordx4 v[118:121], v[70:71], off offset:64
	v_add_co_u32_e32 v68, vcc, s13, v126
	s_addc_u32 s5, s5, 0
	s_nop 0
	v_addc_co_u32_e32 v69, vcc, 0, v127, vcc
	v_add_co_u32_e32 v138, vcc, s12, v126
	s_mov_b32 s12, 0x98000
	s_nop 0
	v_addc_co_u32_e32 v139, vcc, 0, v127, vcc
	v_add_co_u32_e32 v126, vcc, s12, v126
	s_cmpk_eq_i32 s4, 0x200
	s_nop 0
	v_addc_co_u32_e32 v127, vcc, 0, v127, vcc
	s_waitcnt vmcnt(0) lgkmcnt(0)
	v_mfma_f32_16x16x32_bf16 v[56:59], v[82:85], v[86:89], v[56:59]
	v_mfma_f32_16x16x32_bf16 v[52:55], v[82:85], v[98:101], v[52:55]
	v_mfma_f32_16x16x32_bf16 v[48:51], v[82:85], v[106:109], v[48:51]
	v_mfma_f32_16x16x32_bf16 v[44:47], v[82:85], v[114:117], v[44:47]
	global_load_dwordx4 v[82:85], v[68:69], off
	global_load_dwordx4 v[122:125], v[68:69], off offset:64
	v_mfma_f32_16x16x32_bf16 v[56:59], v[94:97], v[90:93], v[56:59]
	v_mfma_f32_16x16x32_bf16 v[52:55], v[94:97], v[102:105], v[52:55]
	v_mfma_f32_16x16x32_bf16 v[48:51], v[94:97], v[110:113], v[48:51]
	v_mfma_f32_16x16x32_bf16 v[44:47], v[94:97], v[118:121], v[44:47]
	s_waitcnt vmcnt(0) lgkmcnt(0)
	v_mfma_f32_16x16x32_bf16 v[12:15], v[82:85], v[86:89], v[12:15]
	v_mfma_f32_16x16x32_bf16 v[8:11], v[82:85], v[98:101], v[8:11]
	v_mfma_f32_16x16x32_bf16 v[4:7], v[82:85], v[106:109], v[4:7]
	v_mfma_f32_16x16x32_bf16 v[0:3], v[82:85], v[114:117], v[0:3]
	global_load_dwordx4 v[82:85], v[138:139], off
	global_load_dwordx4 v[130:133], v[138:139], off offset:64
	global_load_dwordx4 v[134:137], v[126:127], off
	v_mfma_f32_16x16x32_bf16 v[12:15], v[122:125], v[90:93], v[12:15]
	v_mfma_f32_16x16x32_bf16 v[8:11], v[122:125], v[102:105], v[8:11]
	v_mfma_f32_16x16x32_bf16 v[4:7], v[122:125], v[110:113], v[4:7]
	v_mfma_f32_16x16x32_bf16 v[0:3], v[122:125], v[118:121], v[0:3]
	s_waitcnt vmcnt(0) lgkmcnt(0)
	v_mfma_f32_16x16x32_bf16 v[16:19], v[82:85], v[86:89], v[16:19]
	v_mfma_f32_16x16x32_bf16 v[24:27], v[82:85], v[98:101], v[24:27]
	v_mfma_f32_16x16x32_bf16 v[28:31], v[82:85], v[106:109], v[28:31]
	v_mfma_f32_16x16x32_bf16 v[36:39], v[82:85], v[114:117], v[36:39]
	global_load_dwordx4 v[82:85], v[126:127], off offset:64
	v_mfma_f32_16x16x32_bf16 v[20:23], v[134:137], v[86:89], v[20:23]
	global_load_dwordx4 v[86:89], v[76:77], off offset:128
	v_mfma_f32_16x16x32_bf16 v[32:35], v[134:137], v[98:101], v[32:35]
	v_mfma_f32_16x16x32_bf16 v[40:43], v[134:137], v[106:109], v[40:43]
	v_mfma_f32_16x16x32_bf16 v[60:63], v[134:137], v[114:117], v[60:63]
	v_mfma_f32_16x16x32_bf16 v[16:19], v[130:133], v[90:93], v[16:19]
	v_mfma_f32_16x16x32_bf16 v[24:27], v[130:133], v[102:105], v[24:27]
	v_mfma_f32_16x16x32_bf16 v[28:31], v[130:133], v[110:113], v[28:31]
	s_waitcnt vmcnt(0) lgkmcnt(0)
	v_mfma_f32_16x16x32_bf16 v[20:23], v[82:85], v[90:93], v[20:23]
	v_mfma_f32_16x16x32_bf16 v[32:35], v[82:85], v[102:105], v[32:35]
	v_mfma_f32_16x16x32_bf16 v[40:43], v[82:85], v[110:113], v[40:43]
	v_mfma_f32_16x16x32_bf16 v[60:63], v[82:85], v[118:121], v[60:63]
	global_load_dwordx4 v[82:85], v[78:79], off offset:128
	global_load_dwordx4 v[90:93], v[78:79], off offset:192
	s_nop 0
	global_load_dwordx4 v[76:79], v[76:77], off offset:192
	s_nop 0
	global_load_dwordx4 v[94:97], v[74:75], off offset:128
	global_load_dwordx4 v[98:101], v[74:75], off offset:192
	global_load_dwordx4 v[102:105], v[72:73], off offset:128
	s_nop 0
	global_load_dwordx4 v[72:75], v[72:73], off offset:192
	s_nop 0
	global_load_dwordx4 v[106:109], v[70:71], off offset:128
	global_load_dwordx4 v[110:113], v[70:71], off offset:192
	v_mfma_f32_16x16x32_bf16 v[36:39], v[130:133], v[118:121], v[36:39]
	s_waitcnt vmcnt(0) lgkmcnt(0)
	v_mfma_f32_16x16x32_bf16 v[56:59], v[86:89], v[82:85], v[56:59]
	v_mfma_f32_16x16x32_bf16 v[52:55], v[86:89], v[94:97], v[52:55]
	v_mfma_f32_16x16x32_bf16 v[48:51], v[86:89], v[102:105], v[48:51]
	v_mfma_f32_16x16x32_bf16 v[44:47], v[86:89], v[106:109], v[44:47]
	global_load_dwordx4 v[86:89], v[68:69], off offset:128
	s_nop 0
	global_load_dwordx4 v[68:71], v[68:69], off offset:192
	s_waitcnt vmcnt(0) lgkmcnt(0)
	v_mfma_f32_16x16x32_bf16 v[12:15], v[86:89], v[82:85], v[12:15]
	v_mfma_f32_16x16x32_bf16 v[8:11], v[86:89], v[94:97], v[8:11]
	v_mfma_f32_16x16x32_bf16 v[4:7], v[86:89], v[102:105], v[4:7]
	v_mfma_f32_16x16x32_bf16 v[0:3], v[86:89], v[106:109], v[0:3]
	global_load_dwordx4 v[86:89], v[138:139], off offset:128
	global_load_dwordx4 v[114:117], v[138:139], off offset:192
	global_load_dwordx4 v[118:121], v[126:127], off offset:128
	s_waitcnt vmcnt(0) lgkmcnt(0)
	v_mfma_f32_16x16x32_bf16 v[16:19], v[86:89], v[82:85], v[16:19]
	v_mfma_f32_16x16x32_bf16 v[24:27], v[86:89], v[94:97], v[24:27]
	v_mfma_f32_16x16x32_bf16 v[28:31], v[86:89], v[102:105], v[28:31]
	v_mfma_f32_16x16x32_bf16 v[36:39], v[86:89], v[106:109], v[36:39]
	global_load_dwordx4 v[86:89], v[126:127], off offset:192
	v_mfma_f32_16x16x32_bf16 v[20:23], v[118:121], v[82:85], v[20:23]
	v_mfma_f32_16x16x32_bf16 v[32:35], v[118:121], v[94:97], v[32:35]
	v_mfma_f32_16x16x32_bf16 v[40:43], v[118:121], v[102:105], v[40:43]
	v_mfma_f32_16x16x32_bf16 v[60:63], v[118:121], v[106:109], v[60:63]
	v_mfma_f32_16x16x32_bf16 v[56:59], v[76:79], v[90:93], v[56:59]
	v_mfma_f32_16x16x32_bf16 v[52:55], v[76:79], v[98:101], v[52:55]
	v_mfma_f32_16x16x32_bf16 v[48:51], v[76:79], v[72:75], v[48:51]
	v_mfma_f32_16x16x32_bf16 v[44:47], v[76:79], v[110:113], v[44:47]
	v_mfma_f32_16x16x32_bf16 v[12:15], v[68:71], v[90:93], v[12:15]
	v_mfma_f32_16x16x32_bf16 v[8:11], v[68:71], v[98:101], v[8:11]
	v_mfma_f32_16x16x32_bf16 v[4:7], v[68:71], v[72:75], v[4:7]
	v_mfma_f32_16x16x32_bf16 v[0:3], v[68:71], v[110:113], v[0:3]
	v_mfma_f32_16x16x32_bf16 v[16:19], v[114:117], v[90:93], v[16:19]
	v_mfma_f32_16x16x32_bf16 v[24:27], v[114:117], v[98:101], v[24:27]
	v_mfma_f32_16x16x32_bf16 v[28:31], v[114:117], v[72:75], v[28:31]
	v_mfma_f32_16x16x32_bf16 v[36:39], v[114:117], v[110:113], v[36:39]
	s_waitcnt vmcnt(0) lgkmcnt(0)
	v_mfma_f32_16x16x32_bf16 v[20:23], v[86:89], v[90:93], v[20:23]
	v_mfma_f32_16x16x32_bf16 v[32:35], v[86:89], v[98:101], v[32:35]
	v_mfma_f32_16x16x32_bf16 v[40:43], v[86:89], v[72:75], v[40:43]
	v_mfma_f32_16x16x32_bf16 v[60:63], v[86:89], v[110:113], v[60:63]
	s_cbranch_scc0 .LBB0_884
	v_and_b32_e32 v65, 63, v81
	s_ashr_i32 s4, s3, 7
	v_lshl_add_u32 v65, v65, 4, 0
	s_lshl_b32 s5, s4, 4
	v_lshl_add_u32 v66, s14, 14, v65
	s_addk_i32 s5, 0x4000
	ds_write_b128 v66, v[56:59]
	ds_write_b128 v66, v[52:55] offset:1024
	ds_write_b128 v66, v[48:51] offset:2048
	ds_write_b128 v66, v[44:47] offset:3072
	ds_write_b128 v66, v[12:15] offset:4096
	ds_write_b128 v66, v[8:11] offset:5120
	ds_write_b128 v66, v[4:7] offset:6144
	ds_write_b128 v66, v[0:3] offset:7168
	ds_write_b128 v66, v[16:19] offset:8192
	ds_write_b128 v66, v[24:27] offset:9216
	ds_write_b128 v66, v[28:31] offset:10240
	ds_write_b128 v66, v[36:39] offset:11264
	ds_write_b128 v66, v[20:23] offset:12288
	ds_write_b128 v66, v[32:35] offset:13312
	ds_write_b128 v66, v[40:43] offset:14336
	ds_write_b128 v66, v[60:63] offset:15360
	v_or_b32_e32 v0, s5, v80
	v_ashrrev_i32_e32 v1, 31, v0
	v_bfe_u32 v64, v81, 4, 2
	v_lshlrev_b64 v[2:3], 7, v[0:1]
	v_lshl_add_u64 v[2:3], s[10:11], 0, v[2:3]
	v_lshlrev_b32_e32 v128, 5, v64
	v_lshl_add_u64 v[6:7], v[2:3], 0, v[128:129]
	s_waitcnt lgkmcnt(0)
	s_barrier
	global_load_dwordx4 v[2:5], v[6:7], off
	s_nop 0
	global_load_dwordx4 v[6:9], v[6:7], off offset:16
	s_bfe_u32 s3, s3, 0x10006
	s_lshl_b32 s5, s3, 2
	s_add_i32 s5, s5, s4
	v_lshl_add_u32 v62, s5, 10, v65
	ds_read_b128 v[10:13], v62
	ds_read_b128 v[14:17], v62 offset:8192
	ds_read_b128 v[18:21], v62 offset:16384
	ds_read_b128 v[22:25], v62 offset:24576
	ds_read_b128 v[26:29], v62 offset:32768
	ds_read_b128 v[30:33], v62 offset:40960
	ds_read_b128 v[34:37], v62 offset:49152
	ds_read_b128 v[38:41], v62 offset:57344
	s_waitcnt lgkmcnt(0)
	v_pk_add_f32 v[10:11], v[10:11], 0 op_sel_hi:[1,0]
	v_add_u32_e32 v42, 0x10000, v62
	v_add_u32_e32 v46, 0x12000, v62
	v_add_u32_e32 v50, 0x14000, v62
	v_add_u32_e32 v54, 0x16000, v62
	v_add_u32_e32 v58, 0x18000, v62
	v_pk_add_f32 v[10:11], v[10:11], v[18:19]
	v_add_u32_e32 v63, 0x1a000, v62
	ds_read_b128 v[42:45], v42
	ds_read_b128 v[46:49], v46
	ds_read_b128 v[50:53], v50
	ds_read_b128 v[54:57], v54
	ds_read_b128 v[58:61], v58
	ds_read_b128 v[66:69], v63
	v_pk_add_f32 v[10:11], v[10:11], v[26:27]
	v_pk_add_f32 v[12:13], v[12:13], 0 op_sel_hi:[1,0]
	v_pk_add_f32 v[10:11], v[10:11], v[34:35]
	v_pk_add_f32 v[12:13], v[12:13], v[20:21]
	s_waitcnt lgkmcnt(0)
	v_pk_add_f32 v[10:11], v[10:11], v[42:43]
	v_pk_add_f32 v[14:15], v[14:15], 0 op_sel_hi:[1,0]
	v_pk_add_f32 v[10:11], v[10:11], v[50:51]
	v_pk_add_f32 v[14:15], v[14:15], v[22:23]
	v_pk_add_f32 v[20:21], v[10:11], v[58:59]
	v_pk_add_f32 v[12:13], v[12:13], v[28:29]
	v_pk_add_f32 v[14:15], v[14:15], v[30:31]
	v_pk_add_f32 v[12:13], v[12:13], v[36:37]
	v_pk_add_f32 v[14:15], v[14:15], v[38:39]
	v_pk_add_f32 v[12:13], v[12:13], v[44:45]
	v_pk_add_f32 v[14:15], v[14:15], v[46:47]
	v_pk_add_f32 v[12:13], v[12:13], v[52:53]
	v_pk_add_f32 v[14:15], v[14:15], v[54:55]
	v_pk_add_f32 v[18:19], v[12:13], v[60:61]
	v_pk_add_f32 v[14:15], v[14:15], v[66:67]
	v_pk_add_f32 v[16:17], v[16:17], 0 op_sel_hi:[1,0]
	s_mov_b64 s[4:5], -1
	v_pk_add_f32 v[16:17], v[16:17], v[24:25]
	s_cmp_gt_i32 s0, 7
	v_pk_add_f32 v[16:17], v[16:17], v[32:33]
	v_lshlrev_b64 v[0:1], 12, v[0:1]
	v_pk_add_f32 v[16:17], v[16:17], v[40:41]
	s_waitcnt vmcnt(0)
	v_mov_b32_e32 v10, v2
	v_mov_b32_e32 v11, v6
	v_mov_b32_e32 v6, v3
	v_pk_add_f32 v[2:3], v[10:11], v[6:7]
	v_mov_b32_e32 v6, v4
	v_mov_b32_e32 v7, v8
	v_mov_b32_e32 v8, v5
	v_pk_add_f32 v[4:5], v[6:7], v[8:9]
	v_add_u32_e32 v9, 0x1e000, v62
	v_pk_add_f32 v[2:3], v[2:3], v[4:5]
	v_pk_add_f32 v[16:17], v[16:17], v[48:49]
	v_add_f32_e32 v6, v2, v3
	v_and_b32_e32 v3, 64, v214
	v_xor_b32_e32 v2, 16, v214
	v_add_u32_e32 v7, 64, v3
	v_cmp_lt_i32_e32 vcc, v2, v7
	v_pk_add_f32 v[16:17], v[16:17], v[56:57]
	s_nop 0
	v_cndmask_b32_e32 v2, v214, v2, vcc
	v_lshlrev_b32_e32 v2, 2, v2
	ds_bpermute_b32 v8, v2, v6
	v_add_u32_e32 v2, 0x1c000, v62
	ds_read_b128 v[2:5], v2
	ds_read_b128 v[10:13], v9
	v_pk_add_f32 v[16:17], v[16:17], v[68:69]
	s_waitcnt lgkmcnt(2)
	v_add_f32_e32 v22, v6, v8
	v_xor_b32_e32 v6, 32, v214
	v_cmp_lt_i32_e32 vcc, v6, v7
	s_waitcnt lgkmcnt(1)
	v_pk_add_f32 v[8:9], v[20:21], v[2:3]
	s_waitcnt lgkmcnt(0)
	v_pk_add_f32 v[2:3], v[16:17], v[12:13]
	v_cndmask_b32_e32 v6, v214, v6, vcc
	v_lshlrev_b32_e32 v6, 2, v6
	ds_bpermute_b32 v23, v6, v22
	v_pk_add_f32 v[6:7], v[18:19], v[4:5]
	v_pk_add_f32 v[4:5], v[14:15], v[10:11]
	s_waitcnt lgkmcnt(0)
	v_add_f32_e32 v10, v22, v23
	v_fmamk_f32 v10, v10, 0x3a000000, v190
	v_mul_f32_e32 v11, 0x4b800000, v10
	v_cmp_gt_f32_e32 vcc, s70, v10
	s_nop 1
	v_cndmask_b32_e32 v10, v10, v11, vcc
	v_rsq_f32_e32 v10, v10
	v_lshlrev_b32_e32 v11, 2, v64
	v_lshl_or_b32 v11, s3, 4, v11
	v_or_b32_e32 v11, s1, v11
	v_mul_f32_e32 v12, 0x45800000, v10
	v_cndmask_b32_e32 v10, v10, v12, vcc
	v_lshlrev_b32_e32 v128, 1, v11
	s_cbranch_scc0 .LBB0_887
	v_pk_mul_f32 v[12:13], v[6:7], v[2:3]
	v_pk_mul_f32 v[14:15], v[8:9], v[4:5]
	v_mul_f32_e32 v16, v10, v10
	v_pk_mul_f32 v[12:13], v[12:13], v[16:17] op_sel_hi:[1,0]
	v_pk_mul_f32 v[14:15], v[14:15], v[16:17] op_sel_hi:[1,0]
	s_mov_b32 s3, s95
	v_cvt_pk_bf16_f32 v14, v14, v15
	v_cvt_pk_bf16_f32 v15, v12, v13
	v_lshl_add_u64 v[12:13], s[8:9], 0, v[0:1]
	v_lshl_add_u64 v[12:13], v[12:13], 0, s[2:3]
	v_lshl_add_u64 v[12:13], v[12:13], 0, v[128:129]
	v_add_co_u32_e32 v12, vcc, 0xfffff800, v12
	s_mov_b64 s[4:5], 0
	s_nop 0
	v_addc_co_u32_e32 v13, vcc, -1, v13, vcc
	global_store_dwordx2 v[12:13], v[14:15], off
.LBB0_887:
	s_andn2_b64 vcc, exec, s[4:5]
	s_cbranch_vccnz .LBB0_889
	v_lshl_add_u64 v[0:1], s[6:7], 0, v[0:1]
	s_ashr_i32 s3, s2, 31
	v_lshl_add_u64 v[0:1], s[2:3], 1, v[0:1]
	v_lshl_add_u64 v[0:1], v[0:1], 0, v[128:129]
	v_pk_mul_f32 v[8:9], v[8:9], v[10:11] op_sel_hi:[1,0]
	v_pk_mul_f32 v[4:5], v[4:5], v[10:11] op_sel_hi:[1,0]
	v_pk_mul_f32 v[6:7], v[6:7], v[10:11] op_sel_hi:[1,0]
	v_cvt_pk_bf16_f32 v8, v8, v9
	v_pk_mul_f32 v[2:3], v[2:3], v[10:11] op_sel_hi:[1,0]
	v_cvt_pk_bf16_f32 v9, v6, v7
	global_store_dwordx2 v[0:1], v[8:9], off
	v_cvt_pk_bf16_f32 v4, v4, v5
	v_cvt_pk_bf16_f32 v5, v2, v3
	global_store_dwordx2 v[0:1], v[4:5], off offset:256

.LBB0_934:
	s_or_b64 exec, exec, s[34:35]
	s_mul_i32 s2, s62, 0x6000
	s_waitcnt lgkmcnt(0)
	s_barrier
	s_load_dwordx2 s[4:5], s[74:75], 0x98
	s_waitcnt lgkmcnt(0)
	s_load_dwordx2 s[0:1], s[74:75], 32
	s_waitcnt lgkmcnt(0)
	s_mul_hi_u32 s3, s62, 0x6000
	s_add_u32 s2, s0, s2
	s_addc_u32 s3, s1, s3
	s_mov_b32 s1, s80
	v_mov_b32_e32 v0, v210
	s_movk_i32 s0, 0x2000
	v_lshlrev_b32_e32 v1, 3, v0
	v_and_b32_e32 v2, 0x7f8, v1
	v_lshlrev_b32_e32 v128, 2, v2
	v_lshl_add_u64 v[4:5], s[2:3], 0, v[128:129]
	v_add_co_u32_e32 v6, vcc, s0, v4
	s_mov_b32 s6, s73
	s_nop 0
	v_addc_co_u32_e32 v7, vcc, 0, v5, vcc
	v_add_co_u32_e32 v28, vcc, 0x4000, v4
	v_ashrrev_i32_e32 v1, 8, v0
	s_nop 0
	v_addc_co_u32_e32 v29, vcc, 0, v5, vcc
	global_load_dwordx4 v[8:11], v[4:5], off
	global_load_dwordx4 v[12:15], v[4:5], off offset:16
	global_load_dwordx4 v[16:19], v[6:7], off
	global_load_dwordx4 v[20:23], v[6:7], off offset:16
	global_load_dwordx4 v[24:27], v[28:29], off
	s_nop 0
	global_load_dwordx4 v[28:31], v[28:29], off offset:16
	s_movk_i32 s0, 0x1f3
	v_lshl_add_u32 v50, s6, 1, v1
	v_cmp_gt_i32_e32 vcc, s0, v50
	s_and_saveexec_b64 s[2:3], vcc
	s_cbranch_execz .LBB0_943
	v_lshlrev_b32_e32 v128, 1, v2
	v_lshl_add_u64 v[2:3], s[4:5], 0, v[128:129]
	s_mov_b64 s[8:9], 0x330d0000
	v_lshl_add_u64 v[32:33], v[2:3], 0, s[8:9]
	v_mov_b32_e32 v2, 4
	v_lshlrev_b32_sdwa v128, v2, v0 dst_sel:DWORD dst_unused:UNUSED_PAD src0_sel:DWORD src1_sel:BYTE_0
	v_lshl_add_u64 v[2:3], s[4:5], 0, v[128:129]
	s_mov_b64 s[4:5], 0x371d0000
	s_mulk_i32 s6, 0x42
	s_waitcnt vmcnt(0) lgkmcnt(0)
	v_mov_b32_e32 v4, v17
	v_mov_b32_e32 v5, v19
	v_mov_b32_e32 v6, v21
	v_mov_b32_e32 v7, v23
	s_lshl_b32 s0, s1, 1
	v_swap_b32 v17, v24
	v_swap_b32 v19, v26
	v_swap_b32 v21, v28
	v_swap_b32 v23, v30
	v_lshl_add_u64 v[34:35], v[2:3], 0, s[4:5]
	v_mad_i32_i24 v36, v1, 33, s6
	s_mulk_i32 s1, 0x42
	s_mov_b64 s[4:5], 0
.LBB0_936:
	v_lshl_add_u32 v38, v50, 5, v50
	v_mul_hi_i32 v0, v38, s97
	v_lshrrev_b32_e32 v1, 31, v0
	v_ashrrev_i32_e32 v0, 11, v0
	v_add_u32_e32 v0, v0, v1
	v_mul_i32_i24_e32 v0, 0x1010, v0
	v_sub_u32_e32 v51, v38, v0
	v_cmp_lt_i32_e32 vcc, 0, v51
	v_mov_b32_e32 v40, 0
	v_ashrrev_i32_e32 v39, 31, v38
	v_mov_b32_e32 v41, 0
	v_mov_b32_e32 v42, 0
	v_mov_b32_e32 v43, 0
	v_mov_b32_e32 v44, 0
	v_mov_b32_e32 v45, 0
	v_mov_b32_e32 v46, 0
	v_mov_b32_e32 v47, 0
	s_and_saveexec_b64 s[6:7], vcc
	s_cbranch_execz .LBB0_938
	v_lshlrev_b64 v[0:1], 12, v[38:39]
	v_lshl_add_u64 v[0:1], v[32:33], 0, v[0:1]
	v_add_co_u32_e32 v0, vcc, 0xfffff000, v0
	s_nop 1
	v_addc_co_u32_e32 v1, vcc, -1, v1, vcc
	global_load_dwordx4 v[0:3], v[0:1], off
	s_waitcnt vmcnt(0) lgkmcnt(0)
	v_lshlrev_b32_e32 v40, 16, v0
	v_and_b32_e32 v41, 0xffff0000, v0
	v_lshlrev_b32_e32 v42, 16, v1
	v_and_b32_e32 v43, 0xffff0000, v1
	v_lshlrev_b32_e32 v44, 16, v2
	v_and_b32_e32 v45, 0xffff0000, v2
	v_lshlrev_b32_e32 v46, 16, v3
	v_and_b32_e32 v47, 0xffff0000, v3
.LBB0_938:
	s_or_b64 exec, exec, s[6:7]
	v_mov_b32_e32 v128, v129
	v_mov_b32_e32 v130, v129
	v_mov_b32_e32 v131, v129
	v_mov_b32_e32 v132, v129
	v_mov_b32_e32 v133, v129
	v_mov_b32_e32 v134, v129
	v_mov_b32_e32 v135, v129
	v_mov_b64_e32 v[0:1], v[128:129]
	v_cmp_lt_i32_e32 vcc, 1, v51
	v_mov_b64_e32 v[2:3], v[130:131]
	v_mov_b64_e32 v[4:5], v[132:133]
	v_mov_b64_e32 v[6:7], v[134:135]
	s_and_saveexec_b64 s[6:7], vcc
	s_cbranch_execz .LBB0_940
	v_lshlrev_b64 v[0:1], 12, v[38:39]
	v_lshl_add_u64 v[0:1], v[32:33], 0, v[0:1]
	v_add_co_u32_e32 v0, vcc, 0xffffe000, v0
	s_nop 1
	v_addc_co_u32_e32 v1, vcc, -1, v1, vcc
	global_load_dwordx4 v[4:7], v[0:1], off
	s_waitcnt vmcnt(0) lgkmcnt(0)
	v_lshlrev_b32_e32 v0, 16, v4
	v_and_b32_e32 v1, 0xffff0000, v4
	v_lshlrev_b32_e32 v2, 16, v5
	v_and_b32_e32 v3, 0xffff0000, v5
	v_lshlrev_b32_e32 v4, 16, v6
	v_and_b32_e32 v5, 0xffff0000, v6
	v_lshlrev_b32_e32 v6, 16, v7
	v_and_b32_e32 v7, 0xffff0000, v7

.LBB0_941:
	v_add_co_u32_e32 v48, vcc, 0xfbf00000, v38
	s_mov_b32 s8, 0xf7e00000
	s_nop 0
	v_addc_co_u32_e32 v49, vcc, -1, v39, vcc
	global_load_dwordx4 v[52:55], v[48:49], off
	v_add_co_u32_e32 v48, vcc, s8, v38
	s_movk_i32 s8, 0x1010
	s_nop 0
	v_addc_co_u32_e32 v49, vcc, -1, v39, vcc
	global_load_dwordx4 v[56:59], v[48:49], off
	v_cmp_eq_u32_e32 vcc, 0, v51
	v_add_u32_e32 v37, -1, v37
	s_waitcnt vmcnt(0) lgkmcnt(0)
	v_and_b32_e32 v61, 0xffff0000, v54
	v_cndmask_b32_e64 v81, v0, 0, vcc
	v_cndmask_b32_e64 v0, v40, 0, vcc
	v_cndmask_b32_e64 v76, v5, 0, vcc
	v_cndmask_b32_e64 v80, v1, 0, vcc
	v_cndmask_b32_e64 v5, v45, 0, vcc
	v_cndmask_b32_e64 v1, v41, 0, vcc
	v_mov_b32_e32 v40, v0
	v_lshlrev_b32_e32 v41, 16, v52
	v_cndmask_b32_e64 v74, v7, 0, vcc
	v_cndmask_b32_e64 v78, v3, 0, vcc
	v_cndmask_b32_e64 v79, v2, 0, vcc
	v_cndmask_b32_e64 v7, v47, 0, vcc
	v_cndmask_b32_e64 v3, v43, 0, vcc
	v_cndmask_b32_e64 v2, v42, 0, vcc
	v_mov_b32_e32 v42, v1
	v_mov_b32_e32 v60, v5
	v_and_b32_e32 v43, 0xffff0000, v52
	v_lshlrev_b32_e32 v45, 16, v53
	v_and_b32_e32 v47, 0xffff0000, v53
	v_pk_mul_f32 v[52:53], v[16:17], v[40:41]
	v_lshlrev_b32_e32 v49, 16, v54
	v_lshlrev_b32_e32 v63, 16, v55
	v_and_b32_e32 v65, 0xffff0000, v55
	v_pk_mul_f32 v[54:55], v[24:25], v[42:43]
	v_pk_mul_f32 v[68:69], v[28:29], v[60:61]
	v_fma_f32 v40, v8, v81, v52
	v_cndmask_b32_e64 v75, v6, 0, vcc
	v_cndmask_b32_e64 v77, v4, 0, vcc
	v_cndmask_b32_e64 v6, v46, 0, vcc
	v_cndmask_b32_e64 v4, v44, 0, vcc
	v_mov_b32_e32 v44, v2
	v_mov_b32_e32 v46, v3
	v_lshlrev_b32_e32 v82, 16, v56
	v_fma_f32 v42, v9, v80, v54
	v_fma_f32 v52, v13, v76, v68
	v_add_f32_e32 v40, v40, v53
	v_mov_b32_e32 v48, v4
	v_mov_b32_e32 v62, v6
	v_mov_b32_e32 v64, v7
	v_and_b32_e32 v83, 0xffff0000, v56
	v_lshlrev_b32_e32 v84, 16, v57
	v_and_b32_e32 v85, 0xffff0000, v57
	v_lshlrev_b32_e32 v86, 16, v58
	v_and_b32_e32 v87, 0xffff0000, v58
	v_lshlrev_b32_e32 v88, 16, v59
	v_and_b32_e32 v89, 0xffff0000, v59
	v_pk_mul_f32 v[56:57], v[18:19], v[44:45]
	v_pk_mul_f32 v[58:59], v[26:27], v[46:47]
	v_add_f32_e32 v42, v42, v55
	v_add_f32_e32 v52, v52, v69
	v_mul_f32_e32 v40, v40, v82
	v_pk_mul_f32 v[66:67], v[20:21], v[48:49]
	v_pk_mul_f32 v[70:71], v[22:23], v[62:63]
	v_pk_mul_f32 v[72:73], v[30:31], v[64:65]
	v_fma_f32 v44, v10, v79, v56
	v_fma_f32 v46, v11, v78, v58
	v_mul_f32_e32 v42, v42, v83
	v_mul_f32_e32 v55, v52, v87
	v_cvt_pk_bf16_f32 v52, v40, v42
	v_add_u32_e32 v40, 1, v51
	v_fma_f32 v48, v12, v77, v66
	v_fma_f32 v54, v14, v75, v70
	v_fma_f32 v56, v15, v74, v72
	v_add_f32_e32 v44, v44, v57
	v_add_f32_e32 v46, v46, v59
	v_cmp_ne_u32_e32 vcc, s8, v40
	v_add_f32_e32 v48, v48, v67
	v_add_f32_e32 v53, v54, v71
	v_add_f32_e32 v54, v56, v73
	v_mul_f32_e32 v44, v44, v84
	v_mul_f32_e32 v46, v46, v85
	v_cndmask_b32_e32 v51, 0, v40, vcc
	s_mov_b64 s[8:9], 0x1000
	v_cmp_eq_u32_e32 vcc, 0, v37
	v_mul_f32_e32 v48, v48, v86
	v_mul_f32_e32 v56, v53, v88
	v_mul_f32_e32 v57, v54, v89
	v_cvt_pk_bf16_f32 v53, v44, v46
	v_cvt_pk_bf16_f32 v54, v48, v55
	v_cvt_pk_bf16_f32 v55, v56, v57
	global_store_dwordx4 v[38:39], v[52:55], off
	v_lshl_add_u64 v[38:39], v[38:39], 0, s[8:9]
	s_or_b64 s[6:7], vcc, s[6:7]
	v_mov_b32_e32 v40, v41
	v_mov_b32_e32 v41, v43
	v_mov_b32_e32 v42, v45
	v_mov_b32_e32 v43, v47
	v_mov_b32_e32 v44, v49
	v_mov_b32_e32 v45, v61
	v_mov_b32_e32 v46, v63
	v_mov_b32_e32 v47, v65
	s_andn2_b64 exec, exec, s[6:7]
	s_cbranch_execnz .LBB0_941
	s_or_b64 exec, exec, s[6:7]
	v_add_u32_e32 v50, s0, v50
	s_movk_i32 s6, 0x1f2
	v_cmp_lt_i32_e32 vcc, s6, v50
	s_or_b64 s[4:5], vcc, s[4:5]
	v_add_u32_e32 v36, s1, v36
	s_andn2_b64 exec, exec, s[4:5]
	s_cbranch_execnz .LBB0_936

.LBB0_1009:
	v_lshl_add_u32 v222, s26, 8, v156
	v_lshl_or_b32 v223, s24, 8, v158
	s_lshl_b32 s94, s24, 2
	s_add_i32 s94, s94, s44
	s_lshl_b32 s94, s94, 2
	v_lshlrev_b32_e32 v220, 12, v222
	v_lshl_add_u32 v220, v223, 1, v220
	v_lshlrev_b32_e32 v221, 7, v222
	v_add_u32_e32 v221, s94, v221
	s_mov_b32 s24, s8
	s_mov_b32 s25, s9
	global_load_dwordx4 v[130:133], v220, s[24:25]
	global_load_dwordx4 v[134:137], v220, s[24:25] offset:256
	s_add_u32 s24, s24, 0x10000
	s_addc_u32 s25, s25, 0
	global_load_dwordx4 v[148:151], v220, s[24:25]
	global_load_dwordx4 v[152:155], v220, s[24:25] offset:256
	s_add_u32 s24, s24, 0x10000
	s_addc_u32 s25, s25, 0
	global_load_dwordx4 v[160:163], v220, s[24:25]
	global_load_dwordx4 v[164:167], v220, s[24:25] offset:256
	s_add_u32 s24, s24, 0x10000
	s_addc_u32 s25, s25, 0
	global_load_dwordx4 v[168:171], v220, s[24:25]
	global_load_dwordx4 v[172:175], v220, s[24:25] offset:256
	s_add_u32 s24, s24, 0x50000
	s_addc_u32 s25, s25, 0
	global_load_dwordx4 v[176:179], v220, s[24:25]
	global_load_dwordx4 v[192:195], v220, s[24:25] offset:256
	s_add_u32 s24, s24, 0x10000
	s_addc_u32 s25, s25, 0
	global_load_dwordx4 v[196:199], v220, s[24:25]
	global_load_dwordx4 v[200:203], v220, s[24:25] offset:256
	s_add_u32 s24, s24, 0x10000
	s_addc_u32 s25, s25, 0
	global_load_dwordx4 v[204:207], v220, s[24:25]
	global_load_dwordx4 v[216:219], v220, s[24:25] offset:256
	s_mov_b32 s24, s8
	s_mov_b32 s25, s9
	s_waitcnt vmcnt(12)
	v_and_b32_e32 v222, 0xffff0000, v130
	v_lshlrev_b32_e32 v130, 16, v130
	v_and_b32_e32 v223, 0xffff0000, v131
	v_lshlrev_b32_e32 v131, 16, v131
	v_and_b32_e32 v224, 0xffff0000, v132
	v_lshlrev_b32_e32 v132, 16, v132
	v_and_b32_e32 v225, 0xffff0000, v133
	v_lshlrev_b32_e32 v133, 16, v133
	v_add_f32_e32 v124, v124, v130
	v_add_f32_e32 v125, v125, v222
	v_add_f32_e32 v126, v126, v131
	v_add_f32_e32 v127, v127, v223
	v_add_f32_e32 v120, v120, v132
	v_add_f32_e32 v121, v121, v224
	v_add_f32_e32 v122, v122, v133
	v_add_f32_e32 v123, v123, v225
	v_cvt_pk_bf16_f32 v130, v124, v125
	v_cvt_pk_bf16_f32 v131, v126, v127
	v_cvt_pk_bf16_f32 v132, v120, v121
	v_cvt_pk_bf16_f32 v133, v122, v123
	v_and_b32_e32 v222, 0xffff0000, v134
	v_lshlrev_b32_e32 v134, 16, v134
	v_and_b32_e32 v223, 0xffff0000, v135
	v_lshlrev_b32_e32 v135, 16, v135
	v_and_b32_e32 v224, 0xffff0000, v136
	v_lshlrev_b32_e32 v136, 16, v136
	v_and_b32_e32 v225, 0xffff0000, v137
	v_lshlrev_b32_e32 v137, 16, v137
	v_add_f32_e32 v116, v116, v134
	v_add_f32_e32 v117, v117, v222
	v_add_f32_e32 v118, v118, v135
	v_add_f32_e32 v119, v119, v223
	v_add_f32_e32 v112, v112, v136
	v_add_f32_e32 v113, v113, v224
	v_add_f32_e32 v114, v114, v137
	v_add_f32_e32 v115, v115, v225
	v_cvt_pk_bf16_f32 v134, v116, v117
	v_cvt_pk_bf16_f32 v135, v118, v119
	v_cvt_pk_bf16_f32 v136, v112, v113
	v_cvt_pk_bf16_f32 v137, v114, v115
	global_store_dwordx4 v220, v[130:133], s[24:25]
	global_store_dwordx4 v220, v[134:137], s[24:25] offset:256
	v_mul_f32_e32 v222, v112, v112
	v_mul_f32_e32 v223, v120, v120
	v_fmac_f32_e32 v222, v113, v113
	v_fmac_f32_e32 v223, v121, v121
	v_fmac_f32_e32 v222, v114, v114
	v_fmac_f32_e32 v223, v122, v122
	v_fmac_f32_e32 v222, v115, v115
	v_fmac_f32_e32 v223, v123, v123
	v_fmac_f32_e32 v222, v116, v116
	v_fmac_f32_e32 v223, v124, v124
	v_fmac_f32_e32 v222, v117, v117
	v_fmac_f32_e32 v223, v125, v125
	v_fmac_f32_e32 v222, v118, v118
	v_fmac_f32_e32 v223, v126, v126
	v_fmac_f32_e32 v222, v119, v119
	v_fmac_f32_e32 v223, v127, v127
	v_add_f32_e32 v112, v222, v223
	s_add_u32 s24, s24, 0xb0000
	s_addc_u32 s25, s25, 0
	global_load_dwordx4 v[130:133], v220, s[24:25]
	global_load_dwordx4 v[134:137], v220, s[24:25] offset:256
	s_mov_b32 s24, s8
	s_mov_b32 s25, s9
	s_waitcnt vmcnt(14)
	v_and_b32_e32 v222, 0xffff0000, v148
	v_lshlrev_b32_e32 v148, 16, v148
	v_and_b32_e32 v223, 0xffff0000, v149
	v_lshlrev_b32_e32 v149, 16, v149
	v_and_b32_e32 v224, 0xffff0000, v150
	v_lshlrev_b32_e32 v150, 16, v150
	v_and_b32_e32 v225, 0xffff0000, v151
	v_lshlrev_b32_e32 v151, 16, v151
	v_add_f32_e32 v108, v108, v148
	v_add_f32_e32 v109, v109, v222
	v_add_f32_e32 v110, v110, v149
	v_add_f32_e32 v111, v111, v223
	v_add_f32_e32 v104, v104, v150
	v_add_f32_e32 v105, v105, v224
	v_add_f32_e32 v106, v106, v151
	v_add_f32_e32 v107, v107, v225
	v_cvt_pk_bf16_f32 v148, v108, v109
	v_cvt_pk_bf16_f32 v149, v110, v111
	v_cvt_pk_bf16_f32 v150, v104, v105
	v_cvt_pk_bf16_f32 v151, v106, v107
	v_and_b32_e32 v222, 0xffff0000, v152
	v_lshlrev_b32_e32 v152, 16, v152
	v_and_b32_e32 v223, 0xffff0000, v153
	v_lshlrev_b32_e32 v153, 16, v153
	v_and_b32_e32 v224, 0xffff0000, v154
	v_lshlrev_b32_e32 v154, 16, v154
	v_and_b32_e32 v225, 0xffff0000, v155
	v_lshlrev_b32_e32 v155, 16, v155
	v_add_f32_e32 v100, v100, v152
	v_add_f32_e32 v101, v101, v222
	v_add_f32_e32 v102, v102, v153
	v_add_f32_e32 v103, v103, v223
	v_add_f32_e32 v96, v96, v154
	v_add_f32_e32 v97, v97, v224
	v_add_f32_e32 v98, v98, v155
	v_add_f32_e32 v99, v99, v225
	v_cvt_pk_bf16_f32 v152, v100, v101
	v_cvt_pk_bf16_f32 v153, v102, v103
	v_cvt_pk_bf16_f32 v154, v96, v97
	v_cvt_pk_bf16_f32 v155, v98, v99
	s_add_u32 s24, s24, 0x10000
	s_addc_u32 s25, s25, 0
	global_store_dwordx4 v220, v[148:151], s[24:25]
	global_store_dwordx4 v220, v[152:155], s[24:25] offset:256
	v_mul_f32_e32 v222, v96, v96
	v_mul_f32_e32 v223, v104, v104
	v_fmac_f32_e32 v222, v97, v97
	v_fmac_f32_e32 v223, v105, v105
	v_fmac_f32_e32 v222, v98, v98
	v_fmac_f32_e32 v223, v106, v106
	v_fmac_f32_e32 v222, v99, v99
	v_fmac_f32_e32 v223, v107, v107
	v_fmac_f32_e32 v222, v100, v100
	v_fmac_f32_e32 v223, v108, v108
	v_fmac_f32_e32 v222, v101, v101
	v_fmac_f32_e32 v223, v109, v109
	v_fmac_f32_e32 v222, v102, v102
	v_fmac_f32_e32 v223, v110, v110
	v_fmac_f32_e32 v222, v103, v103
	v_fmac_f32_e32 v223, v111, v111
	v_add_f32_e32 v96, v222, v223
	s_waitcnt vmcnt(14)
	v_and_b32_e32 v222, 0xffff0000, v160
	v_lshlrev_b32_e32 v160, 16, v160
	v_and_b32_e32 v223, 0xffff0000, v161
	v_lshlrev_b32_e32 v161, 16, v161
	v_and_b32_e32 v224, 0xffff0000, v162
	v_lshlrev_b32_e32 v162, 16, v162
	v_and_b32_e32 v225, 0xffff0000, v163
	v_lshlrev_b32_e32 v163, 16, v163
	v_add_f32_e32 v92, v92, v160
	v_add_f32_e32 v93, v93, v222
	v_add_f32_e32 v94, v94, v161
	v_add_f32_e32 v95, v95, v223
	v_add_f32_e32 v88, v88, v162
	v_add_f32_e32 v89, v89, v224
	v_add_f32_e32 v90, v90, v163
	v_add_f32_e32 v91, v91, v225
	v_cvt_pk_bf16_f32 v160, v92, v93
	v_cvt_pk_bf16_f32 v161, v94, v95
	v_cvt_pk_bf16_f32 v162, v88, v89
	v_cvt_pk_bf16_f32 v163, v90, v91
	v_and_b32_e32 v222, 0xffff0000, v164
	v_lshlrev_b32_e32 v164, 16, v164
	v_and_b32_e32 v223, 0xffff0000, v165
	v_lshlrev_b32_e32 v165, 16, v165
	v_and_b32_e32 v224, 0xffff0000, v166
	v_lshlrev_b32_e32 v166, 16, v166
	v_and_b32_e32 v225, 0xffff0000, v167
	v_lshlrev_b32_e32 v167, 16, v167
	v_add_f32_e32 v84, v84, v164
	v_add_f32_e32 v85, v85, v222
	v_add_f32_e32 v86, v86, v165
	v_add_f32_e32 v87, v87, v223
	v_add_f32_e32 v80, v80, v166
	v_add_f32_e32 v81, v81, v224
	v_add_f32_e32 v82, v82, v167
	v_add_f32_e32 v83, v83, v225
	v_cvt_pk_bf16_f32 v164, v84, v85
	v_cvt_pk_bf16_f32 v165, v86, v87
	v_cvt_pk_bf16_f32 v166, v80, v81
	v_cvt_pk_bf16_f32 v167, v82, v83
	s_add_u32 s24, s24, 0x10000
	s_addc_u32 s25, s25, 0
	global_store_dwordx4 v220, v[160:163], s[24:25]
	global_store_dwordx4 v220, v[164:167], s[24:25] offset:256
	v_mul_f32_e32 v222, v80, v80
	v_mul_f32_e32 v223, v88, v88
	v_fmac_f32_e32 v222, v81, v81
	v_fmac_f32_e32 v223, v89, v89
	v_fmac_f32_e32 v222, v82, v82
	v_fmac_f32_e32 v223, v90, v90
	v_fmac_f32_e32 v222, v83, v83
	v_fmac_f32_e32 v223, v91, v91
	v_fmac_f32_e32 v222, v84, v84
	v_fmac_f32_e32 v223, v92, v92
	v_fmac_f32_e32 v222, v85, v85
	v_fmac_f32_e32 v223, v93, v93
	v_fmac_f32_e32 v222, v86, v86
	v_fmac_f32_e32 v223, v94, v94
	v_fmac_f32_e32 v222, v87, v87
	v_fmac_f32_e32 v223, v95, v95
	v_add_f32_e32 v80, v222, v223
	s_waitcnt vmcnt(14)
	v_and_b32_e32 v222, 0xffff0000, v168
	v_lshlrev_b32_e32 v168, 16, v168
	v_and_b32_e32 v223, 0xffff0000, v169
	v_lshlrev_b32_e32 v169, 16, v169
	v_and_b32_e32 v224, 0xffff0000, v170
	v_lshlrev_b32_e32 v170, 16, v170
	v_and_b32_e32 v225, 0xffff0000, v171
	v_lshlrev_b32_e32 v171, 16, v171
	v_add_f32_e32 v76, v76, v168
	v_add_f32_e32 v77, v77, v222
	v_add_f32_e32 v78, v78, v169
	v_add_f32_e32 v79, v79, v223
	v_add_f32_e32 v72, v72, v170
	v_add_f32_e32 v73, v73, v224
	v_add_f32_e32 v74, v74, v171
	v_add_f32_e32 v75, v75, v225
	v_cvt_pk_bf16_f32 v168, v76, v77
	v_cvt_pk_bf16_f32 v169, v78, v79
	v_cvt_pk_bf16_f32 v170, v72, v73
	v_cvt_pk_bf16_f32 v171, v74, v75
	v_and_b32_e32 v222, 0xffff0000, v172
	v_lshlrev_b32_e32 v172, 16, v172
	v_and_b32_e32 v223, 0xffff0000, v173
	v_lshlrev_b32_e32 v173, 16, v173
	v_and_b32_e32 v224, 0xffff0000, v174
	v_lshlrev_b32_e32 v174, 16, v174
	v_and_b32_e32 v225, 0xffff0000, v175
	v_lshlrev_b32_e32 v175, 16, v175
	v_add_f32_e32 v68, v68, v172
	v_add_f32_e32 v69, v69, v222
	v_add_f32_e32 v70, v70, v173
	v_add_f32_e32 v71, v71, v223
	v_add_f32_e32 v64, v64, v174
	v_add_f32_e32 v65, v65, v224
	v_add_f32_e32 v66, v66, v175
	v_add_f32_e32 v67, v67, v225
	v_cvt_pk_bf16_f32 v172, v68, v69
	v_cvt_pk_bf16_f32 v173, v70, v71
	v_cvt_pk_bf16_f32 v174, v64, v65
	v_cvt_pk_bf16_f32 v175, v66, v67
	s_add_u32 s24, s24, 0x10000
	s_addc_u32 s25, s25, 0
	global_store_dwordx4 v220, v[168:171], s[24:25]
	global_store_dwordx4 v220, v[172:175], s[24:25] offset:256
	v_mul_f32_e32 v222, v64, v64
	v_mul_f32_e32 v223, v72, v72
	v_fmac_f32_e32 v222, v65, v65
	v_fmac_f32_e32 v223, v73, v73
	v_fmac_f32_e32 v222, v66, v66
	v_fmac_f32_e32 v223, v74, v74
	v_fmac_f32_e32 v222, v67, v67
	v_fmac_f32_e32 v223, v75, v75
	v_fmac_f32_e32 v222, v68, v68
	v_fmac_f32_e32 v223, v76, v76
	v_fmac_f32_e32 v222, v69, v69
	v_fmac_f32_e32 v223, v77, v77
	v_fmac_f32_e32 v222, v70, v70
	v_fmac_f32_e32 v223, v78, v78
	v_fmac_f32_e32 v222, v71, v71
	v_fmac_f32_e32 v223, v79, v79
	v_add_f32_e32 v64, v222, v223
	s_waitcnt vmcnt(14)
	v_and_b32_e32 v222, 0xffff0000, v176
	v_lshlrev_b32_e32 v176, 16, v176
	v_and_b32_e32 v223, 0xffff0000, v177
	v_lshlrev_b32_e32 v177, 16, v177
	v_and_b32_e32 v224, 0xffff0000, v178
	v_lshlrev_b32_e32 v178, 16, v178
	v_and_b32_e32 v225, 0xffff0000, v179
	v_lshlrev_b32_e32 v179, 16, v179
	v_add_f32_e32 v60, v60, v176
	v_add_f32_e32 v61, v61, v222
	v_add_f32_e32 v62, v62, v177
	v_add_f32_e32 v63, v63, v223
	v_add_f32_e32 v56, v56, v178
	v_add_f32_e32 v57, v57, v224
	v_add_f32_e32 v58, v58, v179
	v_add_f32_e32 v59, v59, v225
	v_cvt_pk_bf16_f32 v176, v60, v61
	v_cvt_pk_bf16_f32 v177, v62, v63
	v_cvt_pk_bf16_f32 v178, v56, v57
	v_cvt_pk_bf16_f32 v179, v58, v59
	v_and_b32_e32 v222, 0xffff0000, v192
	v_lshlrev_b32_e32 v192, 16, v192
	v_and_b32_e32 v223, 0xffff0000, v193
	v_lshlrev_b32_e32 v193, 16, v193
	v_and_b32_e32 v224, 0xffff0000, v194
	v_lshlrev_b32_e32 v194, 16, v194
	v_and_b32_e32 v225, 0xffff0000, v195
	v_lshlrev_b32_e32 v195, 16, v195
	v_add_f32_e32 v52, v52, v192
	v_add_f32_e32 v53, v53, v222
	v_add_f32_e32 v54, v54, v193
	v_add_f32_e32 v55, v55, v223
	v_add_f32_e32 v48, v48, v194
	v_add_f32_e32 v49, v49, v224
	v_add_f32_e32 v50, v50, v195
	v_add_f32_e32 v51, v51, v225
	v_cvt_pk_bf16_f32 v192, v52, v53
	v_cvt_pk_bf16_f32 v193, v54, v55
	v_cvt_pk_bf16_f32 v194, v48, v49
	v_cvt_pk_bf16_f32 v195, v50, v51
	s_add_u32 s24, s24, 0x50000
	s_addc_u32 s25, s25, 0
	global_store_dwordx4 v220, v[176:179], s[24:25]
	global_store_dwordx4 v220, v[192:195], s[24:25] offset:256
	v_mul_f32_e32 v222, v48, v48
	v_mul_f32_e32 v223, v56, v56
	v_fmac_f32_e32 v222, v49, v49
	v_fmac_f32_e32 v223, v57, v57
	v_fmac_f32_e32 v222, v50, v50
	v_fmac_f32_e32 v223, v58, v58
	v_fmac_f32_e32 v222, v51, v51
	v_fmac_f32_e32 v223, v59, v59
	v_fmac_f32_e32 v222, v52, v52
	v_fmac_f32_e32 v223, v60, v60
	v_fmac_f32_e32 v222, v53, v53
	v_fmac_f32_e32 v223, v61, v61
	v_fmac_f32_e32 v222, v54, v54
	v_fmac_f32_e32 v223, v62, v62
	v_fmac_f32_e32 v222, v55, v55
	v_fmac_f32_e32 v223, v63, v63
	v_add_f32_e32 v48, v222, v223
	s_waitcnt vmcnt(14)
	v_and_b32_e32 v222, 0xffff0000, v196
	v_lshlrev_b32_e32 v196, 16, v196
	v_and_b32_e32 v223, 0xffff0000, v197
	v_lshlrev_b32_e32 v197, 16, v197
	v_and_b32_e32 v224, 0xffff0000, v198
	v_lshlrev_b32_e32 v198, 16, v198
	v_and_b32_e32 v225, 0xffff0000, v199
	v_lshlrev_b32_e32 v199, 16, v199
	v_add_f32_e32 v44, v44, v196
	v_add_f32_e32 v45, v45, v222
	v_add_f32_e32 v46, v46, v197
	v_add_f32_e32 v47, v47, v223
	v_add_f32_e32 v40, v40, v198
	v_add_f32_e32 v41, v41, v224
	v_add_f32_e32 v42, v42, v199
	v_add_f32_e32 v43, v43, v225
	v_cvt_pk_bf16_f32 v196, v44, v45
	v_cvt_pk_bf16_f32 v197, v46, v47
	v_cvt_pk_bf16_f32 v198, v40, v41
	v_cvt_pk_bf16_f32 v199, v42, v43
	v_and_b32_e32 v222, 0xffff0000, v200
	v_lshlrev_b32_e32 v200, 16, v200
	v_and_b32_e32 v223, 0xffff0000, v201
	v_lshlrev_b32_e32 v201, 16, v201
	v_and_b32_e32 v224, 0xffff0000, v202
	v_lshlrev_b32_e32 v202, 16, v202
	v_and_b32_e32 v225, 0xffff0000, v203
	v_lshlrev_b32_e32 v203, 16, v203
	v_add_f32_e32 v36, v36, v200
	v_add_f32_e32 v37, v37, v222
	v_add_f32_e32 v38, v38, v201
	v_add_f32_e32 v39, v39, v223
	v_add_f32_e32 v32, v32, v202
	v_add_f32_e32 v33, v33, v224
	v_add_f32_e32 v34, v34, v203
	v_add_f32_e32 v35, v35, v225
	v_cvt_pk_bf16_f32 v200, v36, v37
	v_cvt_pk_bf16_f32 v201, v38, v39
	v_cvt_pk_bf16_f32 v202, v32, v33
	v_cvt_pk_bf16_f32 v203, v34, v35
	s_add_u32 s24, s24, 0x10000
	s_addc_u32 s25, s25, 0
	global_store_dwordx4 v220, v[196:199], s[24:25]
	global_store_dwordx4 v220, v[200:203], s[24:25] offset:256
	v_mul_f32_e32 v222, v32, v32
	v_mul_f32_e32 v223, v40, v40
	v_fmac_f32_e32 v222, v33, v33
	v_fmac_f32_e32 v223, v41, v41
	v_fmac_f32_e32 v222, v34, v34
	v_fmac_f32_e32 v223, v42, v42
	v_fmac_f32_e32 v222, v35, v35
	v_fmac_f32_e32 v223, v43, v43
	v_fmac_f32_e32 v222, v36, v36
	v_fmac_f32_e32 v223, v44, v44
	v_fmac_f32_e32 v222, v37, v37
	v_fmac_f32_e32 v223, v45, v45
	v_fmac_f32_e32 v222, v38, v38
	v_fmac_f32_e32 v223, v46, v46
	v_fmac_f32_e32 v222, v39, v39
	v_fmac_f32_e32 v223, v47, v47
	v_add_f32_e32 v32, v222, v223
	s_waitcnt vmcnt(14)
	v_and_b32_e32 v222, 0xffff0000, v204
	v_lshlrev_b32_e32 v204, 16, v204
	v_and_b32_e32 v223, 0xffff0000, v205
	v_lshlrev_b32_e32 v205, 16, v205
	v_and_b32_e32 v224, 0xffff0000, v206
	v_lshlrev_b32_e32 v206, 16, v206
	v_and_b32_e32 v225, 0xffff0000, v207
	v_lshlrev_b32_e32 v207, 16, v207
	v_add_f32_e32 v28, v28, v204
	v_add_f32_e32 v29, v29, v222
	v_add_f32_e32 v30, v30, v205
	v_add_f32_e32 v31, v31, v223
	v_add_f32_e32 v24, v24, v206
	v_add_f32_e32 v25, v25, v224
	v_add_f32_e32 v26, v26, v207
	v_add_f32_e32 v27, v27, v225
	v_cvt_pk_bf16_f32 v204, v28, v29
	v_cvt_pk_bf16_f32 v205, v30, v31
	v_cvt_pk_bf16_f32 v206, v24, v25
	v_cvt_pk_bf16_f32 v207, v26, v27
	v_and_b32_e32 v222, 0xffff0000, v216
	v_lshlrev_b32_e32 v216, 16, v216
	v_and_b32_e32 v223, 0xffff0000, v217
	v_lshlrev_b32_e32 v217, 16, v217
	v_and_b32_e32 v224, 0xffff0000, v218
	v_lshlrev_b32_e32 v218, 16, v218
	v_and_b32_e32 v225, 0xffff0000, v219
	v_lshlrev_b32_e32 v219, 16, v219
	v_add_f32_e32 v20, v20, v216
	v_add_f32_e32 v21, v21, v222
	v_add_f32_e32 v22, v22, v217
	v_add_f32_e32 v23, v23, v223
	v_add_f32_e32 v16, v16, v218
	v_add_f32_e32 v17, v17, v224
	v_add_f32_e32 v18, v18, v219
	v_add_f32_e32 v19, v19, v225
	v_cvt_pk_bf16_f32 v216, v20, v21
	v_cvt_pk_bf16_f32 v217, v22, v23
	v_cvt_pk_bf16_f32 v218, v16, v17
	v_cvt_pk_bf16_f32 v219, v18, v19
	s_add_u32 s24, s24, 0x10000
	s_addc_u32 s25, s25, 0
	global_store_dwordx4 v220, v[204:207], s[24:25]
	global_store_dwordx4 v220, v[216:219], s[24:25] offset:256
	v_mul_f32_e32 v222, v16, v16
	v_mul_f32_e32 v223, v24, v24
	v_fmac_f32_e32 v222, v17, v17
	v_fmac_f32_e32 v223, v25, v25
	v_fmac_f32_e32 v222, v18, v18
	v_fmac_f32_e32 v223, v26, v26
	v_fmac_f32_e32 v222, v19, v19
	v_fmac_f32_e32 v223, v27, v27
	v_fmac_f32_e32 v222, v20, v20
	v_fmac_f32_e32 v223, v28, v28
	v_fmac_f32_e32 v222, v21, v21
	v_fmac_f32_e32 v223, v29, v29
	v_fmac_f32_e32 v222, v22, v22
	v_fmac_f32_e32 v223, v30, v30
	v_fmac_f32_e32 v222, v23, v23
	v_fmac_f32_e32 v223, v31, v31
	v_add_f32_e32 v16, v222, v223
	s_waitcnt vmcnt(12)
	v_and_b32_e32 v222, 0xffff0000, v130
	v_lshlrev_b32_e32 v130, 16, v130
	v_and_b32_e32 v223, 0xffff0000, v131
	v_lshlrev_b32_e32 v131, 16, v131
	v_and_b32_e32 v224, 0xffff0000, v132
	v_lshlrev_b32_e32 v132, 16, v132
	v_and_b32_e32 v225, 0xffff0000, v133
	v_lshlrev_b32_e32 v133, 16, v133
	v_add_f32_e32 v12, v12, v130
	v_add_f32_e32 v13, v13, v222
	v_add_f32_e32 v14, v14, v131
	v_add_f32_e32 v15, v15, v223
	v_add_f32_e32 v8, v8, v132
	v_add_f32_e32 v9, v9, v224
	v_add_f32_e32 v10, v10, v133
	v_add_f32_e32 v11, v11, v225
	v_cvt_pk_bf16_f32 v130, v12, v13
	v_cvt_pk_bf16_f32 v131, v14, v15
	v_cvt_pk_bf16_f32 v132, v8, v9
	v_cvt_pk_bf16_f32 v133, v10, v11
	v_and_b32_e32 v222, 0xffff0000, v134
	v_lshlrev_b32_e32 v134, 16, v134
	v_and_b32_e32 v223, 0xffff0000, v135
	v_lshlrev_b32_e32 v135, 16, v135
	v_and_b32_e32 v224, 0xffff0000, v136
	v_lshlrev_b32_e32 v136, 16, v136
	v_and_b32_e32 v225, 0xffff0000, v137
	v_lshlrev_b32_e32 v137, 16, v137
	v_add_f32_e32 v4, v4, v134
	v_add_f32_e32 v5, v5, v222
	v_add_f32_e32 v6, v6, v135
	v_add_f32_e32 v7, v7, v223
	v_add_f32_e32 v0, v0, v136
	v_add_f32_e32 v1, v1, v224
	v_add_f32_e32 v2, v2, v137
	v_add_f32_e32 v3, v3, v225
	v_cvt_pk_bf16_f32 v134, v4, v5
	v_cvt_pk_bf16_f32 v135, v6, v7
	v_cvt_pk_bf16_f32 v136, v0, v1
	v_cvt_pk_bf16_f32 v137, v2, v3
	s_add_u32 s24, s24, 0x10000
	s_addc_u32 s25, s25, 0
	global_store_dwordx4 v220, v[130:133], s[24:25]
	global_store_dwordx4 v220, v[134:137], s[24:25] offset:256
	v_mul_f32_e32 v222, v0, v0
	v_mul_f32_e32 v223, v8, v8
	v_fmac_f32_e32 v222, v1, v1
	v_fmac_f32_e32 v223, v9, v9
	v_fmac_f32_e32 v222, v2, v2
	v_fmac_f32_e32 v223, v10, v10
	v_fmac_f32_e32 v222, v3, v3
	v_fmac_f32_e32 v223, v11, v11
	v_fmac_f32_e32 v222, v4, v4
	v_fmac_f32_e32 v223, v12, v12
	v_fmac_f32_e32 v222, v5, v5
	v_fmac_f32_e32 v223, v13, v13
	v_fmac_f32_e32 v222, v6, v6
	v_fmac_f32_e32 v223, v14, v14
	v_fmac_f32_e32 v222, v7, v7
	v_fmac_f32_e32 v223, v15, v15
	v_add_f32_e32 v0, v222, v223
	v_xor_b32_e32 v224, 16, v214
	v_xor_b32_e32 v225, 32, v214
	v_lshlrev_b32_e32 v224, 2, v224
	v_lshlrev_b32_e32 v225, 2, v225
	ds_bpermute_b32 v113, v224, v112
	ds_bpermute_b32 v97, v224, v96
	ds_bpermute_b32 v81, v224, v80
	ds_bpermute_b32 v65, v224, v64
	ds_bpermute_b32 v49, v224, v48
	ds_bpermute_b32 v33, v224, v32
	ds_bpermute_b32 v17, v224, v16
	ds_bpermute_b32 v1, v224, v0
	s_waitcnt lgkmcnt(0)
	v_add_f32_e32 v112, v112, v113
	v_add_f32_e32 v96, v96, v97
	v_add_f32_e32 v80, v80, v81
	v_add_f32_e32 v64, v64, v65
	v_add_f32_e32 v48, v48, v49
	v_add_f32_e32 v32, v32, v33
	v_add_f32_e32 v16, v16, v17
	v_add_f32_e32 v0, v0, v1
	ds_bpermute_b32 v113, v225, v112
	ds_bpermute_b32 v97, v225, v96
	ds_bpermute_b32 v81, v225, v80
	ds_bpermute_b32 v65, v225, v64
	ds_bpermute_b32 v49, v225, v48
	ds_bpermute_b32 v33, v225, v32
	ds_bpermute_b32 v17, v225, v16
	ds_bpermute_b32 v1, v225, v0
	s_waitcnt lgkmcnt(0)
	v_add_f32_e32 v112, v112, v113
	v_add_f32_e32 v96, v96, v97
	v_add_f32_e32 v80, v80, v81
	v_add_f32_e32 v64, v64, v65
	v_add_f32_e32 v48, v48, v49
	v_add_f32_e32 v32, v32, v33
	v_add_f32_e32 v16, v16, v17
	v_add_f32_e32 v0, v0, v1
	s_mov_b32 s24, s6
	s_mov_b32 s25, s7
	s_and_saveexec_b64 s[26:27], s[2:3]
	global_store_dword v221, v112, s[24:25]
	global_store_dword v221, v96, s[24:25] offset:2048
	s_add_u32 s24, s24, 0x1000
	s_addc_u32 s25, s25, 0
	global_store_dword v221, v80, s[24:25]
	global_store_dword v221, v64, s[24:25] offset:2048
	s_add_u32 s24, s24, 0x3000
	s_addc_u32 s25, s25, 0
	global_store_dword v221, v48, s[24:25]
	global_store_dword v221, v32, s[24:25] offset:2048
	s_add_u32 s24, s24, 0x1000
	s_addc_u32 s25, s25, 0
	global_store_dword v221, v16, s[24:25]
	global_store_dword v221, v0, s[24:25] offset:2048
	s_or_b64 exec, exec, s[26:27]
	s_andn2_b64 vcc, exec, s[4:5]
	s_mov_b64 s[4:5], -1
	s_cbranch_vccnz .LBB0_998
	s_andn2_b64 vcc, exec, s[12:13]
	s_cbranch_vccnz .LBB0_997
	s_barrier
	s_branch .LBB0_997

.LBB0_1031:
	v_lshl_add_u64 v[68:69], v[66:67], 0, s[10:11]
	s_mov_b32 s5, 0x3b1d0000
	v_add_co_u32_e32 v78, vcc, s5, v68
	s_mov_b32 s12, 0x3b1e0000
	s_nop 0
	v_addc_co_u32_e32 v79, vcc, 0, v69, vcc
	v_add_co_u32_e32 v74, vcc, s12, v68
	s_mov_b32 s13, 0x3b1f0000
	s_nop 0
	v_addc_co_u32_e32 v75, vcc, 0, v69, vcc
	v_add_co_u32_e32 v72, vcc, s13, v68
	s_mov_b32 s14, 0x3b200000
	s_nop 0
	v_addc_co_u32_e32 v73, vcc, 0, v69, vcc
	v_add_co_u32_e32 v70, vcc, s14, v68
	v_lshl_add_u64 v[126:127], v[64:65], 0, s[10:11]
	s_mov_b32 s15, 0x3008000
	v_addc_co_u32_e32 v71, vcc, 0, v69, vcc
	v_add_co_u32_e32 v76, vcc, s15, v126
	s_mov_b32 s16, 0x3018000
	s_nop 0
	v_addc_co_u32_e32 v77, vcc, 0, v127, vcc
	global_load_dwordx4 v[82:85], v[76:77], off
	global_load_dwordx4 v[86:89], v[78:79], off
	global_load_dwordx4 v[90:93], v[78:79], off offset:64
	global_load_dwordx4 v[94:97], v[76:77], off offset:64
	global_load_dwordx4 v[98:101], v[74:75], off
	global_load_dwordx4 v[102:105], v[74:75], off offset:64
	global_load_dwordx4 v[106:109], v[72:73], off
	global_load_dwordx4 v[110:113], v[72:73], off offset:64
	global_load_dwordx4 v[114:117], v[70:71], off
	global_load_dwordx4 v[118:121], v[70:71], off offset:64
	v_add_co_u32_e32 v68, vcc, s16, v126
	s_mov_b32 s5, 0x3088000
	s_nop 0
	v_addc_co_u32_e32 v69, vcc, 0, v127, vcc
	v_add_co_u32_e32 v138, vcc, s5, v126
	s_mov_b32 s5, 0x3098000
	s_nop 0
	v_addc_co_u32_e32 v139, vcc, 0, v127, vcc
	v_add_co_u32_e32 v126, vcc, s5, v126
	s_add_u32 s10, s10, 0x100
	s_nop 0
	v_addc_co_u32_e32 v127, vcc, 0, v127, vcc
	s_addc_u32 s11, s11, 0
	s_cmpk_eq_i32 s10, 0x200
	s_waitcnt vmcnt(0) lgkmcnt(0)
	v_mfma_f32_16x16x32_bf16 v[56:59], v[82:85], v[86:89], v[56:59]
	v_mfma_f32_16x16x32_bf16 v[52:55], v[82:85], v[98:101], v[52:55]
	v_mfma_f32_16x16x32_bf16 v[48:51], v[82:85], v[106:109], v[48:51]
	v_mfma_f32_16x16x32_bf16 v[44:47], v[82:85], v[114:117], v[44:47]
	global_load_dwordx4 v[82:85], v[68:69], off
	global_load_dwordx4 v[122:125], v[68:69], off offset:64
	v_mfma_f32_16x16x32_bf16 v[56:59], v[94:97], v[90:93], v[56:59]
	v_mfma_f32_16x16x32_bf16 v[52:55], v[94:97], v[102:105], v[52:55]
	v_mfma_f32_16x16x32_bf16 v[48:51], v[94:97], v[110:113], v[48:51]
	v_mfma_f32_16x16x32_bf16 v[44:47], v[94:97], v[118:121], v[44:47]
	s_waitcnt vmcnt(0) lgkmcnt(0)
	v_mfma_f32_16x16x32_bf16 v[12:15], v[82:85], v[86:89], v[12:15]
	v_mfma_f32_16x16x32_bf16 v[8:11], v[82:85], v[98:101], v[8:11]
	v_mfma_f32_16x16x32_bf16 v[4:7], v[82:85], v[106:109], v[4:7]
	v_mfma_f32_16x16x32_bf16 v[0:3], v[82:85], v[114:117], v[0:3]
	global_load_dwordx4 v[82:85], v[138:139], off
	global_load_dwordx4 v[130:133], v[138:139], off offset:64
	global_load_dwordx4 v[134:137], v[126:127], off
	v_mfma_f32_16x16x32_bf16 v[12:15], v[122:125], v[90:93], v[12:15]
	v_mfma_f32_16x16x32_bf16 v[8:11], v[122:125], v[102:105], v[8:11]
	v_mfma_f32_16x16x32_bf16 v[4:7], v[122:125], v[110:113], v[4:7]
	v_mfma_f32_16x16x32_bf16 v[0:3], v[122:125], v[118:121], v[0:3]
	s_waitcnt vmcnt(0) lgkmcnt(0)
	v_mfma_f32_16x16x32_bf16 v[16:19], v[82:85], v[86:89], v[16:19]
	v_mfma_f32_16x16x32_bf16 v[24:27], v[82:85], v[98:101], v[24:27]
	v_mfma_f32_16x16x32_bf16 v[28:31], v[82:85], v[106:109], v[28:31]
	v_mfma_f32_16x16x32_bf16 v[36:39], v[82:85], v[114:117], v[36:39]
	global_load_dwordx4 v[82:85], v[126:127], off offset:64
	v_mfma_f32_16x16x32_bf16 v[20:23], v[134:137], v[86:89], v[20:23]
	global_load_dwordx4 v[86:89], v[76:77], off offset:128
	v_mfma_f32_16x16x32_bf16 v[32:35], v[134:137], v[98:101], v[32:35]
	v_mfma_f32_16x16x32_bf16 v[40:43], v[134:137], v[106:109], v[40:43]
	v_mfma_f32_16x16x32_bf16 v[60:63], v[134:137], v[114:117], v[60:63]
	v_mfma_f32_16x16x32_bf16 v[16:19], v[130:133], v[90:93], v[16:19]
	v_mfma_f32_16x16x32_bf16 v[24:27], v[130:133], v[102:105], v[24:27]
	v_mfma_f32_16x16x32_bf16 v[28:31], v[130:133], v[110:113], v[28:31]
	s_waitcnt vmcnt(0) lgkmcnt(0)
	v_mfma_f32_16x16x32_bf16 v[20:23], v[82:85], v[90:93], v[20:23]
	v_mfma_f32_16x16x32_bf16 v[32:35], v[82:85], v[102:105], v[32:35]
	v_mfma_f32_16x16x32_bf16 v[40:43], v[82:85], v[110:113], v[40:43]
	v_mfma_f32_16x16x32_bf16 v[60:63], v[82:85], v[118:121], v[60:63]
	global_load_dwordx4 v[82:85], v[78:79], off offset:128
	global_load_dwordx4 v[90:93], v[78:79], off offset:192
	s_nop 0
	global_load_dwordx4 v[76:79], v[76:77], off offset:192
	s_nop 0
	global_load_dwordx4 v[94:97], v[74:75], off offset:128
	global_load_dwordx4 v[98:101], v[74:75], off offset:192
	global_load_dwordx4 v[102:105], v[72:73], off offset:128
	s_nop 0
	global_load_dwordx4 v[72:75], v[72:73], off offset:192
	s_nop 0
	global_load_dwordx4 v[106:109], v[70:71], off offset:128
	global_load_dwordx4 v[110:113], v[70:71], off offset:192
	v_mfma_f32_16x16x32_bf16 v[36:39], v[130:133], v[118:121], v[36:39]
	s_waitcnt vmcnt(0) lgkmcnt(0)
	v_mfma_f32_16x16x32_bf16 v[56:59], v[86:89], v[82:85], v[56:59]
	v_mfma_f32_16x16x32_bf16 v[52:55], v[86:89], v[94:97], v[52:55]
	v_mfma_f32_16x16x32_bf16 v[48:51], v[86:89], v[102:105], v[48:51]
	v_mfma_f32_16x16x32_bf16 v[44:47], v[86:89], v[106:109], v[44:47]
	global_load_dwordx4 v[86:89], v[68:69], off offset:128
	s_nop 0
	global_load_dwordx4 v[68:71], v[68:69], off offset:192
	s_waitcnt vmcnt(0) lgkmcnt(0)
	v_mfma_f32_16x16x32_bf16 v[12:15], v[86:89], v[82:85], v[12:15]
	v_mfma_f32_16x16x32_bf16 v[8:11], v[86:89], v[94:97], v[8:11]
	v_mfma_f32_16x16x32_bf16 v[4:7], v[86:89], v[102:105], v[4:7]
	v_mfma_f32_16x16x32_bf16 v[0:3], v[86:89], v[106:109], v[0:3]
	global_load_dwordx4 v[86:89], v[138:139], off offset:128
	global_load_dwordx4 v[114:117], v[138:139], off offset:192
	global_load_dwordx4 v[118:121], v[126:127], off offset:128
	s_waitcnt vmcnt(0) lgkmcnt(0)
	v_mfma_f32_16x16x32_bf16 v[16:19], v[86:89], v[82:85], v[16:19]
	v_mfma_f32_16x16x32_bf16 v[24:27], v[86:89], v[94:97], v[24:27]
	v_mfma_f32_16x16x32_bf16 v[28:31], v[86:89], v[102:105], v[28:31]
	v_mfma_f32_16x16x32_bf16 v[36:39], v[86:89], v[106:109], v[36:39]
	global_load_dwordx4 v[86:89], v[126:127], off offset:192
	v_mfma_f32_16x16x32_bf16 v[20:23], v[118:121], v[82:85], v[20:23]
	v_mfma_f32_16x16x32_bf16 v[32:35], v[118:121], v[94:97], v[32:35]
	v_mfma_f32_16x16x32_bf16 v[40:43], v[118:121], v[102:105], v[40:43]
	v_mfma_f32_16x16x32_bf16 v[60:63], v[118:121], v[106:109], v[60:63]
	v_mfma_f32_16x16x32_bf16 v[56:59], v[76:79], v[90:93], v[56:59]
	v_mfma_f32_16x16x32_bf16 v[52:55], v[76:79], v[98:101], v[52:55]
	v_mfma_f32_16x16x32_bf16 v[48:51], v[76:79], v[72:75], v[48:51]
	v_mfma_f32_16x16x32_bf16 v[44:47], v[76:79], v[110:113], v[44:47]
	v_mfma_f32_16x16x32_bf16 v[12:15], v[68:71], v[90:93], v[12:15]
	v_mfma_f32_16x16x32_bf16 v[8:11], v[68:71], v[98:101], v[8:11]
	v_mfma_f32_16x16x32_bf16 v[4:7], v[68:71], v[72:75], v[4:7]
	v_mfma_f32_16x16x32_bf16 v[0:3], v[68:71], v[110:113], v[0:3]
	v_mfma_f32_16x16x32_bf16 v[16:19], v[114:117], v[90:93], v[16:19]
	v_mfma_f32_16x16x32_bf16 v[24:27], v[114:117], v[98:101], v[24:27]
	v_mfma_f32_16x16x32_bf16 v[28:31], v[114:117], v[72:75], v[28:31]
	v_mfma_f32_16x16x32_bf16 v[36:39], v[114:117], v[110:113], v[36:39]
	s_waitcnt vmcnt(0) lgkmcnt(0)
	v_mfma_f32_16x16x32_bf16 v[20:23], v[86:89], v[90:93], v[20:23]
	v_mfma_f32_16x16x32_bf16 v[32:35], v[86:89], v[98:101], v[32:35]
	v_mfma_f32_16x16x32_bf16 v[40:43], v[86:89], v[72:75], v[40:43]
	v_mfma_f32_16x16x32_bf16 v[60:63], v[86:89], v[110:113], v[60:63]
	s_cbranch_scc0 .LBB0_1031
	v_and_b32_e32 v65, 63, v81
	v_lshl_add_u32 v66, v65, 4, 0
	s_ashr_i32 s10, s0, 7
	v_bfe_u32 v64, v81, 4, 2
	v_lshl_add_u32 v67, s3, 14, v66
	s_lshl_b32 s5, s10, 4
	ds_write_b128 v67, v[56:59]
	ds_write_b128 v67, v[52:55] offset:1024
	ds_write_b128 v67, v[48:51] offset:2048
	ds_write_b128 v67, v[44:47] offset:3072
	ds_write_b128 v67, v[12:15] offset:4096
	ds_write_b128 v67, v[8:11] offset:5120
	ds_write_b128 v67, v[4:7] offset:6144
	ds_write_b128 v67, v[0:3] offset:7168
	ds_write_b128 v67, v[16:19] offset:8192
	ds_write_b128 v67, v[24:27] offset:9216
	ds_write_b128 v67, v[28:31] offset:10240
	ds_write_b128 v67, v[36:39] offset:11264
	ds_write_b128 v67, v[20:23] offset:12288
	ds_write_b128 v67, v[32:35] offset:13312
	ds_write_b128 v67, v[40:43] offset:14336
	ds_write_b128 v67, v[60:63] offset:15360
	s_bfe_u32 s3, s0, 0x10006
	s_addk_i32 s5, 0x4000
	v_lshlrev_b32_e32 v1, 2, v64
	v_or_b32_e32 v0, s5, v80
	v_lshl_or_b32 v1, s3, 4, v1
	v_or_b32_e32 v4, s1, v1
	v_ashrrev_i32_e32 v1, 31, v0
	v_lshlrev_b64 v[2:3], 12, v[0:1]
	s_ashr_i32 s5, s4, 31
	v_lshl_add_u64 v[2:3], s[8:9], 0, v[2:3]
	v_lshl_add_u64 v[2:3], s[4:5], 1, v[2:3]
	v_lshlrev_b32_e32 v128, 1, v4
	v_lshl_add_u64 v[14:15], v[2:3], 0, v[128:129]
	s_waitcnt lgkmcnt(0)
	s_barrier
	global_load_dwordx2 v[16:17], v[14:15], off
	global_load_dwordx2 v[18:19], v[14:15], off offset:256
	s_lshl_b32 s1, s3, 2
	s_add_i32 s1, s1, s10
	v_lshl_add_u32 v28, s1, 10, v66
	ds_read_b128 v[2:5], v28
	ds_read_b128 v[6:9], v28 offset:8192
	ds_read_b128 v[10:13], v28 offset:16384
	s_waitcnt lgkmcnt(0)
	v_pk_add_f32 v[20:21], v[4:5], 0 op_sel_hi:[1,0]
	v_pk_add_f32 v[22:23], v[2:3], 0 op_sel_hi:[1,0]
	ds_read_b128 v[2:5], v28 offset:24576
	v_pk_add_f32 v[24:25], v[8:9], 0 op_sel_hi:[1,0]
	v_pk_add_f32 v[26:27], v[6:7], 0 op_sel_hi:[1,0]
	ds_read_b128 v[6:9], v28 offset:32768
	v_pk_add_f32 v[22:23], v[22:23], v[10:11]
	s_waitcnt lgkmcnt(0)
	v_pk_add_f32 v[24:25], v[24:25], v[4:5]
	v_pk_add_f32 v[26:27], v[26:27], v[2:3]
	ds_read_b128 v[2:5], v28 offset:49152
	v_pk_add_f32 v[20:21], v[20:21], v[12:13]
	ds_read_b128 v[10:13], v28 offset:40960
	v_pk_add_f32 v[22:23], v[22:23], v[6:7]
	v_pk_add_f32 v[20:21], v[20:21], v[8:9]
	ds_read_b128 v[6:9], v28 offset:57344
	s_waitcnt lgkmcnt(0)
	v_pk_add_f32 v[22:23], v[22:23], v[2:3]
	v_add_u32_e32 v2, 0x10000, v28
	v_pk_add_f32 v[20:21], v[20:21], v[4:5]
	ds_read_b128 v[2:5], v2
	v_pk_add_f32 v[10:11], v[26:27], v[10:11]
	v_pk_add_f32 v[12:13], v[24:25], v[12:13]
	v_pk_add_f32 v[10:11], v[10:11], v[6:7]
	v_add_u32_e32 v6, 0x12000, v28
	v_pk_add_f32 v[12:13], v[12:13], v[8:9]
	ds_read_b128 v[6:9], v6
	s_waitcnt lgkmcnt(0)
	v_pk_add_f32 v[22:23], v[22:23], v[2:3]
	v_add_u32_e32 v2, 0x14000, v28
	v_pk_add_f32 v[20:21], v[20:21], v[4:5]
	ds_read_b128 v[2:5], v2
	v_pk_add_f32 v[10:11], v[10:11], v[6:7]
	v_add_u32_e32 v6, 0x16000, v28
	v_pk_add_f32 v[12:13], v[12:13], v[8:9]
	ds_read_b128 v[6:9], v6
	s_waitcnt lgkmcnt(0)
	v_pk_add_f32 v[22:23], v[22:23], v[2:3]
	v_add_u32_e32 v2, 0x18000, v28
	v_pk_add_f32 v[20:21], v[20:21], v[4:5]
	ds_read_b128 v[2:5], v2
	v_pk_add_f32 v[26:27], v[10:11], v[6:7]
	v_add_u32_e32 v6, 0x1a000, v28
	v_pk_add_f32 v[24:25], v[12:13], v[8:9]
	ds_read_b128 v[6:9], v6
	s_waitcnt lgkmcnt(0)
	v_pk_add_f32 v[22:23], v[22:23], v[2:3]
	v_add_u32_e32 v2, 0x1c000, v28
	v_add_u32_e32 v10, 0x1e000, v28
	v_pk_add_f32 v[20:21], v[20:21], v[4:5]
	ds_read_b128 v[2:5], v2
	ds_read_b128 v[10:13], v10
	v_pk_add_f32 v[6:7], v[26:27], v[6:7]
	v_pk_add_f32 v[8:9], v[24:25], v[8:9]
	s_waitcnt lgkmcnt(0)
	v_pk_add_f32 v[2:3], v[22:23], v[2:3]
	v_pk_add_f32 v[6:7], v[6:7], v[10:11]
	v_pk_add_f32 v[4:5], v[20:21], v[4:5]
	v_pk_add_f32 v[8:9], v[8:9], v[12:13]
	s_waitcnt vmcnt(0)
	v_lshlrev_b32_e32 v10, 16, v16
	v_and_b32_e32 v11, 0xffff0000, v16
	v_pk_add_f32 v[2:3], v[2:3], v[10:11]
	v_lshlrev_b32_e32 v10, 16, v18
	v_and_b32_e32 v11, 0xffff0000, v18
	v_lshlrev_b32_e32 v12, 16, v17
	v_and_b32_e32 v13, 0xffff0000, v17
	v_pk_add_f32 v[6:7], v[6:7], v[10:11]
	v_pk_add_f32 v[4:5], v[4:5], v[12:13]
	v_lshlrev_b32_e32 v12, 16, v19
	v_and_b32_e32 v13, 0xffff0000, v19
	v_mul_f32_e32 v10, v6, v6
	v_mul_f32_e32 v11, v7, v7
	v_pk_add_f32 v[8:9], v[8:9], v[12:13]
	v_fmac_f32_e32 v10, v2, v2
	v_fmac_f32_e32 v11, v3, v3
	v_add_f32_e32 v10, v10, v11
	v_mul_f32_e32 v11, v8, v8
	v_fmac_f32_e32 v11, v4, v4
	v_add_f32_e32 v10, v11, v10
	v_mul_f32_e32 v11, v9, v9
	v_fmac_f32_e32 v11, v5, v5
	v_and_b32_e32 v12, 64, v214
	v_add_f32_e32 v10, v11, v10
	v_xor_b32_e32 v11, 16, v214
	v_add_u32_e32 v12, 64, v12
	v_cmp_lt_i32_e32 vcc, v11, v12
	v_cvt_pk_bf16_f32 v2, v2, v3
	v_cvt_pk_bf16_f32 v3, v4, v5
	v_xor_b32_e32 v5, 32, v214
	global_store_dwordx2 v[14:15], v[2:3], off
	v_cndmask_b32_e32 v11, v214, v11, vcc
	v_lshlrev_b32_e32 v11, 2, v11
	ds_bpermute_b32 v11, v11, v10
	v_cmp_lt_i32_e32 vcc, v5, v12
	v_cvt_pk_bf16_f32 v2, v6, v7
	v_cvt_pk_bf16_f32 v3, v8, v9
	global_store_dwordx2 v[14:15], v[2:3], off offset:256
	s_waitcnt lgkmcnt(0)
	v_add_f32_e32 v4, v10, v11
	v_cndmask_b32_e32 v5, v214, v5, vcc
	v_lshlrev_b32_e32 v5, 2, v5
	ds_bpermute_b32 v5, v5, v4
	v_cmp_gt_u32_e32 vcc, 16, v65
	s_waitcnt lgkmcnt(0)
	v_add_f32_e32 v2, v4, v5
	s_and_saveexec_b64 s[4:5], vcc
	s_and_b32 s1, s0, 0xffffffc0
	s_add_i32 s1, s1, 0
	v_lshl_add_u32 v3, v80, 2, s1
	v_add_u32_e32 v3, 0x20100, v3
	ds_write_b32 v3, v2
	s_or_b64 exec, exec, s[4:5]
	v_or_b32_e32 v3, s3, v64
	v_cmp_eq_u32_e32 vcc, 0, v3
	s_waitcnt lgkmcnt(0)
	s_barrier
	s_and_saveexec_b64 s[4:5], vcc
	s_cbranch_execz .LBB0_1036
	s_andn2_b32 s0, s0, 63
	s_add_i32 s0, s0, 0
	s_add_i32 s0, s0, 0x20100
	v_lshl_add_u32 v3, v80, 2, s0
	ds_read_b32 v3, v3 offset:64
	v_lshlrev_b64 v[0:1], 7, v[0:1]
	v_lshl_add_u64 v[0:1], s[6:7], 0, v[0:1]
	s_ashr_i32 s3, s2, 31
	v_lshl_add_u64 v[0:1], s[2:3], 2, v[0:1]
	s_waitcnt lgkmcnt(0)
	v_add_f32_e32 v2, v2, v3
	global_store_dword v[0:1], v2, off

.LBB0_1090:
	s_add_u32 s20, s20, s18
	s_addc_u32 s21, s21, s19
	s_add_u32 s22, s0, s20
	s_addc_u32 s23, s1, s21
	v_cmp_gt_i64_e32 vcc, s[22:23], v[186:187]
	s_mov_b64 s[22:23], -1
	s_cbranch_vccnz .LBB0_1085
	v_lshl_add_u32 v4, s25, 8, v2
	v_ashrrev_i32_e32 v5, 31, v4
	v_lshl_add_u32 v6, s27, 8, v2
	v_lshlrev_b64 v[4:5], 7, v[4:5]
	v_ashrrev_i32_e32 v7, 31, v6
	v_lshl_add_u64 v[4:5], v[0:1], 0, v[4:5]
	v_lshlrev_b64 v[6:7], 7, v[6:7]
	v_lshl_add_u64 v[6:7], v[0:1], 0, v[6:7]
	global_load_dwordx4 v[10:13], v[4:5], off
	global_load_dwordx4 v[14:17], v[4:5], off offset:16
	global_load_dwordx4 v[18:21], v[4:5], off offset:32
	global_load_dwordx4 v[22:25], v[4:5], off offset:48
	global_load_dwordx4 v[26:29], v[6:7], off
	global_load_dwordx4 v[30:33], v[6:7], off offset:16
	global_load_dwordx4 v[34:37], v[6:7], off offset:32
	global_load_dwordx4 v[38:41], v[6:7], off offset:48
	v_mov_b32_e32 v5, v129
	v_mov_b32_e32 v4, v129
	s_waitcnt vmcnt(0) lgkmcnt(0)
	v_pk_add_f32 v[6:7], v[12:13], v[16:17]
	v_pk_add_f32 v[10:11], v[10:11], v[14:15]
	v_pk_add_f32 v[12:13], v[20:21], v[24:25]
	v_pk_add_f32 v[14:15], v[18:19], v[22:23]
	v_pk_add_f32 v[16:17], v[28:29], v[32:33]
	v_pk_add_f32 v[18:19], v[26:27], v[30:31]
	v_pk_add_f32 v[20:21], v[36:37], v[40:41]
	v_pk_add_f32 v[22:23], v[34:35], v[38:39]
	v_pk_add_f32 v[6:7], v[6:7], v[12:13]
	v_pk_add_f32 v[10:11], v[10:11], v[14:15]
	v_pk_add_f32 v[12:13], v[16:17], v[20:21]
	v_pk_add_f32 v[14:15], v[18:19], v[22:23]
	v_add_f32_e32 v9, v10, v11
	v_add_f32_e32 v6, v6, v7
	v_add_f32_e32 v10, v14, v15
	v_add_f32_e32 v11, v12, v13
	v_add_f32_e32 v7, v9, v6
	v_add_f32_e32 v6, v10, v11
	s_nop 0
	v_mov_b32_dpp v5, v7 quad_perm:[1,0,3,2] row_mask:0xf bank_mask:0xf
	v_mov_b32_dpp v4, v6 quad_perm:[1,0,3,2] row_mask:0xf bank_mask:0xf
	s_and_saveexec_b64 s[22:23], s[2:3]
	s_cbranch_execz .LBB0_1084
	v_add_f32_e32 v5, v7, v5
	v_fmamk_f32 v5, v5, 0x3a000000, v190
	v_mul_f32_e32 v7, 0x4b800000, v5
	v_cmp_gt_f32_e32 vcc, s70, v5
	s_nop 1
	v_cndmask_b32_e32 v5, v5, v7, vcc
	v_rsq_f32_e32 v5, v5
	s_nop 0
	v_mul_f32_e32 v7, 0x45800000, v5
	v_cndmask_b32_e32 v5, v5, v7, vcc
	s_andn2_b64 vcc, exec, s[4:5]
	ds_write_b32 v3, v5
	s_cbranch_vccnz .LBB0_1084
	v_add_f32_e32 v4, v6, v4
	v_fmamk_f32 v4, v4, 0x3a000000, v190
	v_mul_f32_e32 v5, 0x4b800000, v4
	v_cmp_gt_f32_e32 vcc, s70, v4
	s_nop 1
	v_cndmask_b32_e32 v4, v4, v5, vcc
	v_rsq_f32_e32 v4, v4
	s_nop 0
	v_mul_f32_e32 v5, 0x45800000, v4
	v_cndmask_b32_e32 v4, v4, v5, vcc
	ds_write_b32 v3, v4 offset:1024
	s_branch .LBB0_1084

.LBB0_1104:
	v_lshl_add_u32 v142, s49, 10, v152
	ds_read2_b32 v[160:161], v142 offset1:16
	ds_read2_b32 v[148:149], v142 offset0:32 offset1:48
	ds_read2_b32 v[146:147], v142 offset0:128 offset1:144
	ds_read2_b32 v[142:143], v142 offset0:160 offset1:176
	v_pk_mul_f32 v[168:169], v[124:125], v[92:93]
	s_waitcnt lgkmcnt(0)
	v_mul_f32_e32 v158, v160, v160
	v_mul_f32_e32 v160, 0xbfb8aa3b, v160
	v_pk_mul_f32 v[164:165], v[124:125], v[160:161] op_sel_hi:[1,0]
	v_pk_mul_f32 v[162:163], v[126:127], v[160:161] op_sel_hi:[1,0]
	v_exp_f32_e32 v155, v164
	v_exp_f32_e32 v159, v165
	v_exp_f32_e32 v164, v162
	v_exp_f32_e32 v165, v163
	v_add_f32_e32 v155, 1.0, v155
	v_rcp_f32_e32 v162, v155
	v_add_f32_e32 v155, 1.0, v159
	v_rcp_f32_e32 v163, v155
	v_add_f32_e32 v155, 1.0, v164
	v_rcp_f32_e32 v164, v155
	v_add_f32_e32 v155, 1.0, v165
	v_rcp_f32_e32 v165, v155
	v_pk_mul_f32 v[168:169], v[168:169], v[158:159] op_sel_hi:[1,0]
	v_pk_mul_f32 v[166:167], v[126:127], v[94:95]
	v_pk_mul_f32 v[162:163], v[168:169], v[162:163]
	v_pk_mul_f32 v[168:169], v[120:121], v[160:161] op_sel_hi:[1,0]
	v_pk_mul_f32 v[166:167], v[166:167], v[158:159] op_sel_hi:[1,0]
	v_exp_f32_e32 v155, v168
	v_pk_mul_f32 v[164:165], v[166:167], v[164:165]
	v_pk_mul_f32 v[166:167], v[122:123], v[160:161] op_sel_hi:[1,0]
	v_exp_f32_e32 v159, v169
	v_exp_f32_e32 v160, v166
	v_exp_f32_e32 v169, v167
	v_add_f32_e32 v155, 1.0, v155
	s_add_u32 s36, s51, 0xffffff00
	v_rcp_f32_e32 v166, v155
	v_add_f32_e32 v155, 1.0, v159
	s_addc_u32 s37, s52, -1
	s_lshl_b32 s38, s46, 7
	v_rcp_f32_e32 v167, v155
	v_add_f32_e32 v155, 1.0, v160
	v_lshl_add_u32 v154, s18, 8, v150
	s_ashr_i32 s39, s38, 31
	v_mov_b64_e32 v[144:145], s[6:7]
	s_movk_i32 s27, 0x2c00
	v_rcp_f32_e32 v168, v155
	v_add_f32_e32 v155, 1.0, v169
	v_mad_i64_i32 v[156:157], s[40:41], v154, s27, v[144:145]
	s_lshl_b64 s[38:39], s[38:39], 1
	v_rcp_f32_e32 v169, v155
	v_lshl_add_u64 v[156:157], v[156:157], 0, s[38:39]
	v_pk_mul_f32 v[170:171], v[122:123], v[90:91]
	v_pk_mul_f32 v[172:173], v[120:121], v[88:89]
	v_lshl_add_u64 v[156:157], v[156:157], 0, s[94:95]
	v_pk_mul_f32 v[170:171], v[170:171], v[158:159] op_sel_hi:[1,0]
	v_pk_mul_f32 v[158:159], v[172:173], v[158:159] op_sel_hi:[1,0]
	v_mul_f32_e32 v160, 0xbfb8aa3b, v161
	v_pk_mul_f32 v[158:159], v[158:159], v[166:167]
	v_lshl_add_u64 v[166:167], v[156:157], 0, v[128:129]
	v_cvt_pk_bf16_f32 v156, v162, v163
	v_cvt_pk_bf16_f32 v157, v164, v165
	v_or_b32_e32 v155, 16, v154
	v_pk_mul_f32 v[164:165], v[116:117], v[160:161] op_sel_hi:[1,0]
	v_pk_mul_f32 v[168:169], v[170:171], v[168:169]
	v_cvt_pk_bf16_f32 v158, v158, v159
	v_pk_mul_f32 v[162:163], v[118:119], v[160:161] op_sel_hi:[1,0]
	v_cvt_pk_bf16_f32 v159, v168, v169
	global_store_dwordx4 v[166:167], v[156:159], off
	v_pk_mul_f32 v[166:167], v[118:119], v[86:87]
	v_pk_mul_f32 v[168:169], v[116:117], v[84:85]
	v_mad_i64_i32 v[156:157], s[40:41], v155, s27, v[144:145]
	v_exp_f32_e32 v155, v164
	v_exp_f32_e32 v159, v165
	v_mul_f32_e32 v158, v161, v161
	v_exp_f32_e32 v161, v162
	v_exp_f32_e32 v165, v163
	v_add_f32_e32 v155, 1.0, v155
	v_rcp_f32_e32 v162, v155
	v_add_f32_e32 v155, 1.0, v159
	v_rcp_f32_e32 v163, v155
	v_add_f32_e32 v155, 1.0, v161
	v_rcp_f32_e32 v164, v155
	v_add_f32_e32 v155, 1.0, v165
	v_rcp_f32_e32 v165, v155
	v_pk_mul_f32 v[166:167], v[166:167], v[158:159] op_sel_hi:[1,0]
	v_pk_mul_f32 v[168:169], v[168:169], v[158:159] op_sel_hi:[1,0]
	v_pk_mul_f32 v[170:171], v[112:113], v[80:81]
	v_pk_mul_f32 v[164:165], v[166:167], v[164:165]
	v_pk_mul_f32 v[166:167], v[114:115], v[160:161] op_sel_hi:[1,0]
	v_pk_mul_f32 v[160:161], v[112:113], v[160:161] op_sel_hi:[1,0]
	v_exp_f32_e32 v166, v166
	v_exp_f32_e32 v155, v160
	v_exp_f32_e32 v159, v161
	v_exp_f32_e32 v167, v167
	v_pk_mul_f32 v[162:163], v[168:169], v[162:163]
	v_add_f32_e32 v155, 1.0, v155
	v_rcp_f32_e32 v160, v155
	v_add_f32_e32 v155, 1.0, v159
	v_rcp_f32_e32 v161, v155
	v_add_f32_e32 v155, 1.0, v166
	v_rcp_f32_e32 v166, v155
	v_add_f32_e32 v155, 1.0, v167
	v_rcp_f32_e32 v167, v155
	v_pk_mul_f32 v[168:169], v[114:115], v[82:83]
	v_lshl_add_u64 v[156:157], v[156:157], 0, s[38:39]
	v_pk_mul_f32 v[168:169], v[168:169], v[158:159] op_sel_hi:[1,0]
	v_pk_mul_f32 v[158:159], v[170:171], v[158:159] op_sel_hi:[1,0]
	v_lshl_add_u64 v[156:157], v[156:157], 0, s[94:95]
	v_pk_mul_f32 v[158:159], v[158:159], v[160:161]
	v_lshl_add_u64 v[160:161], v[156:157], 0, v[128:129]
	v_cvt_pk_bf16_f32 v156, v162, v163
	v_cvt_pk_bf16_f32 v157, v164, v165
	v_cvt_pk_bf16_f32 v158, v158, v159
	v_pk_mul_f32 v[166:167], v[168:169], v[166:167]
	v_or_b32_e32 v155, 32, v154
	v_cvt_pk_bf16_f32 v159, v166, v167
	global_store_dwordx4 v[160:161], v[156:159], off
	v_pk_mul_f32 v[166:167], v[108:109], v[76:77]
	v_pk_mul_f32 v[164:165], v[110:111], v[78:79]
	v_mul_f32_e32 v158, v148, v148
	v_mul_f32_e32 v148, 0xbfb8aa3b, v148
	v_pk_mul_f32 v[162:163], v[108:109], v[148:149] op_sel_hi:[1,0]
	v_mad_i64_i32 v[156:157], s[40:41], v155, s27, v[144:145]
	v_exp_f32_e32 v155, v162
	v_pk_mul_f32 v[160:161], v[110:111], v[148:149] op_sel_hi:[1,0]
	v_exp_f32_e32 v159, v163
	v_exp_f32_e32 v162, v160
	v_exp_f32_e32 v163, v161
	v_add_f32_e32 v155, 1.0, v155
	v_rcp_f32_e32 v160, v155
	v_add_f32_e32 v155, 1.0, v159
	v_rcp_f32_e32 v161, v155
	v_add_f32_e32 v155, 1.0, v162
	v_rcp_f32_e32 v162, v155
	v_add_f32_e32 v155, 1.0, v163
	v_rcp_f32_e32 v163, v155
	v_pk_mul_f32 v[166:167], v[166:167], v[158:159] op_sel_hi:[1,0]
	v_pk_mul_f32 v[164:165], v[164:165], v[158:159] op_sel_hi:[1,0]
	v_pk_mul_f32 v[160:161], v[166:167], v[160:161]
	v_pk_mul_f32 v[166:167], v[104:105], v[148:149] op_sel_hi:[1,0]
	v_pk_mul_f32 v[162:163], v[164:165], v[162:163]
	v_pk_mul_f32 v[164:165], v[106:107], v[148:149] op_sel_hi:[1,0]
	v_exp_f32_e32 v148, v166
	v_exp_f32_e32 v155, v167
	v_exp_f32_e32 v159, v164
	v_exp_f32_e32 v167, v165
	v_add_f32_e32 v148, 1.0, v148
	v_rcp_f32_e32 v164, v148
	v_add_f32_e32 v148, 1.0, v155
	v_rcp_f32_e32 v165, v148
	v_add_f32_e32 v148, 1.0, v159
	v_rcp_f32_e32 v166, v148
	v_add_f32_e32 v148, 1.0, v167
	v_rcp_f32_e32 v167, v148
	v_pk_mul_f32 v[168:169], v[106:107], v[74:75]
	v_pk_mul_f32 v[170:171], v[104:105], v[72:73]
	v_lshl_add_u64 v[156:157], v[156:157], 0, s[38:39]
	v_pk_mul_f32 v[168:169], v[168:169], v[158:159] op_sel_hi:[1,0]
	v_pk_mul_f32 v[158:159], v[170:171], v[158:159] op_sel_hi:[1,0]
	v_lshl_add_u64 v[156:157], v[156:157], 0, s[94:95]
	v_pk_mul_f32 v[158:159], v[158:159], v[164:165]
	v_lshl_add_u64 v[164:165], v[156:157], 0, v[128:129]
	v_cvt_pk_bf16_f32 v156, v160, v161
	v_cvt_pk_bf16_f32 v157, v162, v163
	v_cvt_pk_bf16_f32 v158, v158, v159
	v_pk_mul_f32 v[166:167], v[168:169], v[166:167]
	v_or_b32_e32 v148, 48, v154
	v_cvt_pk_bf16_f32 v159, v166, v167
	global_store_dwordx4 v[164:165], v[156:159], off
	v_pk_mul_f32 v[164:165], v[102:103], v[70:71]
	v_pk_mul_f32 v[166:167], v[100:101], v[68:69]
	v_mul_f32_e32 v158, 0xbfb8aa3b, v149
	v_pk_mul_f32 v[162:163], v[100:101], v[158:159] op_sel_hi:[1,0]
	v_mad_i64_i32 v[156:157], s[40:41], v148, s27, v[144:145]
	v_mul_f32_e32 v148, v149, v149
	v_exp_f32_e32 v149, v162
	v_pk_mul_f32 v[160:161], v[102:103], v[158:159] op_sel_hi:[1,0]
	v_exp_f32_e32 v155, v163
	v_exp_f32_e32 v159, v160
	v_exp_f32_e32 v163, v161
	v_add_f32_e32 v149, 1.0, v149
	v_rcp_f32_e32 v160, v149
	v_add_f32_e32 v149, 1.0, v155
	v_rcp_f32_e32 v161, v149
	v_add_f32_e32 v149, 1.0, v159
	v_rcp_f32_e32 v162, v149
	v_add_f32_e32 v149, 1.0, v163
	v_rcp_f32_e32 v163, v149
	v_pk_mul_f32 v[164:165], v[164:165], v[148:149] op_sel_hi:[1,0]
	v_pk_mul_f32 v[166:167], v[166:167], v[148:149] op_sel_hi:[1,0]
	v_lshl_add_u64 v[156:157], v[156:157], 0, s[38:39]
	v_pk_mul_f32 v[162:163], v[164:165], v[162:163]
	v_pk_mul_f32 v[164:165], v[98:99], v[158:159] op_sel_hi:[1,0]
	v_pk_mul_f32 v[158:159], v[96:97], v[158:159] op_sel_hi:[1,0]
	v_exp_f32_e32 v164, v164
	v_exp_f32_e32 v149, v158
	v_exp_f32_e32 v155, v159
	v_exp_f32_e32 v165, v165
	v_pk_mul_f32 v[160:161], v[166:167], v[160:161]
	v_add_f32_e32 v149, 1.0, v149
	v_rcp_f32_e32 v158, v149
	v_add_f32_e32 v149, 1.0, v155
	v_rcp_f32_e32 v159, v149
	v_add_f32_e32 v149, 1.0, v164
	v_rcp_f32_e32 v164, v149
	v_add_f32_e32 v149, 1.0, v165
	v_rcp_f32_e32 v165, v149
	v_pk_mul_f32 v[166:167], v[98:99], v[66:67]
	v_lshl_add_u64 v[156:157], v[156:157], 0, s[94:95]
	v_pk_mul_f32 v[168:169], v[96:97], v[64:65]
	v_pk_mul_f32 v[166:167], v[166:167], v[148:149] op_sel_hi:[1,0]
	v_pk_mul_f32 v[148:149], v[168:169], v[148:149] op_sel_hi:[1,0]
	v_pk_mul_f32 v[164:165], v[166:167], v[164:165]
	v_lshl_add_u64 v[166:167], v[156:157], 0, v[128:129]
	v_cvt_pk_bf16_f32 v156, v160, v161
	v_pk_mul_f32 v[148:149], v[148:149], v[158:159]
	v_cvt_pk_bf16_f32 v157, v162, v163
	v_pk_mul_f32 v[162:163], v[62:63], v[30:31]
	v_cvt_pk_bf16_f32 v158, v148, v149
	v_cvt_pk_bf16_f32 v159, v164, v165
	global_store_dwordx4 v[166:167], v[156:159], off
	v_pk_mul_f32 v[164:165], v[60:61], v[28:29]
	v_add_u32_e32 v148, 0x80, v154
	v_mul_f32_e32 v156, v146, v146
	v_mul_f32_e32 v146, 0xbfb8aa3b, v146
	v_pk_mul_f32 v[160:161], v[60:61], v[146:147] op_sel_hi:[1,0]
	v_pk_mul_f32 v[158:159], v[62:63], v[146:147] op_sel_hi:[1,0]
	v_exp_f32_e32 v155, v160
	v_exp_f32_e32 v157, v161
	v_exp_f32_e32 v160, v158
	v_exp_f32_e32 v161, v159
	v_add_f32_e32 v155, 1.0, v155
	v_rcp_f32_e32 v158, v155
	v_add_f32_e32 v155, 1.0, v157
	v_rcp_f32_e32 v159, v155
	v_add_f32_e32 v155, 1.0, v160
	v_rcp_f32_e32 v160, v155
	v_add_f32_e32 v155, 1.0, v161
	v_rcp_f32_e32 v161, v155
	v_pk_mul_f32 v[164:165], v[164:165], v[156:157] op_sel_hi:[1,0]
	v_pk_mul_f32 v[162:163], v[162:163], v[156:157] op_sel_hi:[1,0]
	v_pk_mul_f32 v[158:159], v[164:165], v[158:159]
	v_pk_mul_f32 v[164:165], v[56:57], v[146:147] op_sel_hi:[1,0]
	v_pk_mul_f32 v[160:161], v[162:163], v[160:161]
	v_pk_mul_f32 v[162:163], v[58:59], v[146:147] op_sel_hi:[1,0]
	v_exp_f32_e32 v146, v164
	v_exp_f32_e32 v155, v165
	v_exp_f32_e32 v157, v162
	v_exp_f32_e32 v165, v163
	v_add_f32_e32 v146, 1.0, v146
	v_rcp_f32_e32 v162, v146
	v_add_f32_e32 v146, 1.0, v155
	v_rcp_f32_e32 v163, v146
	v_add_f32_e32 v146, 1.0, v157
	v_rcp_f32_e32 v164, v146
	v_add_f32_e32 v146, 1.0, v165
	v_mad_i64_i32 v[148:149], s[40:41], v148, s27, v[144:145]
	v_rcp_f32_e32 v165, v146
	v_lshl_add_u64 v[148:149], v[148:149], 0, s[38:39]
	v_pk_mul_f32 v[166:167], v[58:59], v[26:27]
	v_pk_mul_f32 v[168:169], v[56:57], v[24:25]
	v_lshl_add_u64 v[148:149], v[148:149], 0, s[94:95]
	v_pk_mul_f32 v[166:167], v[166:167], v[156:157] op_sel_hi:[1,0]
	v_pk_mul_f32 v[156:157], v[168:169], v[156:157] op_sel_hi:[1,0]
	v_lshl_add_u64 v[148:149], v[148:149], 0, v[128:129]
	v_pk_mul_f32 v[162:163], v[156:157], v[162:163]
	v_cvt_pk_bf16_f32 v156, v158, v159
	v_pk_mul_f32 v[164:165], v[166:167], v[164:165]
	v_cvt_pk_bf16_f32 v157, v160, v161
	v_cvt_pk_bf16_f32 v158, v162, v163
	v_add_u32_e32 v146, 0x90, v154
	v_cvt_pk_bf16_f32 v159, v164, v165
	global_store_dwordx4 v[148:149], v[156:159], off
	v_mad_i64_i32 v[148:149], s[40:41], v146, s27, v[144:145]
	s_nop 0
	v_mul_f32_e32 v156, 0xbfb8aa3b, v147
	v_pk_mul_f32 v[160:161], v[52:53], v[156:157] op_sel_hi:[1,0]
	v_mul_f32_e32 v146, v147, v147
	v_exp_f32_e32 v147, v160
	v_pk_mul_f32 v[158:159], v[54:55], v[156:157] op_sel_hi:[1,0]
	v_exp_f32_e32 v155, v161
	v_exp_f32_e32 v157, v158
	v_exp_f32_e32 v161, v159
	v_add_f32_e32 v147, 1.0, v147
	v_rcp_f32_e32 v158, v147
	v_add_f32_e32 v147, 1.0, v155
	v_rcp_f32_e32 v159, v147
	v_add_f32_e32 v147, 1.0, v157
	v_rcp_f32_e32 v160, v147
	v_add_f32_e32 v147, 1.0, v161
	v_rcp_f32_e32 v161, v147
	v_pk_mul_f32 v[162:163], v[54:55], v[22:23]
	v_pk_mul_f32 v[164:165], v[52:53], v[20:21]
	v_pk_mul_f32 v[162:163], v[162:163], v[146:147] op_sel_hi:[1,0]
	v_pk_mul_f32 v[164:165], v[164:165], v[146:147] op_sel_hi:[1,0]
	v_pk_mul_f32 v[160:161], v[162:163], v[160:161]
	v_pk_mul_f32 v[162:163], v[50:51], v[156:157] op_sel_hi:[1,0]
	v_pk_mul_f32 v[156:157], v[48:49], v[156:157] op_sel_hi:[1,0]
	v_exp_f32_e32 v162, v162
	v_exp_f32_e32 v147, v156
	v_exp_f32_e32 v155, v157
	v_exp_f32_e32 v163, v163
	v_lshl_add_u64 v[148:149], v[148:149], 0, s[38:39]
	v_add_f32_e32 v147, 1.0, v147
	v_rcp_f32_e32 v156, v147
	v_add_f32_e32 v147, 1.0, v155
	v_rcp_f32_e32 v157, v147
	v_add_f32_e32 v147, 1.0, v162
	v_rcp_f32_e32 v162, v147
	v_add_f32_e32 v147, 1.0, v163
	v_rcp_f32_e32 v163, v147
	v_pk_mul_f32 v[158:159], v[164:165], v[158:159]
	v_pk_mul_f32 v[164:165], v[50:51], v[18:19]
	v_pk_mul_f32 v[166:167], v[48:49], v[16:17]
	v_lshl_add_u64 v[148:149], v[148:149], 0, s[94:95]
	v_pk_mul_f32 v[164:165], v[164:165], v[146:147] op_sel_hi:[1,0]
	v_pk_mul_f32 v[146:147], v[166:167], v[146:147] op_sel_hi:[1,0]
	v_pk_mul_f32 v[162:163], v[164:165], v[162:163]
	v_pk_mul_f32 v[156:157], v[146:147], v[156:157]
	v_lshl_add_u64 v[164:165], v[148:149], 0, v[128:129]
	v_cvt_pk_bf16_f32 v146, v158, v159
	v_cvt_pk_bf16_f32 v147, v160, v161
	v_cvt_pk_bf16_f32 v148, v156, v157
	v_cvt_pk_bf16_f32 v149, v162, v163
	global_store_dwordx4 v[164:165], v[146:149], off
	v_pk_mul_f32 v[162:163], v[44:45], v[12:13]
	v_pk_mul_f32 v[160:161], v[46:47], v[14:15]
	v_mul_f32_e32 v148, v142, v142
	v_mul_f32_e32 v142, 0xbfb8aa3b, v142
	v_pk_mul_f32 v[158:159], v[44:45], v[142:143] op_sel_hi:[1,0]
	v_pk_mul_f32 v[156:157], v[46:47], v[142:143] op_sel_hi:[1,0]
	v_exp_f32_e32 v149, v158
	v_exp_f32_e32 v155, v159
	v_exp_f32_e32 v158, v156
	v_exp_f32_e32 v159, v157
	v_add_f32_e32 v149, 1.0, v149
	v_rcp_f32_e32 v156, v149
	v_add_f32_e32 v149, 1.0, v155
	v_rcp_f32_e32 v157, v149
	v_add_f32_e32 v149, 1.0, v158
	v_rcp_f32_e32 v158, v149
	v_add_f32_e32 v149, 1.0, v159
	v_rcp_f32_e32 v159, v149
	v_pk_mul_f32 v[162:163], v[162:163], v[148:149] op_sel_hi:[1,0]
	v_pk_mul_f32 v[160:161], v[160:161], v[148:149] op_sel_hi:[1,0]
	v_pk_mul_f32 v[156:157], v[162:163], v[156:157]
	v_pk_mul_f32 v[162:163], v[40:41], v[142:143] op_sel_hi:[1,0]
	v_pk_mul_f32 v[158:159], v[160:161], v[158:159]
	v_pk_mul_f32 v[160:161], v[42:43], v[142:143] op_sel_hi:[1,0]
	v_exp_f32_e32 v142, v162
	v_exp_f32_e32 v149, v163
	v_exp_f32_e32 v155, v160
	v_exp_f32_e32 v163, v161
	v_add_f32_e32 v142, 1.0, v142
	v_rcp_f32_e32 v160, v142
	v_add_f32_e32 v142, 1.0, v149
	v_rcp_f32_e32 v161, v142
	v_add_f32_e32 v142, 1.0, v155
	v_add_u32_e32 v146, 0xa0, v154
	v_rcp_f32_e32 v162, v142
	v_add_f32_e32 v142, 1.0, v163
	v_mad_i64_i32 v[146:147], s[40:41], v146, s27, v[144:145]
	v_rcp_f32_e32 v163, v142
	v_lshl_add_u64 v[146:147], v[146:147], 0, s[38:39]
	v_pk_mul_f32 v[164:165], v[42:43], v[10:11]
	v_pk_mul_f32 v[166:167], v[40:41], v[8:9]
	v_lshl_add_u64 v[146:147], v[146:147], 0, s[94:95]
	v_pk_mul_f32 v[164:165], v[164:165], v[148:149] op_sel_hi:[1,0]
	v_pk_mul_f32 v[148:149], v[166:167], v[148:149] op_sel_hi:[1,0]
	v_pk_mul_f32 v[162:163], v[164:165], v[162:163]
	v_pk_mul_f32 v[148:149], v[148:149], v[160:161]
	v_lshl_add_u64 v[160:161], v[146:147], 0, v[128:129]
	v_cvt_pk_bf16_f32 v146, v156, v157
	v_cvt_pk_bf16_f32 v147, v158, v159
	v_cvt_pk_bf16_f32 v148, v148, v149
	v_cvt_pk_bf16_f32 v149, v162, v163
	global_store_dwordx4 v[160:161], v[146:149], off
	v_add_u32_e32 v142, 0xb0, v154
	v_mad_i64_i32 v[144:145], s[40:41], v142, s27, v[144:145]
	v_mul_f32_e32 v146, 0xbfb8aa3b, v143
	v_pk_mul_f32 v[154:155], v[36:37], v[146:147] op_sel_hi:[1,0]
	v_mul_f32_e32 v142, v143, v143
	v_exp_f32_e32 v143, v154
	v_pk_mul_f32 v[148:149], v[38:39], v[146:147] op_sel_hi:[1,0]
	v_exp_f32_e32 v147, v155
	v_exp_f32_e32 v154, v148
	v_exp_f32_e32 v155, v149
	v_add_f32_e32 v143, 1.0, v143
	v_rcp_f32_e32 v148, v143
	v_add_f32_e32 v143, 1.0, v147
	v_rcp_f32_e32 v149, v143
	v_add_f32_e32 v143, 1.0, v154
	v_rcp_f32_e32 v154, v143
	v_add_f32_e32 v143, 1.0, v155
	v_rcp_f32_e32 v155, v143
	v_pk_mul_f32 v[156:157], v[38:39], v[6:7]
	v_pk_mul_f32 v[158:159], v[36:37], v[4:5]
	v_pk_mul_f32 v[156:157], v[156:157], v[142:143] op_sel_hi:[1,0]
	v_pk_mul_f32 v[158:159], v[158:159], v[142:143] op_sel_hi:[1,0]
	v_pk_mul_f32 v[154:155], v[156:157], v[154:155]
	v_pk_mul_f32 v[156:157], v[34:35], v[146:147] op_sel_hi:[1,0]
	v_pk_mul_f32 v[146:147], v[32:33], v[146:147] op_sel_hi:[1,0]
	v_exp_f32_e32 v156, v156
	v_exp_f32_e32 v143, v146
	v_exp_f32_e32 v147, v147
	v_exp_f32_e32 v157, v157
	v_lshl_add_u64 v[144:145], v[144:145], 0, s[38:39]
	v_add_f32_e32 v143, 1.0, v143
	v_rcp_f32_e32 v146, v143
	v_add_f32_e32 v143, 1.0, v147
	v_rcp_f32_e32 v147, v143
	v_add_f32_e32 v143, 1.0, v156
	v_rcp_f32_e32 v156, v143
	v_add_f32_e32 v143, 1.0, v157
	v_rcp_f32_e32 v157, v143
	v_pk_mul_f32 v[148:149], v[158:159], v[148:149]
	v_pk_mul_f32 v[158:159], v[34:35], v[2:3]
	v_lshl_add_u64 v[144:145], v[144:145], 0, s[94:95]
	v_pk_mul_f32 v[160:161], v[32:33], v[0:1]
	v_pk_mul_f32 v[158:159], v[158:159], v[142:143] op_sel_hi:[1,0]
	v_pk_mul_f32 v[142:143], v[160:161], v[142:143] op_sel_hi:[1,0]
	v_pk_mul_f32 v[156:157], v[158:159], v[156:157]
	v_lshl_add_u64 v[158:159], v[144:145], 0, v[128:129]
	s_andn2_b64 vcc, exec, s[4:5]
	v_pk_mul_f32 v[146:147], v[142:143], v[146:147]
	v_cvt_pk_bf16_f32 v142, v148, v149
	v_cvt_pk_bf16_f32 v143, v154, v155
	s_nop 0
	v_cvt_pk_bf16_f32 v144, v146, v147
	v_cvt_pk_bf16_f32 v145, v156, v157
	global_store_dwordx4 v[158:159], v[142:145], off
	s_cbranch_vccnz .LBB0_1107
	s_andn2_b64 vcc, exec, s[20:21]
	s_cbranch_vccnz .LBB0_1097
	s_barrier
	s_branch .LBB0_1097

.LBB0_1111:
	v_lshl_add_u64 v[68:69], v[66:67], 0, s[2:3]
	v_add_co_u32_e32 v78, vcc, s84, v68
	v_lshl_add_u64 v[126:127], v[64:65], 0, s[2:3]
	s_nop 0
	v_addc_co_u32_e32 v79, vcc, 0, v69, vcc
	v_add_co_u32_e32 v74, vcc, s85, v68
	s_mov_b32 s10, 0x7008000
	s_nop 0
	v_addc_co_u32_e32 v75, vcc, 0, v69, vcc
	v_add_co_u32_e32 v72, vcc, s88, v68
	s_mov_b32 s11, 0x7018000
	s_nop 0
	v_addc_co_u32_e32 v73, vcc, 0, v69, vcc
	v_add_co_u32_e32 v70, vcc, s89, v68
	s_add_u32 s2, s2, 0x100
	s_nop 0
	v_addc_co_u32_e32 v71, vcc, 0, v69, vcc
	v_add_co_u32_e32 v76, vcc, s10, v126
	s_mov_b32 s10, 0x7088000
	s_nop 0
	v_addc_co_u32_e32 v77, vcc, 0, v127, vcc
	global_load_dwordx4 v[82:85], v[76:77], off
	global_load_dwordx4 v[86:89], v[78:79], off
	global_load_dwordx4 v[90:93], v[78:79], off offset:64
	global_load_dwordx4 v[94:97], v[76:77], off offset:64
	global_load_dwordx4 v[98:101], v[74:75], off
	global_load_dwordx4 v[102:105], v[74:75], off offset:64
	global_load_dwordx4 v[106:109], v[72:73], off
	global_load_dwordx4 v[110:113], v[72:73], off offset:64
	global_load_dwordx4 v[114:117], v[70:71], off
	global_load_dwordx4 v[118:121], v[70:71], off offset:64
	v_add_co_u32_e32 v68, vcc, s11, v126
	s_addc_u32 s3, s3, 0
	s_nop 0
	v_addc_co_u32_e32 v69, vcc, 0, v127, vcc
	v_add_co_u32_e32 v138, vcc, s10, v126
	s_mov_b32 s10, 0x7098000
	s_nop 0
	v_addc_co_u32_e32 v139, vcc, 0, v127, vcc
	v_add_co_u32_e32 v126, vcc, s10, v126
	s_cmpk_eq_i32 s2, 0x200
	s_nop 0
	v_addc_co_u32_e32 v127, vcc, 0, v127, vcc
	s_waitcnt vmcnt(0) lgkmcnt(0)
	v_mfma_f32_16x16x32_bf16 v[56:59], v[82:85], v[86:89], v[56:59]
	v_mfma_f32_16x16x32_bf16 v[52:55], v[82:85], v[98:101], v[52:55]
	v_mfma_f32_16x16x32_bf16 v[48:51], v[82:85], v[106:109], v[48:51]
	v_mfma_f32_16x16x32_bf16 v[44:47], v[82:85], v[114:117], v[44:47]
	global_load_dwordx4 v[82:85], v[68:69], off
	global_load_dwordx4 v[122:125], v[68:69], off offset:64
	v_mfma_f32_16x16x32_bf16 v[56:59], v[94:97], v[90:93], v[56:59]
	v_mfma_f32_16x16x32_bf16 v[52:55], v[94:97], v[102:105], v[52:55]
	v_mfma_f32_16x16x32_bf16 v[48:51], v[94:97], v[110:113], v[48:51]
	v_mfma_f32_16x16x32_bf16 v[44:47], v[94:97], v[118:121], v[44:47]
	s_waitcnt vmcnt(0) lgkmcnt(0)
	v_mfma_f32_16x16x32_bf16 v[12:15], v[82:85], v[86:89], v[12:15]
	v_mfma_f32_16x16x32_bf16 v[8:11], v[82:85], v[98:101], v[8:11]
	v_mfma_f32_16x16x32_bf16 v[4:7], v[82:85], v[106:109], v[4:7]
	v_mfma_f32_16x16x32_bf16 v[0:3], v[82:85], v[114:117], v[0:3]
	global_load_dwordx4 v[82:85], v[138:139], off
	global_load_dwordx4 v[130:133], v[138:139], off offset:64
	global_load_dwordx4 v[134:137], v[126:127], off
	v_mfma_f32_16x16x32_bf16 v[12:15], v[122:125], v[90:93], v[12:15]
	v_mfma_f32_16x16x32_bf16 v[8:11], v[122:125], v[102:105], v[8:11]
	v_mfma_f32_16x16x32_bf16 v[4:7], v[122:125], v[110:113], v[4:7]
	v_mfma_f32_16x16x32_bf16 v[0:3], v[122:125], v[118:121], v[0:3]
	s_waitcnt vmcnt(0) lgkmcnt(0)
	v_mfma_f32_16x16x32_bf16 v[16:19], v[82:85], v[86:89], v[16:19]
	v_mfma_f32_16x16x32_bf16 v[24:27], v[82:85], v[98:101], v[24:27]
	v_mfma_f32_16x16x32_bf16 v[28:31], v[82:85], v[106:109], v[28:31]
	v_mfma_f32_16x16x32_bf16 v[36:39], v[82:85], v[114:117], v[36:39]
	global_load_dwordx4 v[82:85], v[126:127], off offset:64
	v_mfma_f32_16x16x32_bf16 v[20:23], v[134:137], v[86:89], v[20:23]
	global_load_dwordx4 v[86:89], v[76:77], off offset:128
	v_mfma_f32_16x16x32_bf16 v[32:35], v[134:137], v[98:101], v[32:35]
	v_mfma_f32_16x16x32_bf16 v[40:43], v[134:137], v[106:109], v[40:43]
	v_mfma_f32_16x16x32_bf16 v[60:63], v[134:137], v[114:117], v[60:63]
	v_mfma_f32_16x16x32_bf16 v[16:19], v[130:133], v[90:93], v[16:19]
	v_mfma_f32_16x16x32_bf16 v[24:27], v[130:133], v[102:105], v[24:27]
	v_mfma_f32_16x16x32_bf16 v[28:31], v[130:133], v[110:113], v[28:31]
	s_waitcnt vmcnt(0) lgkmcnt(0)
	v_mfma_f32_16x16x32_bf16 v[20:23], v[82:85], v[90:93], v[20:23]
	v_mfma_f32_16x16x32_bf16 v[32:35], v[82:85], v[102:105], v[32:35]
	v_mfma_f32_16x16x32_bf16 v[40:43], v[82:85], v[110:113], v[40:43]
	v_mfma_f32_16x16x32_bf16 v[60:63], v[82:85], v[118:121], v[60:63]
	global_load_dwordx4 v[82:85], v[78:79], off offset:128
	global_load_dwordx4 v[90:93], v[78:79], off offset:192
	s_nop 0
	global_load_dwordx4 v[76:79], v[76:77], off offset:192
	s_nop 0
	global_load_dwordx4 v[94:97], v[74:75], off offset:128
	global_load_dwordx4 v[98:101], v[74:75], off offset:192
	global_load_dwordx4 v[102:105], v[72:73], off offset:128
	s_nop 0
	global_load_dwordx4 v[72:75], v[72:73], off offset:192
	s_nop 0
	global_load_dwordx4 v[106:109], v[70:71], off offset:128
	global_load_dwordx4 v[110:113], v[70:71], off offset:192
	v_mfma_f32_16x16x32_bf16 v[36:39], v[130:133], v[118:121], v[36:39]
	s_waitcnt vmcnt(0) lgkmcnt(0)
	v_mfma_f32_16x16x32_bf16 v[56:59], v[86:89], v[82:85], v[56:59]
	v_mfma_f32_16x16x32_bf16 v[52:55], v[86:89], v[94:97], v[52:55]
	v_mfma_f32_16x16x32_bf16 v[48:51], v[86:89], v[102:105], v[48:51]
	v_mfma_f32_16x16x32_bf16 v[44:47], v[86:89], v[106:109], v[44:47]
	global_load_dwordx4 v[86:89], v[68:69], off offset:128
	s_nop 0
	global_load_dwordx4 v[68:71], v[68:69], off offset:192
	s_waitcnt vmcnt(0) lgkmcnt(0)
	v_mfma_f32_16x16x32_bf16 v[12:15], v[86:89], v[82:85], v[12:15]
	v_mfma_f32_16x16x32_bf16 v[8:11], v[86:89], v[94:97], v[8:11]
	v_mfma_f32_16x16x32_bf16 v[4:7], v[86:89], v[102:105], v[4:7]
	v_mfma_f32_16x16x32_bf16 v[0:3], v[86:89], v[106:109], v[0:3]
	global_load_dwordx4 v[86:89], v[138:139], off offset:128
	global_load_dwordx4 v[114:117], v[138:139], off offset:192
	global_load_dwordx4 v[118:121], v[126:127], off offset:128
	s_waitcnt vmcnt(0) lgkmcnt(0)
	v_mfma_f32_16x16x32_bf16 v[16:19], v[86:89], v[82:85], v[16:19]
	v_mfma_f32_16x16x32_bf16 v[24:27], v[86:89], v[94:97], v[24:27]
	v_mfma_f32_16x16x32_bf16 v[28:31], v[86:89], v[102:105], v[28:31]
	v_mfma_f32_16x16x32_bf16 v[36:39], v[86:89], v[106:109], v[36:39]
	global_load_dwordx4 v[86:89], v[126:127], off offset:192
	v_mfma_f32_16x16x32_bf16 v[20:23], v[118:121], v[82:85], v[20:23]
	v_mfma_f32_16x16x32_bf16 v[32:35], v[118:121], v[94:97], v[32:35]
	v_mfma_f32_16x16x32_bf16 v[40:43], v[118:121], v[102:105], v[40:43]
	v_mfma_f32_16x16x32_bf16 v[60:63], v[118:121], v[106:109], v[60:63]
	v_mfma_f32_16x16x32_bf16 v[56:59], v[76:79], v[90:93], v[56:59]
	v_mfma_f32_16x16x32_bf16 v[52:55], v[76:79], v[98:101], v[52:55]
	v_mfma_f32_16x16x32_bf16 v[48:51], v[76:79], v[72:75], v[48:51]
	v_mfma_f32_16x16x32_bf16 v[44:47], v[76:79], v[110:113], v[44:47]
	v_mfma_f32_16x16x32_bf16 v[12:15], v[68:71], v[90:93], v[12:15]
	v_mfma_f32_16x16x32_bf16 v[8:11], v[68:71], v[98:101], v[8:11]
	v_mfma_f32_16x16x32_bf16 v[4:7], v[68:71], v[72:75], v[4:7]
	v_mfma_f32_16x16x32_bf16 v[0:3], v[68:71], v[110:113], v[0:3]
	v_mfma_f32_16x16x32_bf16 v[16:19], v[114:117], v[90:93], v[16:19]
	v_mfma_f32_16x16x32_bf16 v[24:27], v[114:117], v[98:101], v[24:27]
	v_mfma_f32_16x16x32_bf16 v[28:31], v[114:117], v[72:75], v[28:31]
	v_mfma_f32_16x16x32_bf16 v[36:39], v[114:117], v[110:113], v[36:39]
	s_waitcnt vmcnt(0) lgkmcnt(0)
	v_mfma_f32_16x16x32_bf16 v[20:23], v[86:89], v[90:93], v[20:23]
	v_mfma_f32_16x16x32_bf16 v[32:35], v[86:89], v[98:101], v[32:35]
	v_mfma_f32_16x16x32_bf16 v[40:43], v[86:89], v[72:75], v[40:43]
	v_mfma_f32_16x16x32_bf16 v[60:63], v[86:89], v[110:113], v[60:63]
	s_cbranch_scc0 .LBB0_1111
	v_and_b32_e32 v65, 63, v81
	s_ashr_i32 s2, s4, 7
	v_lshl_add_u32 v65, v65, 4, 0
	s_lshl_b32 s3, s2, 4
	v_lshl_add_u32 v66, s5, 14, v65
	s_addk_i32 s3, 0x4000
	ds_write_b128 v66, v[56:59]
	ds_write_b128 v66, v[52:55] offset:1024
	ds_write_b128 v66, v[48:51] offset:2048
	ds_write_b128 v66, v[44:47] offset:3072
	ds_write_b128 v66, v[12:15] offset:4096
	ds_write_b128 v66, v[8:11] offset:5120
	ds_write_b128 v66, v[4:7] offset:6144
	ds_write_b128 v66, v[0:3] offset:7168
	ds_write_b128 v66, v[16:19] offset:8192
	ds_write_b128 v66, v[24:27] offset:9216
	ds_write_b128 v66, v[28:31] offset:10240
	ds_write_b128 v66, v[36:39] offset:11264
	ds_write_b128 v66, v[20:23] offset:12288
	ds_write_b128 v66, v[32:35] offset:13312
	ds_write_b128 v66, v[40:43] offset:14336
	ds_write_b128 v66, v[60:63] offset:15360
	v_or_b32_e32 v0, s3, v80
	v_ashrrev_i32_e32 v1, 31, v0
	v_bfe_u32 v64, v81, 4, 2
	v_lshlrev_b64 v[2:3], 7, v[0:1]
	v_lshl_add_u64 v[2:3], s[8:9], 0, v[2:3]
	v_lshlrev_b32_e32 v128, 5, v64
	v_lshl_add_u64 v[6:7], v[2:3], 0, v[128:129]
	s_waitcnt lgkmcnt(0)
	s_barrier
	global_load_dwordx4 v[2:5], v[6:7], off
	s_nop 0
	global_load_dwordx4 v[6:9], v[6:7], off offset:16
	s_bfe_u32 s3, s4, 0x10006
	s_lshl_b32 s4, s3, 2
	s_add_i32 s4, s4, s2
	v_lshl_add_u32 v1, s4, 10, v65
	ds_read_b128 v[10:13], v1
	ds_read_b128 v[14:17], v1 offset:8192
	ds_read_b128 v[18:21], v1 offset:16384
	ds_read_b128 v[22:25], v1 offset:24576
	ds_read_b128 v[26:29], v1 offset:32768
	ds_read_b128 v[30:33], v1 offset:40960
	ds_read_b128 v[34:37], v1 offset:49152
	ds_read_b128 v[38:41], v1 offset:57344
	s_waitcnt lgkmcnt(0)
	v_pk_add_f32 v[10:11], v[10:11], 0 op_sel_hi:[1,0]
	v_add_u32_e32 v42, 0x10000, v1
	v_pk_add_f32 v[10:11], v[10:11], v[18:19]
	v_add_u32_e32 v46, 0x12000, v1
	v_add_u32_e32 v50, 0x14000, v1
	v_add_u32_e32 v54, 0x16000, v1
	v_add_u32_e32 v58, 0x18000, v1
	v_add_u32_e32 v62, 0x1a000, v1
	ds_read_b128 v[42:45], v42
	ds_read_b128 v[46:49], v46
	ds_read_b128 v[50:53], v50
	ds_read_b128 v[54:57], v54
	ds_read_b128 v[58:61], v58
	ds_read_b128 v[66:69], v62
	v_pk_add_f32 v[14:15], v[14:15], 0 op_sel_hi:[1,0]
	v_pk_add_f32 v[12:13], v[12:13], 0 op_sel_hi:[1,0]
	v_pk_add_f32 v[14:15], v[14:15], v[22:23]
	v_pk_add_f32 v[12:13], v[12:13], v[20:21]
	v_pk_add_f32 v[10:11], v[10:11], v[26:27]
	v_pk_add_f32 v[14:15], v[14:15], v[30:31]
	v_pk_add_f32 v[12:13], v[12:13], v[28:29]
	v_pk_add_f32 v[10:11], v[10:11], v[34:35]
	v_pk_add_f32 v[14:15], v[14:15], v[38:39]
	v_pk_add_f32 v[12:13], v[12:13], v[36:37]
	s_waitcnt lgkmcnt(0)
	v_pk_add_f32 v[10:11], v[10:11], v[42:43]
	v_pk_add_f32 v[14:15], v[14:15], v[46:47]
	v_pk_add_f32 v[12:13], v[12:13], v[44:45]
	v_pk_add_f32 v[10:11], v[10:11], v[50:51]
	v_pk_add_f32 v[14:15], v[14:15], v[54:55]
	v_pk_add_f32 v[12:13], v[12:13], v[52:53]
	v_pk_add_f32 v[10:11], v[10:11], v[58:59]
	v_pk_add_f32 v[14:15], v[14:15], v[66:67]
	v_pk_add_f32 v[12:13], v[12:13], v[60:61]
	v_pk_add_f32 v[16:17], v[16:17], 0 op_sel_hi:[1,0]
	s_lshl_b32 s0, s0, 7
	v_pk_add_f32 v[16:17], v[16:17], v[24:25]
	s_waitcnt vmcnt(0)
	v_mov_b32_e32 v18, v2
	v_mov_b32_e32 v19, v6
	v_mov_b32_e32 v6, v3
	v_mov_b32_e32 v2, v4
	v_mov_b32_e32 v3, v8
	v_mov_b32_e32 v8, v5
	v_pk_add_f32 v[4:5], v[18:19], v[6:7]
	v_pk_add_f32 v[2:3], v[2:3], v[8:9]
	v_pk_add_f32 v[16:17], v[16:17], v[32:33]
	v_pk_add_f32 v[2:3], v[4:5], v[2:3]
	v_and_b32_e32 v4, 64, v214
	v_add_f32_e32 v2, v2, v3
	v_xor_b32_e32 v3, 16, v214
	v_add_u32_e32 v4, 64, v4
	v_cmp_lt_i32_e32 vcc, v3, v4
	v_pk_add_f32 v[16:17], v[16:17], v[40:41]
	s_nop 0
	v_cndmask_b32_e32 v3, v214, v3, vcc
	v_lshlrev_b32_e32 v3, 2, v3
	ds_bpermute_b32 v3, v3, v2
	v_pk_add_f32 v[16:17], v[16:17], v[48:49]
	s_waitcnt lgkmcnt(0)
	v_add_f32_e32 v18, v2, v3
	v_xor_b32_e32 v2, 32, v214
	v_cmp_lt_i32_e32 vcc, v2, v4
	v_pk_add_f32 v[16:17], v[16:17], v[56:57]
	s_nop 0
	v_cndmask_b32_e32 v2, v214, v2, vcc
	v_lshlrev_b32_e32 v2, 2, v2
	ds_bpermute_b32 v19, v2, v18
	v_add_u32_e32 v2, 0x1c000, v1
	v_add_u32_e32 v1, 0x1e000, v1
	ds_read_b128 v[2:5], v2
	ds_read_b128 v[6:9], v1
	v_pk_add_f32 v[16:17], v[16:17], v[68:69]
	s_waitcnt lgkmcnt(2)
	v_add_f32_e32 v1, v18, v19
	v_fmamk_f32 v1, v1, 0x3a000000, v190
	v_mul_f32_e32 v18, 0x4b800000, v1
	v_cmp_gt_f32_e32 vcc, s70, v1
	s_waitcnt lgkmcnt(1)
	v_pk_add_f32 v[2:3], v[10:11], v[2:3]
	s_waitcnt lgkmcnt(0)
	v_pk_add_f32 v[6:7], v[14:15], v[6:7]
	v_cndmask_b32_e32 v1, v1, v18, vcc
	v_rsq_f32_e32 v1, v1
	v_pk_add_f32 v[4:5], v[12:13], v[4:5]
	v_mov_b32_e32 v12, v6
	v_mov_b32_e32 v13, v2
	v_mul_f32_e32 v10, 0x45800000, v1
	v_cndmask_b32_e32 v10, v1, v10, vcc
	v_pk_mul_f32 v[12:13], v[12:13], v[10:11] op_sel_hi:[1,0]
	v_lshlrev_b32_e32 v2, 2, v64
	v_mul_f32_e32 v1, 0xbfb8aa3b, v13
	v_exp_f32_e32 v1, v1
	v_lshl_or_b32 v6, s3, 4, v2
	v_mov_b32_e32 v2, v7
	v_pk_mul_f32 v[2:3], v[2:3], v[10:11] op_sel_hi:[1,0]
	v_add_f32_e32 v1, 1.0, v1
	v_mul_f32_e32 v7, 0xbfb8aa3b, v3
	v_rcp_f32_e32 v1, v1
	v_exp_f32_e32 v7, v7
	v_pk_add_f32 v[8:9], v[16:17], v[8:9]
	v_or_b32_e32 v11, s1, v6
	v_mul_f32_e32 v1, v13, v1
	v_add_f32_e32 v6, 1.0, v7
	v_mul_f32_e32 v1, v12, v1
	v_rcp_f32_e32 v12, v6
	v_mov_b32_e32 v6, v8
	v_mov_b32_e32 v7, v4
	v_pk_mul_f32 v[6:7], v[6:7], v[10:11] op_sel_hi:[1,0]
	v_mul_f32_e32 v3, v3, v12
	v_mul_f32_e32 v4, 0xbfb8aa3b, v7
	v_exp_f32_e32 v8, v4
	v_mov_b32_e32 v4, v9
	v_pk_mul_f32 v[4:5], v[4:5], v[10:11] op_sel_hi:[1,0]
	v_mul_f32_e32 v2, v2, v3
	v_mul_f32_e32 v9, 0xbfb8aa3b, v5
	v_exp_f32_e32 v9, v9
	v_add_f32_e32 v8, 1.0, v8
	v_rcp_f32_e32 v8, v8
	v_cvt_pk_bf16_f32 v2, v1, v2
	v_add_f32_e32 v9, 1.0, v9
	v_rcp_f32_e32 v9, v9
	v_mul_f32_e32 v3, v7, v8
	v_mul_f32_e32 v3, v6, v3
	s_movk_i32 s1, 0x2c00
	v_mul_f32_e32 v5, v5, v9
	v_mul_f32_e32 v4, v4, v5
	v_cvt_pk_bf16_f32 v3, v3, v4
	v_mov_b64_e32 v[4:5], s[6:7]
	v_mad_i64_i32 v[0:1], s[2:3], v0, s1, v[4:5]
	s_ashr_i32 s1, s0, 31
	v_lshl_add_u64 v[0:1], s[0:1], 1, v[0:1]
	v_lshlrev_b32_e32 v128, 1, v11
	v_lshl_add_u64 v[0:1], v[0:1], 0, v[128:129]
	global_store_dwordx2 v[0:1], v[2:3], off
	s_waitcnt lgkmcnt(0)
	s_barrier

.LBB0_1184:
	v_lshl_add_u32 v218, s46, 8, v156
	v_lshl_or_b32 v219, s45, 8, v158
	s_lshl_b32 s94, s45, 2
	s_add_i32 s94, s94, s37
	s_lshl_b32 s94, s94, 2
	v_lshlrev_b32_e32 v216, 12, v218
	v_lshl_add_u32 v216, v219, 1, v216
	v_lshlrev_b32_e32 v217, 7, v218
	v_add_u32_e32 v217, s94, v217
	s_mov_b32 s22, s10
	s_mov_b32 s23, s11
	global_load_dwordx4 v[130:133], v216, s[22:23]
	global_load_dwordx4 v[134:137], v216, s[22:23] offset:256
	s_add_u32 s22, s22, 0x10000
	s_addc_u32 s23, s23, 0
	global_load_dwordx4 v[148:151], v216, s[22:23]
	global_load_dwordx4 v[152:155], v216, s[22:23] offset:256
	s_add_u32 s22, s22, 0x10000
	s_addc_u32 s23, s23, 0
	global_load_dwordx4 v[160:163], v216, s[22:23]
	global_load_dwordx4 v[164:167], v216, s[22:23] offset:256
	s_add_u32 s22, s22, 0x10000
	s_addc_u32 s23, s23, 0
	global_load_dwordx4 v[168:171], v216, s[22:23]
	global_load_dwordx4 v[172:175], v216, s[22:23] offset:256
	s_add_u32 s22, s22, 0x50000
	s_addc_u32 s23, s23, 0
	global_load_dwordx4 v[176:179], v216, s[22:23]
	global_load_dwordx4 v[180:183], v216, s[22:23] offset:256
	s_add_u32 s22, s22, 0x10000
	s_addc_u32 s23, s23, 0
	global_load_dwordx4 v[192:195], v216, s[22:23]
	global_load_dwordx4 v[196:199], v216, s[22:23] offset:256
	s_add_u32 s22, s22, 0x10000
	s_addc_u32 s23, s23, 0
	global_load_dwordx4 v[200:203], v216, s[22:23]
	global_load_dwordx4 v[204:207], v216, s[22:23] offset:256
	s_mov_b32 s22, s10
	s_mov_b32 s23, s11
	s_waitcnt vmcnt(12)
	v_and_b32_e32 v218, 0xffff0000, v130
	v_lshlrev_b32_e32 v130, 16, v130
	v_and_b32_e32 v219, 0xffff0000, v131
	v_lshlrev_b32_e32 v131, 16, v131
	v_and_b32_e32 v220, 0xffff0000, v132
	v_lshlrev_b32_e32 v132, 16, v132
	v_and_b32_e32 v221, 0xffff0000, v133
	v_lshlrev_b32_e32 v133, 16, v133
	v_add_f32_e32 v124, v124, v130
	v_add_f32_e32 v125, v125, v218
	v_add_f32_e32 v126, v126, v131
	v_add_f32_e32 v127, v127, v219
	v_add_f32_e32 v120, v120, v132
	v_add_f32_e32 v121, v121, v220
	v_add_f32_e32 v122, v122, v133
	v_add_f32_e32 v123, v123, v221
	v_cvt_pk_bf16_f32 v130, v124, v125
	v_cvt_pk_bf16_f32 v131, v126, v127
	v_cvt_pk_bf16_f32 v132, v120, v121
	v_cvt_pk_bf16_f32 v133, v122, v123
	v_and_b32_e32 v218, 0xffff0000, v134
	v_lshlrev_b32_e32 v134, 16, v134
	v_and_b32_e32 v219, 0xffff0000, v135
	v_lshlrev_b32_e32 v135, 16, v135
	v_and_b32_e32 v220, 0xffff0000, v136
	v_lshlrev_b32_e32 v136, 16, v136
	v_and_b32_e32 v221, 0xffff0000, v137
	v_lshlrev_b32_e32 v137, 16, v137
	v_add_f32_e32 v116, v116, v134
	v_add_f32_e32 v117, v117, v218
	v_add_f32_e32 v118, v118, v135
	v_add_f32_e32 v119, v119, v219
	v_add_f32_e32 v112, v112, v136
	v_add_f32_e32 v113, v113, v220
	v_add_f32_e32 v114, v114, v137
	v_add_f32_e32 v115, v115, v221
	v_cvt_pk_bf16_f32 v134, v116, v117
	v_cvt_pk_bf16_f32 v135, v118, v119
	v_cvt_pk_bf16_f32 v136, v112, v113
	v_cvt_pk_bf16_f32 v137, v114, v115
	global_store_dwordx4 v216, v[130:133], s[22:23]
	global_store_dwordx4 v216, v[134:137], s[22:23] offset:256
	v_mul_f32_e32 v218, v112, v112
	v_mul_f32_e32 v219, v120, v120
	v_fmac_f32_e32 v218, v113, v113
	v_fmac_f32_e32 v219, v121, v121
	v_fmac_f32_e32 v218, v114, v114
	v_fmac_f32_e32 v219, v122, v122
	v_fmac_f32_e32 v218, v115, v115
	v_fmac_f32_e32 v219, v123, v123
	v_fmac_f32_e32 v218, v116, v116
	v_fmac_f32_e32 v219, v124, v124
	v_fmac_f32_e32 v218, v117, v117
	v_fmac_f32_e32 v219, v125, v125
	v_fmac_f32_e32 v218, v118, v118
	v_fmac_f32_e32 v219, v126, v126
	v_fmac_f32_e32 v218, v119, v119
	v_fmac_f32_e32 v219, v127, v127
	v_add_f32_e32 v112, v218, v219
	s_add_u32 s22, s22, 0xb0000
	s_addc_u32 s23, s23, 0
	global_load_dwordx4 v[130:133], v216, s[22:23]
	global_load_dwordx4 v[134:137], v216, s[22:23] offset:256
	s_mov_b32 s22, s10
	s_mov_b32 s23, s11
	s_waitcnt vmcnt(14)
	v_and_b32_e32 v218, 0xffff0000, v148
	v_lshlrev_b32_e32 v148, 16, v148
	v_and_b32_e32 v219, 0xffff0000, v149
	v_lshlrev_b32_e32 v149, 16, v149
	v_and_b32_e32 v220, 0xffff0000, v150
	v_lshlrev_b32_e32 v150, 16, v150
	v_and_b32_e32 v221, 0xffff0000, v151
	v_lshlrev_b32_e32 v151, 16, v151
	v_add_f32_e32 v108, v108, v148
	v_add_f32_e32 v109, v109, v218
	v_add_f32_e32 v110, v110, v149
	v_add_f32_e32 v111, v111, v219
	v_add_f32_e32 v104, v104, v150
	v_add_f32_e32 v105, v105, v220
	v_add_f32_e32 v106, v106, v151
	v_add_f32_e32 v107, v107, v221
	v_cvt_pk_bf16_f32 v148, v108, v109
	v_cvt_pk_bf16_f32 v149, v110, v111
	v_cvt_pk_bf16_f32 v150, v104, v105
	v_cvt_pk_bf16_f32 v151, v106, v107
	v_and_b32_e32 v218, 0xffff0000, v152
	v_lshlrev_b32_e32 v152, 16, v152
	v_and_b32_e32 v219, 0xffff0000, v153
	v_lshlrev_b32_e32 v153, 16, v153
	v_and_b32_e32 v220, 0xffff0000, v154
	v_lshlrev_b32_e32 v154, 16, v154
	v_and_b32_e32 v221, 0xffff0000, v155
	v_lshlrev_b32_e32 v155, 16, v155
	v_add_f32_e32 v100, v100, v152
	v_add_f32_e32 v101, v101, v218
	v_add_f32_e32 v102, v102, v153
	v_add_f32_e32 v103, v103, v219
	v_add_f32_e32 v96, v96, v154
	v_add_f32_e32 v97, v97, v220
	v_add_f32_e32 v98, v98, v155
	v_add_f32_e32 v99, v99, v221
	v_cvt_pk_bf16_f32 v152, v100, v101
	v_cvt_pk_bf16_f32 v153, v102, v103
	v_cvt_pk_bf16_f32 v154, v96, v97
	v_cvt_pk_bf16_f32 v155, v98, v99
	s_add_u32 s22, s22, 0x10000
	s_addc_u32 s23, s23, 0
	global_store_dwordx4 v216, v[148:151], s[22:23]
	global_store_dwordx4 v216, v[152:155], s[22:23] offset:256
	v_mul_f32_e32 v218, v96, v96
	v_mul_f32_e32 v219, v104, v104
	v_fmac_f32_e32 v218, v97, v97
	v_fmac_f32_e32 v219, v105, v105
	v_fmac_f32_e32 v218, v98, v98
	v_fmac_f32_e32 v219, v106, v106
	v_fmac_f32_e32 v218, v99, v99
	v_fmac_f32_e32 v219, v107, v107
	v_fmac_f32_e32 v218, v100, v100
	v_fmac_f32_e32 v219, v108, v108
	v_fmac_f32_e32 v218, v101, v101
	v_fmac_f32_e32 v219, v109, v109
	v_fmac_f32_e32 v218, v102, v102
	v_fmac_f32_e32 v219, v110, v110
	v_fmac_f32_e32 v218, v103, v103
	v_fmac_f32_e32 v219, v111, v111
	v_add_f32_e32 v96, v218, v219
	s_waitcnt vmcnt(14)
	v_and_b32_e32 v218, 0xffff0000, v160
	v_lshlrev_b32_e32 v160, 16, v160
	v_and_b32_e32 v219, 0xffff0000, v161
	v_lshlrev_b32_e32 v161, 16, v161
	v_and_b32_e32 v220, 0xffff0000, v162
	v_lshlrev_b32_e32 v162, 16, v162
	v_and_b32_e32 v221, 0xffff0000, v163
	v_lshlrev_b32_e32 v163, 16, v163
	v_add_f32_e32 v92, v92, v160
	v_add_f32_e32 v93, v93, v218
	v_add_f32_e32 v94, v94, v161
	v_add_f32_e32 v95, v95, v219
	v_add_f32_e32 v88, v88, v162
	v_add_f32_e32 v89, v89, v220
	v_add_f32_e32 v90, v90, v163
	v_add_f32_e32 v91, v91, v221
	v_cvt_pk_bf16_f32 v160, v92, v93
	v_cvt_pk_bf16_f32 v161, v94, v95
	v_cvt_pk_bf16_f32 v162, v88, v89
	v_cvt_pk_bf16_f32 v163, v90, v91
	v_and_b32_e32 v218, 0xffff0000, v164
	v_lshlrev_b32_e32 v164, 16, v164
	v_and_b32_e32 v219, 0xffff0000, v165
	v_lshlrev_b32_e32 v165, 16, v165
	v_and_b32_e32 v220, 0xffff0000, v166
	v_lshlrev_b32_e32 v166, 16, v166
	v_and_b32_e32 v221, 0xffff0000, v167
	v_lshlrev_b32_e32 v167, 16, v167
	v_add_f32_e32 v84, v84, v164
	v_add_f32_e32 v85, v85, v218
	v_add_f32_e32 v86, v86, v165
	v_add_f32_e32 v87, v87, v219
	v_add_f32_e32 v80, v80, v166
	v_add_f32_e32 v81, v81, v220
	v_add_f32_e32 v82, v82, v167
	v_add_f32_e32 v83, v83, v221
	v_cvt_pk_bf16_f32 v164, v84, v85
	v_cvt_pk_bf16_f32 v165, v86, v87
	v_cvt_pk_bf16_f32 v166, v80, v81
	v_cvt_pk_bf16_f32 v167, v82, v83
	s_add_u32 s22, s22, 0x10000
	s_addc_u32 s23, s23, 0
	global_store_dwordx4 v216, v[160:163], s[22:23]
	global_store_dwordx4 v216, v[164:167], s[22:23] offset:256
	v_mul_f32_e32 v218, v80, v80
	v_mul_f32_e32 v219, v88, v88
	v_fmac_f32_e32 v218, v81, v81
	v_fmac_f32_e32 v219, v89, v89
	v_fmac_f32_e32 v218, v82, v82
	v_fmac_f32_e32 v219, v90, v90
	v_fmac_f32_e32 v218, v83, v83
	v_fmac_f32_e32 v219, v91, v91
	v_fmac_f32_e32 v218, v84, v84
	v_fmac_f32_e32 v219, v92, v92
	v_fmac_f32_e32 v218, v85, v85
	v_fmac_f32_e32 v219, v93, v93
	v_fmac_f32_e32 v218, v86, v86
	v_fmac_f32_e32 v219, v94, v94
	v_fmac_f32_e32 v218, v87, v87
	v_fmac_f32_e32 v219, v95, v95
	v_add_f32_e32 v80, v218, v219
	s_waitcnt vmcnt(14)
	v_and_b32_e32 v218, 0xffff0000, v168
	v_lshlrev_b32_e32 v168, 16, v168
	v_and_b32_e32 v219, 0xffff0000, v169
	v_lshlrev_b32_e32 v169, 16, v169
	v_and_b32_e32 v220, 0xffff0000, v170
	v_lshlrev_b32_e32 v170, 16, v170
	v_and_b32_e32 v221, 0xffff0000, v171
	v_lshlrev_b32_e32 v171, 16, v171
	v_add_f32_e32 v76, v76, v168
	v_add_f32_e32 v77, v77, v218
	v_add_f32_e32 v78, v78, v169
	v_add_f32_e32 v79, v79, v219
	v_add_f32_e32 v72, v72, v170
	v_add_f32_e32 v73, v73, v220
	v_add_f32_e32 v74, v74, v171
	v_add_f32_e32 v75, v75, v221
	v_cvt_pk_bf16_f32 v168, v76, v77
	v_cvt_pk_bf16_f32 v169, v78, v79
	v_cvt_pk_bf16_f32 v170, v72, v73
	v_cvt_pk_bf16_f32 v171, v74, v75
	v_and_b32_e32 v218, 0xffff0000, v172
	v_lshlrev_b32_e32 v172, 16, v172
	v_and_b32_e32 v219, 0xffff0000, v173
	v_lshlrev_b32_e32 v173, 16, v173
	v_and_b32_e32 v220, 0xffff0000, v174
	v_lshlrev_b32_e32 v174, 16, v174
	v_and_b32_e32 v221, 0xffff0000, v175
	v_lshlrev_b32_e32 v175, 16, v175
	v_add_f32_e32 v68, v68, v172
	v_add_f32_e32 v69, v69, v218
	v_add_f32_e32 v70, v70, v173
	v_add_f32_e32 v71, v71, v219
	v_add_f32_e32 v64, v64, v174
	v_add_f32_e32 v65, v65, v220
	v_add_f32_e32 v66, v66, v175
	v_add_f32_e32 v67, v67, v221
	v_cvt_pk_bf16_f32 v172, v68, v69
	v_cvt_pk_bf16_f32 v173, v70, v71
	v_cvt_pk_bf16_f32 v174, v64, v65
	v_cvt_pk_bf16_f32 v175, v66, v67
	s_add_u32 s22, s22, 0x10000
	s_addc_u32 s23, s23, 0
	global_store_dwordx4 v216, v[168:171], s[22:23]
	global_store_dwordx4 v216, v[172:175], s[22:23] offset:256
	v_mul_f32_e32 v218, v64, v64
	v_mul_f32_e32 v219, v72, v72
	v_fmac_f32_e32 v218, v65, v65
	v_fmac_f32_e32 v219, v73, v73
	v_fmac_f32_e32 v218, v66, v66
	v_fmac_f32_e32 v219, v74, v74
	v_fmac_f32_e32 v218, v67, v67
	v_fmac_f32_e32 v219, v75, v75
	v_fmac_f32_e32 v218, v68, v68
	v_fmac_f32_e32 v219, v76, v76
	v_fmac_f32_e32 v218, v69, v69
	v_fmac_f32_e32 v219, v77, v77
	v_fmac_f32_e32 v218, v70, v70
	v_fmac_f32_e32 v219, v78, v78
	v_fmac_f32_e32 v218, v71, v71
	v_fmac_f32_e32 v219, v79, v79
	v_add_f32_e32 v64, v218, v219
	s_waitcnt vmcnt(14)
	v_and_b32_e32 v218, 0xffff0000, v176
	v_lshlrev_b32_e32 v176, 16, v176
	v_and_b32_e32 v219, 0xffff0000, v177
	v_lshlrev_b32_e32 v177, 16, v177
	v_and_b32_e32 v220, 0xffff0000, v178
	v_lshlrev_b32_e32 v178, 16, v178
	v_and_b32_e32 v221, 0xffff0000, v179
	v_lshlrev_b32_e32 v179, 16, v179
	v_add_f32_e32 v60, v60, v176
	v_add_f32_e32 v61, v61, v218
	v_add_f32_e32 v62, v62, v177
	v_add_f32_e32 v63, v63, v219
	v_add_f32_e32 v56, v56, v178
	v_add_f32_e32 v57, v57, v220
	v_add_f32_e32 v58, v58, v179
	v_add_f32_e32 v59, v59, v221
	v_cvt_pk_bf16_f32 v176, v60, v61
	v_cvt_pk_bf16_f32 v177, v62, v63
	v_cvt_pk_bf16_f32 v178, v56, v57
	v_cvt_pk_bf16_f32 v179, v58, v59
	v_and_b32_e32 v218, 0xffff0000, v180
	v_lshlrev_b32_e32 v180, 16, v180
	v_and_b32_e32 v219, 0xffff0000, v181
	v_lshlrev_b32_e32 v181, 16, v181
	v_and_b32_e32 v220, 0xffff0000, v182
	v_lshlrev_b32_e32 v182, 16, v182
	v_and_b32_e32 v221, 0xffff0000, v183
	v_lshlrev_b32_e32 v183, 16, v183
	v_add_f32_e32 v52, v52, v180
	v_add_f32_e32 v53, v53, v218
	v_add_f32_e32 v54, v54, v181
	v_add_f32_e32 v55, v55, v219
	v_add_f32_e32 v48, v48, v182
	v_add_f32_e32 v49, v49, v220
	v_add_f32_e32 v50, v50, v183
	v_add_f32_e32 v51, v51, v221
	v_cvt_pk_bf16_f32 v180, v52, v53
	v_cvt_pk_bf16_f32 v181, v54, v55
	v_cvt_pk_bf16_f32 v182, v48, v49
	v_cvt_pk_bf16_f32 v183, v50, v51
	s_add_u32 s22, s22, 0x50000
	s_addc_u32 s23, s23, 0
	global_store_dwordx4 v216, v[176:179], s[22:23]
	global_store_dwordx4 v216, v[180:183], s[22:23] offset:256
	v_mul_f32_e32 v218, v48, v48
	v_mul_f32_e32 v219, v56, v56
	v_fmac_f32_e32 v218, v49, v49
	v_fmac_f32_e32 v219, v57, v57
	v_fmac_f32_e32 v218, v50, v50
	v_fmac_f32_e32 v219, v58, v58
	v_fmac_f32_e32 v218, v51, v51
	v_fmac_f32_e32 v219, v59, v59
	v_fmac_f32_e32 v218, v52, v52
	v_fmac_f32_e32 v219, v60, v60
	v_fmac_f32_e32 v218, v53, v53
	v_fmac_f32_e32 v219, v61, v61
	v_fmac_f32_e32 v218, v54, v54
	v_fmac_f32_e32 v219, v62, v62
	v_fmac_f32_e32 v218, v55, v55
	v_fmac_f32_e32 v219, v63, v63
	v_add_f32_e32 v48, v218, v219
	s_waitcnt vmcnt(14)
	v_and_b32_e32 v218, 0xffff0000, v192
	v_lshlrev_b32_e32 v192, 16, v192
	v_and_b32_e32 v219, 0xffff0000, v193
	v_lshlrev_b32_e32 v193, 16, v193
	v_and_b32_e32 v220, 0xffff0000, v194
	v_lshlrev_b32_e32 v194, 16, v194
	v_and_b32_e32 v221, 0xffff0000, v195
	v_lshlrev_b32_e32 v195, 16, v195
	v_add_f32_e32 v44, v44, v192
	v_add_f32_e32 v45, v45, v218
	v_add_f32_e32 v46, v46, v193
	v_add_f32_e32 v47, v47, v219
	v_add_f32_e32 v40, v40, v194
	v_add_f32_e32 v41, v41, v220
	v_add_f32_e32 v42, v42, v195
	v_add_f32_e32 v43, v43, v221
	v_cvt_pk_bf16_f32 v192, v44, v45
	v_cvt_pk_bf16_f32 v193, v46, v47
	v_cvt_pk_bf16_f32 v194, v40, v41
	v_cvt_pk_bf16_f32 v195, v42, v43
	v_and_b32_e32 v218, 0xffff0000, v196
	v_lshlrev_b32_e32 v196, 16, v196
	v_and_b32_e32 v219, 0xffff0000, v197
	v_lshlrev_b32_e32 v197, 16, v197
	v_and_b32_e32 v220, 0xffff0000, v198
	v_lshlrev_b32_e32 v198, 16, v198
	v_and_b32_e32 v221, 0xffff0000, v199
	v_lshlrev_b32_e32 v199, 16, v199
	v_add_f32_e32 v36, v36, v196
	v_add_f32_e32 v37, v37, v218
	v_add_f32_e32 v38, v38, v197
	v_add_f32_e32 v39, v39, v219
	v_add_f32_e32 v32, v32, v198
	v_add_f32_e32 v33, v33, v220
	v_add_f32_e32 v34, v34, v199
	v_add_f32_e32 v35, v35, v221
	v_cvt_pk_bf16_f32 v196, v36, v37
	v_cvt_pk_bf16_f32 v197, v38, v39
	v_cvt_pk_bf16_f32 v198, v32, v33
	v_cvt_pk_bf16_f32 v199, v34, v35
	s_add_u32 s22, s22, 0x10000
	s_addc_u32 s23, s23, 0
	global_store_dwordx4 v216, v[192:195], s[22:23]
	global_store_dwordx4 v216, v[196:199], s[22:23] offset:256
	v_mul_f32_e32 v218, v32, v32
	v_mul_f32_e32 v219, v40, v40
	v_fmac_f32_e32 v218, v33, v33
	v_fmac_f32_e32 v219, v41, v41
	v_fmac_f32_e32 v218, v34, v34
	v_fmac_f32_e32 v219, v42, v42
	v_fmac_f32_e32 v218, v35, v35
	v_fmac_f32_e32 v219, v43, v43
	v_fmac_f32_e32 v218, v36, v36
	v_fmac_f32_e32 v219, v44, v44
	v_fmac_f32_e32 v218, v37, v37
	v_fmac_f32_e32 v219, v45, v45
	v_fmac_f32_e32 v218, v38, v38
	v_fmac_f32_e32 v219, v46, v46
	v_fmac_f32_e32 v218, v39, v39
	v_fmac_f32_e32 v219, v47, v47
	v_add_f32_e32 v32, v218, v219
	s_waitcnt vmcnt(14)
	v_and_b32_e32 v218, 0xffff0000, v200
	v_lshlrev_b32_e32 v200, 16, v200
	v_and_b32_e32 v219, 0xffff0000, v201
	v_lshlrev_b32_e32 v201, 16, v201
	v_and_b32_e32 v220, 0xffff0000, v202
	v_lshlrev_b32_e32 v202, 16, v202
	v_and_b32_e32 v221, 0xffff0000, v203
	v_lshlrev_b32_e32 v203, 16, v203
	v_add_f32_e32 v28, v28, v200
	v_add_f32_e32 v29, v29, v218
	v_add_f32_e32 v30, v30, v201
	v_add_f32_e32 v31, v31, v219
	v_add_f32_e32 v24, v24, v202
	v_add_f32_e32 v25, v25, v220
	v_add_f32_e32 v26, v26, v203
	v_add_f32_e32 v27, v27, v221
	v_cvt_pk_bf16_f32 v200, v28, v29
	v_cvt_pk_bf16_f32 v201, v30, v31
	v_cvt_pk_bf16_f32 v202, v24, v25
	v_cvt_pk_bf16_f32 v203, v26, v27
	v_and_b32_e32 v218, 0xffff0000, v204
	v_lshlrev_b32_e32 v204, 16, v204
	v_and_b32_e32 v219, 0xffff0000, v205
	v_lshlrev_b32_e32 v205, 16, v205
	v_and_b32_e32 v220, 0xffff0000, v206
	v_lshlrev_b32_e32 v206, 16, v206
	v_and_b32_e32 v221, 0xffff0000, v207
	v_lshlrev_b32_e32 v207, 16, v207
	v_add_f32_e32 v20, v20, v204
	v_add_f32_e32 v21, v21, v218
	v_add_f32_e32 v22, v22, v205
	v_add_f32_e32 v23, v23, v219
	v_add_f32_e32 v16, v16, v206
	v_add_f32_e32 v17, v17, v220
	v_add_f32_e32 v18, v18, v207
	v_add_f32_e32 v19, v19, v221
	v_cvt_pk_bf16_f32 v204, v20, v21
	v_cvt_pk_bf16_f32 v205, v22, v23
	v_cvt_pk_bf16_f32 v206, v16, v17
	v_cvt_pk_bf16_f32 v207, v18, v19
	s_add_u32 s22, s22, 0x10000
	s_addc_u32 s23, s23, 0
	global_store_dwordx4 v216, v[200:203], s[22:23]
	global_store_dwordx4 v216, v[204:207], s[22:23] offset:256
	v_mul_f32_e32 v218, v16, v16
	v_mul_f32_e32 v219, v24, v24
	v_fmac_f32_e32 v218, v17, v17
	v_fmac_f32_e32 v219, v25, v25
	v_fmac_f32_e32 v218, v18, v18
	v_fmac_f32_e32 v219, v26, v26
	v_fmac_f32_e32 v218, v19, v19
	v_fmac_f32_e32 v219, v27, v27
	v_fmac_f32_e32 v218, v20, v20
	v_fmac_f32_e32 v219, v28, v28
	v_fmac_f32_e32 v218, v21, v21
	v_fmac_f32_e32 v219, v29, v29
	v_fmac_f32_e32 v218, v22, v22
	v_fmac_f32_e32 v219, v30, v30
	v_fmac_f32_e32 v218, v23, v23
	v_fmac_f32_e32 v219, v31, v31
	v_add_f32_e32 v16, v218, v219
	s_waitcnt vmcnt(12)
	v_and_b32_e32 v218, 0xffff0000, v130
	v_lshlrev_b32_e32 v130, 16, v130
	v_and_b32_e32 v219, 0xffff0000, v131
	v_lshlrev_b32_e32 v131, 16, v131
	v_and_b32_e32 v220, 0xffff0000, v132
	v_lshlrev_b32_e32 v132, 16, v132
	v_and_b32_e32 v221, 0xffff0000, v133
	v_lshlrev_b32_e32 v133, 16, v133
	v_add_f32_e32 v12, v12, v130
	v_add_f32_e32 v13, v13, v218
	v_add_f32_e32 v14, v14, v131
	v_add_f32_e32 v15, v15, v219
	v_add_f32_e32 v8, v8, v132
	v_add_f32_e32 v9, v9, v220
	v_add_f32_e32 v10, v10, v133
	v_add_f32_e32 v11, v11, v221
	v_cvt_pk_bf16_f32 v130, v12, v13
	v_cvt_pk_bf16_f32 v131, v14, v15
	v_cvt_pk_bf16_f32 v132, v8, v9
	v_cvt_pk_bf16_f32 v133, v10, v11
	v_and_b32_e32 v218, 0xffff0000, v134
	v_lshlrev_b32_e32 v134, 16, v134
	v_and_b32_e32 v219, 0xffff0000, v135
	v_lshlrev_b32_e32 v135, 16, v135
	v_and_b32_e32 v220, 0xffff0000, v136
	v_lshlrev_b32_e32 v136, 16, v136
	v_and_b32_e32 v221, 0xffff0000, v137
	v_lshlrev_b32_e32 v137, 16, v137
	v_add_f32_e32 v4, v4, v134
	v_add_f32_e32 v5, v5, v218
	v_add_f32_e32 v6, v6, v135
	v_add_f32_e32 v7, v7, v219
	v_add_f32_e32 v0, v0, v136
	v_add_f32_e32 v1, v1, v220
	v_add_f32_e32 v2, v2, v137
	v_add_f32_e32 v3, v3, v221
	v_cvt_pk_bf16_f32 v134, v4, v5
	v_cvt_pk_bf16_f32 v135, v6, v7
	v_cvt_pk_bf16_f32 v136, v0, v1
	v_cvt_pk_bf16_f32 v137, v2, v3
	s_add_u32 s22, s22, 0x10000
	s_addc_u32 s23, s23, 0
	global_store_dwordx4 v216, v[130:133], s[22:23]
	global_store_dwordx4 v216, v[134:137], s[22:23] offset:256
	v_mul_f32_e32 v218, v0, v0
	v_mul_f32_e32 v219, v8, v8
	v_fmac_f32_e32 v218, v1, v1
	v_fmac_f32_e32 v219, v9, v9
	v_fmac_f32_e32 v218, v2, v2
	v_fmac_f32_e32 v219, v10, v10
	v_fmac_f32_e32 v218, v3, v3
	v_fmac_f32_e32 v219, v11, v11
	v_fmac_f32_e32 v218, v4, v4
	v_fmac_f32_e32 v219, v12, v12
	v_fmac_f32_e32 v218, v5, v5
	v_fmac_f32_e32 v219, v13, v13
	v_fmac_f32_e32 v218, v6, v6
	v_fmac_f32_e32 v219, v14, v14
	v_fmac_f32_e32 v218, v7, v7
	v_fmac_f32_e32 v219, v15, v15
	v_add_f32_e32 v0, v218, v219
	v_xor_b32_e32 v220, 16, v214
	v_xor_b32_e32 v221, 32, v214
	v_lshlrev_b32_e32 v220, 2, v220
	v_lshlrev_b32_e32 v221, 2, v221
	ds_bpermute_b32 v113, v220, v112
	ds_bpermute_b32 v97, v220, v96
	ds_bpermute_b32 v81, v220, v80
	ds_bpermute_b32 v65, v220, v64
	ds_bpermute_b32 v49, v220, v48
	ds_bpermute_b32 v33, v220, v32
	ds_bpermute_b32 v17, v220, v16
	ds_bpermute_b32 v1, v220, v0
	s_waitcnt lgkmcnt(0)
	v_add_f32_e32 v112, v112, v113
	v_add_f32_e32 v96, v96, v97
	v_add_f32_e32 v80, v80, v81
	v_add_f32_e32 v64, v64, v65
	v_add_f32_e32 v48, v48, v49
	v_add_f32_e32 v32, v32, v33
	v_add_f32_e32 v16, v16, v17
	v_add_f32_e32 v0, v0, v1
	ds_bpermute_b32 v113, v221, v112
	ds_bpermute_b32 v97, v221, v96
	ds_bpermute_b32 v81, v221, v80
	ds_bpermute_b32 v65, v221, v64
	ds_bpermute_b32 v49, v221, v48
	ds_bpermute_b32 v33, v221, v32
	ds_bpermute_b32 v17, v221, v16
	ds_bpermute_b32 v1, v221, v0
	s_waitcnt lgkmcnt(0)
	v_add_f32_e32 v112, v112, v113
	v_add_f32_e32 v96, v96, v97
	v_add_f32_e32 v80, v80, v81
	v_add_f32_e32 v64, v64, v65
	v_add_f32_e32 v48, v48, v49
	v_add_f32_e32 v32, v32, v33
	v_add_f32_e32 v16, v16, v17
	v_add_f32_e32 v0, v0, v1
	s_mov_b32 s22, s8
	s_mov_b32 s23, s9
	s_and_saveexec_b64 s[24:25], s[2:3]
	global_store_dword v217, v112, s[22:23]
	global_store_dword v217, v96, s[22:23] offset:2048
	s_add_u32 s22, s22, 0x1000
	s_addc_u32 s23, s23, 0
	global_store_dword v217, v80, s[22:23]
	global_store_dword v217, v64, s[22:23] offset:2048
	s_add_u32 s22, s22, 0x3000
	s_addc_u32 s23, s23, 0
	global_store_dword v217, v48, s[22:23]
	global_store_dword v217, v32, s[22:23] offset:2048
	s_add_u32 s22, s22, 0x1000
	s_addc_u32 s23, s23, 0
	global_store_dword v217, v16, s[22:23]
	global_store_dword v217, v0, s[22:23] offset:2048
	s_or_b64 exec, exec, s[24:25]
	s_and_b64 vcc, exec, s[4:5]
	s_mov_b64 s[4:5], -1
	s_cbranch_vccnz .LBB0_1169
	s_andn2_b64 vcc, exec, s[16:17]
	s_cbranch_vccnz .LBB0_1168
	s_barrier
	s_branch .LBB0_1168

.LBB0_1205:
	v_mov_b32_e32 v97, v210
	s_mov_b32 s2, s73
	s_cmp_gt_i32 s2, 31
	v_readfirstlane_b32 s1, v97
	s_cbranch_scc1 .LBB0_1211
	v_and_b32_e32 v96, 15, v97
	s_ashr_i32 s5, s1, 6
	v_mul_u32_u24_e32 v0, 0x1600, v96
	v_lshlrev_b32_e32 v128, 1, v0
	s_mul_i32 s6, s5, 0x2c0
	s_lshl_b32 s3, s2, 5
	s_waitcnt lgkmcnt(0)
	v_lshl_add_u64 v[0:1], s[14:15], 0, v[128:129]
	v_and_b32_e32 v128, 48, v97
	s_ashr_i32 s7, s6, 31
	s_lshl_b32 s4, s2, 6
	s_and_b32 s3, s3, 0x60
	v_lshl_add_u64 v[0:1], v[0:1], 0, v[128:129]
	s_lshl_b64 s[6:7], s[6:7], 1
	s_and_b32 s4, s4, 0xffffff00
	v_lshl_add_u64 v[28:29], v[0:1], 0, s[6:7]
	v_or_b32_e32 v0, s3, v96
	v_or_b32_e32 v2, s4, v0
	v_mov_b64_e32 v[0:1], s[12:13]
	s_movk_i32 s12, 0x2c00
	v_mad_i64_i32 v[0:1], s[12:13], v2, s12, v[0:1]
	v_lshl_add_u64 v[0:1], v[0:1], 0, v[128:129]
	v_lshl_add_u64 v[24:25], v[0:1], 0, s[6:7]
	s_mov_b32 s6, 0xb000000
	v_add_co_u32_e32 v0, vcc, s6, v28
	s_mov_b32 s6, 0xb02c000
	s_nop 0
	v_addc_co_u32_e32 v1, vcc, 0, v29, vcc
	v_add_co_u32_e32 v86, vcc, s6, v28
	s_mov_b32 s6, 0xb058000
	s_nop 0
	v_addc_co_u32_e32 v87, vcc, 0, v29, vcc
	v_add_co_u32_e32 v84, vcc, s6, v28
	s_mov_b64 s[6:7], 0xb000000
	s_nop 0
	v_addc_co_u32_e32 v85, vcc, 0, v29, vcc
	v_lshl_add_u64 v[26:27], v[28:29], 0, s[6:7]
	s_mov_b32 s6, 0xb084000
	v_add_co_u32_e32 v92, vcc, s6, v28
	s_mov_b32 s6, 0x2c000
	s_nop 0
	v_addc_co_u32_e32 v93, vcc, 0, v29, vcc
	v_add_co_u32_e32 v94, vcc, s6, v24
	s_mov_b32 s6, 0x160000
	s_nop 0
	v_addc_co_u32_e32 v95, vcc, 0, v25, vcc
	global_load_dwordx4 v[8:11], v[24:25], off
	v_add_co_u32_e32 v90, vcc, s6, v24
	s_mov_b32 s6, 0x18c000
	s_nop 0
	v_addc_co_u32_e32 v91, vcc, 0, v25, vcc
	v_add_co_u32_e32 v88, vcc, s6, v24
	global_load_dwordx4 v[0:3], v[0:1], off
	s_nop 0
	v_addc_co_u32_e32 v89, vcc, 0, v25, vcc
	global_load_dwordx4 v[4:7], v[86:87], off
	global_load_dwordx4 v[12:15], v[84:85], off
	global_load_dwordx4 v[20:23], v[24:25], off offset:1344
	global_load_dwordx4 v[16:19], v[26:27], off offset:1344
	global_load_dwordx4 v[34:37], v[86:87], off offset:64
	global_load_dwordx4 v[42:45], v[92:93], off
	global_load_dwordx4 v[46:49], v[84:85], off offset:64
	global_load_dwordx4 v[54:57], v[92:93], off offset:64
	global_load_dwordx4 v[58:61], v[94:95], off
	global_load_dwordx4 v[62:65], v[94:95], off offset:64
	global_load_dwordx4 v[78:81], v[90:91], off
	global_load_dwordx4 v[98:101], v[90:91], off offset:64
	global_load_dwordx4 v[114:117], v[88:89], off
	global_load_dwordx4 v[118:121], v[88:89], off offset:64
	global_load_dwordx4 v[122:125], v[24:25], off offset:64
	global_load_dwordx4 v[134:137], v[24:25], off offset:128
	global_load_dwordx4 v[130:133], v[26:27], off offset:64
	s_ashr_i32 s7, s1, 7
	s_and_b32 s6, s5, 1
	s_waitcnt vmcnt(0) lgkmcnt(0)
	v_mfma_f32_16x16x32_bf16 v[30:33], v[8:11], v[0:3], 0
	v_mfma_f32_16x16x32_bf16 v[38:41], v[8:11], v[4:7], 0
	v_mfma_f32_16x16x32_bf16 v[50:53], v[8:11], v[12:15], 0
	v_mfma_f32_16x16x32_bf16 v[8:11], v[8:11], v[42:45], 0
	v_mfma_f32_16x16x32_bf16 v[66:69], v[58:61], v[0:3], 0
	v_mfma_f32_16x16x32_bf16 v[70:73], v[58:61], v[4:7], 0
	v_mfma_f32_16x16x32_bf16 v[74:77], v[58:61], v[12:15], 0
	v_mfma_f32_16x16x32_bf16 v[58:61], v[58:61], v[42:45], 0
	v_mfma_f32_16x16x32_bf16 v[102:105], v[78:81], v[0:3], 0
	v_mfma_f32_16x16x32_bf16 v[106:109], v[78:81], v[4:7], 0
	v_mfma_f32_16x16x32_bf16 v[110:113], v[78:81], v[12:15], 0
	v_mfma_f32_16x16x32_bf16 v[78:81], v[78:81], v[42:45], 0
	v_mfma_f32_16x16x32_bf16 v[0:3], v[114:117], v[0:3], 0
	v_mfma_f32_16x16x32_bf16 v[4:7], v[114:117], v[4:7], 0
	v_mfma_f32_16x16x32_bf16 v[12:15], v[114:117], v[12:15], 0
	v_mfma_f32_16x16x32_bf16 v[42:45], v[114:117], v[42:45], 0
	global_load_dwordx4 v[114:117], v[26:27], off offset:128
	v_mfma_f32_16x16x32_bf16 v[28:31], v[122:125], v[130:133], v[30:33]
	v_mfma_f32_16x16x32_bf16 v[38:41], v[122:125], v[34:37], v[38:41]
	v_mfma_f32_16x16x32_bf16 v[50:53], v[122:125], v[46:49], v[50:53]
	v_mfma_f32_16x16x32_bf16 v[8:11], v[122:125], v[54:57], v[8:11]
	v_mfma_f32_16x16x32_bf16 v[66:69], v[62:65], v[130:133], v[66:69]
	v_mfma_f32_16x16x32_bf16 v[70:73], v[62:65], v[34:37], v[70:73]
	v_mfma_f32_16x16x32_bf16 v[74:77], v[62:65], v[46:49], v[74:77]
	v_mfma_f32_16x16x32_bf16 v[58:61], v[62:65], v[54:57], v[58:61]
	v_mfma_f32_16x16x32_bf16 v[62:65], v[98:101], v[130:133], v[102:105]
	v_mfma_f32_16x16x32_bf16 v[102:105], v[98:101], v[34:37], v[106:109]
	v_mfma_f32_16x16x32_bf16 v[106:109], v[98:101], v[46:49], v[110:113]
	v_mfma_f32_16x16x32_bf16 v[78:81], v[98:101], v[54:57], v[78:81]
	v_mfma_f32_16x16x32_bf16 v[0:3], v[118:121], v[130:133], v[0:3]
	v_mfma_f32_16x16x32_bf16 v[4:7], v[118:121], v[34:37], v[4:7]
	v_mfma_f32_16x16x32_bf16 v[12:15], v[118:121], v[46:49], v[12:15]
	v_mfma_f32_16x16x32_bf16 v[32:35], v[118:121], v[54:57], v[42:45]
	s_nop 2
	global_load_dwordx4 v[42:45], v[86:87], off offset:128
	global_load_dwordx4 v[46:49], v[86:87], off offset:192
	global_load_dwordx4 v[54:57], v[84:85], off offset:128
	global_load_dwordx4 v[98:101], v[84:85], off offset:192
	global_load_dwordx4 v[110:113], v[92:93], off offset:128
	global_load_dwordx4 v[118:121], v[92:93], off offset:192
	global_load_dwordx4 v[122:125], v[94:95], off offset:128
	global_load_dwordx4 v[130:133], v[94:95], off offset:192
	s_waitcnt vmcnt(0) lgkmcnt(0)
	v_mfma_f32_16x16x32_bf16 v[28:31], v[134:137], v[114:117], v[28:31]
	v_mfma_f32_16x16x32_bf16 v[36:39], v[134:137], v[42:45], v[38:41]
	v_mfma_f32_16x16x32_bf16 v[50:53], v[134:137], v[54:57], v[50:53]
	v_mfma_f32_16x16x32_bf16 v[8:11], v[134:137], v[110:113], v[8:11]
	v_mfma_f32_16x16x32_bf16 v[66:69], v[122:125], v[114:117], v[66:69]
	v_mfma_f32_16x16x32_bf16 v[70:73], v[122:125], v[42:45], v[70:73]
	v_mfma_f32_16x16x32_bf16 v[74:77], v[122:125], v[54:57], v[74:77]
	v_mfma_f32_16x16x32_bf16 v[58:61], v[122:125], v[110:113], v[58:61]
	global_load_dwordx4 v[122:125], v[90:91], off offset:128
	global_load_dwordx4 v[134:137], v[90:91], off offset:192
	s_waitcnt vmcnt(0) lgkmcnt(0)
	v_mfma_f32_16x16x32_bf16 v[62:65], v[122:125], v[114:117], v[62:65]
	v_mfma_f32_16x16x32_bf16 v[102:105], v[122:125], v[42:45], v[102:105]
	v_mfma_f32_16x16x32_bf16 v[106:109], v[122:125], v[54:57], v[106:109]
	v_mfma_f32_16x16x32_bf16 v[78:81], v[122:125], v[110:113], v[78:81]
	global_load_dwordx4 v[122:125], v[88:89], off offset:128
	global_load_dwordx4 v[138:141], v[88:89], off offset:192
	s_waitcnt vmcnt(0) lgkmcnt(0)
	v_mfma_f32_16x16x32_bf16 v[0:3], v[122:125], v[114:117], v[0:3]
	global_load_dwordx4 v[114:117], v[24:25], off offset:192
	v_mfma_f32_16x16x32_bf16 v[4:7], v[122:125], v[42:45], v[4:7]
	global_load_dwordx4 v[40:43], v[26:27], off offset:192
	v_mfma_f32_16x16x32_bf16 v[12:15], v[122:125], v[54:57], v[12:15]
	global_load_dwordx4 v[54:57], v[24:25], off offset:256
	v_mfma_f32_16x16x32_bf16 v[32:35], v[122:125], v[110:113], v[32:35]
	global_load_dwordx4 v[110:113], v[26:27], off offset:256
	s_waitcnt vmcnt(0) lgkmcnt(0)
	v_mfma_f32_16x16x32_bf16 v[28:31], v[114:117], v[40:43], v[28:31]
	v_mfma_f32_16x16x32_bf16 v[36:39], v[114:117], v[46:49], v[36:39]
	v_mfma_f32_16x16x32_bf16 v[50:53], v[114:117], v[98:101], v[50:53]
	v_mfma_f32_16x16x32_bf16 v[8:11], v[114:117], v[118:121], v[8:11]
	v_mfma_f32_16x16x32_bf16 v[66:69], v[130:133], v[40:43], v[66:69]
	v_mfma_f32_16x16x32_bf16 v[70:73], v[130:133], v[46:49], v[70:73]
	v_mfma_f32_16x16x32_bf16 v[74:77], v[130:133], v[98:101], v[74:77]
	v_mfma_f32_16x16x32_bf16 v[58:61], v[130:133], v[118:121], v[58:61]
	v_mfma_f32_16x16x32_bf16 v[62:65], v[134:137], v[40:43], v[62:65]
	v_mfma_f32_16x16x32_bf16 v[102:105], v[134:137], v[46:49], v[102:105]
	v_mfma_f32_16x16x32_bf16 v[106:109], v[134:137], v[98:101], v[106:109]
	v_mfma_f32_16x16x32_bf16 v[78:81], v[134:137], v[118:121], v[78:81]
	v_mfma_f32_16x16x32_bf16 v[0:3], v[138:141], v[40:43], v[0:3]
	v_mfma_f32_16x16x32_bf16 v[4:7], v[138:141], v[46:49], v[4:7]
	global_load_dwordx4 v[40:43], v[86:87], off offset:256
	global_load_dwordx4 v[44:47], v[86:87], off offset:320
	v_mfma_f32_16x16x32_bf16 v[12:15], v[138:141], v[98:101], v[12:15]
	global_load_dwordx4 v[98:101], v[84:85], off offset:256
	global_load_dwordx4 v[114:117], v[84:85], off offset:320
	v_mfma_f32_16x16x32_bf16 v[32:35], v[138:141], v[118:121], v[32:35]
	global_load_dwordx4 v[118:121], v[92:93], off offset:256
	global_load_dwordx4 v[122:125], v[92:93], off offset:320
	v_mfma_f32_16x16x32_bf16 v[28:31], v[54:57], v[110:113], v[28:31]
	s_waitcnt vmcnt(0) lgkmcnt(0)
	v_mfma_f32_16x16x32_bf16 v[36:39], v[54:57], v[40:43], v[36:39]
	v_mfma_f32_16x16x32_bf16 v[48:51], v[54:57], v[98:101], v[50:53]
	v_mfma_f32_16x16x32_bf16 v[8:11], v[54:57], v[118:121], v[8:11]
	s_nop 1
	global_load_dwordx4 v[52:55], v[94:95], off offset:256
	global_load_dwordx4 v[130:133], v[94:95], off offset:320
	s_waitcnt vmcnt(0) lgkmcnt(0)
	v_mfma_f32_16x16x32_bf16 v[66:69], v[52:55], v[110:113], v[66:69]
	v_mfma_f32_16x16x32_bf16 v[70:73], v[52:55], v[40:43], v[70:73]
	v_mfma_f32_16x16x32_bf16 v[74:77], v[52:55], v[98:101], v[74:77]
	v_mfma_f32_16x16x32_bf16 v[52:55], v[52:55], v[118:121], v[58:61]
	s_nop 2
	global_load_dwordx4 v[56:59], v[90:91], off offset:256
	global_load_dwordx4 v[134:137], v[90:91], off offset:320
	s_waitcnt vmcnt(0) lgkmcnt(0)
	v_mfma_f32_16x16x32_bf16 v[60:63], v[56:59], v[110:113], v[62:65]
	v_mfma_f32_16x16x32_bf16 v[102:105], v[56:59], v[40:43], v[102:105]
	v_mfma_f32_16x16x32_bf16 v[106:109], v[56:59], v[98:101], v[106:109]
	v_mfma_f32_16x16x32_bf16 v[56:59], v[56:59], v[118:121], v[78:81]
	s_nop 2
	global_load_dwordx4 v[78:81], v[88:89], off offset:256
	global_load_dwordx4 v[138:141], v[88:89], off offset:320
	s_waitcnt vmcnt(0) lgkmcnt(0)
	v_mfma_f32_16x16x32_bf16 v[0:3], v[78:81], v[110:113], v[0:3]
	global_load_dwordx4 v[110:113], v[24:25], off offset:320
	v_mfma_f32_16x16x32_bf16 v[4:7], v[78:81], v[40:43], v[4:7]
	global_load_dwordx4 v[40:43], v[26:27], off offset:320
	v_mfma_f32_16x16x32_bf16 v[12:15], v[78:81], v[98:101], v[12:15]
	global_load_dwordx4 v[98:101], v[24:25], off offset:384
	v_mfma_f32_16x16x32_bf16 v[32:35], v[78:81], v[118:121], v[32:35]
	global_load_dwordx4 v[78:81], v[26:27], off offset:384
	s_waitcnt vmcnt(0) lgkmcnt(0)
	v_mfma_f32_16x16x32_bf16 v[28:31], v[110:113], v[40:43], v[28:31]
	v_mfma_f32_16x16x32_bf16 v[36:39], v[110:113], v[44:47], v[36:39]
	v_mfma_f32_16x16x32_bf16 v[48:51], v[110:113], v[114:117], v[48:51]
	v_mfma_f32_16x16x32_bf16 v[8:11], v[110:113], v[122:125], v[8:11]
	v_mfma_f32_16x16x32_bf16 v[64:67], v[130:133], v[40:43], v[66:69]
	v_mfma_f32_16x16x32_bf16 v[68:71], v[130:133], v[44:47], v[70:73]
	v_mfma_f32_16x16x32_bf16 v[72:75], v[130:133], v[114:117], v[74:77]
	v_mfma_f32_16x16x32_bf16 v[52:55], v[130:133], v[122:125], v[52:55]
	v_mfma_f32_16x16x32_bf16 v[60:63], v[134:137], v[40:43], v[60:63]
	v_mfma_f32_16x16x32_bf16 v[102:105], v[134:137], v[44:47], v[102:105]
	v_mfma_f32_16x16x32_bf16 v[106:109], v[134:137], v[114:117], v[106:109]
	v_mfma_f32_16x16x32_bf16 v[56:59], v[134:137], v[122:125], v[56:59]
	v_mfma_f32_16x16x32_bf16 v[0:3], v[138:141], v[40:43], v[0:3]
	v_mfma_f32_16x16x32_bf16 v[4:7], v[138:141], v[44:47], v[4:7]
	global_load_dwordx4 v[40:43], v[86:87], off offset:384
	global_load_dwordx4 v[44:47], v[86:87], off offset:448
	v_mfma_f32_16x16x32_bf16 v[12:15], v[138:141], v[114:117], v[12:15]
	global_load_dwordx4 v[110:113], v[84:85], off offset:384
	global_load_dwordx4 v[114:117], v[84:85], off offset:448
	v_mfma_f32_16x16x32_bf16 v[32:35], v[138:141], v[122:125], v[32:35]
	global_load_dwordx4 v[118:121], v[92:93], off offset:384
	global_load_dwordx4 v[122:125], v[92:93], off offset:448
	v_mfma_f32_16x16x32_bf16 v[28:31], v[98:101], v[78:81], v[28:31]
	s_waitcnt vmcnt(0) lgkmcnt(0)
	v_mfma_f32_16x16x32_bf16 v[36:39], v[98:101], v[40:43], v[36:39]
	v_mfma_f32_16x16x32_bf16 v[48:51], v[98:101], v[110:113], v[48:51]
	v_mfma_f32_16x16x32_bf16 v[8:11], v[98:101], v[118:121], v[8:11]
	global_load_dwordx4 v[98:101], v[94:95], off offset:384
	global_load_dwordx4 v[130:133], v[94:95], off offset:448
	s_waitcnt vmcnt(0) lgkmcnt(0)
	v_mfma_f32_16x16x32_bf16 v[64:67], v[98:101], v[78:81], v[64:67]
	v_mfma_f32_16x16x32_bf16 v[68:71], v[98:101], v[40:43], v[68:71]
	v_mfma_f32_16x16x32_bf16 v[72:75], v[98:101], v[110:113], v[72:75]
	v_mfma_f32_16x16x32_bf16 v[52:55], v[98:101], v[118:121], v[52:55]
	global_load_dwordx4 v[98:101], v[90:91], off offset:384
	global_load_dwordx4 v[134:137], v[90:91], off offset:448
	s_waitcnt vmcnt(0) lgkmcnt(0)
	v_mfma_f32_16x16x32_bf16 v[60:63], v[98:101], v[78:81], v[60:63]
	v_mfma_f32_16x16x32_bf16 v[102:105], v[98:101], v[40:43], v[102:105]
	v_mfma_f32_16x16x32_bf16 v[106:109], v[98:101], v[110:113], v[106:109]
	v_mfma_f32_16x16x32_bf16 v[56:59], v[98:101], v[118:121], v[56:59]
	global_load_dwordx4 v[98:101], v[88:89], off offset:384
	global_load_dwordx4 v[138:141], v[88:89], off offset:448
	s_waitcnt vmcnt(0) lgkmcnt(0)
	v_mfma_f32_16x16x32_bf16 v[0:3], v[98:101], v[78:81], v[0:3]
	global_load_dwordx4 v[76:79], v[24:25], off offset:448
	global_load_dwordx4 v[80:83], v[24:25], off offset:512
	v_mfma_f32_16x16x32_bf16 v[4:7], v[98:101], v[40:43], v[4:7]
	global_load_dwordx4 v[40:43], v[26:27], off offset:448
	v_mfma_f32_16x16x32_bf16 v[12:15], v[98:101], v[110:113], v[12:15]
	v_mfma_f32_16x16x32_bf16 v[32:35], v[98:101], v[118:121], v[32:35]
	global_load_dwordx4 v[98:101], v[26:27], off offset:512
	s_waitcnt vmcnt(0) lgkmcnt(0)
	v_mfma_f32_16x16x32_bf16 v[28:31], v[76:79], v[40:43], v[28:31]
	v_mfma_f32_16x16x32_bf16 v[36:39], v[76:79], v[44:47], v[36:39]
	v_mfma_f32_16x16x32_bf16 v[48:51], v[76:79], v[114:117], v[48:51]
	v_mfma_f32_16x16x32_bf16 v[8:11], v[76:79], v[122:125], v[8:11]
	v_mfma_f32_16x16x32_bf16 v[64:67], v[130:133], v[40:43], v[64:67]
	v_mfma_f32_16x16x32_bf16 v[68:71], v[130:133], v[44:47], v[68:71]
	v_mfma_f32_16x16x32_bf16 v[72:75], v[130:133], v[114:117], v[72:75]
	v_mfma_f32_16x16x32_bf16 v[60:63], v[134:137], v[40:43], v[60:63]
	v_mfma_f32_16x16x32_bf16 v[76:79], v[134:137], v[44:47], v[102:105]
	v_mfma_f32_16x16x32_bf16 v[102:105], v[134:137], v[114:117], v[106:109]
	v_mfma_f32_16x16x32_bf16 v[0:3], v[138:141], v[40:43], v[0:3]
	v_mfma_f32_16x16x32_bf16 v[4:7], v[138:141], v[44:47], v[4:7]
	global_load_dwordx4 v[40:43], v[86:87], off offset:512
	global_load_dwordx4 v[44:47], v[86:87], off offset:576
	global_load_dwordx4 v[106:109], v[84:85], off offset:512
	global_load_dwordx4 v[110:113], v[84:85], off offset:576
	v_mfma_f32_16x16x32_bf16 v[12:15], v[138:141], v[114:117], v[12:15]
	global_load_dwordx4 v[114:117], v[92:93], off offset:512
	global_load_dwordx4 v[118:121], v[92:93], off offset:576
	v_mfma_f32_16x16x32_bf16 v[52:55], v[130:133], v[122:125], v[52:55]
	v_mfma_f32_16x16x32_bf16 v[56:59], v[134:137], v[122:125], v[56:59]
	v_mfma_f32_16x16x32_bf16 v[32:35], v[138:141], v[122:125], v[32:35]
	v_mfma_f32_16x16x32_bf16 v[28:31], v[80:83], v[98:101], v[28:31]
	s_waitcnt vmcnt(0) lgkmcnt(0)
	v_mfma_f32_16x16x32_bf16 v[36:39], v[80:83], v[40:43], v[36:39]
	v_mfma_f32_16x16x32_bf16 v[48:51], v[80:83], v[106:109], v[48:51]
	v_mfma_f32_16x16x32_bf16 v[8:11], v[80:83], v[114:117], v[8:11]
	global_load_dwordx4 v[80:83], v[94:95], off offset:512
	global_load_dwordx4 v[122:125], v[94:95], off offset:576
	s_waitcnt vmcnt(0) lgkmcnt(0)
	v_mfma_f32_16x16x32_bf16 v[64:67], v[80:83], v[98:101], v[64:67]
	v_mfma_f32_16x16x32_bf16 v[68:71], v[80:83], v[40:43], v[68:71]
	v_mfma_f32_16x16x32_bf16 v[72:75], v[80:83], v[106:109], v[72:75]
	v_mfma_f32_16x16x32_bf16 v[52:55], v[80:83], v[114:117], v[52:55]
	global_load_dwordx4 v[80:83], v[90:91], off offset:512
	global_load_dwordx4 v[130:133], v[90:91], off offset:576
	s_waitcnt vmcnt(0) lgkmcnt(0)
	v_mfma_f32_16x16x32_bf16 v[60:63], v[80:83], v[98:101], v[60:63]
	v_mfma_f32_16x16x32_bf16 v[76:79], v[80:83], v[40:43], v[76:79]
	v_mfma_f32_16x16x32_bf16 v[102:105], v[80:83], v[106:109], v[102:105]
	v_mfma_f32_16x16x32_bf16 v[56:59], v[80:83], v[114:117], v[56:59]
	global_load_dwordx4 v[80:83], v[88:89], off offset:512
	global_load_dwordx4 v[134:137], v[88:89], off offset:576
	s_waitcnt vmcnt(0) lgkmcnt(0)
	v_mfma_f32_16x16x32_bf16 v[0:3], v[80:83], v[98:101], v[0:3]
	global_load_dwordx4 v[98:101], v[24:25], off offset:576
	v_mfma_f32_16x16x32_bf16 v[4:7], v[80:83], v[40:43], v[4:7]
	global_load_dwordx4 v[40:43], v[26:27], off offset:576
	v_mfma_f32_16x16x32_bf16 v[12:15], v[80:83], v[106:109], v[12:15]
	global_load_dwordx4 v[106:109], v[24:25], off offset:640
	v_mfma_f32_16x16x32_bf16 v[32:35], v[80:83], v[114:117], v[32:35]
	global_load_dwordx4 v[80:83], v[26:27], off offset:640
	s_waitcnt vmcnt(0) lgkmcnt(0)
	v_mfma_f32_16x16x32_bf16 v[28:31], v[98:101], v[40:43], v[28:31]
	v_mfma_f32_16x16x32_bf16 v[36:39], v[98:101], v[44:47], v[36:39]
	v_mfma_f32_16x16x32_bf16 v[48:51], v[98:101], v[110:113], v[48:51]
	v_mfma_f32_16x16x32_bf16 v[8:11], v[98:101], v[118:121], v[8:11]
	v_mfma_f32_16x16x32_bf16 v[64:67], v[122:125], v[40:43], v[64:67]
	v_mfma_f32_16x16x32_bf16 v[68:71], v[122:125], v[44:47], v[68:71]
	v_mfma_f32_16x16x32_bf16 v[72:75], v[122:125], v[110:113], v[72:75]
	v_mfma_f32_16x16x32_bf16 v[52:55], v[122:125], v[118:121], v[52:55]
	v_mfma_f32_16x16x32_bf16 v[60:63], v[130:133], v[40:43], v[60:63]
	v_mfma_f32_16x16x32_bf16 v[76:79], v[130:133], v[44:47], v[76:79]
	v_mfma_f32_16x16x32_bf16 v[98:101], v[130:133], v[110:113], v[102:105]
	v_mfma_f32_16x16x32_bf16 v[56:59], v[130:133], v[118:121], v[56:59]
	v_mfma_f32_16x16x32_bf16 v[0:3], v[134:137], v[40:43], v[0:3]
	v_mfma_f32_16x16x32_bf16 v[4:7], v[134:137], v[44:47], v[4:7]
	global_load_dwordx4 v[40:43], v[86:87], off offset:640
	global_load_dwordx4 v[44:47], v[86:87], off offset:704
	v_mfma_f32_16x16x32_bf16 v[12:15], v[134:137], v[110:113], v[12:15]
	global_load_dwordx4 v[102:105], v[84:85], off offset:640
	global_load_dwordx4 v[110:113], v[84:85], off offset:704
	v_mfma_f32_16x16x32_bf16 v[32:35], v[134:137], v[118:121], v[32:35]
	global_load_dwordx4 v[114:117], v[92:93], off offset:640
	global_load_dwordx4 v[118:121], v[92:93], off offset:704
	v_mfma_f32_16x16x32_bf16 v[28:31], v[106:109], v[80:83], v[28:31]
	s_waitcnt vmcnt(0) lgkmcnt(0)
	v_mfma_f32_16x16x32_bf16 v[36:39], v[106:109], v[40:43], v[36:39]
	v_mfma_f32_16x16x32_bf16 v[48:51], v[106:109], v[102:105], v[48:51]
	v_mfma_f32_16x16x32_bf16 v[8:11], v[106:109], v[114:117], v[8:11]
	global_load_dwordx4 v[106:109], v[94:95], off offset:640
	global_load_dwordx4 v[122:125], v[94:95], off offset:704
	s_waitcnt vmcnt(0) lgkmcnt(0)
	v_mfma_f32_16x16x32_bf16 v[64:67], v[106:109], v[80:83], v[64:67]
	v_mfma_f32_16x16x32_bf16 v[68:71], v[106:109], v[40:43], v[68:71]
	v_mfma_f32_16x16x32_bf16 v[72:75], v[106:109], v[102:105], v[72:75]
	v_mfma_f32_16x16x32_bf16 v[52:55], v[106:109], v[114:117], v[52:55]
	global_load_dwordx4 v[106:109], v[90:91], off offset:640
	global_load_dwordx4 v[130:133], v[90:91], off offset:704
	s_waitcnt vmcnt(0) lgkmcnt(0)
	v_mfma_f32_16x16x32_bf16 v[60:63], v[106:109], v[80:83], v[60:63]
	v_mfma_f32_16x16x32_bf16 v[76:79], v[106:109], v[40:43], v[76:79]
	v_mfma_f32_16x16x32_bf16 v[98:101], v[106:109], v[102:105], v[98:101]
	v_mfma_f32_16x16x32_bf16 v[56:59], v[106:109], v[114:117], v[56:59]
	global_load_dwordx4 v[106:109], v[88:89], off offset:640
	global_load_dwordx4 v[134:137], v[88:89], off offset:704
	s_waitcnt vmcnt(0) lgkmcnt(0)
	v_mfma_f32_16x16x32_bf16 v[0:3], v[106:109], v[80:83], v[0:3]
	global_load_dwordx4 v[80:83], v[24:25], off offset:704
	v_mfma_f32_16x16x32_bf16 v[4:7], v[106:109], v[40:43], v[4:7]
	global_load_dwordx4 v[40:43], v[26:27], off offset:704
	v_mfma_f32_16x16x32_bf16 v[12:15], v[106:109], v[102:105], v[12:15]
	global_load_dwordx4 v[102:105], v[24:25], off offset:768
	v_mfma_f32_16x16x32_bf16 v[32:35], v[106:109], v[114:117], v[32:35]
	global_load_dwordx4 v[106:109], v[26:27], off offset:768
	s_waitcnt vmcnt(0) lgkmcnt(0)
	v_mfma_f32_16x16x32_bf16 v[28:31], v[80:83], v[40:43], v[28:31]
	v_mfma_f32_16x16x32_bf16 v[36:39], v[80:83], v[44:47], v[36:39]
	v_mfma_f32_16x16x32_bf16 v[48:51], v[80:83], v[110:113], v[48:51]
	v_mfma_f32_16x16x32_bf16 v[8:11], v[80:83], v[118:121], v[8:11]
	v_mfma_f32_16x16x32_bf16 v[64:67], v[122:125], v[40:43], v[64:67]
	v_mfma_f32_16x16x32_bf16 v[68:71], v[122:125], v[44:47], v[68:71]
	v_mfma_f32_16x16x32_bf16 v[72:75], v[122:125], v[110:113], v[72:75]
	v_mfma_f32_16x16x32_bf16 v[52:55], v[122:125], v[118:121], v[52:55]
	v_mfma_f32_16x16x32_bf16 v[60:63], v[130:133], v[40:43], v[60:63]
	v_mfma_f32_16x16x32_bf16 v[76:79], v[130:133], v[44:47], v[76:79]
	v_mfma_f32_16x16x32_bf16 v[80:83], v[130:133], v[110:113], v[98:101]
	v_mfma_f32_16x16x32_bf16 v[56:59], v[130:133], v[118:121], v[56:59]
	v_mfma_f32_16x16x32_bf16 v[0:3], v[134:137], v[40:43], v[0:3]
	v_mfma_f32_16x16x32_bf16 v[4:7], v[134:137], v[44:47], v[4:7]
	global_load_dwordx4 v[40:43], v[86:87], off offset:768
	global_load_dwordx4 v[44:47], v[86:87], off offset:832
	v_mfma_f32_16x16x32_bf16 v[12:15], v[134:137], v[110:113], v[12:15]
	global_load_dwordx4 v[98:101], v[84:85], off offset:768
	global_load_dwordx4 v[110:113], v[84:85], off offset:832
	v_mfma_f32_16x16x32_bf16 v[32:35], v[134:137], v[118:121], v[32:35]
	global_load_dwordx4 v[114:117], v[92:93], off offset:768
	global_load_dwordx4 v[118:121], v[92:93], off offset:832
	v_mfma_f32_16x16x32_bf16 v[28:31], v[102:105], v[106:109], v[28:31]
	s_waitcnt vmcnt(0) lgkmcnt(0)
	v_mfma_f32_16x16x32_bf16 v[36:39], v[102:105], v[40:43], v[36:39]
	v_mfma_f32_16x16x32_bf16 v[48:51], v[102:105], v[98:101], v[48:51]
	v_mfma_f32_16x16x32_bf16 v[8:11], v[102:105], v[114:117], v[8:11]
	global_load_dwordx4 v[102:105], v[94:95], off offset:768
	global_load_dwordx4 v[122:125], v[94:95], off offset:832
	s_waitcnt vmcnt(0) lgkmcnt(0)
	v_mfma_f32_16x16x32_bf16 v[64:67], v[102:105], v[106:109], v[64:67]
	v_mfma_f32_16x16x32_bf16 v[68:71], v[102:105], v[40:43], v[68:71]
	v_mfma_f32_16x16x32_bf16 v[72:75], v[102:105], v[98:101], v[72:75]
	v_mfma_f32_16x16x32_bf16 v[52:55], v[102:105], v[114:117], v[52:55]
	global_load_dwordx4 v[102:105], v[90:91], off offset:768
	global_load_dwordx4 v[130:133], v[90:91], off offset:832
	s_waitcnt vmcnt(0) lgkmcnt(0)
	v_mfma_f32_16x16x32_bf16 v[60:63], v[102:105], v[106:109], v[60:63]
	v_mfma_f32_16x16x32_bf16 v[76:79], v[102:105], v[40:43], v[76:79]
	v_mfma_f32_16x16x32_bf16 v[80:83], v[102:105], v[98:101], v[80:83]
	v_mfma_f32_16x16x32_bf16 v[56:59], v[102:105], v[114:117], v[56:59]
	global_load_dwordx4 v[102:105], v[88:89], off offset:768
	global_load_dwordx4 v[134:137], v[88:89], off offset:832
	s_waitcnt vmcnt(0) lgkmcnt(0)
	v_mfma_f32_16x16x32_bf16 v[0:3], v[102:105], v[106:109], v[0:3]
	global_load_dwordx4 v[106:109], v[24:25], off offset:832
	v_mfma_f32_16x16x32_bf16 v[4:7], v[102:105], v[40:43], v[4:7]
	global_load_dwordx4 v[40:43], v[26:27], off offset:832
	v_mfma_f32_16x16x32_bf16 v[12:15], v[102:105], v[98:101], v[12:15]
	global_load_dwordx4 v[98:101], v[24:25], off offset:896
	v_mfma_f32_16x16x32_bf16 v[32:35], v[102:105], v[114:117], v[32:35]
	global_load_dwordx4 v[102:105], v[26:27], off offset:896
	s_waitcnt vmcnt(0) lgkmcnt(0)
	v_mfma_f32_16x16x32_bf16 v[28:31], v[106:109], v[40:43], v[28:31]
	v_mfma_f32_16x16x32_bf16 v[36:39], v[106:109], v[44:47], v[36:39]
	v_mfma_f32_16x16x32_bf16 v[48:51], v[106:109], v[110:113], v[48:51]
	v_mfma_f32_16x16x32_bf16 v[8:11], v[106:109], v[118:121], v[8:11]
	v_mfma_f32_16x16x32_bf16 v[64:67], v[122:125], v[40:43], v[64:67]
	v_mfma_f32_16x16x32_bf16 v[68:71], v[122:125], v[44:47], v[68:71]
	v_mfma_f32_16x16x32_bf16 v[72:75], v[122:125], v[110:113], v[72:75]
	v_mfma_f32_16x16x32_bf16 v[52:55], v[122:125], v[118:121], v[52:55]
	v_mfma_f32_16x16x32_bf16 v[60:63], v[130:133], v[40:43], v[60:63]
	v_mfma_f32_16x16x32_bf16 v[76:79], v[130:133], v[44:47], v[76:79]
	v_mfma_f32_16x16x32_bf16 v[80:83], v[130:133], v[110:113], v[80:83]
	v_mfma_f32_16x16x32_bf16 v[56:59], v[130:133], v[118:121], v[56:59]
	v_mfma_f32_16x16x32_bf16 v[0:3], v[134:137], v[40:43], v[0:3]
	v_mfma_f32_16x16x32_bf16 v[4:7], v[134:137], v[44:47], v[4:7]
	global_load_dwordx4 v[40:43], v[86:87], off offset:896
	global_load_dwordx4 v[44:47], v[86:87], off offset:960
	v_mfma_f32_16x16x32_bf16 v[12:15], v[134:137], v[110:113], v[12:15]
	global_load_dwordx4 v[106:109], v[84:85], off offset:896
	global_load_dwordx4 v[110:113], v[84:85], off offset:960
	v_mfma_f32_16x16x32_bf16 v[32:35], v[134:137], v[118:121], v[32:35]
	global_load_dwordx4 v[114:117], v[92:93], off offset:896
	global_load_dwordx4 v[118:121], v[92:93], off offset:960
	v_mfma_f32_16x16x32_bf16 v[28:31], v[98:101], v[102:105], v[28:31]
	s_waitcnt vmcnt(0) lgkmcnt(0)
	v_mfma_f32_16x16x32_bf16 v[36:39], v[98:101], v[40:43], v[36:39]
	v_mfma_f32_16x16x32_bf16 v[48:51], v[98:101], v[106:109], v[48:51]
	v_mfma_f32_16x16x32_bf16 v[8:11], v[98:101], v[114:117], v[8:11]
	global_load_dwordx4 v[98:101], v[94:95], off offset:896
	global_load_dwordx4 v[122:125], v[94:95], off offset:960
	s_waitcnt vmcnt(0) lgkmcnt(0)
	v_mfma_f32_16x16x32_bf16 v[64:67], v[98:101], v[102:105], v[64:67]
	v_mfma_f32_16x16x32_bf16 v[68:71], v[98:101], v[40:43], v[68:71]
	v_mfma_f32_16x16x32_bf16 v[72:75], v[98:101], v[106:109], v[72:75]
	v_mfma_f32_16x16x32_bf16 v[52:55], v[98:101], v[114:117], v[52:55]
	global_load_dwordx4 v[98:101], v[90:91], off offset:896
	global_load_dwordx4 v[130:133], v[90:91], off offset:960
	s_waitcnt vmcnt(0) lgkmcnt(0)
	v_mfma_f32_16x16x32_bf16 v[60:63], v[98:101], v[102:105], v[60:63]
	v_mfma_f32_16x16x32_bf16 v[76:79], v[98:101], v[40:43], v[76:79]
	v_mfma_f32_16x16x32_bf16 v[80:83], v[98:101], v[106:109], v[80:83]
	v_mfma_f32_16x16x32_bf16 v[56:59], v[98:101], v[114:117], v[56:59]
	global_load_dwordx4 v[98:101], v[88:89], off offset:896
	global_load_dwordx4 v[134:137], v[88:89], off offset:960
	s_waitcnt vmcnt(0) lgkmcnt(0)
	v_mfma_f32_16x16x32_bf16 v[0:3], v[98:101], v[102:105], v[0:3]
	global_load_dwordx4 v[102:105], v[24:25], off offset:960
	v_mfma_f32_16x16x32_bf16 v[4:7], v[98:101], v[40:43], v[4:7]
	global_load_dwordx4 v[40:43], v[26:27], off offset:960
	v_mfma_f32_16x16x32_bf16 v[12:15], v[98:101], v[106:109], v[12:15]
	global_load_dwordx4 v[106:109], v[24:25], off offset:1024
	v_mfma_f32_16x16x32_bf16 v[32:35], v[98:101], v[114:117], v[32:35]
	global_load_dwordx4 v[98:101], v[26:27], off offset:1024
	s_waitcnt vmcnt(0) lgkmcnt(0)
	v_mfma_f32_16x16x32_bf16 v[28:31], v[102:105], v[40:43], v[28:31]
	v_mfma_f32_16x16x32_bf16 v[36:39], v[102:105], v[44:47], v[36:39]
	v_mfma_f32_16x16x32_bf16 v[48:51], v[102:105], v[110:113], v[48:51]
	v_mfma_f32_16x16x32_bf16 v[8:11], v[102:105], v[118:121], v[8:11]
	v_mfma_f32_16x16x32_bf16 v[64:67], v[122:125], v[40:43], v[64:67]
	v_mfma_f32_16x16x32_bf16 v[68:71], v[122:125], v[44:47], v[68:71]
	v_mfma_f32_16x16x32_bf16 v[72:75], v[122:125], v[110:113], v[72:75]
	v_mfma_f32_16x16x32_bf16 v[52:55], v[122:125], v[118:121], v[52:55]
	v_mfma_f32_16x16x32_bf16 v[60:63], v[130:133], v[40:43], v[60:63]
	v_mfma_f32_16x16x32_bf16 v[76:79], v[130:133], v[44:47], v[76:79]
	v_mfma_f32_16x16x32_bf16 v[80:83], v[130:133], v[110:113], v[80:83]
	v_mfma_f32_16x16x32_bf16 v[56:59], v[130:133], v[118:121], v[56:59]
	v_mfma_f32_16x16x32_bf16 v[0:3], v[134:137], v[40:43], v[0:3]
	v_mfma_f32_16x16x32_bf16 v[4:7], v[134:137], v[44:47], v[4:7]
	global_load_dwordx4 v[40:43], v[86:87], off offset:1024
	global_load_dwordx4 v[44:47], v[86:87], off offset:1088
	v_mfma_f32_16x16x32_bf16 v[12:15], v[134:137], v[110:113], v[12:15]
	global_load_dwordx4 v[102:105], v[84:85], off offset:1024
	global_load_dwordx4 v[110:113], v[84:85], off offset:1088
	v_mfma_f32_16x16x32_bf16 v[32:35], v[134:137], v[118:121], v[32:35]
	global_load_dwordx4 v[114:117], v[92:93], off offset:1024
	global_load_dwordx4 v[118:121], v[92:93], off offset:1088
	v_mfma_f32_16x16x32_bf16 v[28:31], v[106:109], v[98:101], v[28:31]
	s_waitcnt vmcnt(0) lgkmcnt(0)
	v_mfma_f32_16x16x32_bf16 v[36:39], v[106:109], v[40:43], v[36:39]
	v_mfma_f32_16x16x32_bf16 v[48:51], v[106:109], v[102:105], v[48:51]
	v_mfma_f32_16x16x32_bf16 v[8:11], v[106:109], v[114:117], v[8:11]
	global_load_dwordx4 v[106:109], v[94:95], off offset:1024
	global_load_dwordx4 v[122:125], v[94:95], off offset:1088
	s_waitcnt vmcnt(0) lgkmcnt(0)
	v_mfma_f32_16x16x32_bf16 v[64:67], v[106:109], v[98:101], v[64:67]
	v_mfma_f32_16x16x32_bf16 v[68:71], v[106:109], v[40:43], v[68:71]
	v_mfma_f32_16x16x32_bf16 v[72:75], v[106:109], v[102:105], v[72:75]
	v_mfma_f32_16x16x32_bf16 v[52:55], v[106:109], v[114:117], v[52:55]
	global_load_dwordx4 v[106:109], v[90:91], off offset:1024
	global_load_dwordx4 v[130:133], v[90:91], off offset:1088
	s_waitcnt vmcnt(0) lgkmcnt(0)
	v_mfma_f32_16x16x32_bf16 v[60:63], v[106:109], v[98:101], v[60:63]
	v_mfma_f32_16x16x32_bf16 v[76:79], v[106:109], v[40:43], v[76:79]
	v_mfma_f32_16x16x32_bf16 v[80:83], v[106:109], v[102:105], v[80:83]
	v_mfma_f32_16x16x32_bf16 v[56:59], v[106:109], v[114:117], v[56:59]
	global_load_dwordx4 v[106:109], v[88:89], off offset:1024
	global_load_dwordx4 v[134:137], v[88:89], off offset:1088
	s_waitcnt vmcnt(0) lgkmcnt(0)
	v_mfma_f32_16x16x32_bf16 v[0:3], v[106:109], v[98:101], v[0:3]
	global_load_dwordx4 v[98:101], v[24:25], off offset:1088
	v_mfma_f32_16x16x32_bf16 v[4:7], v[106:109], v[40:43], v[4:7]
	global_load_dwordx4 v[40:43], v[26:27], off offset:1088
	v_mfma_f32_16x16x32_bf16 v[12:15], v[106:109], v[102:105], v[12:15]
	global_load_dwordx4 v[102:105], v[24:25], off offset:1152
	v_mfma_f32_16x16x32_bf16 v[32:35], v[106:109], v[114:117], v[32:35]
	global_load_dwordx4 v[106:109], v[26:27], off offset:1152
	s_waitcnt vmcnt(0) lgkmcnt(0)
	v_mfma_f32_16x16x32_bf16 v[28:31], v[98:101], v[40:43], v[28:31]
	v_mfma_f32_16x16x32_bf16 v[36:39], v[98:101], v[44:47], v[36:39]
	v_mfma_f32_16x16x32_bf16 v[48:51], v[98:101], v[110:113], v[48:51]
	v_mfma_f32_16x16x32_bf16 v[8:11], v[98:101], v[118:121], v[8:11]
	v_mfma_f32_16x16x32_bf16 v[64:67], v[122:125], v[40:43], v[64:67]
	v_mfma_f32_16x16x32_bf16 v[68:71], v[122:125], v[44:47], v[68:71]
	v_mfma_f32_16x16x32_bf16 v[72:75], v[122:125], v[110:113], v[72:75]
	v_mfma_f32_16x16x32_bf16 v[52:55], v[122:125], v[118:121], v[52:55]
	v_mfma_f32_16x16x32_bf16 v[60:63], v[130:133], v[40:43], v[60:63]
	v_mfma_f32_16x16x32_bf16 v[76:79], v[130:133], v[44:47], v[76:79]
	v_mfma_f32_16x16x32_bf16 v[80:83], v[130:133], v[110:113], v[80:83]
	v_mfma_f32_16x16x32_bf16 v[56:59], v[130:133], v[118:121], v[56:59]
	v_mfma_f32_16x16x32_bf16 v[0:3], v[134:137], v[40:43], v[0:3]
	global_load_dwordx4 v[40:43], v[86:87], off offset:1152
	global_load_dwordx4 v[98:101], v[86:87], off offset:1216
	v_mfma_f32_16x16x32_bf16 v[4:7], v[134:137], v[44:47], v[4:7]
	v_mfma_f32_16x16x32_bf16 v[12:15], v[134:137], v[110:113], v[12:15]
	global_load_dwordx4 v[44:47], v[84:85], off offset:1152
	global_load_dwordx4 v[110:113], v[84:85], off offset:1216
	v_mfma_f32_16x16x32_bf16 v[32:35], v[134:137], v[118:121], v[32:35]
	global_load_dwordx4 v[114:117], v[92:93], off offset:1152
	global_load_dwordx4 v[118:121], v[92:93], off offset:1216
	v_mfma_f32_16x16x32_bf16 v[28:31], v[102:105], v[106:109], v[28:31]
	s_waitcnt vmcnt(0) lgkmcnt(0)
	v_mfma_f32_16x16x32_bf16 v[36:39], v[102:105], v[40:43], v[36:39]
	v_mfma_f32_16x16x32_bf16 v[48:51], v[102:105], v[44:47], v[48:51]
	v_mfma_f32_16x16x32_bf16 v[8:11], v[102:105], v[114:117], v[8:11]
	global_load_dwordx4 v[102:105], v[94:95], off offset:1152
	global_load_dwordx4 v[122:125], v[94:95], off offset:1216
	s_waitcnt vmcnt(0) lgkmcnt(0)
	v_mfma_f32_16x16x32_bf16 v[64:67], v[102:105], v[106:109], v[64:67]
	v_mfma_f32_16x16x32_bf16 v[130:133], v[102:105], v[40:43], v[68:71]
	v_mfma_f32_16x16x32_bf16 v[134:137], v[102:105], v[44:47], v[72:75]
	v_mfma_f32_16x16x32_bf16 v[102:105], v[102:105], v[114:117], v[52:55]
	s_nop 2
	global_load_dwordx4 v[52:55], v[90:91], off offset:1152
	global_load_dwordx4 v[138:141], v[90:91], off offset:1216
	s_waitcnt vmcnt(0) lgkmcnt(0)
	v_mfma_f32_16x16x32_bf16 v[142:145], v[52:55], v[106:109], v[60:63]
	v_mfma_f32_16x16x32_bf16 v[146:149], v[52:55], v[40:43], v[76:79]
	v_mfma_f32_16x16x32_bf16 v[150:153], v[52:55], v[44:47], v[80:83]
	v_mfma_f32_16x16x32_bf16 v[154:157], v[52:55], v[114:117], v[56:59]
	global_load_dwordx4 v[52:55], v[88:89], off offset:1152
	global_load_dwordx4 v[158:161], v[88:89], off offset:1216
	global_load_dwordx4 v[68:71], v[24:25], off offset:1280
	global_load_dwordx4 v[56:59], v[24:25], off offset:1216
	s_waitcnt vmcnt(0) lgkmcnt(0)
	v_mfma_f32_16x16x32_bf16 v[162:165], v[52:55], v[40:43], v[4:7]
	s_nop 2
	global_load_dwordx4 v[4:7], v[26:27], off offset:1216
	v_mfma_f32_16x16x32_bf16 v[106:109], v[52:55], v[106:109], v[0:3]
	v_mfma_f32_16x16x32_bf16 v[12:15], v[52:55], v[44:47], v[12:15]
	s_nop 1
	global_load_dwordx4 v[0:3], v[26:27], off offset:1280
	v_mfma_f32_16x16x32_bf16 v[32:35], v[52:55], v[114:117], v[32:35]
	s_waitcnt vmcnt(0) lgkmcnt(0)
	v_mfma_f32_16x16x32_bf16 v[28:31], v[56:59], v[4:7], v[28:31]
	v_mfma_f32_16x16x32_bf16 v[80:83], v[56:59], v[98:101], v[36:39]
	v_mfma_f32_16x16x32_bf16 v[76:79], v[56:59], v[110:113], v[48:51]
	v_mfma_f32_16x16x32_bf16 v[72:75], v[56:59], v[118:121], v[8:11]
	v_mfma_f32_16x16x32_bf16 v[52:55], v[122:125], v[4:7], v[64:67]
	v_mfma_f32_16x16x32_bf16 v[56:59], v[122:125], v[98:101], v[130:133]
	v_mfma_f32_16x16x32_bf16 v[60:63], v[122:125], v[110:113], v[134:137]
	v_mfma_f32_16x16x32_bf16 v[64:67], v[122:125], v[118:121], v[102:105]
	v_mfma_f32_16x16x32_bf16 v[40:43], v[138:141], v[4:7], v[142:145]
	v_mfma_f32_16x16x32_bf16 v[44:47], v[138:141], v[98:101], v[146:149]
	v_mfma_f32_16x16x32_bf16 v[48:51], v[138:141], v[110:113], v[150:153]
	v_mfma_f32_16x16x32_bf16 v[4:7], v[158:161], v[4:7], v[106:109]
	v_mfma_f32_16x16x32_bf16 v[8:11], v[158:161], v[98:101], v[162:165]
	v_mfma_f32_16x16x32_bf16 v[12:15], v[158:161], v[110:113], v[12:15]
	v_mfma_f32_16x16x32_bf16 v[24:27], v[158:161], v[118:121], v[32:35]
	s_nop 2
	global_load_dwordx4 v[32:35], v[86:87], off offset:1280
	global_load_dwordx4 v[98:101], v[86:87], off offset:1344
	global_load_dwordx4 v[102:105], v[84:85], off offset:1280
	s_nop 0
	global_load_dwordx4 v[84:87], v[84:85], off offset:1344
	s_nop 0
	global_load_dwordx4 v[106:109], v[92:93], off offset:1280
	global_load_dwordx4 v[110:113], v[92:93], off offset:1344
	v_mfma_f32_16x16x32_bf16 v[28:31], v[68:71], v[0:3], v[28:31]
	s_waitcnt vmcnt(0) lgkmcnt(0)
	v_mfma_f32_16x16x32_bf16 v[80:83], v[68:71], v[32:35], v[80:83]
	v_mfma_f32_16x16x32_bf16 v[76:79], v[68:71], v[102:105], v[76:79]
	v_mfma_f32_16x16x32_bf16 v[68:71], v[68:71], v[106:109], v[72:75]
	s_nop 2
	global_load_dwordx4 v[72:75], v[94:95], off offset:1280
	s_nop 0
	global_load_dwordx4 v[92:95], v[94:95], off offset:1344
	s_waitcnt vmcnt(0) lgkmcnt(0)
	v_mfma_f32_16x16x32_bf16 v[52:55], v[72:75], v[0:3], v[52:55]
	v_mfma_f32_16x16x32_bf16 v[56:59], v[72:75], v[32:35], v[56:59]
	v_mfma_f32_16x16x32_bf16 v[60:63], v[72:75], v[102:105], v[60:63]
	v_mfma_f32_16x16x32_bf16 v[64:67], v[72:75], v[106:109], v[64:67]
	global_load_dwordx4 v[72:75], v[90:91], off offset:1280
	global_load_dwordx4 v[114:117], v[90:91], off offset:1344
	v_mfma_f32_16x16x32_bf16 v[36:39], v[138:141], v[118:121], v[154:157]
	global_load_dwordx4 v[118:121], v[88:89], off offset:1280
	s_waitcnt vmcnt(0) lgkmcnt(0)
	v_mfma_f32_16x16x32_bf16 v[40:43], v[72:75], v[0:3], v[40:43]
	v_mfma_f32_16x16x32_bf16 v[44:47], v[72:75], v[32:35], v[44:47]
	v_mfma_f32_16x16x32_bf16 v[48:51], v[72:75], v[102:105], v[48:51]
	v_mfma_f32_16x16x32_bf16 v[36:39], v[72:75], v[106:109], v[36:39]
	global_load_dwordx4 v[72:75], v[88:89], off offset:1344
	v_mfma_f32_16x16x32_bf16 v[4:7], v[118:121], v[0:3], v[4:7]
	v_bfe_u32 v2, v97, 4, 2
	v_lshlrev_b32_e32 v1, 2, v2
	v_lshl_or_b32 v1, s6, 4, v1
	v_mfma_f32_16x16x32_bf16 v[8:11], v[118:121], v[32:35], v[8:11]
	v_mfma_f32_16x16x32_bf16 v[12:15], v[118:121], v[102:105], v[12:15]
	v_mfma_f32_16x16x32_bf16 v[28:31], v[20:23], v[16:19], v[28:31]
	v_mfma_f32_16x16x32_bf16 v[32:35], v[20:23], v[98:101], v[80:83]
	v_mfma_f32_16x16x32_bf16 v[76:79], v[20:23], v[84:87], v[76:79]
	v_mfma_f32_16x16x32_bf16 v[20:23], v[20:23], v[110:113], v[68:71]
	s_nop 2
	v_and_b32_e32 v68, 63, v97
	v_mfma_f32_16x16x32_bf16 v[24:27], v[118:121], v[106:109], v[24:27]
	v_lshl_add_u32 v3, v68, 4, 0
	v_lshl_add_u32 v0, s5, 14, v3
	ds_write_b128 v0, v[28:31]
	ds_write_b128 v0, v[32:35] offset:1024
	ds_write_b128 v0, v[76:79] offset:2048
	v_mfma_f32_16x16x32_bf16 v[60:63], v[92:95], v[84:87], v[60:63]
	s_lshl_b32 s5, s7, 4
	s_addk_i32 s5, 0x4000
	v_mfma_f32_16x16x32_bf16 v[44:47], v[114:117], v[98:101], v[44:47]
	s_waitcnt vmcnt(0) lgkmcnt(0)
	v_mfma_f32_16x16x32_bf16 v[4:7], v[72:75], v[16:19], v[4:7]
	v_mfma_f32_16x16x32_bf16 v[52:55], v[92:95], v[16:19], v[52:55]
	v_mfma_f32_16x16x32_bf16 v[64:67], v[92:95], v[110:113], v[64:67]
	v_mfma_f32_16x16x32_bf16 v[48:51], v[114:117], v[84:87], v[48:51]
	v_mfma_f32_16x16x32_bf16 v[8:11], v[72:75], v[98:101], v[8:11]
	v_mfma_f32_16x16x32_bf16 v[56:59], v[92:95], v[98:101], v[56:59]
	ds_write_b128 v0, v[20:23] offset:3072
	s_nop 2
	ds_write_b128 v0, v[52:55] offset:4096
	s_nop 2
	ds_write_b128 v0, v[56:59] offset:5120
	v_mfma_f32_16x16x32_bf16 v[40:43], v[114:117], v[16:19], v[40:43]
	ds_write_b128 v0, v[60:63] offset:6144
	ds_write_b128 v0, v[64:67] offset:7168
	s_nop 5
	ds_write_b128 v0, v[40:43] offset:8192
	v_mfma_f32_16x16x32_bf16 v[28:31], v[114:117], v[110:113], v[36:39]
	ds_write_b128 v0, v[44:47] offset:9216
	ds_write_b128 v0, v[48:51] offset:10240
	s_nop 5
	ds_write_b128 v0, v[28:31] offset:11264
	v_mfma_f32_16x16x32_bf16 v[12:15], v[72:75], v[84:87], v[12:15]
	ds_write_b128 v0, v[4:7] offset:12288
	ds_write_b128 v0, v[8:11] offset:13312
	s_nop 5
	ds_write_b128 v0, v[12:15] offset:14336
	v_mfma_f32_16x16x32_bf16 v[4:7], v[72:75], v[110:113], v[24:27]
	s_nop 7
	ds_write_b128 v0, v[4:7] offset:15360
	v_or_b32_e32 v0, s5, v96
	v_or_b32_e32 v6, s3, v1
	v_ashrrev_i32_e32 v1, 31, v0
	v_lshlrev_b64 v[4:5], 12, v[0:1]
	s_ashr_i32 s5, s4, 31
	v_lshl_add_u64 v[4:5], s[10:11], 0, v[4:5]
	v_lshl_add_u64 v[4:5], s[4:5], 1, v[4:5]
	v_lshlrev_b32_e32 v128, 1, v6
	v_lshl_add_u64 v[16:17], v[4:5], 0, v[128:129]
	s_waitcnt lgkmcnt(0)
	s_barrier
	global_load_dwordx2 v[18:19], v[16:17], off
	global_load_dwordx2 v[20:21], v[16:17], off offset:256
	s_lshl_b32 s3, s6, 2
	s_add_i32 s3, s3, s7
	v_lshl_add_u32 v3, s3, 10, v3
	ds_read_b128 v[4:7], v3
	ds_read_b128 v[8:11], v3 offset:8192
	ds_read_b128 v[12:15], v3 offset:16384
	s_waitcnt lgkmcnt(0)
	v_pk_add_f32 v[22:23], v[6:7], 0 op_sel_hi:[1,0]
	v_pk_add_f32 v[24:25], v[4:5], 0 op_sel_hi:[1,0]
	ds_read_b128 v[4:7], v3 offset:24576
	v_pk_add_f32 v[26:27], v[10:11], 0 op_sel_hi:[1,0]
	v_pk_add_f32 v[28:29], v[8:9], 0 op_sel_hi:[1,0]
	v_pk_add_f32 v[22:23], v[22:23], v[14:15]
	v_pk_add_f32 v[24:25], v[24:25], v[12:13]
	ds_read_b128 v[8:11], v3 offset:32768
	ds_read_b128 v[12:15], v3 offset:40960
	s_waitcnt lgkmcnt(0)
	v_pk_add_f32 v[26:27], v[26:27], v[6:7]
	v_pk_add_f32 v[28:29], v[28:29], v[4:5]
	ds_read_b128 v[4:7], v3 offset:49152
	v_pk_add_f32 v[22:23], v[22:23], v[10:11]
	v_pk_add_f32 v[24:25], v[24:25], v[8:9]
	v_pk_add_f32 v[28:29], v[28:29], v[12:13]
	ds_read_b128 v[8:11], v3 offset:57344
	v_add_u32_e32 v12, 0x12000, v3
	v_pk_add_f32 v[26:27], v[26:27], v[14:15]
	s_waitcnt lgkmcnt(0)
	v_pk_add_f32 v[24:25], v[24:25], v[4:5]
	v_add_u32_e32 v4, 0x10000, v3
	ds_read_b128 v[12:15], v12
	v_pk_add_f32 v[22:23], v[22:23], v[6:7]
	ds_read_b128 v[4:7], v4
	v_pk_add_f32 v[8:9], v[28:29], v[8:9]
	v_pk_add_f32 v[10:11], v[26:27], v[10:11]
	s_waitcnt lgkmcnt(0)
	v_pk_add_f32 v[28:29], v[8:9], v[12:13]
	v_add_u32_e32 v8, 0x16000, v3
	v_pk_add_f32 v[26:27], v[10:11], v[14:15]
	ds_read_b128 v[8:11], v8
	v_pk_add_f32 v[24:25], v[24:25], v[4:5]
	v_add_u32_e32 v4, 0x14000, v3
	v_pk_add_f32 v[22:23], v[22:23], v[6:7]
	ds_read_b128 v[4:7], v4
	v_add_u32_e32 v12, 0x18000, v3
	ds_read_b128 v[12:15], v12
	s_waitcnt lgkmcnt(0)
	v_pk_add_f32 v[28:29], v[28:29], v[8:9]
	v_add_u32_e32 v8, 0x1c000, v3
	v_pk_add_f32 v[26:27], v[26:27], v[10:11]
	ds_read_b128 v[8:11], v8
	v_pk_add_f32 v[24:25], v[24:25], v[4:5]
	v_add_u32_e32 v4, 0x1a000, v3
	v_pk_add_f32 v[22:23], v[22:23], v[6:7]
	ds_read_b128 v[4:7], v4
	v_add_u32_e32 v3, 0x1e000, v3
	v_pk_add_f32 v[22:23], v[22:23], v[14:15]
	v_pk_add_f32 v[24:25], v[24:25], v[12:13]
	ds_read_b128 v[12:15], v3
	s_waitcnt lgkmcnt(0)
	v_pk_add_f32 v[4:5], v[28:29], v[4:5]
	v_pk_add_f32 v[8:9], v[24:25], v[8:9]
	v_pk_add_f32 v[6:7], v[26:27], v[6:7]
	v_pk_add_f32 v[10:11], v[22:23], v[10:11]
	v_pk_add_f32 v[4:5], v[4:5], v[12:13]
	v_pk_add_f32 v[6:7], v[6:7], v[14:15]
	s_waitcnt vmcnt(0)
	v_lshlrev_b32_e32 v12, 16, v18
	v_and_b32_e32 v13, 0xffff0000, v18
	v_pk_add_f32 v[8:9], v[8:9], v[12:13]
	v_lshlrev_b32_e32 v12, 16, v20
	v_and_b32_e32 v13, 0xffff0000, v20
	v_lshlrev_b32_e32 v14, 16, v19
	v_and_b32_e32 v15, 0xffff0000, v19
	v_pk_add_f32 v[4:5], v[4:5], v[12:13]
	v_pk_add_f32 v[10:11], v[10:11], v[14:15]
	v_lshlrev_b32_e32 v14, 16, v21
	v_and_b32_e32 v15, 0xffff0000, v21
	v_mul_f32_e32 v3, v4, v4
	v_mul_f32_e32 v12, v5, v5
	v_pk_add_f32 v[6:7], v[6:7], v[14:15]
	v_fmac_f32_e32 v3, v8, v8
	v_fmac_f32_e32 v12, v9, v9
	v_add_f32_e32 v3, v3, v12
	v_mul_f32_e32 v12, v6, v6
	v_fmac_f32_e32 v12, v10, v10
	v_add_f32_e32 v3, v12, v3
	v_mul_f32_e32 v12, v7, v7
	v_fmac_f32_e32 v12, v11, v11
	v_and_b32_e32 v13, 64, v214
	v_add_f32_e32 v3, v12, v3
	v_xor_b32_e32 v12, 16, v214
	v_add_u32_e32 v13, 64, v13
	v_cmp_lt_i32_e32 vcc, v12, v13
	v_cvt_pk_bf16_f32 v8, v8, v9
	v_cvt_pk_bf16_f32 v9, v10, v11
	v_xor_b32_e32 v10, 32, v214
	global_store_dwordx2 v[16:17], v[8:9], off
	v_cndmask_b32_e32 v12, v214, v12, vcc
	v_lshlrev_b32_e32 v12, 2, v12
	ds_bpermute_b32 v12, v12, v3
	v_cmp_lt_i32_e32 vcc, v10, v13
	v_cvt_pk_bf16_f32 v4, v4, v5
	v_cvt_pk_bf16_f32 v5, v6, v7
	global_store_dwordx2 v[16:17], v[4:5], off offset:256
	s_waitcnt lgkmcnt(0)
	v_add_f32_e32 v3, v3, v12
	v_cndmask_b32_e32 v10, v214, v10, vcc
	v_lshlrev_b32_e32 v10, 2, v10
	ds_bpermute_b32 v10, v10, v3
	v_cmp_gt_u32_e32 vcc, 16, v68
	s_waitcnt lgkmcnt(0)
	v_add_f32_e32 v3, v3, v10
	s_and_saveexec_b64 s[4:5], vcc
	s_and_b32 s3, s1, 0xffffffc0
	s_add_i32 s3, s3, 0
	v_lshl_add_u32 v4, v96, 2, s3
	v_add_u32_e32 v4, 0x20100, v4
	ds_write_b32 v4, v3
	s_or_b64 exec, exec, s[4:5]
	v_or_b32_e32 v2, s6, v2
	v_cmp_eq_u32_e32 vcc, 0, v2
	s_waitcnt lgkmcnt(0)
	s_barrier
	s_and_saveexec_b64 s[4:5], vcc
	s_cbranch_execz .LBB0_1210
	s_andn2_b32 s1, s1, 63
	s_add_i32 s1, s1, 0
	s_add_i32 s1, s1, 0x20100
	v_lshl_add_u32 v2, v96, 2, s1
	ds_read_b32 v2, v2 offset:64
	v_lshlrev_b64 v[0:1], 7, v[0:1]
	v_lshl_add_u64 v[0:1], s[8:9], 0, v[0:1]
	s_ashr_i32 s3, s2, 31
	v_lshl_add_u64 v[0:1], s[2:3], 2, v[0:1]
	s_waitcnt lgkmcnt(0)
	v_add_f32_e32 v2, v3, v2
	global_store_dword v[0:1], v2, off

.LBB0_1282:
	v_lshl_add_u32 v152, s43, 8, v158
	v_or_b32_e32 v154, 16, v152
	v_ashrrev_i32_e32 v155, 31, v154
	v_lshl_or_b32 v150, s44, 8, v160
	v_lshlrev_b64 v[130:131], 12, v[154:155]
	v_ashrrev_i32_e32 v151, 31, v150
	v_lshl_add_u64 v[130:131], s[8:9], 0, v[130:131]
	v_lshl_add_u64 v[134:135], v[150:151], 1, v[130:131]
	global_load_dwordx4 v[130:133], v[134:135], off
	s_nop 0
	global_load_dwordx4 v[134:137], v[134:135], off offset:256
	v_mul_hi_i32 v128, v152, s97
	v_lshrrev_b32_e32 v153, 31, v128
	v_ashrrev_i32_e32 v128, 11, v128
	v_add_u32_e32 v156, v128, v153
	s_movk_i32 s22, 0xeff0
	v_mad_i32_i24 v128, v156, s22, v152
	v_cmp_lt_i32_e32 vcc, 15, v128
	s_and_saveexec_b64 s[22:23], vcc
	s_cbranch_execz .LBB0_1284
	v_ashrrev_i32_e32 v153, 31, v152
	v_lshlrev_b64 v[162:163], 12, v[152:153]
	v_lshl_add_u64 v[162:163], s[8:9], 0, v[162:163]
	v_lshl_add_u64 v[166:167], v[150:151], 1, v[162:163]
	global_load_dwordx4 v[162:165], v[166:167], off offset:256
	s_nop 0
	global_load_dwordx4 v[166:169], v[166:167], off
	v_ashrrev_i32_e32 v157, 31, v156
	v_add_u32_e32 v128, -16, v128
	v_lshlrev_b64 v[156:157], 25, v[156:157]
	v_lshl_add_u64 v[156:157], s[6:7], 0, v[156:157]
	s_waitcnt vmcnt(0) lgkmcnt(0)
	v_lshlrev_b32_e32 v170, 16, v164
	v_and_b32_e32 v171, 0xffff0000, v164
	v_lshlrev_b32_e32 v164, 16, v165
	v_and_b32_e32 v165, 0xffff0000, v165
	v_pk_add_f32 v[118:119], v[118:119], v[164:165]
	v_lshlrev_b32_e32 v164, 16, v162
	v_and_b32_e32 v165, 0xffff0000, v162
	v_lshlrev_b32_e32 v162, 16, v163
	v_and_b32_e32 v163, 0xffff0000, v163
	v_pk_add_f32 v[114:115], v[114:115], v[162:163]
	v_lshlrev_b32_e32 v162, 16, v168
	v_and_b32_e32 v163, 0xffff0000, v168
	v_pk_add_f32 v[124:125], v[124:125], v[162:163]
	v_lshlrev_b32_e32 v162, 16, v166
	v_and_b32_e32 v163, 0xffff0000, v166
	v_pk_add_f32 v[112:113], v[112:113], v[164:165]
	v_lshlrev_b32_e32 v164, 16, v169
	v_and_b32_e32 v165, 0xffff0000, v169
	v_pk_add_f32 v[120:121], v[120:121], v[162:163]
	v_lshlrev_b64 v[162:163], 13, v[128:129]
	v_pk_add_f32 v[126:127], v[126:127], v[164:165]
	v_lshlrev_b32_e32 v164, 16, v167
	v_and_b32_e32 v165, 0xffff0000, v167
	v_lshl_add_u64 v[156:157], v[156:157], 0, v[162:163]
	v_pk_add_f32 v[122:123], v[122:123], v[164:165]
	v_lshl_add_u64 v[156:157], v[150:151], 2, v[156:157]
	v_pk_add_f32 v[116:117], v[116:117], v[170:171]
	global_store_dwordx4 v[156:157], v[120:123], off
	global_store_dwordx4 v[156:157], v[124:127], off offset:16
	global_store_dwordx4 v[156:157], v[112:115], off offset:512
	global_store_dwordx4 v[156:157], v[116:119], off offset:528
.LBB0_1284:
	s_or_b64 exec, exec, s[22:23]
	v_or_b32_e32 v120, 32, v152
	v_ashrrev_i32_e32 v121, 31, v120
	v_lshlrev_b64 v[112:113], 12, v[120:121]
	v_lshl_add_u64 v[112:113], s[8:9], 0, v[112:113]
	v_lshl_add_u64 v[116:117], v[150:151], 1, v[112:113]
	global_load_dwordx4 v[112:115], v[116:117], off
	s_nop 0
	global_load_dwordx4 v[116:119], v[116:117], off offset:256
	v_mul_hi_i32 v121, v154, s97
	v_lshrrev_b32_e32 v122, 31, v121
	v_ashrrev_i32_e32 v121, 11, v121
	v_add_u32_e32 v122, v121, v122
	s_movk_i32 s22, 0xeff0
	v_mad_i32_i24 v121, v122, s22, v154
	v_cmp_lt_i32_e32 vcc, 15, v121
	s_and_saveexec_b64 s[22:23], vcc
	s_cbranch_execz .LBB0_1286
	s_waitcnt vmcnt(0) lgkmcnt(0)
	v_lshlrev_b32_e32 v124, 16, v136
	v_and_b32_e32 v125, 0xffff0000, v136
	v_pk_add_f32 v[100:101], v[100:101], v[124:125]
	v_lshlrev_b32_e32 v124, 16, v134
	v_and_b32_e32 v125, 0xffff0000, v134
	v_lshlrev_b32_e32 v126, 16, v137
	v_and_b32_e32 v127, 0xffff0000, v137
	v_pk_add_f32 v[96:97], v[96:97], v[124:125]
	v_lshlrev_b32_e32 v124, 16, v132
	v_and_b32_e32 v125, 0xffff0000, v132
	v_ashrrev_i32_e32 v123, 31, v122
	v_pk_add_f32 v[102:103], v[102:103], v[126:127]
	v_lshlrev_b32_e32 v126, 16, v135
	v_and_b32_e32 v127, 0xffff0000, v135
	v_pk_add_f32 v[108:109], v[108:109], v[124:125]
	v_lshlrev_b32_e32 v124, 16, v130
	v_and_b32_e32 v125, 0xffff0000, v130
	v_add_u32_e32 v128, -16, v121
	v_lshlrev_b64 v[122:123], 25, v[122:123]
	v_pk_add_f32 v[98:99], v[98:99], v[126:127]
	v_lshlrev_b32_e32 v126, 16, v133
	v_and_b32_e32 v127, 0xffff0000, v133
	v_pk_add_f32 v[104:105], v[104:105], v[124:125]
	v_lshl_add_u64 v[122:123], s[6:7], 0, v[122:123]
	v_lshlrev_b64 v[124:125], 13, v[128:129]
	v_pk_add_f32 v[110:111], v[110:111], v[126:127]
	v_lshlrev_b32_e32 v126, 16, v131
	v_and_b32_e32 v127, 0xffff0000, v131
	v_lshl_add_u64 v[122:123], v[122:123], 0, v[124:125]
	v_pk_add_f32 v[106:107], v[106:107], v[126:127]
	v_lshl_add_u64 v[122:123], v[150:151], 2, v[122:123]
	global_store_dwordx4 v[122:123], v[104:107], off
	global_store_dwordx4 v[122:123], v[108:111], off offset:16
	global_store_dwordx4 v[122:123], v[96:99], off offset:512
	global_store_dwordx4 v[122:123], v[100:103], off offset:528
.LBB0_1286:
	s_or_b64 exec, exec, s[22:23]
	v_or_b32_e32 v104, 48, v152
	v_ashrrev_i32_e32 v105, 31, v104
	v_lshlrev_b64 v[96:97], 12, v[104:105]
	v_lshl_add_u64 v[96:97], s[8:9], 0, v[96:97]
	v_lshl_add_u64 v[100:101], v[150:151], 1, v[96:97]
	global_load_dwordx4 v[96:99], v[100:101], off
	s_nop 0
	global_load_dwordx4 v[100:103], v[100:101], off offset:256
	v_mul_hi_i32 v105, v120, s97
	v_lshrrev_b32_e32 v106, 31, v105
	v_ashrrev_i32_e32 v105, 11, v105
	v_add_u32_e32 v106, v105, v106
	s_movk_i32 s22, 0xeff0
	v_mad_i32_i24 v105, v106, s22, v120
	v_cmp_lt_i32_e32 vcc, 15, v105
	s_and_saveexec_b64 s[22:23], vcc
	s_cbranch_execz .LBB0_1288
	s_waitcnt vmcnt(0) lgkmcnt(0)
	v_lshlrev_b32_e32 v108, 16, v118
	v_and_b32_e32 v109, 0xffff0000, v118
	v_pk_add_f32 v[84:85], v[84:85], v[108:109]
	v_lshlrev_b32_e32 v108, 16, v116
	v_and_b32_e32 v109, 0xffff0000, v116
	v_lshlrev_b32_e32 v110, 16, v119
	v_and_b32_e32 v111, 0xffff0000, v119
	v_pk_add_f32 v[80:81], v[80:81], v[108:109]
	v_lshlrev_b32_e32 v108, 16, v114
	v_and_b32_e32 v109, 0xffff0000, v114
	v_ashrrev_i32_e32 v107, 31, v106
	v_pk_add_f32 v[86:87], v[86:87], v[110:111]
	v_lshlrev_b32_e32 v110, 16, v117
	v_and_b32_e32 v111, 0xffff0000, v117
	v_pk_add_f32 v[92:93], v[92:93], v[108:109]
	v_lshlrev_b32_e32 v108, 16, v112
	v_and_b32_e32 v109, 0xffff0000, v112
	v_add_u32_e32 v128, -16, v105
	v_lshlrev_b64 v[106:107], 25, v[106:107]
	v_pk_add_f32 v[82:83], v[82:83], v[110:111]
	v_lshlrev_b32_e32 v110, 16, v115
	v_and_b32_e32 v111, 0xffff0000, v115
	v_pk_add_f32 v[88:89], v[88:89], v[108:109]
	v_lshl_add_u64 v[106:107], s[6:7], 0, v[106:107]
	v_lshlrev_b64 v[108:109], 13, v[128:129]
	v_pk_add_f32 v[94:95], v[94:95], v[110:111]
	v_lshlrev_b32_e32 v110, 16, v113
	v_and_b32_e32 v111, 0xffff0000, v113
	v_lshl_add_u64 v[106:107], v[106:107], 0, v[108:109]
	v_pk_add_f32 v[90:91], v[90:91], v[110:111]
	v_lshl_add_u64 v[106:107], v[150:151], 2, v[106:107]
	global_store_dwordx4 v[106:107], v[88:91], off
	global_store_dwordx4 v[106:107], v[92:95], off offset:16
	global_store_dwordx4 v[106:107], v[80:83], off offset:512
	global_store_dwordx4 v[106:107], v[84:87], off offset:528
.LBB0_1288:
	s_or_b64 exec, exec, s[22:23]
	v_add_u32_e32 v88, 0x80, v152
	v_ashrrev_i32_e32 v89, 31, v88
	v_lshlrev_b64 v[80:81], 12, v[88:89]
	v_lshl_add_u64 v[80:81], s[8:9], 0, v[80:81]
	v_lshl_add_u64 v[84:85], v[150:151], 1, v[80:81]
	global_load_dwordx4 v[80:83], v[84:85], off
	s_nop 0
	global_load_dwordx4 v[84:87], v[84:85], off offset:256
	v_mul_hi_i32 v89, v104, s97
	v_lshrrev_b32_e32 v90, 31, v89
	v_ashrrev_i32_e32 v89, 11, v89
	v_add_u32_e32 v90, v89, v90
	s_movk_i32 s22, 0xeff0
	v_mad_i32_i24 v89, v90, s22, v104
	v_cmp_lt_i32_e32 vcc, 15, v89
	s_and_saveexec_b64 s[22:23], vcc
	s_cbranch_execz .LBB0_1290
	s_waitcnt vmcnt(0) lgkmcnt(0)
	v_lshlrev_b32_e32 v92, 16, v102
	v_and_b32_e32 v93, 0xffff0000, v102
	v_pk_add_f32 v[68:69], v[68:69], v[92:93]
	v_lshlrev_b32_e32 v92, 16, v100
	v_and_b32_e32 v93, 0xffff0000, v100
	v_lshlrev_b32_e32 v94, 16, v103
	v_and_b32_e32 v95, 0xffff0000, v103
	v_pk_add_f32 v[64:65], v[64:65], v[92:93]
	v_lshlrev_b32_e32 v92, 16, v98
	v_and_b32_e32 v93, 0xffff0000, v98
	v_ashrrev_i32_e32 v91, 31, v90
	v_pk_add_f32 v[70:71], v[70:71], v[94:95]
	v_lshlrev_b32_e32 v94, 16, v101
	v_and_b32_e32 v95, 0xffff0000, v101
	v_pk_add_f32 v[76:77], v[76:77], v[92:93]
	v_lshlrev_b32_e32 v92, 16, v96
	v_and_b32_e32 v93, 0xffff0000, v96
	v_add_u32_e32 v128, -16, v89
	v_lshlrev_b64 v[90:91], 25, v[90:91]
	v_pk_add_f32 v[66:67], v[66:67], v[94:95]
	v_lshlrev_b32_e32 v94, 16, v99
	v_and_b32_e32 v95, 0xffff0000, v99
	v_pk_add_f32 v[72:73], v[72:73], v[92:93]
	v_lshl_add_u64 v[90:91], s[6:7], 0, v[90:91]
	v_lshlrev_b64 v[92:93], 13, v[128:129]
	v_pk_add_f32 v[78:79], v[78:79], v[94:95]
	v_lshlrev_b32_e32 v94, 16, v97
	v_and_b32_e32 v95, 0xffff0000, v97
	v_lshl_add_u64 v[90:91], v[90:91], 0, v[92:93]
	v_pk_add_f32 v[74:75], v[74:75], v[94:95]
	v_lshl_add_u64 v[90:91], v[150:151], 2, v[90:91]
	global_store_dwordx4 v[90:91], v[72:75], off
	global_store_dwordx4 v[90:91], v[76:79], off offset:16
	global_store_dwordx4 v[90:91], v[64:67], off offset:512
	global_store_dwordx4 v[90:91], v[68:71], off offset:528
.LBB0_1290:
	s_or_b64 exec, exec, s[22:23]
	v_or_b32_e32 v72, 16, v88
	v_ashrrev_i32_e32 v73, 31, v72
	v_lshlrev_b64 v[64:65], 12, v[72:73]
	v_lshl_add_u64 v[64:65], s[8:9], 0, v[64:65]
	v_lshl_add_u64 v[68:69], v[150:151], 1, v[64:65]
	global_load_dwordx4 v[64:67], v[68:69], off
	s_nop 0
	global_load_dwordx4 v[68:71], v[68:69], off offset:256
	v_mul_hi_i32 v73, v88, s97
	v_lshrrev_b32_e32 v74, 31, v73
	v_ashrrev_i32_e32 v73, 11, v73
	v_add_u32_e32 v74, v73, v74
	s_movk_i32 s22, 0xeff0
	v_mad_i32_i24 v73, v74, s22, v88
	v_cmp_lt_i32_e32 vcc, 15, v73
	s_and_saveexec_b64 s[22:23], vcc
	s_cbranch_execz .LBB0_1292
	s_waitcnt vmcnt(0) lgkmcnt(0)
	v_lshlrev_b32_e32 v76, 16, v86
	v_and_b32_e32 v77, 0xffff0000, v86
	v_pk_add_f32 v[52:53], v[52:53], v[76:77]
	v_lshlrev_b32_e32 v76, 16, v84
	v_and_b32_e32 v77, 0xffff0000, v84
	v_lshlrev_b32_e32 v78, 16, v87
	v_and_b32_e32 v79, 0xffff0000, v87
	v_pk_add_f32 v[48:49], v[48:49], v[76:77]
	v_lshlrev_b32_e32 v76, 16, v82
	v_and_b32_e32 v77, 0xffff0000, v82
	v_ashrrev_i32_e32 v75, 31, v74
	v_pk_add_f32 v[54:55], v[54:55], v[78:79]
	v_lshlrev_b32_e32 v78, 16, v85
	v_and_b32_e32 v79, 0xffff0000, v85
	v_pk_add_f32 v[60:61], v[60:61], v[76:77]
	v_lshlrev_b32_e32 v76, 16, v80
	v_and_b32_e32 v77, 0xffff0000, v80
	v_add_u32_e32 v128, -16, v73
	v_lshlrev_b64 v[74:75], 25, v[74:75]
	v_pk_add_f32 v[50:51], v[50:51], v[78:79]
	v_lshlrev_b32_e32 v78, 16, v83
	v_and_b32_e32 v79, 0xffff0000, v83
	v_pk_add_f32 v[56:57], v[56:57], v[76:77]
	v_lshl_add_u64 v[74:75], s[6:7], 0, v[74:75]
	v_lshlrev_b64 v[76:77], 13, v[128:129]
	v_pk_add_f32 v[62:63], v[62:63], v[78:79]
	v_lshlrev_b32_e32 v78, 16, v81
	v_and_b32_e32 v79, 0xffff0000, v81
	v_lshl_add_u64 v[74:75], v[74:75], 0, v[76:77]
	v_pk_add_f32 v[58:59], v[58:59], v[78:79]
	v_lshl_add_u64 v[74:75], v[150:151], 2, v[74:75]
	global_store_dwordx4 v[74:75], v[56:59], off
	global_store_dwordx4 v[74:75], v[60:63], off offset:16
	global_store_dwordx4 v[74:75], v[48:51], off offset:512
	global_store_dwordx4 v[74:75], v[52:55], off offset:528
.LBB0_1292:
	s_or_b64 exec, exec, s[22:23]
	v_or_b32_e32 v56, 32, v88
	v_ashrrev_i32_e32 v57, 31, v56
	v_lshlrev_b64 v[48:49], 12, v[56:57]
	v_lshl_add_u64 v[48:49], s[8:9], 0, v[48:49]
	v_lshl_add_u64 v[52:53], v[150:151], 1, v[48:49]
	global_load_dwordx4 v[48:51], v[52:53], off
	s_nop 0
	global_load_dwordx4 v[52:55], v[52:53], off offset:256
	v_mul_hi_i32 v57, v72, s97
	v_lshrrev_b32_e32 v58, 31, v57
	v_ashrrev_i32_e32 v57, 11, v57
	v_add_u32_e32 v58, v57, v58
	s_movk_i32 s22, 0xeff0
	v_mad_i32_i24 v57, v58, s22, v72
	v_cmp_lt_i32_e32 vcc, 15, v57
	s_and_saveexec_b64 s[22:23], vcc
	s_cbranch_execz .LBB0_1294
	s_waitcnt vmcnt(0) lgkmcnt(0)
	v_lshlrev_b32_e32 v60, 16, v70
	v_and_b32_e32 v61, 0xffff0000, v70
	v_pk_add_f32 v[36:37], v[36:37], v[60:61]
	v_lshlrev_b32_e32 v60, 16, v68
	v_and_b32_e32 v61, 0xffff0000, v68
	v_lshlrev_b32_e32 v62, 16, v71
	v_and_b32_e32 v63, 0xffff0000, v71
	v_pk_add_f32 v[32:33], v[32:33], v[60:61]
	v_lshlrev_b32_e32 v60, 16, v66
	v_and_b32_e32 v61, 0xffff0000, v66
	v_ashrrev_i32_e32 v59, 31, v58
	v_pk_add_f32 v[38:39], v[38:39], v[62:63]
	v_lshlrev_b32_e32 v62, 16, v69
	v_and_b32_e32 v63, 0xffff0000, v69
	v_pk_add_f32 v[44:45], v[44:45], v[60:61]
	v_lshlrev_b32_e32 v60, 16, v64
	v_and_b32_e32 v61, 0xffff0000, v64
	v_add_u32_e32 v128, -16, v57
	v_lshlrev_b64 v[58:59], 25, v[58:59]
	v_pk_add_f32 v[34:35], v[34:35], v[62:63]
	v_lshlrev_b32_e32 v62, 16, v67
	v_and_b32_e32 v63, 0xffff0000, v67
	v_pk_add_f32 v[40:41], v[40:41], v[60:61]
	v_lshl_add_u64 v[58:59], s[6:7], 0, v[58:59]
	v_lshlrev_b64 v[60:61], 13, v[128:129]
	v_pk_add_f32 v[46:47], v[46:47], v[62:63]
	v_lshlrev_b32_e32 v62, 16, v65
	v_and_b32_e32 v63, 0xffff0000, v65
	v_lshl_add_u64 v[58:59], v[58:59], 0, v[60:61]
	v_pk_add_f32 v[42:43], v[42:43], v[62:63]
	v_lshl_add_u64 v[58:59], v[150:151], 2, v[58:59]
	global_store_dwordx4 v[58:59], v[40:43], off
	global_store_dwordx4 v[58:59], v[44:47], off offset:16
	global_store_dwordx4 v[58:59], v[32:35], off offset:512
	global_store_dwordx4 v[58:59], v[36:39], off offset:528
.LBB0_1294:
	s_or_b64 exec, exec, s[22:23]
	v_or_b32_e32 v40, 48, v88
	v_ashrrev_i32_e32 v41, 31, v40
	v_lshlrev_b64 v[32:33], 12, v[40:41]
	v_lshl_add_u64 v[32:33], s[8:9], 0, v[32:33]
	v_lshl_add_u64 v[36:37], v[150:151], 1, v[32:33]
	global_load_dwordx4 v[32:35], v[36:37], off
	s_nop 0
	global_load_dwordx4 v[36:39], v[36:37], off offset:256
	v_mul_hi_i32 v41, v56, s97
	v_lshrrev_b32_e32 v42, 31, v41
	v_ashrrev_i32_e32 v41, 11, v41
	v_add_u32_e32 v42, v41, v42
	s_movk_i32 s22, 0xeff0
	v_mad_i32_i24 v41, v42, s22, v56
	v_cmp_lt_i32_e32 vcc, 15, v41
	s_and_saveexec_b64 s[22:23], vcc
	s_cbranch_execz .LBB0_1296
	s_waitcnt vmcnt(0) lgkmcnt(0)
	v_lshlrev_b32_e32 v44, 16, v54
	v_and_b32_e32 v45, 0xffff0000, v54
	v_pk_add_f32 v[20:21], v[20:21], v[44:45]
	v_lshlrev_b32_e32 v44, 16, v52
	v_and_b32_e32 v45, 0xffff0000, v52
	v_lshlrev_b32_e32 v46, 16, v55
	v_and_b32_e32 v47, 0xffff0000, v55
	v_pk_add_f32 v[16:17], v[16:17], v[44:45]
	v_lshlrev_b32_e32 v44, 16, v50
	v_and_b32_e32 v45, 0xffff0000, v50
	v_ashrrev_i32_e32 v43, 31, v42
	v_pk_add_f32 v[22:23], v[22:23], v[46:47]
	v_lshlrev_b32_e32 v46, 16, v53
	v_and_b32_e32 v47, 0xffff0000, v53
	v_pk_add_f32 v[28:29], v[28:29], v[44:45]
	v_lshlrev_b32_e32 v44, 16, v48
	v_and_b32_e32 v45, 0xffff0000, v48
	v_add_u32_e32 v128, -16, v41
	v_lshlrev_b64 v[42:43], 25, v[42:43]
	v_pk_add_f32 v[18:19], v[18:19], v[46:47]
	v_lshlrev_b32_e32 v46, 16, v51
	v_and_b32_e32 v47, 0xffff0000, v51
	v_pk_add_f32 v[24:25], v[24:25], v[44:45]
	v_lshl_add_u64 v[42:43], s[6:7], 0, v[42:43]
	v_lshlrev_b64 v[44:45], 13, v[128:129]
	v_pk_add_f32 v[30:31], v[30:31], v[46:47]
	v_lshlrev_b32_e32 v46, 16, v49
	v_and_b32_e32 v47, 0xffff0000, v49
	v_lshl_add_u64 v[42:43], v[42:43], 0, v[44:45]
	v_pk_add_f32 v[26:27], v[26:27], v[46:47]
	v_lshl_add_u64 v[42:43], v[150:151], 2, v[42:43]
	global_store_dwordx4 v[42:43], v[24:27], off
	global_store_dwordx4 v[42:43], v[28:31], off offset:16
	global_store_dwordx4 v[42:43], v[16:19], off offset:512
	global_store_dwordx4 v[42:43], v[20:23], off offset:528
.LBB0_1296:
	s_or_b64 exec, exec, s[22:23]
	v_mul_hi_i32 v16, v40, s97
	v_lshrrev_b32_e32 v17, 31, v16
	v_ashrrev_i32_e32 v16, 11, v16
	v_add_u32_e32 v16, v16, v17
	s_movk_i32 s22, 0xeff0
	v_mad_i32_i24 v18, v16, s22, v40
	v_cmp_lt_i32_e32 vcc, 15, v18
	s_and_saveexec_b64 s[22:23], vcc
	s_cbranch_execz .LBB0_1298
	s_waitcnt vmcnt(0) lgkmcnt(0)
	v_lshlrev_b32_e32 v20, 16, v38
	v_and_b32_e32 v21, 0xffff0000, v38
	v_lshlrev_b32_e32 v22, 16, v39
	v_and_b32_e32 v23, 0xffff0000, v39
	v_ashrrev_i32_e32 v17, 31, v16
	v_pk_add_f32 v[6:7], v[6:7], v[22:23]
	v_pk_add_f32 v[4:5], v[4:5], v[20:21]
	v_lshlrev_b32_e32 v20, 16, v36
	v_and_b32_e32 v21, 0xffff0000, v36
	v_lshlrev_b32_e32 v22, 16, v37
	v_and_b32_e32 v23, 0xffff0000, v37
	v_add_u32_e32 v128, -16, v18
	v_lshlrev_b64 v[16:17], 25, v[16:17]
	v_pk_add_f32 v[2:3], v[2:3], v[22:23]
	v_pk_add_f32 v[0:1], v[0:1], v[20:21]
	v_lshlrev_b32_e32 v20, 16, v34
	v_and_b32_e32 v21, 0xffff0000, v34
	v_lshlrev_b32_e32 v22, 16, v35
	v_and_b32_e32 v23, 0xffff0000, v35
	v_lshl_add_u64 v[16:17], s[6:7], 0, v[16:17]
	v_lshlrev_b64 v[18:19], 13, v[128:129]
	v_pk_add_f32 v[14:15], v[14:15], v[22:23]
	v_pk_add_f32 v[12:13], v[12:13], v[20:21]
	v_lshlrev_b32_e32 v20, 16, v32
	v_and_b32_e32 v21, 0xffff0000, v32
	v_lshlrev_b32_e32 v22, 16, v33
	v_and_b32_e32 v23, 0xffff0000, v33
	v_lshl_add_u64 v[16:17], v[16:17], 0, v[18:19]
	v_pk_add_f32 v[10:11], v[10:11], v[22:23]
	v_pk_add_f32 v[8:9], v[8:9], v[20:21]
	v_lshl_add_u64 v[16:17], v[150:151], 2, v[16:17]
	global_store_dwordx4 v[16:17], v[8:11], off
	global_store_dwordx4 v[16:17], v[12:15], off offset:16
	global_store_dwordx4 v[16:17], v[0:3], off offset:512
	global_store_dwordx4 v[16:17], v[4:7], off offset:528

.LBB0_1302:
	s_waitcnt vmcnt(0) lgkmcnt(0)
	v_mov_b32_e32 v96, v210
	s_mov_b32 s0, s73
	s_cmp_gt_i32 s0, 31
	v_readfirstlane_b32 s1, v96
	s_cbranch_scc1 .LBB0_1304
	v_and_b32_e32 v97, 15, v96
	s_ashr_i32 s3, s1, 6
	v_mul_u32_u24_e32 v0, 0x1600, v97
	v_lshlrev_b32_e32 v128, 1, v0
	s_mul_i32 s4, s3, 0x2c0
	s_lshl_b32 s2, s0, 6
	s_lshl_b32 s0, s0, 5
	v_lshl_add_u64 v[0:1], s[14:15], 0, v[128:129]
	v_and_b32_e32 v128, 48, v96
	s_ashr_i32 s5, s4, 31
	s_and_b32 s0, s0, 0x60
	v_lshl_add_u64 v[0:1], v[0:1], 0, v[128:129]
	s_lshl_b64 s[4:5], s[4:5], 1
	s_and_b32 s2, s2, 0xffffff00
	v_lshl_add_u64 v[28:29], v[0:1], 0, s[4:5]
	v_or_b32_e32 v0, s0, v97
	v_or_b32_e32 v2, s2, v0
	v_mov_b64_e32 v[0:1], s[12:13]
	s_movk_i32 s10, 0x2c00
	v_mad_i64_i32 v[0:1], s[10:11], v2, s10, v[0:1]
	v_lshl_add_u64 v[0:1], v[0:1], 0, v[128:129]
	v_lshl_add_u64 v[24:25], v[0:1], 0, s[4:5]
	s_mov_b32 s4, 0xb000000
	v_add_co_u32_e32 v0, vcc, s4, v28
	s_mov_b32 s4, 0xb02c000
	s_nop 0
	v_addc_co_u32_e32 v1, vcc, 0, v29, vcc
	v_add_co_u32_e32 v86, vcc, s4, v28
	s_mov_b32 s4, 0xb058000
	s_nop 0
	v_addc_co_u32_e32 v87, vcc, 0, v29, vcc
	v_add_co_u32_e32 v84, vcc, s4, v28
	s_mov_b64 s[4:5], 0xb000000
	s_nop 0
	v_addc_co_u32_e32 v85, vcc, 0, v29, vcc
	v_lshl_add_u64 v[26:27], v[28:29], 0, s[4:5]
	s_mov_b32 s4, 0xb084000
	v_add_co_u32_e32 v92, vcc, s4, v28
	s_mov_b32 s4, 0x2c000
	s_nop 0
	v_addc_co_u32_e32 v93, vcc, 0, v29, vcc
	v_add_co_u32_e32 v94, vcc, s4, v24
	s_mov_b32 s4, 0x160000
	s_nop 0
	v_addc_co_u32_e32 v95, vcc, 0, v25, vcc
	global_load_dwordx4 v[8:11], v[24:25], off
	v_add_co_u32_e32 v90, vcc, s4, v24
	s_mov_b32 s4, 0x18c000
	s_nop 0
	v_addc_co_u32_e32 v91, vcc, 0, v25, vcc
	v_add_co_u32_e32 v88, vcc, s4, v24
	global_load_dwordx4 v[0:3], v[0:1], off
	s_nop 0
	v_addc_co_u32_e32 v89, vcc, 0, v25, vcc
	global_load_dwordx4 v[4:7], v[86:87], off
	global_load_dwordx4 v[12:15], v[84:85], off
	global_load_dwordx4 v[20:23], v[24:25], off offset:1344
	global_load_dwordx4 v[16:19], v[26:27], off offset:1344
	global_load_dwordx4 v[34:37], v[86:87], off offset:64
	global_load_dwordx4 v[42:45], v[92:93], off
	global_load_dwordx4 v[46:49], v[84:85], off offset:64
	global_load_dwordx4 v[54:57], v[92:93], off offset:64
	global_load_dwordx4 v[58:61], v[94:95], off
	global_load_dwordx4 v[62:65], v[94:95], off offset:64
	global_load_dwordx4 v[78:81], v[90:91], off
	global_load_dwordx4 v[98:101], v[90:91], off offset:64
	global_load_dwordx4 v[114:117], v[88:89], off
	global_load_dwordx4 v[118:121], v[88:89], off offset:64
	global_load_dwordx4 v[122:125], v[24:25], off offset:64
	global_load_dwordx4 v[134:137], v[24:25], off offset:128
	global_load_dwordx4 v[130:133], v[26:27], off offset:64
	s_ashr_i32 s1, s1, 7
	s_and_b32 s4, s3, 1
	s_mov_b64 s[10:11], -1
	s_waitcnt vmcnt(0) lgkmcnt(0)
	v_mfma_f32_16x16x32_bf16 v[30:33], v[8:11], v[0:3], 0
	v_mfma_f32_16x16x32_bf16 v[38:41], v[8:11], v[4:7], 0
	v_mfma_f32_16x16x32_bf16 v[50:53], v[8:11], v[12:15], 0
	v_mfma_f32_16x16x32_bf16 v[8:11], v[8:11], v[42:45], 0
	v_mfma_f32_16x16x32_bf16 v[66:69], v[58:61], v[0:3], 0
	v_mfma_f32_16x16x32_bf16 v[70:73], v[58:61], v[4:7], 0
	v_mfma_f32_16x16x32_bf16 v[74:77], v[58:61], v[12:15], 0
	v_mfma_f32_16x16x32_bf16 v[58:61], v[58:61], v[42:45], 0
	v_mfma_f32_16x16x32_bf16 v[102:105], v[78:81], v[0:3], 0
	v_mfma_f32_16x16x32_bf16 v[106:109], v[78:81], v[4:7], 0
	v_mfma_f32_16x16x32_bf16 v[110:113], v[78:81], v[12:15], 0
	v_mfma_f32_16x16x32_bf16 v[78:81], v[78:81], v[42:45], 0
	v_mfma_f32_16x16x32_bf16 v[0:3], v[114:117], v[0:3], 0
	v_mfma_f32_16x16x32_bf16 v[4:7], v[114:117], v[4:7], 0
	v_mfma_f32_16x16x32_bf16 v[12:15], v[114:117], v[12:15], 0
	v_mfma_f32_16x16x32_bf16 v[42:45], v[114:117], v[42:45], 0
	global_load_dwordx4 v[114:117], v[26:27], off offset:128
	v_mfma_f32_16x16x32_bf16 v[28:31], v[122:125], v[130:133], v[30:33]
	v_mfma_f32_16x16x32_bf16 v[38:41], v[122:125], v[34:37], v[38:41]
	v_mfma_f32_16x16x32_bf16 v[50:53], v[122:125], v[46:49], v[50:53]
	v_mfma_f32_16x16x32_bf16 v[8:11], v[122:125], v[54:57], v[8:11]
	v_mfma_f32_16x16x32_bf16 v[66:69], v[62:65], v[130:133], v[66:69]
	v_mfma_f32_16x16x32_bf16 v[70:73], v[62:65], v[34:37], v[70:73]
	v_mfma_f32_16x16x32_bf16 v[74:77], v[62:65], v[46:49], v[74:77]
	v_mfma_f32_16x16x32_bf16 v[58:61], v[62:65], v[54:57], v[58:61]
	v_mfma_f32_16x16x32_bf16 v[62:65], v[98:101], v[130:133], v[102:105]
	v_mfma_f32_16x16x32_bf16 v[102:105], v[98:101], v[34:37], v[106:109]
	v_mfma_f32_16x16x32_bf16 v[106:109], v[98:101], v[46:49], v[110:113]
	v_mfma_f32_16x16x32_bf16 v[78:81], v[98:101], v[54:57], v[78:81]
	v_mfma_f32_16x16x32_bf16 v[0:3], v[118:121], v[130:133], v[0:3]
	v_mfma_f32_16x16x32_bf16 v[4:7], v[118:121], v[34:37], v[4:7]
	v_mfma_f32_16x16x32_bf16 v[12:15], v[118:121], v[46:49], v[12:15]
	v_mfma_f32_16x16x32_bf16 v[32:35], v[118:121], v[54:57], v[42:45]
	s_nop 2
	global_load_dwordx4 v[42:45], v[86:87], off offset:128
	global_load_dwordx4 v[46:49], v[86:87], off offset:192
	global_load_dwordx4 v[54:57], v[84:85], off offset:128
	global_load_dwordx4 v[98:101], v[84:85], off offset:192
	global_load_dwordx4 v[110:113], v[92:93], off offset:128
	global_load_dwordx4 v[118:121], v[92:93], off offset:192
	global_load_dwordx4 v[122:125], v[94:95], off offset:128
	global_load_dwordx4 v[130:133], v[94:95], off offset:192
	s_waitcnt vmcnt(0) lgkmcnt(0)
	v_mfma_f32_16x16x32_bf16 v[28:31], v[134:137], v[114:117], v[28:31]
	v_mfma_f32_16x16x32_bf16 v[36:39], v[134:137], v[42:45], v[38:41]
	v_mfma_f32_16x16x32_bf16 v[50:53], v[134:137], v[54:57], v[50:53]
	v_mfma_f32_16x16x32_bf16 v[8:11], v[134:137], v[110:113], v[8:11]
	v_mfma_f32_16x16x32_bf16 v[66:69], v[122:125], v[114:117], v[66:69]
	v_mfma_f32_16x16x32_bf16 v[70:73], v[122:125], v[42:45], v[70:73]
	v_mfma_f32_16x16x32_bf16 v[74:77], v[122:125], v[54:57], v[74:77]
	v_mfma_f32_16x16x32_bf16 v[58:61], v[122:125], v[110:113], v[58:61]
	global_load_dwordx4 v[122:125], v[90:91], off offset:128
	global_load_dwordx4 v[134:137], v[90:91], off offset:192
	s_waitcnt vmcnt(0) lgkmcnt(0)
	v_mfma_f32_16x16x32_bf16 v[62:65], v[122:125], v[114:117], v[62:65]
	v_mfma_f32_16x16x32_bf16 v[102:105], v[122:125], v[42:45], v[102:105]
	v_mfma_f32_16x16x32_bf16 v[106:109], v[122:125], v[54:57], v[106:109]
	v_mfma_f32_16x16x32_bf16 v[78:81], v[122:125], v[110:113], v[78:81]
	global_load_dwordx4 v[122:125], v[88:89], off offset:128
	global_load_dwordx4 v[138:141], v[88:89], off offset:192
	s_waitcnt vmcnt(0) lgkmcnt(0)
	v_mfma_f32_16x16x32_bf16 v[0:3], v[122:125], v[114:117], v[0:3]
	global_load_dwordx4 v[114:117], v[24:25], off offset:192
	v_mfma_f32_16x16x32_bf16 v[4:7], v[122:125], v[42:45], v[4:7]
	global_load_dwordx4 v[40:43], v[26:27], off offset:192
	v_mfma_f32_16x16x32_bf16 v[12:15], v[122:125], v[54:57], v[12:15]
	global_load_dwordx4 v[54:57], v[24:25], off offset:256
	v_mfma_f32_16x16x32_bf16 v[32:35], v[122:125], v[110:113], v[32:35]
	global_load_dwordx4 v[110:113], v[26:27], off offset:256
	s_waitcnt vmcnt(0) lgkmcnt(0)
	v_mfma_f32_16x16x32_bf16 v[28:31], v[114:117], v[40:43], v[28:31]
	v_mfma_f32_16x16x32_bf16 v[36:39], v[114:117], v[46:49], v[36:39]
	v_mfma_f32_16x16x32_bf16 v[50:53], v[114:117], v[98:101], v[50:53]
	v_mfma_f32_16x16x32_bf16 v[8:11], v[114:117], v[118:121], v[8:11]
	v_mfma_f32_16x16x32_bf16 v[66:69], v[130:133], v[40:43], v[66:69]
	v_mfma_f32_16x16x32_bf16 v[70:73], v[130:133], v[46:49], v[70:73]
	v_mfma_f32_16x16x32_bf16 v[74:77], v[130:133], v[98:101], v[74:77]
	v_mfma_f32_16x16x32_bf16 v[58:61], v[130:133], v[118:121], v[58:61]
	v_mfma_f32_16x16x32_bf16 v[62:65], v[134:137], v[40:43], v[62:65]
	v_mfma_f32_16x16x32_bf16 v[102:105], v[134:137], v[46:49], v[102:105]
	v_mfma_f32_16x16x32_bf16 v[106:109], v[134:137], v[98:101], v[106:109]
	v_mfma_f32_16x16x32_bf16 v[78:81], v[134:137], v[118:121], v[78:81]
	v_mfma_f32_16x16x32_bf16 v[0:3], v[138:141], v[40:43], v[0:3]
	v_mfma_f32_16x16x32_bf16 v[4:7], v[138:141], v[46:49], v[4:7]
	global_load_dwordx4 v[40:43], v[86:87], off offset:256
	global_load_dwordx4 v[44:47], v[86:87], off offset:320
	v_mfma_f32_16x16x32_bf16 v[12:15], v[138:141], v[98:101], v[12:15]
	global_load_dwordx4 v[98:101], v[84:85], off offset:256
	global_load_dwordx4 v[114:117], v[84:85], off offset:320
	v_mfma_f32_16x16x32_bf16 v[32:35], v[138:141], v[118:121], v[32:35]
	global_load_dwordx4 v[118:121], v[92:93], off offset:256
	global_load_dwordx4 v[122:125], v[92:93], off offset:320
	v_mfma_f32_16x16x32_bf16 v[28:31], v[54:57], v[110:113], v[28:31]
	s_waitcnt vmcnt(0) lgkmcnt(0)
	v_mfma_f32_16x16x32_bf16 v[36:39], v[54:57], v[40:43], v[36:39]
	v_mfma_f32_16x16x32_bf16 v[48:51], v[54:57], v[98:101], v[50:53]
	v_mfma_f32_16x16x32_bf16 v[8:11], v[54:57], v[118:121], v[8:11]
	s_nop 1
	global_load_dwordx4 v[52:55], v[94:95], off offset:256
	global_load_dwordx4 v[130:133], v[94:95], off offset:320
	s_waitcnt vmcnt(0) lgkmcnt(0)
	v_mfma_f32_16x16x32_bf16 v[66:69], v[52:55], v[110:113], v[66:69]
	v_mfma_f32_16x16x32_bf16 v[70:73], v[52:55], v[40:43], v[70:73]
	v_mfma_f32_16x16x32_bf16 v[74:77], v[52:55], v[98:101], v[74:77]
	v_mfma_f32_16x16x32_bf16 v[52:55], v[52:55], v[118:121], v[58:61]
	s_nop 2
	global_load_dwordx4 v[56:59], v[90:91], off offset:256
	global_load_dwordx4 v[134:137], v[90:91], off offset:320
	s_waitcnt vmcnt(0) lgkmcnt(0)
	v_mfma_f32_16x16x32_bf16 v[60:63], v[56:59], v[110:113], v[62:65]
	v_mfma_f32_16x16x32_bf16 v[102:105], v[56:59], v[40:43], v[102:105]
	v_mfma_f32_16x16x32_bf16 v[106:109], v[56:59], v[98:101], v[106:109]
	v_mfma_f32_16x16x32_bf16 v[56:59], v[56:59], v[118:121], v[78:81]
	s_nop 2
	global_load_dwordx4 v[78:81], v[88:89], off offset:256
	global_load_dwordx4 v[138:141], v[88:89], off offset:320
	s_waitcnt vmcnt(0) lgkmcnt(0)
	v_mfma_f32_16x16x32_bf16 v[0:3], v[78:81], v[110:113], v[0:3]
	global_load_dwordx4 v[110:113], v[24:25], off offset:320
	v_mfma_f32_16x16x32_bf16 v[4:7], v[78:81], v[40:43], v[4:7]
	global_load_dwordx4 v[40:43], v[26:27], off offset:320
	v_mfma_f32_16x16x32_bf16 v[12:15], v[78:81], v[98:101], v[12:15]
	global_load_dwordx4 v[98:101], v[24:25], off offset:384
	v_mfma_f32_16x16x32_bf16 v[32:35], v[78:81], v[118:121], v[32:35]
	global_load_dwordx4 v[78:81], v[26:27], off offset:384
	s_waitcnt vmcnt(0) lgkmcnt(0)
	v_mfma_f32_16x16x32_bf16 v[28:31], v[110:113], v[40:43], v[28:31]
	v_mfma_f32_16x16x32_bf16 v[36:39], v[110:113], v[44:47], v[36:39]
	v_mfma_f32_16x16x32_bf16 v[48:51], v[110:113], v[114:117], v[48:51]
	v_mfma_f32_16x16x32_bf16 v[8:11], v[110:113], v[122:125], v[8:11]
	v_mfma_f32_16x16x32_bf16 v[64:67], v[130:133], v[40:43], v[66:69]
	v_mfma_f32_16x16x32_bf16 v[68:71], v[130:133], v[44:47], v[70:73]
	v_mfma_f32_16x16x32_bf16 v[72:75], v[130:133], v[114:117], v[74:77]
	v_mfma_f32_16x16x32_bf16 v[52:55], v[130:133], v[122:125], v[52:55]
	v_mfma_f32_16x16x32_bf16 v[60:63], v[134:137], v[40:43], v[60:63]
	v_mfma_f32_16x16x32_bf16 v[102:105], v[134:137], v[44:47], v[102:105]
	v_mfma_f32_16x16x32_bf16 v[106:109], v[134:137], v[114:117], v[106:109]
	v_mfma_f32_16x16x32_bf16 v[56:59], v[134:137], v[122:125], v[56:59]
	v_mfma_f32_16x16x32_bf16 v[0:3], v[138:141], v[40:43], v[0:3]
	v_mfma_f32_16x16x32_bf16 v[4:7], v[138:141], v[44:47], v[4:7]
	global_load_dwordx4 v[40:43], v[86:87], off offset:384
	global_load_dwordx4 v[44:47], v[86:87], off offset:448
	v_mfma_f32_16x16x32_bf16 v[12:15], v[138:141], v[114:117], v[12:15]
	global_load_dwordx4 v[110:113], v[84:85], off offset:384
	global_load_dwordx4 v[114:117], v[84:85], off offset:448
	v_mfma_f32_16x16x32_bf16 v[32:35], v[138:141], v[122:125], v[32:35]
	global_load_dwordx4 v[118:121], v[92:93], off offset:384
	global_load_dwordx4 v[122:125], v[92:93], off offset:448
	v_mfma_f32_16x16x32_bf16 v[28:31], v[98:101], v[78:81], v[28:31]
	s_waitcnt vmcnt(0) lgkmcnt(0)
	v_mfma_f32_16x16x32_bf16 v[36:39], v[98:101], v[40:43], v[36:39]
	v_mfma_f32_16x16x32_bf16 v[48:51], v[98:101], v[110:113], v[48:51]
	v_mfma_f32_16x16x32_bf16 v[8:11], v[98:101], v[118:121], v[8:11]
	global_load_dwordx4 v[98:101], v[94:95], off offset:384
	global_load_dwordx4 v[130:133], v[94:95], off offset:448
	s_waitcnt vmcnt(0) lgkmcnt(0)
	v_mfma_f32_16x16x32_bf16 v[64:67], v[98:101], v[78:81], v[64:67]
	v_mfma_f32_16x16x32_bf16 v[68:71], v[98:101], v[40:43], v[68:71]
	v_mfma_f32_16x16x32_bf16 v[72:75], v[98:101], v[110:113], v[72:75]
	v_mfma_f32_16x16x32_bf16 v[52:55], v[98:101], v[118:121], v[52:55]
	global_load_dwordx4 v[98:101], v[90:91], off offset:384
	global_load_dwordx4 v[134:137], v[90:91], off offset:448
	s_waitcnt vmcnt(0) lgkmcnt(0)
	v_mfma_f32_16x16x32_bf16 v[60:63], v[98:101], v[78:81], v[60:63]
	v_mfma_f32_16x16x32_bf16 v[102:105], v[98:101], v[40:43], v[102:105]
	v_mfma_f32_16x16x32_bf16 v[106:109], v[98:101], v[110:113], v[106:109]
	v_mfma_f32_16x16x32_bf16 v[56:59], v[98:101], v[118:121], v[56:59]
	global_load_dwordx4 v[98:101], v[88:89], off offset:384
	global_load_dwordx4 v[138:141], v[88:89], off offset:448
	s_waitcnt vmcnt(0) lgkmcnt(0)
	v_mfma_f32_16x16x32_bf16 v[0:3], v[98:101], v[78:81], v[0:3]
	global_load_dwordx4 v[76:79], v[24:25], off offset:448
	global_load_dwordx4 v[80:83], v[24:25], off offset:512
	v_mfma_f32_16x16x32_bf16 v[4:7], v[98:101], v[40:43], v[4:7]
	global_load_dwordx4 v[40:43], v[26:27], off offset:448
	v_mfma_f32_16x16x32_bf16 v[12:15], v[98:101], v[110:113], v[12:15]
	v_mfma_f32_16x16x32_bf16 v[32:35], v[98:101], v[118:121], v[32:35]
	global_load_dwordx4 v[98:101], v[26:27], off offset:512
	s_waitcnt vmcnt(0) lgkmcnt(0)
	v_mfma_f32_16x16x32_bf16 v[28:31], v[76:79], v[40:43], v[28:31]
	v_mfma_f32_16x16x32_bf16 v[36:39], v[76:79], v[44:47], v[36:39]
	v_mfma_f32_16x16x32_bf16 v[48:51], v[76:79], v[114:117], v[48:51]
	v_mfma_f32_16x16x32_bf16 v[8:11], v[76:79], v[122:125], v[8:11]
	v_mfma_f32_16x16x32_bf16 v[64:67], v[130:133], v[40:43], v[64:67]
	v_mfma_f32_16x16x32_bf16 v[68:71], v[130:133], v[44:47], v[68:71]
	v_mfma_f32_16x16x32_bf16 v[72:75], v[130:133], v[114:117], v[72:75]
	v_mfma_f32_16x16x32_bf16 v[60:63], v[134:137], v[40:43], v[60:63]
	v_mfma_f32_16x16x32_bf16 v[76:79], v[134:137], v[44:47], v[102:105]
	v_mfma_f32_16x16x32_bf16 v[102:105], v[134:137], v[114:117], v[106:109]
	v_mfma_f32_16x16x32_bf16 v[0:3], v[138:141], v[40:43], v[0:3]
	v_mfma_f32_16x16x32_bf16 v[4:7], v[138:141], v[44:47], v[4:7]
	global_load_dwordx4 v[40:43], v[86:87], off offset:512
	global_load_dwordx4 v[44:47], v[86:87], off offset:576
	global_load_dwordx4 v[106:109], v[84:85], off offset:512
	global_load_dwordx4 v[110:113], v[84:85], off offset:576
	v_mfma_f32_16x16x32_bf16 v[12:15], v[138:141], v[114:117], v[12:15]
	global_load_dwordx4 v[114:117], v[92:93], off offset:512
	global_load_dwordx4 v[118:121], v[92:93], off offset:576
	v_mfma_f32_16x16x32_bf16 v[52:55], v[130:133], v[122:125], v[52:55]
	v_mfma_f32_16x16x32_bf16 v[56:59], v[134:137], v[122:125], v[56:59]
	v_mfma_f32_16x16x32_bf16 v[32:35], v[138:141], v[122:125], v[32:35]
	v_mfma_f32_16x16x32_bf16 v[28:31], v[80:83], v[98:101], v[28:31]
	s_waitcnt vmcnt(0) lgkmcnt(0)
	v_mfma_f32_16x16x32_bf16 v[36:39], v[80:83], v[40:43], v[36:39]
	v_mfma_f32_16x16x32_bf16 v[48:51], v[80:83], v[106:109], v[48:51]
	v_mfma_f32_16x16x32_bf16 v[8:11], v[80:83], v[114:117], v[8:11]
	global_load_dwordx4 v[80:83], v[94:95], off offset:512
	global_load_dwordx4 v[122:125], v[94:95], off offset:576
	s_waitcnt vmcnt(0) lgkmcnt(0)
	v_mfma_f32_16x16x32_bf16 v[64:67], v[80:83], v[98:101], v[64:67]
	v_mfma_f32_16x16x32_bf16 v[68:71], v[80:83], v[40:43], v[68:71]
	v_mfma_f32_16x16x32_bf16 v[72:75], v[80:83], v[106:109], v[72:75]
	v_mfma_f32_16x16x32_bf16 v[52:55], v[80:83], v[114:117], v[52:55]
	global_load_dwordx4 v[80:83], v[90:91], off offset:512
	global_load_dwordx4 v[130:133], v[90:91], off offset:576
	s_waitcnt vmcnt(0) lgkmcnt(0)
	v_mfma_f32_16x16x32_bf16 v[60:63], v[80:83], v[98:101], v[60:63]
	v_mfma_f32_16x16x32_bf16 v[76:79], v[80:83], v[40:43], v[76:79]
	v_mfma_f32_16x16x32_bf16 v[102:105], v[80:83], v[106:109], v[102:105]
	v_mfma_f32_16x16x32_bf16 v[56:59], v[80:83], v[114:117], v[56:59]
	global_load_dwordx4 v[80:83], v[88:89], off offset:512
	global_load_dwordx4 v[134:137], v[88:89], off offset:576
	s_waitcnt vmcnt(0) lgkmcnt(0)
	v_mfma_f32_16x16x32_bf16 v[0:3], v[80:83], v[98:101], v[0:3]
	global_load_dwordx4 v[98:101], v[24:25], off offset:576
	v_mfma_f32_16x16x32_bf16 v[4:7], v[80:83], v[40:43], v[4:7]
	global_load_dwordx4 v[40:43], v[26:27], off offset:576
	v_mfma_f32_16x16x32_bf16 v[12:15], v[80:83], v[106:109], v[12:15]
	global_load_dwordx4 v[106:109], v[24:25], off offset:640
	v_mfma_f32_16x16x32_bf16 v[32:35], v[80:83], v[114:117], v[32:35]
	global_load_dwordx4 v[80:83], v[26:27], off offset:640
	s_waitcnt vmcnt(0) lgkmcnt(0)
	v_mfma_f32_16x16x32_bf16 v[28:31], v[98:101], v[40:43], v[28:31]
	v_mfma_f32_16x16x32_bf16 v[36:39], v[98:101], v[44:47], v[36:39]
	v_mfma_f32_16x16x32_bf16 v[48:51], v[98:101], v[110:113], v[48:51]
	v_mfma_f32_16x16x32_bf16 v[8:11], v[98:101], v[118:121], v[8:11]
	v_mfma_f32_16x16x32_bf16 v[64:67], v[122:125], v[40:43], v[64:67]
	v_mfma_f32_16x16x32_bf16 v[68:71], v[122:125], v[44:47], v[68:71]
	v_mfma_f32_16x16x32_bf16 v[72:75], v[122:125], v[110:113], v[72:75]
	v_mfma_f32_16x16x32_bf16 v[52:55], v[122:125], v[118:121], v[52:55]
	v_mfma_f32_16x16x32_bf16 v[60:63], v[130:133], v[40:43], v[60:63]
	v_mfma_f32_16x16x32_bf16 v[76:79], v[130:133], v[44:47], v[76:79]
	v_mfma_f32_16x16x32_bf16 v[98:101], v[130:133], v[110:113], v[102:105]
	v_mfma_f32_16x16x32_bf16 v[56:59], v[130:133], v[118:121], v[56:59]
	v_mfma_f32_16x16x32_bf16 v[0:3], v[134:137], v[40:43], v[0:3]
	v_mfma_f32_16x16x32_bf16 v[4:7], v[134:137], v[44:47], v[4:7]
	global_load_dwordx4 v[40:43], v[86:87], off offset:640
	global_load_dwordx4 v[44:47], v[86:87], off offset:704
	v_mfma_f32_16x16x32_bf16 v[12:15], v[134:137], v[110:113], v[12:15]
	global_load_dwordx4 v[102:105], v[84:85], off offset:640
	global_load_dwordx4 v[110:113], v[84:85], off offset:704
	v_mfma_f32_16x16x32_bf16 v[32:35], v[134:137], v[118:121], v[32:35]
	global_load_dwordx4 v[114:117], v[92:93], off offset:640
	global_load_dwordx4 v[118:121], v[92:93], off offset:704
	v_mfma_f32_16x16x32_bf16 v[28:31], v[106:109], v[80:83], v[28:31]
	s_waitcnt vmcnt(0) lgkmcnt(0)
	v_mfma_f32_16x16x32_bf16 v[36:39], v[106:109], v[40:43], v[36:39]
	v_mfma_f32_16x16x32_bf16 v[48:51], v[106:109], v[102:105], v[48:51]
	v_mfma_f32_16x16x32_bf16 v[8:11], v[106:109], v[114:117], v[8:11]
	global_load_dwordx4 v[106:109], v[94:95], off offset:640
	global_load_dwordx4 v[122:125], v[94:95], off offset:704
	s_waitcnt vmcnt(0) lgkmcnt(0)
	v_mfma_f32_16x16x32_bf16 v[64:67], v[106:109], v[80:83], v[64:67]
	v_mfma_f32_16x16x32_bf16 v[68:71], v[106:109], v[40:43], v[68:71]
	v_mfma_f32_16x16x32_bf16 v[72:75], v[106:109], v[102:105], v[72:75]
	v_mfma_f32_16x16x32_bf16 v[52:55], v[106:109], v[114:117], v[52:55]
	global_load_dwordx4 v[106:109], v[90:91], off offset:640
	global_load_dwordx4 v[130:133], v[90:91], off offset:704
	s_waitcnt vmcnt(0) lgkmcnt(0)
	v_mfma_f32_16x16x32_bf16 v[60:63], v[106:109], v[80:83], v[60:63]
	v_mfma_f32_16x16x32_bf16 v[76:79], v[106:109], v[40:43], v[76:79]
	v_mfma_f32_16x16x32_bf16 v[98:101], v[106:109], v[102:105], v[98:101]
	v_mfma_f32_16x16x32_bf16 v[56:59], v[106:109], v[114:117], v[56:59]
	global_load_dwordx4 v[106:109], v[88:89], off offset:640
	global_load_dwordx4 v[134:137], v[88:89], off offset:704
	s_waitcnt vmcnt(0) lgkmcnt(0)
	v_mfma_f32_16x16x32_bf16 v[0:3], v[106:109], v[80:83], v[0:3]
	global_load_dwordx4 v[80:83], v[24:25], off offset:704
	v_mfma_f32_16x16x32_bf16 v[4:7], v[106:109], v[40:43], v[4:7]
	global_load_dwordx4 v[40:43], v[26:27], off offset:704
	v_mfma_f32_16x16x32_bf16 v[12:15], v[106:109], v[102:105], v[12:15]
	global_load_dwordx4 v[102:105], v[24:25], off offset:768
	v_mfma_f32_16x16x32_bf16 v[32:35], v[106:109], v[114:117], v[32:35]
	global_load_dwordx4 v[106:109], v[26:27], off offset:768
	s_waitcnt vmcnt(0) lgkmcnt(0)
	v_mfma_f32_16x16x32_bf16 v[28:31], v[80:83], v[40:43], v[28:31]
	v_mfma_f32_16x16x32_bf16 v[36:39], v[80:83], v[44:47], v[36:39]
	v_mfma_f32_16x16x32_bf16 v[48:51], v[80:83], v[110:113], v[48:51]
	v_mfma_f32_16x16x32_bf16 v[8:11], v[80:83], v[118:121], v[8:11]
	v_mfma_f32_16x16x32_bf16 v[64:67], v[122:125], v[40:43], v[64:67]
	v_mfma_f32_16x16x32_bf16 v[68:71], v[122:125], v[44:47], v[68:71]
	v_mfma_f32_16x16x32_bf16 v[72:75], v[122:125], v[110:113], v[72:75]
	v_mfma_f32_16x16x32_bf16 v[52:55], v[122:125], v[118:121], v[52:55]
	v_mfma_f32_16x16x32_bf16 v[60:63], v[130:133], v[40:43], v[60:63]
	v_mfma_f32_16x16x32_bf16 v[76:79], v[130:133], v[44:47], v[76:79]
	v_mfma_f32_16x16x32_bf16 v[80:83], v[130:133], v[110:113], v[98:101]
	v_mfma_f32_16x16x32_bf16 v[56:59], v[130:133], v[118:121], v[56:59]
	v_mfma_f32_16x16x32_bf16 v[0:3], v[134:137], v[40:43], v[0:3]
	v_mfma_f32_16x16x32_bf16 v[4:7], v[134:137], v[44:47], v[4:7]
	global_load_dwordx4 v[40:43], v[86:87], off offset:768
	global_load_dwordx4 v[44:47], v[86:87], off offset:832
	v_mfma_f32_16x16x32_bf16 v[12:15], v[134:137], v[110:113], v[12:15]
	global_load_dwordx4 v[98:101], v[84:85], off offset:768
	global_load_dwordx4 v[110:113], v[84:85], off offset:832
	v_mfma_f32_16x16x32_bf16 v[32:35], v[134:137], v[118:121], v[32:35]
	global_load_dwordx4 v[114:117], v[92:93], off offset:768
	global_load_dwordx4 v[118:121], v[92:93], off offset:832
	v_mfma_f32_16x16x32_bf16 v[28:31], v[102:105], v[106:109], v[28:31]
	s_waitcnt vmcnt(0) lgkmcnt(0)
	v_mfma_f32_16x16x32_bf16 v[36:39], v[102:105], v[40:43], v[36:39]
	v_mfma_f32_16x16x32_bf16 v[48:51], v[102:105], v[98:101], v[48:51]
	v_mfma_f32_16x16x32_bf16 v[8:11], v[102:105], v[114:117], v[8:11]
	global_load_dwordx4 v[102:105], v[94:95], off offset:768
	global_load_dwordx4 v[122:125], v[94:95], off offset:832
	s_waitcnt vmcnt(0) lgkmcnt(0)
	v_mfma_f32_16x16x32_bf16 v[64:67], v[102:105], v[106:109], v[64:67]
	v_mfma_f32_16x16x32_bf16 v[68:71], v[102:105], v[40:43], v[68:71]
	v_mfma_f32_16x16x32_bf16 v[72:75], v[102:105], v[98:101], v[72:75]
	v_mfma_f32_16x16x32_bf16 v[52:55], v[102:105], v[114:117], v[52:55]
	global_load_dwordx4 v[102:105], v[90:91], off offset:768
	global_load_dwordx4 v[130:133], v[90:91], off offset:832
	s_waitcnt vmcnt(0) lgkmcnt(0)
	v_mfma_f32_16x16x32_bf16 v[60:63], v[102:105], v[106:109], v[60:63]
	v_mfma_f32_16x16x32_bf16 v[76:79], v[102:105], v[40:43], v[76:79]
	v_mfma_f32_16x16x32_bf16 v[80:83], v[102:105], v[98:101], v[80:83]
	v_mfma_f32_16x16x32_bf16 v[56:59], v[102:105], v[114:117], v[56:59]
	global_load_dwordx4 v[102:105], v[88:89], off offset:768
	global_load_dwordx4 v[134:137], v[88:89], off offset:832
	s_waitcnt vmcnt(0) lgkmcnt(0)
	v_mfma_f32_16x16x32_bf16 v[0:3], v[102:105], v[106:109], v[0:3]
	global_load_dwordx4 v[106:109], v[24:25], off offset:832
	v_mfma_f32_16x16x32_bf16 v[4:7], v[102:105], v[40:43], v[4:7]
	global_load_dwordx4 v[40:43], v[26:27], off offset:832
	v_mfma_f32_16x16x32_bf16 v[12:15], v[102:105], v[98:101], v[12:15]
	global_load_dwordx4 v[98:101], v[24:25], off offset:896
	v_mfma_f32_16x16x32_bf16 v[32:35], v[102:105], v[114:117], v[32:35]
	global_load_dwordx4 v[102:105], v[26:27], off offset:896
	s_waitcnt vmcnt(0) lgkmcnt(0)
	v_mfma_f32_16x16x32_bf16 v[28:31], v[106:109], v[40:43], v[28:31]
	v_mfma_f32_16x16x32_bf16 v[36:39], v[106:109], v[44:47], v[36:39]
	v_mfma_f32_16x16x32_bf16 v[48:51], v[106:109], v[110:113], v[48:51]
	v_mfma_f32_16x16x32_bf16 v[8:11], v[106:109], v[118:121], v[8:11]
	v_mfma_f32_16x16x32_bf16 v[64:67], v[122:125], v[40:43], v[64:67]
	v_mfma_f32_16x16x32_bf16 v[68:71], v[122:125], v[44:47], v[68:71]
	v_mfma_f32_16x16x32_bf16 v[72:75], v[122:125], v[110:113], v[72:75]
	v_mfma_f32_16x16x32_bf16 v[52:55], v[122:125], v[118:121], v[52:55]
	v_mfma_f32_16x16x32_bf16 v[60:63], v[130:133], v[40:43], v[60:63]
	v_mfma_f32_16x16x32_bf16 v[76:79], v[130:133], v[44:47], v[76:79]
	v_mfma_f32_16x16x32_bf16 v[80:83], v[130:133], v[110:113], v[80:83]
	v_mfma_f32_16x16x32_bf16 v[56:59], v[130:133], v[118:121], v[56:59]
	v_mfma_f32_16x16x32_bf16 v[0:3], v[134:137], v[40:43], v[0:3]
	v_mfma_f32_16x16x32_bf16 v[4:7], v[134:137], v[44:47], v[4:7]
	global_load_dwordx4 v[40:43], v[86:87], off offset:896
	global_load_dwordx4 v[44:47], v[86:87], off offset:960
	v_mfma_f32_16x16x32_bf16 v[12:15], v[134:137], v[110:113], v[12:15]
	global_load_dwordx4 v[106:109], v[84:85], off offset:896
	global_load_dwordx4 v[110:113], v[84:85], off offset:960
	v_mfma_f32_16x16x32_bf16 v[32:35], v[134:137], v[118:121], v[32:35]
	global_load_dwordx4 v[114:117], v[92:93], off offset:896
	global_load_dwordx4 v[118:121], v[92:93], off offset:960
	v_mfma_f32_16x16x32_bf16 v[28:31], v[98:101], v[102:105], v[28:31]
	s_waitcnt vmcnt(0) lgkmcnt(0)
	v_mfma_f32_16x16x32_bf16 v[36:39], v[98:101], v[40:43], v[36:39]
	v_mfma_f32_16x16x32_bf16 v[48:51], v[98:101], v[106:109], v[48:51]
	v_mfma_f32_16x16x32_bf16 v[8:11], v[98:101], v[114:117], v[8:11]
	global_load_dwordx4 v[98:101], v[94:95], off offset:896
	global_load_dwordx4 v[122:125], v[94:95], off offset:960
	s_waitcnt vmcnt(0) lgkmcnt(0)
	v_mfma_f32_16x16x32_bf16 v[64:67], v[98:101], v[102:105], v[64:67]
	v_mfma_f32_16x16x32_bf16 v[68:71], v[98:101], v[40:43], v[68:71]
	v_mfma_f32_16x16x32_bf16 v[72:75], v[98:101], v[106:109], v[72:75]
	v_mfma_f32_16x16x32_bf16 v[52:55], v[98:101], v[114:117], v[52:55]
	global_load_dwordx4 v[98:101], v[90:91], off offset:896
	global_load_dwordx4 v[130:133], v[90:91], off offset:960
	s_waitcnt vmcnt(0) lgkmcnt(0)
	v_mfma_f32_16x16x32_bf16 v[60:63], v[98:101], v[102:105], v[60:63]
	v_mfma_f32_16x16x32_bf16 v[76:79], v[98:101], v[40:43], v[76:79]
	v_mfma_f32_16x16x32_bf16 v[80:83], v[98:101], v[106:109], v[80:83]
	v_mfma_f32_16x16x32_bf16 v[56:59], v[98:101], v[114:117], v[56:59]
	global_load_dwordx4 v[98:101], v[88:89], off offset:896
	global_load_dwordx4 v[134:137], v[88:89], off offset:960
	s_waitcnt vmcnt(0) lgkmcnt(0)
	v_mfma_f32_16x16x32_bf16 v[0:3], v[98:101], v[102:105], v[0:3]
	global_load_dwordx4 v[102:105], v[24:25], off offset:960
	v_mfma_f32_16x16x32_bf16 v[4:7], v[98:101], v[40:43], v[4:7]
	global_load_dwordx4 v[40:43], v[26:27], off offset:960
	v_mfma_f32_16x16x32_bf16 v[12:15], v[98:101], v[106:109], v[12:15]
	global_load_dwordx4 v[106:109], v[24:25], off offset:1024
	v_mfma_f32_16x16x32_bf16 v[32:35], v[98:101], v[114:117], v[32:35]
	global_load_dwordx4 v[98:101], v[26:27], off offset:1024
	s_waitcnt vmcnt(0) lgkmcnt(0)
	v_mfma_f32_16x16x32_bf16 v[28:31], v[102:105], v[40:43], v[28:31]
	v_mfma_f32_16x16x32_bf16 v[36:39], v[102:105], v[44:47], v[36:39]
	v_mfma_f32_16x16x32_bf16 v[48:51], v[102:105], v[110:113], v[48:51]
	v_mfma_f32_16x16x32_bf16 v[8:11], v[102:105], v[118:121], v[8:11]
	v_mfma_f32_16x16x32_bf16 v[64:67], v[122:125], v[40:43], v[64:67]
	v_mfma_f32_16x16x32_bf16 v[68:71], v[122:125], v[44:47], v[68:71]
	v_mfma_f32_16x16x32_bf16 v[72:75], v[122:125], v[110:113], v[72:75]
	v_mfma_f32_16x16x32_bf16 v[52:55], v[122:125], v[118:121], v[52:55]
	v_mfma_f32_16x16x32_bf16 v[60:63], v[130:133], v[40:43], v[60:63]
	v_mfma_f32_16x16x32_bf16 v[76:79], v[130:133], v[44:47], v[76:79]
	v_mfma_f32_16x16x32_bf16 v[80:83], v[130:133], v[110:113], v[80:83]
	v_mfma_f32_16x16x32_bf16 v[56:59], v[130:133], v[118:121], v[56:59]
	v_mfma_f32_16x16x32_bf16 v[0:3], v[134:137], v[40:43], v[0:3]
	v_mfma_f32_16x16x32_bf16 v[4:7], v[134:137], v[44:47], v[4:7]
	global_load_dwordx4 v[40:43], v[86:87], off offset:1024
	global_load_dwordx4 v[44:47], v[86:87], off offset:1088
	v_mfma_f32_16x16x32_bf16 v[12:15], v[134:137], v[110:113], v[12:15]
	global_load_dwordx4 v[102:105], v[84:85], off offset:1024
	global_load_dwordx4 v[110:113], v[84:85], off offset:1088
	v_mfma_f32_16x16x32_bf16 v[32:35], v[134:137], v[118:121], v[32:35]
	global_load_dwordx4 v[114:117], v[92:93], off offset:1024
	global_load_dwordx4 v[118:121], v[92:93], off offset:1088
	v_mfma_f32_16x16x32_bf16 v[28:31], v[106:109], v[98:101], v[28:31]
	s_waitcnt vmcnt(0) lgkmcnt(0)
	v_mfma_f32_16x16x32_bf16 v[36:39], v[106:109], v[40:43], v[36:39]
	v_mfma_f32_16x16x32_bf16 v[48:51], v[106:109], v[102:105], v[48:51]
	v_mfma_f32_16x16x32_bf16 v[8:11], v[106:109], v[114:117], v[8:11]
	global_load_dwordx4 v[106:109], v[94:95], off offset:1024
	global_load_dwordx4 v[122:125], v[94:95], off offset:1088
	s_waitcnt vmcnt(0) lgkmcnt(0)
	v_mfma_f32_16x16x32_bf16 v[64:67], v[106:109], v[98:101], v[64:67]
	v_mfma_f32_16x16x32_bf16 v[68:71], v[106:109], v[40:43], v[68:71]
	v_mfma_f32_16x16x32_bf16 v[72:75], v[106:109], v[102:105], v[72:75]
	v_mfma_f32_16x16x32_bf16 v[52:55], v[106:109], v[114:117], v[52:55]
	global_load_dwordx4 v[106:109], v[90:91], off offset:1024
	global_load_dwordx4 v[130:133], v[90:91], off offset:1088
	s_waitcnt vmcnt(0) lgkmcnt(0)
	v_mfma_f32_16x16x32_bf16 v[60:63], v[106:109], v[98:101], v[60:63]
	v_mfma_f32_16x16x32_bf16 v[76:79], v[106:109], v[40:43], v[76:79]
	v_mfma_f32_16x16x32_bf16 v[80:83], v[106:109], v[102:105], v[80:83]
	v_mfma_f32_16x16x32_bf16 v[56:59], v[106:109], v[114:117], v[56:59]
	global_load_dwordx4 v[106:109], v[88:89], off offset:1024
	global_load_dwordx4 v[134:137], v[88:89], off offset:1088
	s_waitcnt vmcnt(0) lgkmcnt(0)
	v_mfma_f32_16x16x32_bf16 v[0:3], v[106:109], v[98:101], v[0:3]
	global_load_dwordx4 v[98:101], v[24:25], off offset:1088
	v_mfma_f32_16x16x32_bf16 v[4:7], v[106:109], v[40:43], v[4:7]
	global_load_dwordx4 v[40:43], v[26:27], off offset:1088
	v_mfma_f32_16x16x32_bf16 v[12:15], v[106:109], v[102:105], v[12:15]
	global_load_dwordx4 v[102:105], v[24:25], off offset:1152
	v_mfma_f32_16x16x32_bf16 v[32:35], v[106:109], v[114:117], v[32:35]
	global_load_dwordx4 v[106:109], v[26:27], off offset:1152
	s_waitcnt vmcnt(0) lgkmcnt(0)
	v_mfma_f32_16x16x32_bf16 v[28:31], v[98:101], v[40:43], v[28:31]
	v_mfma_f32_16x16x32_bf16 v[36:39], v[98:101], v[44:47], v[36:39]
	v_mfma_f32_16x16x32_bf16 v[48:51], v[98:101], v[110:113], v[48:51]
	v_mfma_f32_16x16x32_bf16 v[8:11], v[98:101], v[118:121], v[8:11]
	v_mfma_f32_16x16x32_bf16 v[64:67], v[122:125], v[40:43], v[64:67]
	v_mfma_f32_16x16x32_bf16 v[68:71], v[122:125], v[44:47], v[68:71]
	v_mfma_f32_16x16x32_bf16 v[72:75], v[122:125], v[110:113], v[72:75]
	v_mfma_f32_16x16x32_bf16 v[52:55], v[122:125], v[118:121], v[52:55]
	v_mfma_f32_16x16x32_bf16 v[60:63], v[130:133], v[40:43], v[60:63]
	v_mfma_f32_16x16x32_bf16 v[76:79], v[130:133], v[44:47], v[76:79]
	v_mfma_f32_16x16x32_bf16 v[80:83], v[130:133], v[110:113], v[80:83]
	v_mfma_f32_16x16x32_bf16 v[56:59], v[130:133], v[118:121], v[56:59]
	v_mfma_f32_16x16x32_bf16 v[0:3], v[134:137], v[40:43], v[0:3]
	global_load_dwordx4 v[40:43], v[86:87], off offset:1152
	global_load_dwordx4 v[98:101], v[86:87], off offset:1216
	v_mfma_f32_16x16x32_bf16 v[4:7], v[134:137], v[44:47], v[4:7]
	v_mfma_f32_16x16x32_bf16 v[12:15], v[134:137], v[110:113], v[12:15]
	global_load_dwordx4 v[44:47], v[84:85], off offset:1152
	global_load_dwordx4 v[110:113], v[84:85], off offset:1216
	v_mfma_f32_16x16x32_bf16 v[32:35], v[134:137], v[118:121], v[32:35]
	global_load_dwordx4 v[114:117], v[92:93], off offset:1152
	global_load_dwordx4 v[118:121], v[92:93], off offset:1216
	v_mfma_f32_16x16x32_bf16 v[28:31], v[102:105], v[106:109], v[28:31]
	s_waitcnt vmcnt(0) lgkmcnt(0)
	v_mfma_f32_16x16x32_bf16 v[36:39], v[102:105], v[40:43], v[36:39]
	v_mfma_f32_16x16x32_bf16 v[48:51], v[102:105], v[44:47], v[48:51]
	v_mfma_f32_16x16x32_bf16 v[8:11], v[102:105], v[114:117], v[8:11]
	global_load_dwordx4 v[102:105], v[94:95], off offset:1152
	global_load_dwordx4 v[122:125], v[94:95], off offset:1216
	s_waitcnt vmcnt(0) lgkmcnt(0)
	v_mfma_f32_16x16x32_bf16 v[64:67], v[102:105], v[106:109], v[64:67]
	v_mfma_f32_16x16x32_bf16 v[130:133], v[102:105], v[40:43], v[68:71]
	v_mfma_f32_16x16x32_bf16 v[134:137], v[102:105], v[44:47], v[72:75]
	v_mfma_f32_16x16x32_bf16 v[102:105], v[102:105], v[114:117], v[52:55]
	s_nop 2
	global_load_dwordx4 v[52:55], v[90:91], off offset:1152
	global_load_dwordx4 v[138:141], v[90:91], off offset:1216
	s_waitcnt vmcnt(0) lgkmcnt(0)
	v_mfma_f32_16x16x32_bf16 v[142:145], v[52:55], v[106:109], v[60:63]
	v_mfma_f32_16x16x32_bf16 v[146:149], v[52:55], v[40:43], v[76:79]
	v_mfma_f32_16x16x32_bf16 v[150:153], v[52:55], v[44:47], v[80:83]
	v_mfma_f32_16x16x32_bf16 v[154:157], v[52:55], v[114:117], v[56:59]
	global_load_dwordx4 v[52:55], v[88:89], off offset:1152
	global_load_dwordx4 v[158:161], v[88:89], off offset:1216
	global_load_dwordx4 v[68:71], v[24:25], off offset:1280
	global_load_dwordx4 v[56:59], v[24:25], off offset:1216
	s_waitcnt vmcnt(0) lgkmcnt(0)
	v_mfma_f32_16x16x32_bf16 v[162:165], v[52:55], v[40:43], v[4:7]
	s_nop 2
	global_load_dwordx4 v[4:7], v[26:27], off offset:1216
	v_mfma_f32_16x16x32_bf16 v[106:109], v[52:55], v[106:109], v[0:3]
	v_mfma_f32_16x16x32_bf16 v[12:15], v[52:55], v[44:47], v[12:15]
	s_nop 1
	global_load_dwordx4 v[0:3], v[26:27], off offset:1280
	v_mfma_f32_16x16x32_bf16 v[32:35], v[52:55], v[114:117], v[32:35]
	s_waitcnt vmcnt(0) lgkmcnt(0)
	v_mfma_f32_16x16x32_bf16 v[28:31], v[56:59], v[4:7], v[28:31]
	v_mfma_f32_16x16x32_bf16 v[80:83], v[56:59], v[98:101], v[36:39]
	v_mfma_f32_16x16x32_bf16 v[76:79], v[56:59], v[110:113], v[48:51]
	v_mfma_f32_16x16x32_bf16 v[72:75], v[56:59], v[118:121], v[8:11]
	v_mfma_f32_16x16x32_bf16 v[52:55], v[122:125], v[4:7], v[64:67]
	v_mfma_f32_16x16x32_bf16 v[56:59], v[122:125], v[98:101], v[130:133]
	v_mfma_f32_16x16x32_bf16 v[60:63], v[122:125], v[110:113], v[134:137]
	v_mfma_f32_16x16x32_bf16 v[64:67], v[122:125], v[118:121], v[102:105]
	v_mfma_f32_16x16x32_bf16 v[40:43], v[138:141], v[4:7], v[142:145]
	v_mfma_f32_16x16x32_bf16 v[44:47], v[138:141], v[98:101], v[146:149]
	v_mfma_f32_16x16x32_bf16 v[48:51], v[138:141], v[110:113], v[150:153]
	v_mfma_f32_16x16x32_bf16 v[4:7], v[158:161], v[4:7], v[106:109]
	v_mfma_f32_16x16x32_bf16 v[8:11], v[158:161], v[98:101], v[162:165]
	v_mfma_f32_16x16x32_bf16 v[12:15], v[158:161], v[110:113], v[12:15]
	v_mfma_f32_16x16x32_bf16 v[24:27], v[158:161], v[118:121], v[32:35]
	s_nop 2
	global_load_dwordx4 v[32:35], v[86:87], off offset:1280
	global_load_dwordx4 v[98:101], v[86:87], off offset:1344
	global_load_dwordx4 v[102:105], v[84:85], off offset:1280
	s_nop 0
	global_load_dwordx4 v[84:87], v[84:85], off offset:1344
	s_nop 0
	global_load_dwordx4 v[106:109], v[92:93], off offset:1280
	global_load_dwordx4 v[110:113], v[92:93], off offset:1344
	v_mfma_f32_16x16x32_bf16 v[28:31], v[68:71], v[0:3], v[28:31]
	s_waitcnt vmcnt(0) lgkmcnt(0)
	v_mfma_f32_16x16x32_bf16 v[80:83], v[68:71], v[32:35], v[80:83]
	v_mfma_f32_16x16x32_bf16 v[76:79], v[68:71], v[102:105], v[76:79]
	v_mfma_f32_16x16x32_bf16 v[68:71], v[68:71], v[106:109], v[72:75]
	s_nop 2
	global_load_dwordx4 v[72:75], v[94:95], off offset:1280
	s_nop 0
	global_load_dwordx4 v[92:95], v[94:95], off offset:1344
	s_waitcnt vmcnt(0) lgkmcnt(0)
	v_mfma_f32_16x16x32_bf16 v[52:55], v[72:75], v[0:3], v[52:55]
	v_mfma_f32_16x16x32_bf16 v[56:59], v[72:75], v[32:35], v[56:59]
	v_mfma_f32_16x16x32_bf16 v[60:63], v[72:75], v[102:105], v[60:63]
	v_mfma_f32_16x16x32_bf16 v[64:67], v[72:75], v[106:109], v[64:67]
	global_load_dwordx4 v[72:75], v[90:91], off offset:1280
	global_load_dwordx4 v[114:117], v[90:91], off offset:1344
	v_mfma_f32_16x16x32_bf16 v[36:39], v[138:141], v[118:121], v[154:157]
	global_load_dwordx4 v[118:121], v[88:89], off offset:1280
	s_waitcnt vmcnt(0) lgkmcnt(0)
	v_mfma_f32_16x16x32_bf16 v[40:43], v[72:75], v[0:3], v[40:43]
	v_mfma_f32_16x16x32_bf16 v[44:47], v[72:75], v[32:35], v[44:47]
	v_mfma_f32_16x16x32_bf16 v[48:51], v[72:75], v[102:105], v[48:51]
	v_mfma_f32_16x16x32_bf16 v[36:39], v[72:75], v[106:109], v[36:39]
	global_load_dwordx4 v[72:75], v[88:89], off offset:1344
	v_mfma_f32_16x16x32_bf16 v[0:3], v[118:121], v[0:3], v[4:7]
	v_mfma_f32_16x16x32_bf16 v[4:7], v[118:121], v[32:35], v[8:11]
	v_mfma_f32_16x16x32_bf16 v[8:11], v[118:121], v[102:105], v[12:15]
	v_mfma_f32_16x16x32_bf16 v[12:15], v[118:121], v[106:109], v[24:27]
	v_mfma_f32_16x16x32_bf16 v[24:27], v[20:23], v[16:19], v[28:31]
	v_mfma_f32_16x16x32_bf16 v[28:31], v[20:23], v[98:101], v[80:83]
	v_mfma_f32_16x16x32_bf16 v[32:35], v[20:23], v[84:87], v[76:79]
	v_mfma_f32_16x16x32_bf16 v[20:23], v[20:23], v[110:113], v[68:71]
	s_nop 2
	v_and_b32_e32 v68, 63, v96
	v_mfma_f32_16x16x32_bf16 v[60:63], v[92:95], v[84:87], v[60:63]
	v_lshl_add_u32 v68, v68, 4, 0
	v_lshl_add_u32 v69, s3, 14, v68
	ds_write_b128 v69, v[24:27]
	ds_write_b128 v69, v[28:31] offset:1024
	ds_write_b128 v69, v[32:35] offset:2048
	v_mfma_f32_16x16x32_bf16 v[44:47], v[114:117], v[98:101], v[44:47]
	s_lshl_b32 s3, s1, 4
	s_addk_i32 s3, 0x4000
	s_waitcnt vmcnt(0) lgkmcnt(0)
	v_mfma_f32_16x16x32_bf16 v[0:3], v[72:75], v[16:19], v[0:3]
	v_mfma_f32_16x16x32_bf16 v[52:55], v[92:95], v[16:19], v[52:55]
	v_mfma_f32_16x16x32_bf16 v[64:67], v[92:95], v[110:113], v[64:67]
	v_mfma_f32_16x16x32_bf16 v[48:51], v[114:117], v[84:87], v[48:51]
	v_mfma_f32_16x16x32_bf16 v[4:7], v[72:75], v[98:101], v[4:7]
	v_mfma_f32_16x16x32_bf16 v[56:59], v[92:95], v[98:101], v[56:59]
	ds_write_b128 v69, v[20:23] offset:3072
	s_nop 2
	ds_write_b128 v69, v[52:55] offset:4096
	s_nop 2
	ds_write_b128 v69, v[56:59] offset:5120
	v_mfma_f32_16x16x32_bf16 v[40:43], v[114:117], v[16:19], v[40:43]
	ds_write_b128 v69, v[60:63] offset:6144
	ds_write_b128 v69, v[64:67] offset:7168
	s_nop 5
	ds_write_b128 v69, v[40:43] offset:8192
	v_mfma_f32_16x16x32_bf16 v[24:27], v[114:117], v[110:113], v[36:39]
	ds_write_b128 v69, v[44:47] offset:9216
	ds_write_b128 v69, v[48:51] offset:10240
	s_nop 5
	ds_write_b128 v69, v[24:27] offset:11264
	v_mfma_f32_16x16x32_bf16 v[8:11], v[72:75], v[84:87], v[8:11]
	ds_write_b128 v69, v[0:3] offset:12288
	ds_write_b128 v69, v[4:7] offset:13312
	s_nop 5
	ds_write_b128 v69, v[8:11] offset:14336
	v_mfma_f32_16x16x32_bf16 v[0:3], v[72:75], v[110:113], v[12:15]
	s_nop 2
	v_or_b32_e32 v12, s3, v97
	v_ashrrev_i32_e32 v13, 31, v12
	s_nop 2
	ds_write_b128 v69, v[0:3] offset:15360
	v_lshrrev_b32_e32 v0, 2, v96
	v_and_b32_e32 v0, 12, v0
	v_lshl_or_b32 v0, s4, 4, v0
	v_or_b32_e32 v26, s0, v0
	v_lshlrev_b64 v[0:1], 12, v[12:13]
	s_ashr_i32 s3, s2, 31
	v_lshl_add_u64 v[0:1], s[8:9], 0, v[0:1]
	v_lshl_add_u64 v[0:1], s[2:3], 1, v[0:1]
	v_lshlrev_b32_e32 v128, 1, v26
	v_lshl_add_u64 v[0:1], v[0:1], 0, v[128:129]
	s_waitcnt lgkmcnt(0)
	s_barrier
	global_load_dwordx2 v[14:15], v[0:1], off
	global_load_dwordx2 v[16:17], v[0:1], off offset:256
	s_lshl_b32 s0, s4, 2
	s_add_i32 s0, s0, s1
	v_lshl_add_u32 v13, s0, 10, v68
	ds_read_b128 v[0:3], v13
	ds_read_b128 v[4:7], v13 offset:8192
	ds_read_b128 v[8:11], v13 offset:16384
	v_lshlrev_b32_e32 v128, 2, v26
	s_waitcnt lgkmcnt(0)
	v_pk_add_f32 v[18:19], v[2:3], 0 op_sel_hi:[1,0]
	v_pk_add_f32 v[20:21], v[0:1], 0 op_sel_hi:[1,0]
	ds_read_b128 v[0:3], v13 offset:24576
	v_pk_add_f32 v[18:19], v[18:19], v[10:11]
	v_pk_add_f32 v[20:21], v[20:21], v[8:9]
	ds_read_b128 v[8:11], v13 offset:40960
	v_pk_add_f32 v[22:23], v[6:7], 0 op_sel_hi:[1,0]
	v_pk_add_f32 v[24:25], v[4:5], 0 op_sel_hi:[1,0]
	ds_read_b128 v[4:7], v13 offset:32768
	s_waitcnt lgkmcnt(0)
	v_pk_add_f32 v[22:23], v[22:23], v[2:3]
	v_pk_add_f32 v[24:25], v[24:25], v[0:1]
	ds_read_b128 v[0:3], v13 offset:49152
	v_pk_add_f32 v[24:25], v[24:25], v[8:9]
	v_add_u32_e32 v8, 0x12000, v13
	v_pk_add_f32 v[22:23], v[22:23], v[10:11]
	ds_read_b128 v[8:11], v8
	v_pk_add_f32 v[18:19], v[18:19], v[6:7]
	v_pk_add_f32 v[20:21], v[20:21], v[4:5]
	ds_read_b128 v[4:7], v13 offset:57344
	s_waitcnt lgkmcnt(0)
	v_pk_add_f32 v[20:21], v[20:21], v[0:1]
	v_add_u32_e32 v0, 0x10000, v13
	v_pk_add_f32 v[18:19], v[18:19], v[2:3]
	ds_read_b128 v[0:3], v0
	v_pk_add_f32 v[4:5], v[24:25], v[4:5]
	v_pk_add_f32 v[6:7], v[22:23], v[6:7]
	v_pk_add_f32 v[24:25], v[4:5], v[8:9]
	v_add_u32_e32 v4, 0x16000, v13
	v_pk_add_f32 v[22:23], v[6:7], v[10:11]
	ds_read_b128 v[4:7], v4
	s_waitcnt lgkmcnt(0)
	v_pk_add_f32 v[20:21], v[20:21], v[0:1]
	v_add_u32_e32 v0, 0x14000, v13
	v_pk_add_f32 v[18:19], v[18:19], v[2:3]
	ds_read_b128 v[0:3], v0
	v_add_u32_e32 v8, 0x18000, v13
	ds_read_b128 v[8:11], v8
	v_pk_add_f32 v[24:25], v[24:25], v[4:5]
	v_add_u32_e32 v4, 0x1c000, v13
	v_pk_add_f32 v[22:23], v[22:23], v[6:7]
	ds_read_b128 v[4:7], v4
	s_waitcnt lgkmcnt(0)
	v_pk_add_f32 v[20:21], v[20:21], v[0:1]
	v_add_u32_e32 v0, 0x1a000, v13
	v_pk_add_f32 v[18:19], v[18:19], v[2:3]
	ds_read_b128 v[0:3], v0
	v_pk_add_f32 v[20:21], v[20:21], v[8:9]
	v_add_u32_e32 v8, 0x1e000, v13
	v_pk_add_f32 v[18:19], v[18:19], v[10:11]
	ds_read_b128 v[8:11], v8
	s_waitcnt lgkmcnt(0)
	v_pk_add_f32 v[0:1], v[24:25], v[0:1]
	v_pk_add_f32 v[4:5], v[20:21], v[4:5]
	v_pk_add_f32 v[2:3], v[22:23], v[2:3]
	v_pk_add_f32 v[6:7], v[18:19], v[6:7]
	v_pk_add_f32 v[8:9], v[0:1], v[8:9]
	v_pk_add_f32 v[10:11], v[2:3], v[10:11]
	s_waitcnt vmcnt(0)
	v_lshlrev_b32_e32 v0, 16, v14
	v_and_b32_e32 v1, 0xffff0000, v14
	v_pk_add_f32 v[0:1], v[4:5], v[0:1]
	v_lshlrev_b32_e32 v4, 16, v16
	v_and_b32_e32 v5, 0xffff0000, v16
	v_pk_add_f32 v[4:5], v[8:9], v[4:5]
	v_mul_hi_i32 v8, v12, s97
	v_lshlrev_b32_e32 v2, 16, v15
	v_and_b32_e32 v3, 0xffff0000, v15
	v_lshrrev_b32_e32 v9, 31, v8
	v_ashrrev_i32_e32 v8, 11, v8
	v_pk_add_f32 v[2:3], v[6:7], v[2:3]
	v_lshlrev_b32_e32 v6, 16, v17
	v_and_b32_e32 v7, 0xffff0000, v17
	v_add_u32_e32 v8, v8, v9
	v_pk_add_f32 v[6:7], v[10:11], v[6:7]
	v_mul_i32_i24_e32 v10, 0xffffeff0, v8
	v_ashrrev_i32_e32 v9, 31, v8
	v_add3_u32 v10, v12, v10, -16
	v_ashrrev_i32_e32 v11, 31, v10
	v_lshlrev_b64 v[8:9], 25, v[8:9]
	v_lshl_add_u64 v[8:9], s[6:7], 0, v[8:9]
	v_lshlrev_b64 v[10:11], 13, v[10:11]
	v_lshl_add_u64 v[8:9], v[8:9], 0, v[10:11]
	v_lshl_add_u64 v[8:9], s[2:3], 2, v[8:9]
	v_lshl_add_u64 v[8:9], v[8:9], 0, v[128:129]
	global_store_dwordx4 v[8:9], v[0:3], off
	global_store_dwordx4 v[8:9], v[4:7], off offset:512
	s_waitcnt lgkmcnt(0)
	s_barrier
